# speedup vs baseline: 1.0355x; 1.0126x over previous
.LBB0_59:
	s_mov_b64 s[40:41], 0x80
	s_and_b32 s1, s1, 3
	s_add_i32 m0, s27, 0x18000
	v_lshl_add_u64 v[6:7], v[6:7], 0, s[40:41]
	s_lshl_b32 s7, s3, 13
	s_lshl_b32 s10, s1, 5
	s_lshl_b32 s11, s1, 12
	s_waitcnt vmcnt(2)
	s_barrier
	global_load_lds_dwordx4 v[6:7], off
	v_lshl_add_u64 v[4:5], v[4:5], 0, s[40:41]
	s_add_i32 m0, s27, 0x1a000
	s_add_i32 s58, s27, 0x8000
	s_add_i32 s59, s27, 0xa000
	global_load_lds_dwordx4 v[4:5], off
	v_lshl_add_u64 v[0:1], v[0:1], 0, s[40:41]
	s_mov_b32 m0, s58
	s_add_u32 s8, s34, 0x80080
	global_load_lds_dwordx4 v[0:1], off
	v_lshl_add_u64 v[0:1], v[2:3], 0, s[40:41]
	s_mov_b32 m0, s59
	s_addc_u32 s9, s35, 0
	global_load_lds_dwordx4 v[0:1], off
	s_add_i32 m0, s27, 0x1c000
	s_nop 0
	global_load_lds_dwordx4 v138, s[8:9]
	s_add_i32 m0, s27, 0x1e000
	v_bfe_u32 v2, v8, 4, 2
	global_load_lds_dwordx4 v142, s[8:9]
	v_and_b32_e32 v1, 15, v8
	v_lshlrev_b32_e32 v3, 4, v2
	v_lshl_or_b32 v164, s3, 6, v1
	v_lshl_or_b32 v1, v1, 6, v3
	v_lshlrev_b32_e32 v3, 2, v8
	v_and_b32_e32 v3, 32, v3
	v_bitop3_b32 v4, v1, s7, v3 bitop3:0xde
	v_bitop3_b32 v165, v1, s11, v3 bitop3:0xde
	v_lshlrev_b32_e32 v1, 1, v8
	v_and_b32_e32 v144, 32, v1
	v_lshlrev_b32_e32 v1, 15, v9
	v_and_b32_e32 v1, 0xffff0000, v1
	v_lshlrev_b32_e32 v0, 3, v2
	v_cmp_gt_u32_e64 s[16:17], 2, v2
	v_cmp_eq_u32_e64 s[8:9], 0, v2
	v_lshl_add_u32 v1, v10, 12, v1
	v_and_b32_e32 v2, 1, v9
	v_lshl_or_b32 v1, v2, 6, v1
	s_cmpk_lt_u32 s0, 0x100
	v_lshl_add_u32 v148, v11, 1, v1
	v_lshlrev_b32_e32 v1, 15, v12
	s_cselect_b64 s[48:49], -1, 0
	s_bitcmp0_b32 s0, 6
	v_and_b32_e32 v1, 0xffff0000, v1
	s_waitcnt vmcnt(6)
	s_cselect_b64 s[56:57], -1, 0
	s_cmp_eq_u32 s1, 0
	v_readlane_b32 s0, v249, 33
	v_lshl_add_u32 v1, v13, 12, v1
	v_and_b32_e32 v2, 1, v12
	s_mov_b32 s47, 0
	s_cselect_b64 s[76:77], -1, 0
	v_readlane_b32 s1, v249, 34
	v_lshl_or_b32 v1, v2, 6, v1
	s_add_i32 s78, 0, 0x10000
	s_add_i32 s79, 0, 0x14000
	v_or_b32_e32 v166, 16, v164
	v_or_b32_e32 v167, 32, v164
	v_or_b32_e32 v168, 48, v164
	v_add_u32_e32 v169, 0x80, v164
	v_add_u32_e32 v170, 0x90, v164
	v_add_u32_e32 v171, 0xa0, v164
	v_add_u32_e32 v172, 0xb0, v164
	v_lshl_add_u64 v[146:147], s[0:1], 0, v[144:145]
	v_mov_b32_e32 v149, v145
	v_lshl_add_u32 v150, v14, 1, v1
	v_mov_b32_e32 v151, v145
	v_mov_b64_e32 v[152:153], 0xb80
	v_mov_b64_e32 v[154:155], 0xb7f
	v_add_u32_e32 v173, s78, v165
	v_add_u32_e32 v174, s79, v165
	v_add_u32_e32 v175, 0, v4
	s_movk_i32 s92, 0x5c00
	s_lshl_b32 s46, s10, 1
	v_lshlrev_b32_e32 v156, 1, v0
	v_mov_b32_e32 v176, 0x3e0293ee
	v_mov_b32_e32 v177, 0x3e38aa3b
	s_mov_b32 s68, s47
	s_barrier
	s_branch .LBB0_62

.LBB0_65:
	ds_read_b128 v[128:131], v173
	ds_read_b128 v[132:135], v173 offset:1024
	ds_read_b128 v[158:161], v173 offset:2048
	ds_read_b128 v[178:181], v173 offset:3072
	ds_read_b128 v[182:185], v174
	ds_read_b128 v[186:189], v174 offset:1024
	ds_read_b128 v[190:193], v174 offset:2048
	ds_read_b128 v[194:197], v174 offset:3072
	s_add_u32 s3, s14, 0xfff80080
	s_addc_u32 s34, s15, -1
	s_cmp_eq_u32 s37, 28
	s_cselect_b32 s91, s0, s34
	s_cselect_b32 s90, s1, s3
	s_cselect_b32 s35, s7, s36
	s_cselect_b32 s34, s13, s24
	s_add_i32 m0, s27, 0xc000
	ds_read_b128 v[198:201], v175
	ds_read_b128 v[202:205], v175 offset:1024
	ds_read_b128 v[206:209], v175 offset:2048
	ds_read_b128 v[210:213], v175 offset:3072
	ds_read_b128 v[214:217], v175 offset:4096
	ds_read_b128 v[218:221], v175 offset:5120
	ds_read_b128 v[222:225], v175 offset:6144
	ds_read_b128 v[230:233], v175 offset:7168
	global_load_lds_dwordx4 v148, s[14:15]
	s_add_i32 m0, s27, 0xe000
	s_nop 0
	global_load_lds_dwordx4 v150, s[14:15]
	s_waitcnt vmcnt(8)
	s_waitcnt lgkmcnt(0)
	s_barrier
	s_setprio 1
	s_waitcnt lgkmcnt(0)
	v_mfma_f32_16x16x32_bf16 v[124:127], v[128:131], v[198:201], v[124:127]
	v_mfma_f32_16x16x32_bf16 v[120:123], v[158:161], v[198:201], v[120:123]
	v_mfma_f32_16x16x32_bf16 v[108:111], v[128:131], v[206:209], v[108:111]
	v_mfma_f32_16x16x32_bf16 v[104:107], v[158:161], v[206:209], v[104:107]
	v_mfma_f32_16x16x32_bf16 v[92:95], v[128:131], v[214:217], v[92:95]
	v_mfma_f32_16x16x32_bf16 v[88:91], v[158:161], v[214:217], v[88:91]
	v_mfma_f32_16x16x32_bf16 v[76:79], v[128:131], v[222:225], v[76:79]
	v_mfma_f32_16x16x32_bf16 v[72:75], v[158:161], v[222:225], v[72:75]
	v_mfma_f32_16x16x32_bf16 v[124:127], v[132:135], v[202:205], v[124:127]
	v_mfma_f32_16x16x32_bf16 v[120:123], v[178:181], v[202:205], v[120:123]
	v_mfma_f32_16x16x32_bf16 v[108:111], v[132:135], v[210:213], v[108:111]
	v_mfma_f32_16x16x32_bf16 v[104:107], v[178:181], v[210:213], v[104:107]
	v_mfma_f32_16x16x32_bf16 v[92:95], v[132:135], v[218:221], v[92:95]
	v_mfma_f32_16x16x32_bf16 v[88:91], v[178:181], v[218:221], v[88:91]
	v_mfma_f32_16x16x32_bf16 v[76:79], v[132:135], v[230:233], v[76:79]
	v_mfma_f32_16x16x32_bf16 v[72:75], v[178:181], v[230:233], v[72:75]
	s_setprio 0
	s_setprio 1
	v_mfma_f32_16x16x32_bf16 v[116:119], v[182:185], v[198:201], v[116:119]
	v_mfma_f32_16x16x32_bf16 v[112:115], v[190:193], v[198:201], v[112:115]
	v_mfma_f32_16x16x32_bf16 v[100:103], v[182:185], v[206:209], v[100:103]
	v_mfma_f32_16x16x32_bf16 v[96:99], v[190:193], v[206:209], v[96:99]
	v_mfma_f32_16x16x32_bf16 v[84:87], v[182:185], v[214:217], v[84:87]
	v_mfma_f32_16x16x32_bf16 v[80:83], v[190:193], v[214:217], v[80:83]
	v_mfma_f32_16x16x32_bf16 v[68:71], v[182:185], v[222:225], v[68:71]
	v_mfma_f32_16x16x32_bf16 v[64:67], v[190:193], v[222:225], v[64:67]
	v_mfma_f32_16x16x32_bf16 v[116:119], v[186:189], v[202:205], v[116:119]
	v_mfma_f32_16x16x32_bf16 v[112:115], v[194:197], v[202:205], v[112:115]
	v_mfma_f32_16x16x32_bf16 v[100:103], v[186:189], v[210:213], v[100:103]
	v_mfma_f32_16x16x32_bf16 v[96:99], v[194:197], v[210:213], v[96:99]
	v_mfma_f32_16x16x32_bf16 v[84:87], v[186:189], v[218:221], v[84:87]
	v_mfma_f32_16x16x32_bf16 v[80:83], v[194:197], v[218:221], v[80:83]
	v_mfma_f32_16x16x32_bf16 v[68:71], v[186:189], v[230:233], v[68:71]
	v_mfma_f32_16x16x32_bf16 v[64:67], v[194:197], v[230:233], v[64:67]
	s_setprio 0
	s_barrier
	s_add_i32 s3, s78, s25
	v_lshl_add_u64 v[162:163], s[34:35], 0, v[138:139]
	s_mov_b32 m0, s3
	ds_read_b128 v[198:201], v175 offset:16384
	ds_read_b128 v[202:205], v175 offset:17408
	ds_read_b128 v[206:209], v175 offset:18432
	ds_read_b128 v[210:213], v175 offset:19456
	ds_read_b128 v[214:217], v175 offset:20480
	ds_read_b128 v[218:221], v175 offset:21504
	ds_read_b128 v[222:225], v175 offset:22528
	ds_read_b128 v[230:233], v175 offset:23552
	global_load_lds_dwordx4 v[162:163], off
	s_add_i32 m0, s3, 0x2000
	s_add_u32 s42, s34, 0x80000
	v_lshl_add_u64 v[226:227], s[34:35], 0, v[142:143]
	s_addc_u32 s43, s35, 0
	s_add_i32 s3, s79, s25
	global_load_lds_dwordx4 v[226:227], off
	s_mov_b32 m0, s3
	v_lshl_add_u64 v[236:237], s[90:91], 0, v[140:141]
	global_load_lds_dwordx4 v138, s[42:43]
	s_add_i32 m0, s3, 0x2000
	s_nop 0
	global_load_lds_dwordx4 v142, s[42:43]
	v_lshl_add_u64 v[234:235], s[90:91], 0, v[136:137]
	s_mov_b32 m0, s27
	s_nop 0
	global_load_lds_dwordx4 v[234:235], off
	s_mov_b32 m0, s30
	s_nop 0
	global_load_lds_dwordx4 v[236:237], off
	s_waitcnt vmcnt(8)
	s_waitcnt lgkmcnt(0)
	s_barrier
	s_setprio 1
	s_waitcnt lgkmcnt(0)
	v_mfma_f32_16x16x32_bf16 v[60:63], v[128:131], v[198:201], v[60:63]
	v_mfma_f32_16x16x32_bf16 v[56:59], v[158:161], v[198:201], v[56:59]
	v_mfma_f32_16x16x32_bf16 v[44:47], v[128:131], v[206:209], v[44:47]
	v_mfma_f32_16x16x32_bf16 v[40:43], v[158:161], v[206:209], v[40:43]
	v_mfma_f32_16x16x32_bf16 v[28:31], v[128:131], v[214:217], v[28:31]
	v_mfma_f32_16x16x32_bf16 v[24:27], v[158:161], v[214:217], v[24:27]
	v_mfma_f32_16x16x32_bf16 v[12:15], v[128:131], v[222:225], v[12:15]
	v_mfma_f32_16x16x32_bf16 v[8:11], v[158:161], v[222:225], v[8:11]
	v_mfma_f32_16x16x32_bf16 v[60:63], v[132:135], v[202:205], v[60:63]
	v_mfma_f32_16x16x32_bf16 v[56:59], v[178:181], v[202:205], v[56:59]
	v_mfma_f32_16x16x32_bf16 v[44:47], v[132:135], v[210:213], v[44:47]
	v_mfma_f32_16x16x32_bf16 v[40:43], v[178:181], v[210:213], v[40:43]
	v_mfma_f32_16x16x32_bf16 v[28:31], v[132:135], v[218:221], v[28:31]
	v_mfma_f32_16x16x32_bf16 v[24:27], v[178:181], v[218:221], v[24:27]
	v_mfma_f32_16x16x32_bf16 v[12:15], v[132:135], v[230:233], v[12:15]
	v_mfma_f32_16x16x32_bf16 v[8:11], v[178:181], v[230:233], v[8:11]
	s_setprio 0
	s_setprio 1
	v_mfma_f32_16x16x32_bf16 v[52:55], v[182:185], v[198:201], v[52:55]
	v_mfma_f32_16x16x32_bf16 v[48:51], v[190:193], v[198:201], v[48:51]
	v_mfma_f32_16x16x32_bf16 v[36:39], v[182:185], v[206:209], v[36:39]
	v_mfma_f32_16x16x32_bf16 v[32:35], v[190:193], v[206:209], v[32:35]
	v_mfma_f32_16x16x32_bf16 v[20:23], v[182:185], v[214:217], v[20:23]
	v_mfma_f32_16x16x32_bf16 v[16:19], v[190:193], v[214:217], v[16:19]
	v_mfma_f32_16x16x32_bf16 v[4:7], v[182:185], v[222:225], v[4:7]
	v_mfma_f32_16x16x32_bf16 v[0:3], v[190:193], v[222:225], v[0:3]
	v_mfma_f32_16x16x32_bf16 v[52:55], v[186:189], v[202:205], v[52:55]
	v_mfma_f32_16x16x32_bf16 v[48:51], v[194:197], v[202:205], v[48:51]
	v_mfma_f32_16x16x32_bf16 v[36:39], v[186:189], v[210:213], v[36:39]
	v_mfma_f32_16x16x32_bf16 v[32:35], v[194:197], v[210:213], v[32:35]
	v_mfma_f32_16x16x32_bf16 v[20:23], v[186:189], v[218:221], v[20:23]
	v_mfma_f32_16x16x32_bf16 v[16:19], v[194:197], v[218:221], v[16:19]
	v_mfma_f32_16x16x32_bf16 v[4:7], v[186:189], v[230:233], v[4:7]
	v_mfma_f32_16x16x32_bf16 v[0:3], v[194:197], v[230:233], v[0:3]
	s_setprio 0
	s_barrier
	s_add_i32 s3, 0, 0x18000
	v_add_u32_e32 v144, s3, v165
	s_add_i32 s44, 0, 0x1c000
	ds_read_b128 v[128:131], v144
	ds_read_b128 v[132:135], v144 offset:1024
	ds_read_b128 v[158:161], v144 offset:2048
	ds_read_b128 v[178:181], v144 offset:3072
	v_add_u32_e32 v144, s44, v165
	ds_read_b128 v[182:185], v144
	ds_read_b128 v[186:189], v144 offset:1024
	ds_read_b128 v[190:193], v144 offset:2048
	ds_read_b128 v[194:197], v144 offset:3072
	s_add_u32 s42, s90, 0x80000
	s_addc_u32 s43, s91, 0
	s_mov_b32 m0, s31
	ds_read_b128 v[198:201], v175 offset:32768
	ds_read_b128 v[202:205], v175 offset:33792
	ds_read_b128 v[206:209], v175 offset:34816
	ds_read_b128 v[210:213], v175 offset:35840
	ds_read_b128 v[214:217], v175 offset:36864
	ds_read_b128 v[218:221], v175 offset:37888
	ds_read_b128 v[222:225], v175 offset:38912
	ds_read_b128 v[230:233], v175 offset:39936
	global_load_lds_dwordx4 v136, s[42:43]
	s_mov_b32 m0, s33
	s_nop 0
	global_load_lds_dwordx4 v140, s[42:43]
	s_waitcnt vmcnt(8)
	s_waitcnt lgkmcnt(0)
	s_barrier
	s_setprio 1
	s_waitcnt lgkmcnt(0)
	v_mfma_f32_16x16x32_bf16 v[124:127], v[128:131], v[198:201], v[124:127]
	v_mfma_f32_16x16x32_bf16 v[120:123], v[158:161], v[198:201], v[120:123]
	v_mfma_f32_16x16x32_bf16 v[108:111], v[128:131], v[206:209], v[108:111]
	v_mfma_f32_16x16x32_bf16 v[104:107], v[158:161], v[206:209], v[104:107]
	v_mfma_f32_16x16x32_bf16 v[92:95], v[128:131], v[214:217], v[92:95]
	v_mfma_f32_16x16x32_bf16 v[88:91], v[158:161], v[214:217], v[88:91]
	v_mfma_f32_16x16x32_bf16 v[76:79], v[128:131], v[222:225], v[76:79]
	v_mfma_f32_16x16x32_bf16 v[72:75], v[158:161], v[222:225], v[72:75]
	v_mfma_f32_16x16x32_bf16 v[124:127], v[132:135], v[202:205], v[124:127]
	v_mfma_f32_16x16x32_bf16 v[120:123], v[178:181], v[202:205], v[120:123]
	v_mfma_f32_16x16x32_bf16 v[108:111], v[132:135], v[210:213], v[108:111]
	v_mfma_f32_16x16x32_bf16 v[104:107], v[178:181], v[210:213], v[104:107]
	v_mfma_f32_16x16x32_bf16 v[92:95], v[132:135], v[218:221], v[92:95]
	v_mfma_f32_16x16x32_bf16 v[88:91], v[178:181], v[218:221], v[88:91]
	v_mfma_f32_16x16x32_bf16 v[76:79], v[132:135], v[230:233], v[76:79]
	v_mfma_f32_16x16x32_bf16 v[72:75], v[178:181], v[230:233], v[72:75]
	s_setprio 0
	s_setprio 1
	v_mfma_f32_16x16x32_bf16 v[116:119], v[182:185], v[198:201], v[116:119]
	v_mfma_f32_16x16x32_bf16 v[112:115], v[190:193], v[198:201], v[112:115]
	v_mfma_f32_16x16x32_bf16 v[100:103], v[182:185], v[206:209], v[100:103]
	v_mfma_f32_16x16x32_bf16 v[96:99], v[190:193], v[206:209], v[96:99]
	v_mfma_f32_16x16x32_bf16 v[84:87], v[182:185], v[214:217], v[84:87]
	v_mfma_f32_16x16x32_bf16 v[80:83], v[190:193], v[214:217], v[80:83]
	v_mfma_f32_16x16x32_bf16 v[68:71], v[182:185], v[222:225], v[68:71]
	v_mfma_f32_16x16x32_bf16 v[64:67], v[190:193], v[222:225], v[64:67]
	v_mfma_f32_16x16x32_bf16 v[116:119], v[186:189], v[202:205], v[116:119]
	v_mfma_f32_16x16x32_bf16 v[112:115], v[194:197], v[202:205], v[112:115]
	v_mfma_f32_16x16x32_bf16 v[100:103], v[186:189], v[210:213], v[100:103]
	v_mfma_f32_16x16x32_bf16 v[96:99], v[194:197], v[210:213], v[96:99]
	v_mfma_f32_16x16x32_bf16 v[84:87], v[186:189], v[218:221], v[84:87]
	v_mfma_f32_16x16x32_bf16 v[80:83], v[194:197], v[218:221], v[80:83]
	v_mfma_f32_16x16x32_bf16 v[68:71], v[186:189], v[230:233], v[68:71]
	v_mfma_f32_16x16x32_bf16 v[64:67], v[194:197], v[230:233], v[64:67]
	s_setprio 0
	s_barrier
	s_add_i32 s3, s3, s25
	v_lshl_add_u64 v[162:163], v[162:163], 0, s[40:41]
	s_mov_b32 m0, s3
	ds_read_b128 v[198:201], v175 offset:49152
	ds_read_b128 v[202:205], v175 offset:50176
	ds_read_b128 v[206:209], v175 offset:51200
	ds_read_b128 v[210:213], v175 offset:52224
	ds_read_b128 v[214:217], v175 offset:53248
	ds_read_b128 v[218:221], v175 offset:54272
	ds_read_b128 v[222:225], v175 offset:55296
	ds_read_b128 v[230:233], v175 offset:56320
	global_load_lds_dwordx4 v[162:163], off
	s_add_i32 m0, s3, 0x2000
	s_add_u32 s34, s34, 0x80080
	v_lshl_add_u64 v[162:163], v[226:227], 0, s[40:41]
	s_addc_u32 s35, s35, 0
	s_add_i32 s3, s44, s25
	global_load_lds_dwordx4 v[162:163], off
	s_mov_b32 m0, s3
	s_nop 0
	global_load_lds_dwordx4 v138, s[34:35]
	s_add_i32 m0, s3, 0x2000
	s_nop 0
	global_load_lds_dwordx4 v142, s[34:35]
	v_lshl_add_u64 v[162:163], v[234:235], 0, s[40:41]
	s_mov_b32 m0, s58
	s_nop 0
	global_load_lds_dwordx4 v[162:163], off
	v_lshl_add_u64 v[162:163], v[236:237], 0, s[40:41]
	s_mov_b32 m0, s59
	s_nop 0
	global_load_lds_dwordx4 v[162:163], off
	s_waitcnt vmcnt(8)
	s_waitcnt lgkmcnt(0)
	s_barrier
	s_setprio 1
	s_waitcnt lgkmcnt(0)
	v_mfma_f32_16x16x32_bf16 v[60:63], v[128:131], v[198:201], v[60:63]
	v_mfma_f32_16x16x32_bf16 v[56:59], v[158:161], v[198:201], v[56:59]
	v_mfma_f32_16x16x32_bf16 v[44:47], v[128:131], v[206:209], v[44:47]
	v_mfma_f32_16x16x32_bf16 v[40:43], v[158:161], v[206:209], v[40:43]
	v_mfma_f32_16x16x32_bf16 v[28:31], v[128:131], v[214:217], v[28:31]
	v_mfma_f32_16x16x32_bf16 v[24:27], v[158:161], v[214:217], v[24:27]
	v_mfma_f32_16x16x32_bf16 v[12:15], v[128:131], v[222:225], v[12:15]
	v_mfma_f32_16x16x32_bf16 v[8:11], v[158:161], v[222:225], v[8:11]
	v_mfma_f32_16x16x32_bf16 v[60:63], v[132:135], v[202:205], v[60:63]
	v_mfma_f32_16x16x32_bf16 v[56:59], v[178:181], v[202:205], v[56:59]
	v_mfma_f32_16x16x32_bf16 v[44:47], v[132:135], v[210:213], v[44:47]
	v_mfma_f32_16x16x32_bf16 v[40:43], v[178:181], v[210:213], v[40:43]
	v_mfma_f32_16x16x32_bf16 v[28:31], v[132:135], v[218:221], v[28:31]
	v_mfma_f32_16x16x32_bf16 v[24:27], v[178:181], v[218:221], v[24:27]
	v_mfma_f32_16x16x32_bf16 v[12:15], v[132:135], v[230:233], v[12:15]
	v_mfma_f32_16x16x32_bf16 v[8:11], v[178:181], v[230:233], v[8:11]
	s_setprio 0
	s_setprio 1
	v_mfma_f32_16x16x32_bf16 v[52:55], v[182:185], v[198:201], v[52:55]
	v_mfma_f32_16x16x32_bf16 v[48:51], v[190:193], v[198:201], v[48:51]
	v_mfma_f32_16x16x32_bf16 v[36:39], v[182:185], v[206:209], v[36:39]
	v_mfma_f32_16x16x32_bf16 v[32:35], v[190:193], v[206:209], v[32:35]
	v_mfma_f32_16x16x32_bf16 v[20:23], v[182:185], v[214:217], v[20:23]
	v_mfma_f32_16x16x32_bf16 v[16:19], v[190:193], v[214:217], v[16:19]
	v_mfma_f32_16x16x32_bf16 v[4:7], v[182:185], v[222:225], v[4:7]
	v_mfma_f32_16x16x32_bf16 v[0:3], v[190:193], v[222:225], v[0:3]
	v_mfma_f32_16x16x32_bf16 v[52:55], v[186:189], v[202:205], v[52:55]
	v_mfma_f32_16x16x32_bf16 v[48:51], v[194:197], v[202:205], v[48:51]
	v_mfma_f32_16x16x32_bf16 v[36:39], v[186:189], v[210:213], v[36:39]
	v_mfma_f32_16x16x32_bf16 v[32:35], v[194:197], v[210:213], v[32:35]
	v_mfma_f32_16x16x32_bf16 v[20:23], v[186:189], v[218:221], v[20:23]
	v_mfma_f32_16x16x32_bf16 v[16:19], v[194:197], v[218:221], v[16:19]
	v_mfma_f32_16x16x32_bf16 v[4:7], v[186:189], v[230:233], v[4:7]
	v_mfma_f32_16x16x32_bf16 v[0:3], v[194:197], v[230:233], v[0:3]
	s_setprio 0
	s_barrier
	s_add_i32 s37, s37, 2
	s_add_u32 s14, s14, 0x100
	s_addc_u32 s15, s15, 0
	s_add_u32 s24, s24, 0x100
	s_addc_u32 s36, s36, 0
	s_cmp_gt_u32 s37, 29
	s_cbranch_scc0 .LBB0_65
	s_and_b64 vcc, exec, s[48:49]
	s_cbranch_vccz .LBB0_68
	s_barrier

.LBB0_395:
	s_cmp_eq_u32 s56, 0
	s_cselect_b64 s[0:1], -1, 0
	s_or_b64 s[0:1], s[76:77], s[0:1]
	s_and_b64 vcc, exec, s[0:1]
	s_cbranch_vccnz .Lfz1_c0
	s_add_i32 s0, s86, 0xc000
	s_and_b32 s0, s0, 0xc000
	v_add_u32_e32 v0, s0, v234
	ds_read_b64_tr_b16 v[160:161], v0 offset:0x2000
	ds_read_b64_tr_b16 v[162:163], v0 offset:0x2100
	ds_read_b64_tr_b16 v[164:165], v0 offset:0x3000
	ds_read_b64_tr_b16 v[166:167], v0 offset:0x3100
	s_waitcnt lgkmcnt(2)
	s_nop 0
	v_mfma_f32_32x32x16_bf16 v[128:143], v[6:9], v[160:163], v[128:143]
	ds_read_b64_tr_b16 v[168:169], v0 offset:0x2200
	v_mfma_f32_32x32x16_bf16 v[96:111], v[2:5], v[160:163], v[96:111]
	ds_read_b64_tr_b16 v[170:171], v0 offset:0x2300
	s_waitcnt lgkmcnt(2)
	v_mfma_f32_32x32x16_bf16 v[128:143], v[208:211], v[164:167], v[128:143]
	ds_read_b64_tr_b16 v[172:173], v0 offset:0x3200
	v_mfma_f32_32x32x16_bf16 v[96:111], v[10:13], v[164:167], v[96:111]
	ds_read_b64_tr_b16 v[174:175], v0 offset:0x3300
	s_waitcnt lgkmcnt(2)
	v_mfma_f32_32x32x16_bf16 v[112:127], v[6:9], v[168:171], v[112:127]
	ds_read_b64_tr_b16 v[160:161], v0 offset:0x2400
	v_mfma_f32_32x32x16_bf16 v[80:95], v[2:5], v[168:171], v[80:95]
	ds_read_b64_tr_b16 v[162:163], v0 offset:0x2500
	s_waitcnt lgkmcnt(2)
	v_mfma_f32_32x32x16_bf16 v[112:127], v[208:211], v[172:175], v[112:127]
	ds_read_b64_tr_b16 v[164:165], v0 offset:0x3400
	v_mfma_f32_32x32x16_bf16 v[80:95], v[10:13], v[172:175], v[80:95]
	ds_read_b64_tr_b16 v[166:167], v0 offset:0x3500
	s_waitcnt lgkmcnt(2)
	v_mfma_f32_32x32x16_bf16 v[64:79], v[6:9], v[160:163], v[64:79]
	ds_read_b64_tr_b16 v[168:169], v0 offset:0x2600
	v_mfma_f32_32x32x16_bf16 v[32:47], v[2:5], v[160:163], v[32:47]
	ds_read_b64_tr_b16 v[170:171], v0 offset:0x2700
	s_waitcnt lgkmcnt(2)
	v_mfma_f32_32x32x16_bf16 v[64:79], v[208:211], v[164:167], v[64:79]
	ds_read_b64_tr_b16 v[172:173], v0 offset:0x3600
	v_mfma_f32_32x32x16_bf16 v[32:47], v[10:13], v[164:167], v[32:47]
	ds_read_b64_tr_b16 v[174:175], v0 offset:0x3700
	s_waitcnt lgkmcnt(2)
	v_mfma_f32_32x32x16_bf16 v[48:63], v[6:9], v[168:171], v[48:63]
	v_mfma_f32_32x32x16_bf16 v[16:31], v[2:5], v[168:171], v[16:31]
	s_waitcnt lgkmcnt(0)
	v_mfma_f32_32x32x16_bf16 v[48:63], v[208:211], v[172:175], v[48:63]
	v_mfma_f32_32x32x16_bf16 v[16:31], v[10:13], v[172:175], v[16:31]
.Lfz1_c0:
	s_and_b32 s27, s86, 0xc000
	v_add_u32_e32 v241, s27, v233
	ds_read_b128 v[144:147], v241 offset:0
	v_xor_b32_e32 v240, 32, v241
	ds_read_b128 v[148:151], v240 offset:0
	v_xor_b32_e32 v239, 64, v241
	ds_read_b128 v[152:155], v239 offset:0
	v_xor_b32_e32 v0, 0x60, v241
	ds_read_b128 v[156:159], v0 offset:0
	s_waitcnt lgkmcnt(0)
	v_mfma_f32_32x32x16_bf16 v[212:227], v[144:147], v[176:179], 0
	v_mfma_f32_32x32x16_bf16 v[212:227], v[148:151], v[180:183], v[212:227]
	v_mfma_f32_32x32x16_bf16 v[212:227], v[152:155], v[184:187], v[212:227]
	v_mfma_f32_32x32x16_bf16 v[212:227], v[156:159], v[188:191], v[212:227]
	ds_read_b128 v[144:147], v241 offset:0x80
	ds_read_b128 v[148:151], v240 offset:0x80
	ds_read_b128 v[152:155], v239 offset:0x80
	ds_read_b128 v[156:159], v0 offset:0x80
	v_cmp_eq_f32_e32 vcc, 0, v238
	v_cmp_eq_f32_e64 s[10:11], 0, v237
	s_and_b64 s[0:1], vcc, s[10:11]
	s_cmp_eq_u64 s[0:1], exec
	s_waitcnt lgkmcnt(0)
	v_mfma_f32_32x32x16_bf16 v[160:175], v[144:147], v[192:195], 0
	v_mfma_f32_32x32x16_bf16 v[160:175], v[148:151], v[196:199], v[160:175]
	v_mfma_f32_32x32x16_bf16 v[160:175], v[152:155], v[200:203], v[160:175]
	v_mfma_f32_32x32x16_bf16 v[160:175], v[156:159], v[204:207], v[160:175]
	s_cbranch_scc0 .LBB0_397
	v_exp_f32_e32 v144, v212
	v_exp_f32_e32 v145, v213
	v_exp_f32_e32 v146, v214
	v_exp_f32_e32 v147, v215
	v_exp_f32_e32 v148, v216
	v_exp_f32_e32 v149, v217
	v_exp_f32_e32 v150, v218
	v_exp_f32_e32 v151, v219
	v_exp_f32_e32 v152, v220
	v_exp_f32_e32 v153, v221
	v_exp_f32_e32 v154, v222
	v_exp_f32_e32 v155, v223
	v_exp_f32_e32 v156, v224
	v_exp_f32_e32 v157, v225
	v_exp_f32_e32 v158, v226
	v_exp_f32_e32 v159, v227
	v_pk_add_f32 v[252:253], v[144:145], v[146:147]
	v_pk_add_f32 v[254:255], v[148:149], v[150:151]
	v_pk_add_f32 v[252:253], v[152:153], v[252:253]
	v_pk_add_f32 v[254:255], v[154:155], v[254:255]
	v_pk_add_f32 v[252:253], v[156:157], v[252:253]
	v_pk_add_f32 v[254:255], v[158:159], v[254:255]
	v_cvt_pk_bf16_f32 v216, v144, v145
	v_cvt_pk_bf16_f32 v217, v146, v147
	v_cvt_pk_bf16_f32 v218, v148, v149
	v_pk_add_f32 v[252:253], v[252:253], v[254:255]
	v_cvt_pk_bf16_f32 v219, v150, v151
	v_cvt_pk_bf16_f32 v224, v152, v153
	v_cvt_pk_bf16_f32 v225, v154, v155
	v_pk_add_f32 v[252:253], v[252:253], v[252:253] op_sel:[0,1] op_sel_hi:[1,0]
	v_cvt_pk_bf16_f32 v226, v156, v157
	v_cvt_pk_bf16_f32 v227, v158, v159
	v_cmp_lt_f32_e32 vcc, s58, v252
	v_cmp_gt_f32_e64 s[10:11], s59, v252
	s_and_b64 s[0:1], vcc, s[10:11]
	s_cmp_lg_u64 s[0:1], exec
	s_cbranch_scc1 .LBB0_432
	v_add_f32_e32 v15, v15, v252
	v_exp_f32_e32 v144, v160
	v_exp_f32_e32 v145, v161
	v_exp_f32_e32 v146, v162
	v_exp_f32_e32 v147, v163
	v_exp_f32_e32 v148, v164
	v_exp_f32_e32 v149, v165
	v_exp_f32_e32 v150, v166
	v_exp_f32_e32 v151, v167
	v_exp_f32_e32 v152, v168
	v_exp_f32_e32 v153, v169
	v_exp_f32_e32 v154, v170
	v_exp_f32_e32 v155, v171
	v_exp_f32_e32 v156, v172
	v_exp_f32_e32 v157, v173
	v_exp_f32_e32 v158, v174
	v_exp_f32_e32 v159, v175
	v_pk_add_f32 v[252:253], v[144:145], v[146:147]
	v_pk_add_f32 v[254:255], v[148:149], v[150:151]
	v_pk_add_f32 v[252:253], v[152:153], v[252:253]
	v_pk_add_f32 v[254:255], v[154:155], v[254:255]
	v_pk_add_f32 v[252:253], v[156:157], v[252:253]
	v_pk_add_f32 v[254:255], v[158:159], v[254:255]
	v_cvt_pk_bf16_f32 v212, v144, v145
	v_cvt_pk_bf16_f32 v213, v146, v147
	v_cvt_pk_bf16_f32 v214, v148, v149
	v_pk_add_f32 v[252:253], v[252:253], v[254:255]
	v_cvt_pk_bf16_f32 v215, v150, v151
	v_cvt_pk_bf16_f32 v220, v152, v153
	v_cvt_pk_bf16_f32 v221, v154, v155
	v_pk_add_f32 v[252:253], v[252:253], v[252:253] op_sel:[0,1] op_sel_hi:[1,0]
	v_cvt_pk_bf16_f32 v222, v156, v157
	v_cvt_pk_bf16_f32 v223, v158, v159
	v_cmp_lt_f32_e32 vcc, s58, v252
	v_cmp_gt_f32_e64 s[10:11], s59, v252
	s_and_b64 s[0:1], vcc, s[10:11]
	s_cmp_lg_u64 s[0:1], exec
	s_cbranch_scc1 .Lfzsb1_c0
	v_add_f32_e32 v14, v14, v252
	s_branch .LBB0_413
.Lfzsb1_c0:
	v_mov_b32_e32 v242, 1.0
	s_branch .LBB0_438

.LBB0_413:
	v_add_u32_e32 v242, s27, v234
	ds_read_b64_tr_b16 v[160:161], v242 offset:0x0
	ds_read_b64_tr_b16 v[162:163], v242 offset:0x100
	ds_read_b64_tr_b16 v[164:165], v242 offset:0x1000
	ds_read_b64_tr_b16 v[166:167], v242 offset:0x1100
	s_waitcnt lgkmcnt(2)
	s_nop 0
	v_mfma_f32_32x32x16_bf16 v[128:143], v[216:219], v[160:163], v[128:143]
	ds_read_b64_tr_b16 v[168:169], v242 offset:0x200
	v_mfma_f32_32x32x16_bf16 v[96:111], v[212:215], v[160:163], v[96:111]
	ds_read_b64_tr_b16 v[170:171], v242 offset:0x300
	s_waitcnt lgkmcnt(2)
	v_mfma_f32_32x32x16_bf16 v[128:143], v[224:227], v[164:167], v[128:143]
	ds_read_b64_tr_b16 v[172:173], v242 offset:0x1200
	v_mfma_f32_32x32x16_bf16 v[96:111], v[220:223], v[164:167], v[96:111]
	ds_read_b64_tr_b16 v[174:175], v242 offset:0x1300
	s_waitcnt lgkmcnt(2)
	v_mfma_f32_32x32x16_bf16 v[112:127], v[216:219], v[168:171], v[112:127]
	ds_read_b64_tr_b16 v[160:161], v242 offset:0x400
	v_mfma_f32_32x32x16_bf16 v[80:95], v[212:215], v[168:171], v[80:95]
	ds_read_b64_tr_b16 v[162:163], v242 offset:0x500
	s_waitcnt lgkmcnt(2)
	v_mfma_f32_32x32x16_bf16 v[112:127], v[224:227], v[172:175], v[112:127]
	ds_read_b64_tr_b16 v[164:165], v242 offset:0x1400
	v_mfma_f32_32x32x16_bf16 v[80:95], v[220:223], v[172:175], v[80:95]
	ds_read_b64_tr_b16 v[166:167], v242 offset:0x1500
	ds_read_b128 v[144:147], v241 offset:0x2000
	ds_read_b128 v[148:151], v240 offset:0x2000
	ds_read_b128 v[152:155], v239 offset:0x2000
	ds_read_b128 v[156:159], v0 offset:0x2000
	s_waitcnt lgkmcnt(6)
	v_mfma_f32_32x32x16_bf16 v[64:79], v[216:219], v[160:163], v[64:79]
	ds_read_b64_tr_b16 v[168:169], v242 offset:0x600
	v_mfma_f32_32x32x16_bf16 v[32:47], v[212:215], v[160:163], v[32:47]
	ds_read_b64_tr_b16 v[170:171], v242 offset:0x700
	s_waitcnt lgkmcnt(6)
	v_mfma_f32_32x32x16_bf16 v[64:79], v[224:227], v[164:167], v[64:79]
	ds_read_b64_tr_b16 v[172:173], v242 offset:0x1600
	v_mfma_f32_32x32x16_bf16 v[32:47], v[220:223], v[164:167], v[32:47]
	ds_read_b64_tr_b16 v[174:175], v242 offset:0x1700
	s_waitcnt lgkmcnt(2)
	v_mfma_f32_32x32x16_bf16 v[48:63], v[216:219], v[168:171], v[48:63]
	v_mfma_f32_32x32x16_bf16 v[16:31], v[212:215], v[168:171], v[16:31]
	s_waitcnt lgkmcnt(0)
	v_mfma_f32_32x32x16_bf16 v[48:63], v[224:227], v[172:175], v[48:63]
	v_mfma_f32_32x32x16_bf16 v[16:31], v[220:223], v[172:175], v[16:31]
	s_waitcnt lgkmcnt(0)
	v_mfma_f32_32x32x16_bf16 v[212:227], v[144:147], v[176:179], 0
	v_mfma_f32_32x32x16_bf16 v[212:227], v[148:151], v[180:183], v[212:227]
	v_mfma_f32_32x32x16_bf16 v[212:227], v[152:155], v[184:187], v[212:227]
	v_mfma_f32_32x32x16_bf16 v[212:227], v[156:159], v[188:191], v[212:227]
	ds_read_b128 v[144:147], v241 offset:0x2080
	ds_read_b128 v[148:151], v240 offset:0x2080
	ds_read_b128 v[152:155], v239 offset:0x2080
	ds_read_b128 v[156:159], v0 offset:0x2080
	v_cmp_eq_f32_e32 vcc, 0, v238
	v_cmp_eq_f32_e64 s[10:11], 0, v237
	s_and_b64 s[0:1], vcc, s[10:11]
	s_cmp_eq_u64 s[0:1], exec
	s_waitcnt lgkmcnt(0)
	v_mfma_f32_32x32x16_bf16 v[160:175], v[144:147], v[192:195], 0
	v_mfma_f32_32x32x16_bf16 v[160:175], v[148:151], v[196:199], v[160:175]
	v_mfma_f32_32x32x16_bf16 v[160:175], v[152:155], v[200:203], v[160:175]
	v_mfma_f32_32x32x16_bf16 v[160:175], v[156:159], v[204:207], v[160:175]
	s_cbranch_scc0 .Lfz2o_c0
	v_exp_f32_e32 v144, v212
	v_exp_f32_e32 v145, v213
	v_exp_f32_e32 v146, v214
	v_exp_f32_e32 v147, v215
	v_exp_f32_e32 v148, v216
	v_exp_f32_e32 v149, v217
	v_exp_f32_e32 v150, v218
	v_exp_f32_e32 v151, v219
	v_exp_f32_e32 v152, v220
	v_exp_f32_e32 v153, v221
	v_exp_f32_e32 v154, v222
	v_exp_f32_e32 v155, v223
	v_exp_f32_e32 v156, v224
	v_exp_f32_e32 v157, v225
	v_exp_f32_e32 v158, v226
	v_exp_f32_e32 v159, v227
	v_pk_add_f32 v[252:253], v[144:145], v[146:147]
	v_pk_add_f32 v[254:255], v[148:149], v[150:151]
	v_pk_add_f32 v[252:253], v[152:153], v[252:253]
	v_pk_add_f32 v[254:255], v[154:155], v[254:255]
	v_pk_add_f32 v[252:253], v[156:157], v[252:253]
	v_pk_add_f32 v[254:255], v[158:159], v[254:255]
	v_cvt_pk_bf16_f32 v6, v144, v145
	v_cvt_pk_bf16_f32 v7, v146, v147
	v_cvt_pk_bf16_f32 v8, v148, v149
	v_pk_add_f32 v[252:253], v[252:253], v[254:255]
	v_cvt_pk_bf16_f32 v9, v150, v151
	v_cvt_pk_bf16_f32 v208, v152, v153
	v_cvt_pk_bf16_f32 v209, v154, v155
	v_pk_add_f32 v[252:253], v[252:253], v[252:253] op_sel:[0,1] op_sel_hi:[1,0]
	v_cvt_pk_bf16_f32 v210, v156, v157
	v_cvt_pk_bf16_f32 v211, v158, v159
	v_cmp_lt_f32_e32 vcc, s58, v252
	v_cmp_gt_f32_e64 s[10:11], s59, v252
	s_and_b64 s[0:1], vcc, s[10:11]
	s_cmp_lg_u64 s[0:1], exec
	s_cbranch_scc1 .LBB0_444
	v_add_f32_e32 v15, v15, v252
	v_exp_f32_e32 v144, v160
	v_exp_f32_e32 v145, v161
	v_exp_f32_e32 v146, v162
	v_exp_f32_e32 v147, v163
	v_exp_f32_e32 v148, v164
	v_exp_f32_e32 v149, v165
	v_exp_f32_e32 v150, v166
	v_exp_f32_e32 v151, v167
	v_exp_f32_e32 v152, v168
	v_exp_f32_e32 v153, v169
	v_exp_f32_e32 v154, v170
	v_exp_f32_e32 v155, v171
	v_exp_f32_e32 v156, v172
	v_exp_f32_e32 v157, v173
	v_exp_f32_e32 v158, v174
	v_exp_f32_e32 v159, v175
	v_pk_add_f32 v[252:253], v[144:145], v[146:147]
	v_pk_add_f32 v[254:255], v[148:149], v[150:151]
	v_pk_add_f32 v[252:253], v[152:153], v[252:253]
	v_pk_add_f32 v[254:255], v[154:155], v[254:255]
	v_pk_add_f32 v[252:253], v[156:157], v[252:253]
	v_pk_add_f32 v[254:255], v[158:159], v[254:255]
	v_cvt_pk_bf16_f32 v2, v144, v145
	v_cvt_pk_bf16_f32 v3, v146, v147
	v_cvt_pk_bf16_f32 v4, v148, v149
	v_pk_add_f32 v[252:253], v[252:253], v[254:255]
	v_cvt_pk_bf16_f32 v5, v150, v151
	v_cvt_pk_bf16_f32 v10, v152, v153
	v_cvt_pk_bf16_f32 v11, v154, v155
	v_pk_add_f32 v[252:253], v[252:253], v[252:253] op_sel:[0,1] op_sel_hi:[1,0]
	v_cvt_pk_bf16_f32 v12, v156, v157
	v_cvt_pk_bf16_f32 v13, v158, v159
	v_cmp_lt_f32_e32 vcc, s58, v252
	v_cmp_gt_f32_e64 s[10:11], s59, v252
	s_and_b64 s[0:1], vcc, s[10:11]
	s_cmp_lg_u64 s[0:1], exec
	s_cbranch_scc1 .Lfzsb2_c0
	v_add_f32_e32 v14, v14, v252
	s_branch .LBB0_429
.Lfzsb2_c0:
	v_mov_b32_e32 v243, 1.0
	s_branch .LBB0_450
.Lfz2o_c0:
	ds_read_b128 v[144:147], v241 offset:0x2000
	ds_read_b128 v[148:151], v240 offset:0x2000
	ds_read_b128 v[152:155], v239 offset:0x2000
	ds_read_b128 v[156:159], v0 offset:0x2000
	s_waitcnt lgkmcnt(0)
	v_mfma_f32_32x32x16_bf16 v[160:175], v[144:147], v[176:179], 0
	v_cmp_eq_f32_e32 vcc, 0, v238
	s_cmp_eq_u64 vcc, exec
	v_mfma_f32_32x32x16_bf16 v[160:175], v[148:151], v[180:183], v[160:175]
	v_mfma_f32_32x32x16_bf16 v[160:175], v[152:155], v[184:187], v[160:175]
	v_mfma_f32_32x32x16_bf16 v[160:175], v[156:159], v[188:191], v[160:175]
	s_cbranch_scc0 .LBB0_443

.LBB0_429:
	s_andn2_b64 vcc, exec, s[46:47]
	s_cbranch_vccnz .LBB0_388
	ds_read_b64_tr_b16 v[160:161], v242 offset:0x2000
	ds_read_b64_tr_b16 v[162:163], v242 offset:0x2100
	ds_read_b64_tr_b16 v[164:165], v242 offset:0x3000
	ds_read_b64_tr_b16 v[166:167], v242 offset:0x3100
	s_waitcnt lgkmcnt(2)
	s_nop 0
	v_mfma_f32_32x32x16_bf16 v[128:143], v[6:9], v[160:163], v[128:143]
	ds_read_b64_tr_b16 v[168:169], v242 offset:0x2200
	v_mfma_f32_32x32x16_bf16 v[96:111], v[2:5], v[160:163], v[96:111]
	ds_read_b64_tr_b16 v[170:171], v242 offset:0x2300
	s_waitcnt lgkmcnt(2)
	v_mfma_f32_32x32x16_bf16 v[128:143], v[208:211], v[164:167], v[128:143]
	ds_read_b64_tr_b16 v[172:173], v242 offset:0x3200
	v_mfma_f32_32x32x16_bf16 v[96:111], v[10:13], v[164:167], v[96:111]
	ds_read_b64_tr_b16 v[174:175], v242 offset:0x3300
	s_waitcnt lgkmcnt(2)
	v_mfma_f32_32x32x16_bf16 v[112:127], v[6:9], v[168:171], v[112:127]
	ds_read_b64_tr_b16 v[160:161], v242 offset:0x2400
	v_mfma_f32_32x32x16_bf16 v[80:95], v[2:5], v[168:171], v[80:95]
	ds_read_b64_tr_b16 v[162:163], v242 offset:0x2500
	s_waitcnt lgkmcnt(2)
	v_mfma_f32_32x32x16_bf16 v[112:127], v[208:211], v[172:175], v[112:127]
	ds_read_b64_tr_b16 v[164:165], v242 offset:0x3400
	v_mfma_f32_32x32x16_bf16 v[80:95], v[10:13], v[172:175], v[80:95]
	ds_read_b64_tr_b16 v[166:167], v242 offset:0x3500
	s_waitcnt lgkmcnt(2)
	v_mfma_f32_32x32x16_bf16 v[64:79], v[6:9], v[160:163], v[64:79]
	ds_read_b64_tr_b16 v[168:169], v242 offset:0x2600
	v_mfma_f32_32x32x16_bf16 v[32:47], v[2:5], v[160:163], v[32:47]
	ds_read_b64_tr_b16 v[170:171], v242 offset:0x2700
	s_waitcnt lgkmcnt(2)
	v_mfma_f32_32x32x16_bf16 v[64:79], v[208:211], v[164:167], v[64:79]
	ds_read_b64_tr_b16 v[172:173], v242 offset:0x3600
	v_mfma_f32_32x32x16_bf16 v[32:47], v[10:13], v[164:167], v[32:47]
	ds_read_b64_tr_b16 v[174:175], v242 offset:0x3700
	s_waitcnt lgkmcnt(2)
	v_mfma_f32_32x32x16_bf16 v[48:63], v[6:9], v[168:171], v[48:63]
	v_mfma_f32_32x32x16_bf16 v[16:31], v[2:5], v[168:171], v[16:31]
	s_waitcnt lgkmcnt(0)
	v_mfma_f32_32x32x16_bf16 v[48:63], v[208:211], v[172:175], v[48:63]
	v_mfma_f32_32x32x16_bf16 v[16:31], v[10:13], v[172:175], v[16:31]
	s_branch .LBB0_388

.LBB0_463:
	s_and_b64 vcc, exec, s[34:35]
	s_cbranch_vccz .LBB0_465
	s_cmp_lg_u32 0, -1
	s_cselect_b32 s0, 0, 0
	s_add_i32 s0, s0, 0xc000
	v_add_u32_e32 v0, s0, v232
	ds_read_b64_tr_b16 v[160:161], v0 offset:0x2000
	ds_read_b64_tr_b16 v[162:163], v0 offset:0x2100
	ds_read_b64_tr_b16 v[164:165], v0 offset:0x3000
	ds_read_b64_tr_b16 v[166:167], v0 offset:0x3100
	s_waitcnt lgkmcnt(2)
	s_nop 0
	v_mfma_f32_32x32x16_bf16 v[128:143], v[6:9], v[160:163], v[128:143]
	ds_read_b64_tr_b16 v[168:169], v0 offset:0x2200
	v_mfma_f32_32x32x16_bf16 v[96:111], v[2:5], v[160:163], v[96:111]
	ds_read_b64_tr_b16 v[170:171], v0 offset:0x2300
	s_waitcnt lgkmcnt(2)
	v_mfma_f32_32x32x16_bf16 v[128:143], v[208:211], v[164:167], v[128:143]
	ds_read_b64_tr_b16 v[172:173], v0 offset:0x3200
	v_mfma_f32_32x32x16_bf16 v[96:111], v[10:13], v[164:167], v[96:111]
	ds_read_b64_tr_b16 v[174:175], v0 offset:0x3300
	s_waitcnt lgkmcnt(2)
	v_mfma_f32_32x32x16_bf16 v[112:127], v[6:9], v[168:171], v[112:127]
	ds_read_b64_tr_b16 v[160:161], v0 offset:0x2400
	v_mfma_f32_32x32x16_bf16 v[80:95], v[2:5], v[168:171], v[80:95]
	ds_read_b64_tr_b16 v[162:163], v0 offset:0x2500
	s_waitcnt lgkmcnt(2)
	v_mfma_f32_32x32x16_bf16 v[112:127], v[208:211], v[172:175], v[112:127]
	ds_read_b64_tr_b16 v[164:165], v0 offset:0x3400
	v_mfma_f32_32x32x16_bf16 v[80:95], v[10:13], v[172:175], v[80:95]
	ds_read_b64_tr_b16 v[166:167], v0 offset:0x3500
	s_waitcnt lgkmcnt(2)
	v_mfma_f32_32x32x16_bf16 v[64:79], v[6:9], v[160:163], v[64:79]
	ds_read_b64_tr_b16 v[168:169], v0 offset:0x2600
	v_mfma_f32_32x32x16_bf16 v[32:47], v[2:5], v[160:163], v[32:47]
	ds_read_b64_tr_b16 v[170:171], v0 offset:0x2700
	s_waitcnt lgkmcnt(2)
	v_mfma_f32_32x32x16_bf16 v[64:79], v[208:211], v[164:167], v[64:79]
	ds_read_b64_tr_b16 v[172:173], v0 offset:0x3600
	v_mfma_f32_32x32x16_bf16 v[32:47], v[10:13], v[164:167], v[32:47]
	ds_read_b64_tr_b16 v[174:175], v0 offset:0x3700
	s_waitcnt lgkmcnt(2)
	v_mfma_f32_32x32x16_bf16 v[48:63], v[6:9], v[168:171], v[48:63]
	v_mfma_f32_32x32x16_bf16 v[16:31], v[2:5], v[168:171], v[16:31]
	s_waitcnt lgkmcnt(0)
	v_mfma_f32_32x32x16_bf16 v[48:63], v[208:211], v[172:175], v[48:63]
	v_mfma_f32_32x32x16_bf16 v[16:31], v[10:13], v[172:175], v[16:31]

.LBB0_529:
	v_lshrrev_b32_e32 v16, 1, v14
	v_and_b32_e32 v16, 24, v16
	v_and_b32_e32 v15, 15, v14
	v_lshlrev_b32_e32 v17, 1, v16
	v_lshlrev_b32_e32 v14, 2, v14
	v_lshl_or_b32 v150, s0, 6, v15
	v_lshl_or_b32 v15, v15, 6, v17
	s_lshl_b32 s0, s0, 13
	v_and_b32_e32 v14, 32, v14
	v_bitop3_b32 v17, v15, s0, v14 bitop3:0xde
	s_lshl_b32 s0, s1, 5
	s_mov_b64 s[10:11], 0x80
	s_sext_i32_i8 s24, s8
	s_and_b32 s8, s0, 0x60
	s_add_i32 m0, s19, 0x18000
	v_lshl_add_u64 v[6:7], v[6:7], 0, s[10:11]
	s_lshl_b32 s0, s8, 7
	s_waitcnt vmcnt(2)
	s_barrier
	global_load_lds_dwordx4 v[6:7], off
	v_lshl_add_u64 v[4:5], v[4:5], 0, s[10:11]
	s_add_i32 m0, s19, 0x1a000
	s_add_i32 s49, s19, 0x8000
	s_add_i32 s56, s19, 0xa000
	v_bitop3_b32 v151, v15, s0, v14 bitop3:0xde
	global_load_lds_dwordx4 v[4:5], off
	v_lshl_add_u64 v[0:1], v[0:1], 0, s[10:11]
	s_mov_b32 m0, s49
	s_add_u32 s0, s88, 0x40080
	global_load_lds_dwordx4 v[0:1], off
	v_lshl_add_u64 v[0:1], v[2:3], 0, s[10:11]
	s_mov_b32 m0, s56
	s_addc_u32 s1, s89, 0
	global_load_lds_dwordx4 v[0:1], off
	s_add_i32 m0, s19, 0x1c000
	s_nop 0
	global_load_lds_dwordx4 v130, s[0:1]
	s_add_i32 m0, s19, 0x1e000
	s_cmpk_lt_u32 s3, 0x100
	global_load_lds_dwordx4 v134, s[0:1]
	v_lshlrev_b32_e32 v0, 14, v8
	v_and_b32_e32 v0, 0xffff8000, v0
	v_lshl_add_u32 v0, v9, 11, v0
	v_and_b32_e32 v1, 1, v8
	v_lshl_or_b32 v0, v1, 6, v0
	v_lshl_add_u32 v136, v10, 1, v0
	v_lshlrev_b32_e32 v0, 14, v11
	v_and_b32_e32 v0, 0xffff8000, v0
	s_waitcnt vmcnt(6)
	v_lshl_add_u32 v0, v12, 11, v0
	v_and_b32_e32 v1, 1, v11
	s_cselect_b64 s[12:13], -1, 0
	v_lshl_or_b32 v0, v1, 6, v0
	s_add_i32 s57, 0, 0x10000
	s_add_i32 s58, 0, 0x14000
	v_or_b32_e32 v152, s8, v16
	v_mov_b32_e32 v137, v131
	v_lshl_add_u32 v138, v13, 1, v0
	v_mov_b32_e32 v139, v131
	v_mov_b64_e32 v[140:141], 0x200
	v_mov_b64_e32 v[142:143], 0x1ff
	v_add_u32_e32 v153, s57, v151
	v_add_u32_e32 v154, s58, v151
	v_add_u32_e32 v155, 0, v17
	s_movk_i32 s59, 0x5c00
	s_mov_b64 s[14:15], 0x3c00
	s_movk_i32 s68, 0x3000
	s_barrier
	s_branch .LBB0_532

.LBB0_539:
	ds_read_b128 v[144:147], v153
	ds_read_b128 v[156:159], v153 offset:1024
	ds_read_b128 v[160:163], v153 offset:2048
	ds_read_b128 v[164:167], v153 offset:3072
	ds_read_b128 v[168:171], v154
	ds_read_b128 v[172:175], v154 offset:1024
	ds_read_b128 v[176:179], v154 offset:2048
	ds_read_b128 v[180:183], v154 offset:3072
	s_add_u32 s3, s86, 0xfffc0080
	s_addc_u32 s37, s87, -1
	s_cmp_eq_u32 s36, 12
	s_cselect_b32 s91, s0, s37
	s_cselect_b32 s90, s1, s3
	s_cselect_b32 s89, s17, s35
	s_cselect_b32 s88, s27, s33
	s_add_i32 m0, s19, 0xc000
	ds_read_b128 v[184:187], v155
	ds_read_b128 v[188:191], v155 offset:1024
	ds_read_b128 v[192:195], v155 offset:2048
	ds_read_b128 v[196:199], v155 offset:3072
	ds_read_b128 v[200:203], v155 offset:4096
	ds_read_b128 v[204:207], v155 offset:5120
	ds_read_b128 v[208:211], v155 offset:6144
	ds_read_b128 v[212:215], v155 offset:7168
	global_load_lds_dwordx4 v136, s[86:87]
	s_add_i32 m0, s19, 0xe000
	s_nop 0
	global_load_lds_dwordx4 v138, s[86:87]
	s_waitcnt vmcnt(8)
	s_waitcnt lgkmcnt(0)
	s_barrier
	s_setprio 1
	s_waitcnt lgkmcnt(0)
	v_mfma_f32_16x16x32_bf16 v[124:127], v[144:147], v[184:187], v[124:127]
	v_mfma_f32_16x16x32_bf16 v[120:123], v[160:163], v[184:187], v[120:123]
	v_mfma_f32_16x16x32_bf16 v[108:111], v[144:147], v[192:195], v[108:111]
	v_mfma_f32_16x16x32_bf16 v[104:107], v[160:163], v[192:195], v[104:107]
	v_mfma_f32_16x16x32_bf16 v[92:95], v[144:147], v[200:203], v[92:95]
	v_mfma_f32_16x16x32_bf16 v[88:91], v[160:163], v[200:203], v[88:91]
	v_mfma_f32_16x16x32_bf16 v[76:79], v[144:147], v[208:211], v[76:79]
	v_mfma_f32_16x16x32_bf16 v[72:75], v[160:163], v[208:211], v[72:75]
	v_mfma_f32_16x16x32_bf16 v[124:127], v[156:159], v[188:191], v[124:127]
	v_mfma_f32_16x16x32_bf16 v[120:123], v[164:167], v[188:191], v[120:123]
	v_mfma_f32_16x16x32_bf16 v[108:111], v[156:159], v[196:199], v[108:111]
	v_mfma_f32_16x16x32_bf16 v[104:107], v[164:167], v[196:199], v[104:107]
	v_mfma_f32_16x16x32_bf16 v[92:95], v[156:159], v[204:207], v[92:95]
	v_mfma_f32_16x16x32_bf16 v[88:91], v[164:167], v[204:207], v[88:91]
	v_mfma_f32_16x16x32_bf16 v[76:79], v[156:159], v[212:215], v[76:79]
	v_mfma_f32_16x16x32_bf16 v[72:75], v[164:167], v[212:215], v[72:75]
	s_setprio 0
	s_setprio 1
	v_mfma_f32_16x16x32_bf16 v[116:119], v[168:171], v[184:187], v[116:119]
	v_mfma_f32_16x16x32_bf16 v[112:115], v[176:179], v[184:187], v[112:115]
	v_mfma_f32_16x16x32_bf16 v[100:103], v[168:171], v[192:195], v[100:103]
	v_mfma_f32_16x16x32_bf16 v[96:99], v[176:179], v[192:195], v[96:99]
	v_mfma_f32_16x16x32_bf16 v[84:87], v[168:171], v[200:203], v[84:87]
	v_mfma_f32_16x16x32_bf16 v[80:83], v[176:179], v[200:203], v[80:83]
	v_mfma_f32_16x16x32_bf16 v[68:71], v[168:171], v[208:211], v[68:71]
	v_mfma_f32_16x16x32_bf16 v[64:67], v[176:179], v[208:211], v[64:67]
	v_mfma_f32_16x16x32_bf16 v[116:119], v[172:175], v[188:191], v[116:119]
	v_mfma_f32_16x16x32_bf16 v[112:115], v[180:183], v[188:191], v[112:115]
	v_mfma_f32_16x16x32_bf16 v[100:103], v[172:175], v[196:199], v[100:103]
	v_mfma_f32_16x16x32_bf16 v[96:99], v[180:183], v[196:199], v[96:99]
	v_mfma_f32_16x16x32_bf16 v[84:87], v[172:175], v[204:207], v[84:87]
	v_mfma_f32_16x16x32_bf16 v[80:83], v[180:183], v[204:207], v[80:83]
	v_mfma_f32_16x16x32_bf16 v[68:71], v[172:175], v[212:215], v[68:71]
	v_mfma_f32_16x16x32_bf16 v[64:67], v[180:183], v[212:215], v[64:67]
	s_setprio 0
	s_barrier
	s_add_i32 s3, s57, s18
	v_lshl_add_u64 v[148:149], s[88:89], 0, v[130:131]
	s_mov_b32 m0, s3
	ds_read_b128 v[184:187], v155 offset:16384
	ds_read_b128 v[188:191], v155 offset:17408
	ds_read_b128 v[192:195], v155 offset:18432
	ds_read_b128 v[196:199], v155 offset:19456
	ds_read_b128 v[200:203], v155 offset:20480
	ds_read_b128 v[204:207], v155 offset:21504
	ds_read_b128 v[208:211], v155 offset:22528
	ds_read_b128 v[212:215], v155 offset:23552
	global_load_lds_dwordx4 v[148:149], off
	s_add_i32 m0, s3, 0x2000
	s_add_u32 s42, s88, 0x40000
	v_lshl_add_u64 v[216:217], s[88:89], 0, v[134:135]
	s_addc_u32 s43, s89, 0
	s_add_i32 s3, s58, s18
	global_load_lds_dwordx4 v[216:217], off
	s_mov_b32 m0, s3
	v_lshl_add_u64 v[220:221], s[90:91], 0, v[132:133]
	global_load_lds_dwordx4 v130, s[42:43]
	s_add_i32 m0, s3, 0x2000
	s_nop 0
	global_load_lds_dwordx4 v134, s[42:43]
	v_lshl_add_u64 v[218:219], s[90:91], 0, v[128:129]
	s_mov_b32 m0, s19
	s_nop 0
	global_load_lds_dwordx4 v[218:219], off
	s_mov_b32 m0, s25
	s_nop 0
	global_load_lds_dwordx4 v[220:221], off
	s_waitcnt vmcnt(8)
	s_waitcnt lgkmcnt(0)
	s_barrier
	s_setprio 1
	s_waitcnt lgkmcnt(0)
	v_mfma_f32_16x16x32_bf16 v[60:63], v[144:147], v[184:187], v[60:63]
	v_mfma_f32_16x16x32_bf16 v[56:59], v[160:163], v[184:187], v[56:59]
	v_mfma_f32_16x16x32_bf16 v[44:47], v[144:147], v[192:195], v[44:47]
	v_mfma_f32_16x16x32_bf16 v[40:43], v[160:163], v[192:195], v[40:43]
	v_mfma_f32_16x16x32_bf16 v[28:31], v[144:147], v[200:203], v[28:31]
	v_mfma_f32_16x16x32_bf16 v[24:27], v[160:163], v[200:203], v[24:27]
	v_mfma_f32_16x16x32_bf16 v[12:15], v[144:147], v[208:211], v[12:15]
	v_mfma_f32_16x16x32_bf16 v[8:11], v[160:163], v[208:211], v[8:11]
	v_mfma_f32_16x16x32_bf16 v[60:63], v[156:159], v[188:191], v[60:63]
	v_mfma_f32_16x16x32_bf16 v[56:59], v[164:167], v[188:191], v[56:59]
	v_mfma_f32_16x16x32_bf16 v[44:47], v[156:159], v[196:199], v[44:47]
	v_mfma_f32_16x16x32_bf16 v[40:43], v[164:167], v[196:199], v[40:43]
	v_mfma_f32_16x16x32_bf16 v[28:31], v[156:159], v[204:207], v[28:31]
	v_mfma_f32_16x16x32_bf16 v[24:27], v[164:167], v[204:207], v[24:27]
	v_mfma_f32_16x16x32_bf16 v[12:15], v[156:159], v[212:215], v[12:15]
	v_mfma_f32_16x16x32_bf16 v[8:11], v[164:167], v[212:215], v[8:11]
	s_setprio 0
	s_setprio 1
	v_mfma_f32_16x16x32_bf16 v[52:55], v[168:171], v[184:187], v[52:55]
	v_mfma_f32_16x16x32_bf16 v[48:51], v[176:179], v[184:187], v[48:51]
	v_mfma_f32_16x16x32_bf16 v[36:39], v[168:171], v[192:195], v[36:39]
	v_mfma_f32_16x16x32_bf16 v[32:35], v[176:179], v[192:195], v[32:35]
	v_mfma_f32_16x16x32_bf16 v[20:23], v[168:171], v[200:203], v[20:23]
	v_mfma_f32_16x16x32_bf16 v[16:19], v[176:179], v[200:203], v[16:19]
	v_mfma_f32_16x16x32_bf16 v[4:7], v[168:171], v[208:211], v[4:7]
	v_mfma_f32_16x16x32_bf16 v[0:3], v[176:179], v[208:211], v[0:3]
	v_mfma_f32_16x16x32_bf16 v[52:55], v[172:175], v[188:191], v[52:55]
	v_mfma_f32_16x16x32_bf16 v[48:51], v[180:183], v[188:191], v[48:51]
	v_mfma_f32_16x16x32_bf16 v[36:39], v[172:175], v[196:199], v[36:39]
	v_mfma_f32_16x16x32_bf16 v[32:35], v[180:183], v[196:199], v[32:35]
	v_mfma_f32_16x16x32_bf16 v[20:23], v[172:175], v[204:207], v[20:23]
	v_mfma_f32_16x16x32_bf16 v[16:19], v[180:183], v[204:207], v[16:19]
	v_mfma_f32_16x16x32_bf16 v[4:7], v[172:175], v[212:215], v[4:7]
	v_mfma_f32_16x16x32_bf16 v[0:3], v[180:183], v[212:215], v[0:3]
	s_setprio 0
	s_barrier
	s_add_i32 s3, 0, 0x18000
	s_add_i32 s37, 0, 0x1c000
	v_add_u32_e32 v164, s3, v151
	v_add_u32_e32 v180, s37, v151
	ds_read_b128 v[144:147], v164
	ds_read_b128 v[156:159], v164 offset:1024
	ds_read_b128 v[160:163], v164 offset:2048
	ds_read_b128 v[164:167], v164 offset:3072
	ds_read_b128 v[168:171], v180
	ds_read_b128 v[172:175], v180 offset:1024
	ds_read_b128 v[176:179], v180 offset:2048
	ds_read_b128 v[180:183], v180 offset:3072
	s_add_u32 s42, s90, 0x40000
	s_addc_u32 s43, s91, 0
	s_mov_b32 m0, s30
	ds_read_b128 v[184:187], v155 offset:32768
	ds_read_b128 v[188:191], v155 offset:33792
	ds_read_b128 v[192:195], v155 offset:34816
	ds_read_b128 v[196:199], v155 offset:35840
	ds_read_b128 v[200:203], v155 offset:36864
	ds_read_b128 v[204:207], v155 offset:37888
	ds_read_b128 v[208:211], v155 offset:38912
	ds_read_b128 v[212:215], v155 offset:39936
	global_load_lds_dwordx4 v128, s[42:43]
	v_lshl_add_u64 v[222:223], s[42:43], 0, v[132:133]
	s_mov_b32 m0, s31
	s_nop 0
	global_load_lds_dwordx4 v[222:223], off
	s_waitcnt vmcnt(8)
	s_waitcnt lgkmcnt(0)
	s_barrier
	s_setprio 1
	s_waitcnt lgkmcnt(0)
	v_mfma_f32_16x16x32_bf16 v[124:127], v[144:147], v[184:187], v[124:127]
	v_mfma_f32_16x16x32_bf16 v[120:123], v[160:163], v[184:187], v[120:123]
	v_mfma_f32_16x16x32_bf16 v[108:111], v[144:147], v[192:195], v[108:111]
	v_mfma_f32_16x16x32_bf16 v[104:107], v[160:163], v[192:195], v[104:107]
	v_mfma_f32_16x16x32_bf16 v[92:95], v[144:147], v[200:203], v[92:95]
	v_mfma_f32_16x16x32_bf16 v[88:91], v[160:163], v[200:203], v[88:91]
	v_mfma_f32_16x16x32_bf16 v[76:79], v[144:147], v[208:211], v[76:79]
	v_mfma_f32_16x16x32_bf16 v[72:75], v[160:163], v[208:211], v[72:75]
	v_mfma_f32_16x16x32_bf16 v[124:127], v[156:159], v[188:191], v[124:127]
	v_mfma_f32_16x16x32_bf16 v[120:123], v[164:167], v[188:191], v[120:123]
	v_mfma_f32_16x16x32_bf16 v[108:111], v[156:159], v[196:199], v[108:111]
	v_mfma_f32_16x16x32_bf16 v[104:107], v[164:167], v[196:199], v[104:107]
	v_mfma_f32_16x16x32_bf16 v[92:95], v[156:159], v[204:207], v[92:95]
	v_mfma_f32_16x16x32_bf16 v[88:91], v[164:167], v[204:207], v[88:91]
	v_mfma_f32_16x16x32_bf16 v[76:79], v[156:159], v[212:215], v[76:79]
	v_mfma_f32_16x16x32_bf16 v[72:75], v[164:167], v[212:215], v[72:75]
	s_setprio 0
	s_setprio 1
	v_mfma_f32_16x16x32_bf16 v[116:119], v[168:171], v[184:187], v[116:119]
	v_mfma_f32_16x16x32_bf16 v[112:115], v[176:179], v[184:187], v[112:115]
	v_mfma_f32_16x16x32_bf16 v[100:103], v[168:171], v[192:195], v[100:103]
	v_mfma_f32_16x16x32_bf16 v[96:99], v[176:179], v[192:195], v[96:99]
	v_mfma_f32_16x16x32_bf16 v[84:87], v[168:171], v[200:203], v[84:87]
	v_mfma_f32_16x16x32_bf16 v[80:83], v[176:179], v[200:203], v[80:83]
	v_mfma_f32_16x16x32_bf16 v[68:71], v[168:171], v[208:211], v[68:71]
	v_mfma_f32_16x16x32_bf16 v[64:67], v[176:179], v[208:211], v[64:67]
	v_mfma_f32_16x16x32_bf16 v[116:119], v[172:175], v[188:191], v[116:119]
	v_mfma_f32_16x16x32_bf16 v[112:115], v[180:183], v[188:191], v[112:115]
	v_mfma_f32_16x16x32_bf16 v[100:103], v[172:175], v[196:199], v[100:103]
	v_mfma_f32_16x16x32_bf16 v[96:99], v[180:183], v[196:199], v[96:99]
	v_mfma_f32_16x16x32_bf16 v[84:87], v[172:175], v[204:207], v[84:87]
	v_mfma_f32_16x16x32_bf16 v[80:83], v[180:183], v[204:207], v[80:83]
	v_mfma_f32_16x16x32_bf16 v[68:71], v[172:175], v[212:215], v[68:71]
	v_mfma_f32_16x16x32_bf16 v[64:67], v[180:183], v[212:215], v[64:67]
	s_setprio 0
	s_barrier
	s_add_i32 s3, s3, s18
	v_lshl_add_u64 v[148:149], v[148:149], 0, s[10:11]
	s_mov_b32 m0, s3
	ds_read_b128 v[184:187], v155 offset:49152
	ds_read_b128 v[188:191], v155 offset:50176
	ds_read_b128 v[192:195], v155 offset:51200
	ds_read_b128 v[196:199], v155 offset:52224
	ds_read_b128 v[200:203], v155 offset:53248
	ds_read_b128 v[204:207], v155 offset:54272
	ds_read_b128 v[208:211], v155 offset:55296
	ds_read_b128 v[212:215], v155 offset:56320
	global_load_lds_dwordx4 v[148:149], off
	s_add_i32 m0, s3, 0x2000
	s_add_u32 s42, s88, 0x40080
	v_lshl_add_u64 v[148:149], v[216:217], 0, s[10:11]
	s_addc_u32 s43, s89, 0
	s_add_i32 s3, s37, s18
	global_load_lds_dwordx4 v[148:149], off
	s_mov_b32 m0, s3
	s_nop 0
	global_load_lds_dwordx4 v130, s[42:43]
	s_add_i32 m0, s3, 0x2000
	s_nop 0
	global_load_lds_dwordx4 v134, s[42:43]
	v_lshl_add_u64 v[148:149], v[218:219], 0, s[10:11]
	s_mov_b32 m0, s49
	s_nop 0
	global_load_lds_dwordx4 v[148:149], off
	v_lshl_add_u64 v[148:149], v[220:221], 0, s[10:11]
	s_mov_b32 m0, s56
	s_nop 0
	global_load_lds_dwordx4 v[148:149], off
	s_waitcnt vmcnt(8)
	s_waitcnt lgkmcnt(0)
	s_barrier
	s_setprio 1
	s_waitcnt lgkmcnt(0)
	v_mfma_f32_16x16x32_bf16 v[60:63], v[144:147], v[184:187], v[60:63]
	v_mfma_f32_16x16x32_bf16 v[56:59], v[160:163], v[184:187], v[56:59]
	v_mfma_f32_16x16x32_bf16 v[44:47], v[144:147], v[192:195], v[44:47]
	v_mfma_f32_16x16x32_bf16 v[40:43], v[160:163], v[192:195], v[40:43]
	v_mfma_f32_16x16x32_bf16 v[28:31], v[144:147], v[200:203], v[28:31]
	v_mfma_f32_16x16x32_bf16 v[24:27], v[160:163], v[200:203], v[24:27]
	v_mfma_f32_16x16x32_bf16 v[12:15], v[144:147], v[208:211], v[12:15]
	v_mfma_f32_16x16x32_bf16 v[8:11], v[160:163], v[208:211], v[8:11]
	v_mfma_f32_16x16x32_bf16 v[60:63], v[156:159], v[188:191], v[60:63]
	v_mfma_f32_16x16x32_bf16 v[56:59], v[164:167], v[188:191], v[56:59]
	v_mfma_f32_16x16x32_bf16 v[44:47], v[156:159], v[196:199], v[44:47]
	v_mfma_f32_16x16x32_bf16 v[40:43], v[164:167], v[196:199], v[40:43]
	v_mfma_f32_16x16x32_bf16 v[28:31], v[156:159], v[204:207], v[28:31]
	v_mfma_f32_16x16x32_bf16 v[24:27], v[164:167], v[204:207], v[24:27]
	v_mfma_f32_16x16x32_bf16 v[12:15], v[156:159], v[212:215], v[12:15]
	v_mfma_f32_16x16x32_bf16 v[8:11], v[164:167], v[212:215], v[8:11]
	s_setprio 0
	s_setprio 1
	v_mfma_f32_16x16x32_bf16 v[52:55], v[168:171], v[184:187], v[52:55]
	v_mfma_f32_16x16x32_bf16 v[48:51], v[176:179], v[184:187], v[48:51]
	v_mfma_f32_16x16x32_bf16 v[36:39], v[168:171], v[192:195], v[36:39]
	v_mfma_f32_16x16x32_bf16 v[32:35], v[176:179], v[192:195], v[32:35]
	v_mfma_f32_16x16x32_bf16 v[20:23], v[168:171], v[200:203], v[20:23]
	v_mfma_f32_16x16x32_bf16 v[16:19], v[176:179], v[200:203], v[16:19]
	v_mfma_f32_16x16x32_bf16 v[4:7], v[168:171], v[208:211], v[4:7]
	v_mfma_f32_16x16x32_bf16 v[0:3], v[176:179], v[208:211], v[0:3]
	v_mfma_f32_16x16x32_bf16 v[52:55], v[172:175], v[188:191], v[52:55]
	v_mfma_f32_16x16x32_bf16 v[48:51], v[180:183], v[188:191], v[48:51]
	v_mfma_f32_16x16x32_bf16 v[36:39], v[172:175], v[196:199], v[36:39]
	v_mfma_f32_16x16x32_bf16 v[32:35], v[180:183], v[196:199], v[32:35]
	v_mfma_f32_16x16x32_bf16 v[20:23], v[172:175], v[204:207], v[20:23]
	v_mfma_f32_16x16x32_bf16 v[16:19], v[180:183], v[204:207], v[16:19]
	v_mfma_f32_16x16x32_bf16 v[4:7], v[172:175], v[212:215], v[4:7]
	v_mfma_f32_16x16x32_bf16 v[0:3], v[180:183], v[212:215], v[0:3]
	s_setprio 0
	s_barrier
	s_add_i32 s36, s36, 2
	s_add_u32 s86, s86, 0x100
	s_addc_u32 s87, s87, 0
	s_add_u32 s33, s33, 0x100
	s_addc_u32 s35, s35, 0
	s_cmp_gt_u32 s36, 13
	s_cbranch_scc0 .LBB0_539
	s_and_b64 vcc, exec, s[12:13]
	s_cbranch_vccz .LBB0_542
	s_barrier

.LBB0_553:
	v_lshrrev_b32_e32 v16, 1, v14
	v_and_b32_e32 v16, 24, v16
	v_and_b32_e32 v15, 15, v14
	v_lshlrev_b32_e32 v17, 1, v16
	v_lshlrev_b32_e32 v14, 2, v14
	v_lshl_or_b32 v154, s0, 6, v15
	v_lshl_or_b32 v15, v15, 6, v17
	s_lshl_b32 s0, s0, 13
	v_and_b32_e32 v14, 32, v14
	v_bitop3_b32 v17, v15, s0, v14 bitop3:0xde
	s_lshl_b32 s0, s1, 5
	s_mov_b64 s[12:13], 0x80
	s_sext_i32_i8 s7, s8
	s_and_b32 s8, s0, 0x60
	s_add_i32 m0, s19, 0x18000
	v_lshl_add_u64 v[6:7], v[6:7], 0, s[12:13]
	s_lshl_b32 s0, s8, 7
	s_waitcnt vmcnt(2)
	s_barrier
	global_load_lds_dwordx4 v[6:7], off
	v_lshl_add_u64 v[4:5], v[4:5], 0, s[12:13]
	s_add_i32 m0, s19, 0x1a000
	s_add_i32 s58, s19, 0x8000
	s_add_i32 s59, s19, 0xa000
	v_bitop3_b32 v155, v15, s0, v14 bitop3:0xde
	global_load_lds_dwordx4 v[4:5], off
	v_lshl_add_u64 v[2:3], v[2:3], 0, s[12:13]
	s_mov_b32 m0, s58
	s_add_u32 s0, s88, 0x20080
	global_load_lds_dwordx4 v[2:3], off
	v_lshl_add_u64 v[0:1], v[0:1], 0, s[12:13]
	s_mov_b32 m0, s59
	s_addc_u32 s1, s89, 0
	global_load_lds_dwordx4 v[0:1], off
	s_add_i32 m0, s19, 0x1c000
	s_nop 0
	global_load_lds_dwordx4 v130, s[0:1]
	s_add_i32 m0, s19, 0x1e000
	s_cmpk_lt_u32 s3, 0x100
	global_load_lds_dwordx4 v134, s[0:1]
	v_lshlrev_b32_e32 v0, 13, v8
	v_and_b32_e32 v0, 0xffffc000, v0
	v_lshl_add_u32 v0, v9, 10, v0
	v_and_b32_e32 v1, 1, v8
	v_lshl_or_b32 v0, v1, 6, v0
	v_lshl_add_u32 v136, v10, 1, v0
	v_lshlrev_b32_e32 v0, 13, v11
	v_and_b32_e32 v0, 0xffffc000, v0
	s_waitcnt vmcnt(6)
	v_lshl_add_u32 v0, v12, 10, v0
	v_and_b32_e32 v1, 1, v11
	s_cselect_b64 s[14:15], -1, 0
	v_lshl_or_b32 v0, v1, 6, v0
	s_add_i32 s78, 0, 0x10000
	s_add_i32 s79, 0, 0x14000
	v_or_b32_e32 v156, s8, v16
	v_mov_b32_e32 v137, v131
	v_lshl_add_u32 v138, v13, 1, v0
	v_mov_b32_e32 v139, v131
	v_mov_b64_e32 v[140:141], 0x200
	v_mov_b64_e32 v[142:143], 0x1ff
	v_add_u32_e32 v157, s78, v155
	v_add_u32_e32 v158, s79, v155
	v_add_u32_e32 v159, 0, v17
	s_movk_i32 s92, 0x5c00
	s_mov_b64 s[16:17], 0x4c00
	s_barrier
	s_branch .LBB0_556

.LBB0_563:
	ds_read_b128 v[144:147], v157
	ds_read_b128 v[148:151], v157 offset:1024
	ds_read_b128 v[160:163], v157 offset:2048
	ds_read_b128 v[164:167], v157 offset:3072
	ds_read_b128 v[168:171], v158
	ds_read_b128 v[172:175], v158 offset:1024
	ds_read_b128 v[176:179], v158 offset:2048
	ds_read_b128 v[180:183], v158 offset:3072
	s_add_u32 s3, s34, 0xfffe0080
	s_addc_u32 s42, s35, -1
	s_cmp_eq_u32 s37, 4
	s_cselect_b32 s91, s0, s42
	s_cselect_b32 s90, s1, s3
	s_cselect_b32 s89, s24, s36
	s_cselect_b32 s88, s27, s33
	s_add_i32 m0, s19, 0xc000
	ds_read_b128 v[184:187], v159
	ds_read_b128 v[188:191], v159 offset:1024
	ds_read_b128 v[192:195], v159 offset:2048
	ds_read_b128 v[196:199], v159 offset:3072
	ds_read_b128 v[200:203], v159 offset:4096
	ds_read_b128 v[204:207], v159 offset:5120
	ds_read_b128 v[208:211], v159 offset:6144
	ds_read_b128 v[212:215], v159 offset:7168
	global_load_lds_dwordx4 v136, s[34:35]
	s_add_i32 m0, s19, 0xe000
	s_nop 0
	global_load_lds_dwordx4 v138, s[34:35]
	s_waitcnt vmcnt(8)
	s_waitcnt lgkmcnt(0)
	s_barrier
	s_setprio 1
	s_waitcnt lgkmcnt(0)
	v_mfma_f32_16x16x32_bf16 v[124:127], v[144:147], v[184:187], v[124:127]
	v_mfma_f32_16x16x32_bf16 v[120:123], v[160:163], v[184:187], v[120:123]
	v_mfma_f32_16x16x32_bf16 v[108:111], v[144:147], v[192:195], v[108:111]
	v_mfma_f32_16x16x32_bf16 v[104:107], v[160:163], v[192:195], v[104:107]
	v_mfma_f32_16x16x32_bf16 v[92:95], v[144:147], v[200:203], v[92:95]
	v_mfma_f32_16x16x32_bf16 v[88:91], v[160:163], v[200:203], v[88:91]
	v_mfma_f32_16x16x32_bf16 v[76:79], v[144:147], v[208:211], v[76:79]
	v_mfma_f32_16x16x32_bf16 v[72:75], v[160:163], v[208:211], v[72:75]
	v_mfma_f32_16x16x32_bf16 v[124:127], v[148:151], v[188:191], v[124:127]
	v_mfma_f32_16x16x32_bf16 v[120:123], v[164:167], v[188:191], v[120:123]
	v_mfma_f32_16x16x32_bf16 v[108:111], v[148:151], v[196:199], v[108:111]
	v_mfma_f32_16x16x32_bf16 v[104:107], v[164:167], v[196:199], v[104:107]
	v_mfma_f32_16x16x32_bf16 v[92:95], v[148:151], v[204:207], v[92:95]
	v_mfma_f32_16x16x32_bf16 v[88:91], v[164:167], v[204:207], v[88:91]
	v_mfma_f32_16x16x32_bf16 v[76:79], v[148:151], v[212:215], v[76:79]
	v_mfma_f32_16x16x32_bf16 v[72:75], v[164:167], v[212:215], v[72:75]
	s_setprio 0
	s_setprio 1
	v_mfma_f32_16x16x32_bf16 v[116:119], v[168:171], v[184:187], v[116:119]
	v_mfma_f32_16x16x32_bf16 v[112:115], v[176:179], v[184:187], v[112:115]
	v_mfma_f32_16x16x32_bf16 v[100:103], v[168:171], v[192:195], v[100:103]
	v_mfma_f32_16x16x32_bf16 v[96:99], v[176:179], v[192:195], v[96:99]
	v_mfma_f32_16x16x32_bf16 v[84:87], v[168:171], v[200:203], v[84:87]
	v_mfma_f32_16x16x32_bf16 v[80:83], v[176:179], v[200:203], v[80:83]
	v_mfma_f32_16x16x32_bf16 v[68:71], v[168:171], v[208:211], v[68:71]
	v_mfma_f32_16x16x32_bf16 v[64:67], v[176:179], v[208:211], v[64:67]
	v_mfma_f32_16x16x32_bf16 v[116:119], v[172:175], v[188:191], v[116:119]
	v_mfma_f32_16x16x32_bf16 v[112:115], v[180:183], v[188:191], v[112:115]
	v_mfma_f32_16x16x32_bf16 v[100:103], v[172:175], v[196:199], v[100:103]
	v_mfma_f32_16x16x32_bf16 v[96:99], v[180:183], v[196:199], v[96:99]
	v_mfma_f32_16x16x32_bf16 v[84:87], v[172:175], v[204:207], v[84:87]
	v_mfma_f32_16x16x32_bf16 v[80:83], v[180:183], v[204:207], v[80:83]
	v_mfma_f32_16x16x32_bf16 v[68:71], v[172:175], v[212:215], v[68:71]
	v_mfma_f32_16x16x32_bf16 v[64:67], v[180:183], v[212:215], v[64:67]
	s_setprio 0
	s_barrier
	s_add_i32 s3, s78, s18
	v_lshl_add_u64 v[152:153], s[88:89], 0, v[130:131]
	s_mov_b32 m0, s3
	ds_read_b128 v[184:187], v159 offset:16384
	ds_read_b128 v[188:191], v159 offset:17408
	ds_read_b128 v[192:195], v159 offset:18432
	ds_read_b128 v[196:199], v159 offset:19456
	ds_read_b128 v[200:203], v159 offset:20480
	ds_read_b128 v[204:207], v159 offset:21504
	ds_read_b128 v[208:211], v159 offset:22528
	ds_read_b128 v[212:215], v159 offset:23552
	global_load_lds_dwordx4 v[152:153], off
	s_add_i32 m0, s3, 0x2000
	s_add_u32 s42, s88, 0x20000
	v_lshl_add_u64 v[216:217], s[88:89], 0, v[134:135]
	s_addc_u32 s43, s89, 0
	s_add_i32 s3, s79, s18
	global_load_lds_dwordx4 v[216:217], off
	s_mov_b32 m0, s3
	v_lshl_add_u64 v[220:221], s[90:91], 0, v[132:133]
	global_load_lds_dwordx4 v130, s[42:43]
	s_add_i32 m0, s3, 0x2000
	s_nop 0
	global_load_lds_dwordx4 v134, s[42:43]
	v_lshl_add_u64 v[218:219], s[90:91], 0, v[128:129]
	s_mov_b32 m0, s19
	s_nop 0
	global_load_lds_dwordx4 v[218:219], off
	s_mov_b32 m0, s25
	s_nop 0
	global_load_lds_dwordx4 v[220:221], off
	s_waitcnt vmcnt(8)
	s_waitcnt lgkmcnt(0)
	s_barrier
	s_setprio 1
	s_waitcnt lgkmcnt(0)
	v_mfma_f32_16x16x32_bf16 v[60:63], v[144:147], v[184:187], v[60:63]
	v_mfma_f32_16x16x32_bf16 v[56:59], v[160:163], v[184:187], v[56:59]
	v_mfma_f32_16x16x32_bf16 v[44:47], v[144:147], v[192:195], v[44:47]
	v_mfma_f32_16x16x32_bf16 v[40:43], v[160:163], v[192:195], v[40:43]
	v_mfma_f32_16x16x32_bf16 v[28:31], v[144:147], v[200:203], v[28:31]
	v_mfma_f32_16x16x32_bf16 v[24:27], v[160:163], v[200:203], v[24:27]
	v_mfma_f32_16x16x32_bf16 v[12:15], v[144:147], v[208:211], v[12:15]
	v_mfma_f32_16x16x32_bf16 v[8:11], v[160:163], v[208:211], v[8:11]
	v_mfma_f32_16x16x32_bf16 v[60:63], v[148:151], v[188:191], v[60:63]
	v_mfma_f32_16x16x32_bf16 v[56:59], v[164:167], v[188:191], v[56:59]
	v_mfma_f32_16x16x32_bf16 v[44:47], v[148:151], v[196:199], v[44:47]
	v_mfma_f32_16x16x32_bf16 v[40:43], v[164:167], v[196:199], v[40:43]
	v_mfma_f32_16x16x32_bf16 v[28:31], v[148:151], v[204:207], v[28:31]
	v_mfma_f32_16x16x32_bf16 v[24:27], v[164:167], v[204:207], v[24:27]
	v_mfma_f32_16x16x32_bf16 v[12:15], v[148:151], v[212:215], v[12:15]
	v_mfma_f32_16x16x32_bf16 v[8:11], v[164:167], v[212:215], v[8:11]
	s_setprio 0
	s_setprio 1
	v_mfma_f32_16x16x32_bf16 v[52:55], v[168:171], v[184:187], v[52:55]
	v_mfma_f32_16x16x32_bf16 v[48:51], v[176:179], v[184:187], v[48:51]
	v_mfma_f32_16x16x32_bf16 v[36:39], v[168:171], v[192:195], v[36:39]
	v_mfma_f32_16x16x32_bf16 v[32:35], v[176:179], v[192:195], v[32:35]
	v_mfma_f32_16x16x32_bf16 v[20:23], v[168:171], v[200:203], v[20:23]
	v_mfma_f32_16x16x32_bf16 v[16:19], v[176:179], v[200:203], v[16:19]
	v_mfma_f32_16x16x32_bf16 v[4:7], v[168:171], v[208:211], v[4:7]
	v_mfma_f32_16x16x32_bf16 v[0:3], v[176:179], v[208:211], v[0:3]
	v_mfma_f32_16x16x32_bf16 v[52:55], v[172:175], v[188:191], v[52:55]
	v_mfma_f32_16x16x32_bf16 v[48:51], v[180:183], v[188:191], v[48:51]
	v_mfma_f32_16x16x32_bf16 v[36:39], v[172:175], v[196:199], v[36:39]
	v_mfma_f32_16x16x32_bf16 v[32:35], v[180:183], v[196:199], v[32:35]
	v_mfma_f32_16x16x32_bf16 v[20:23], v[172:175], v[204:207], v[20:23]
	v_mfma_f32_16x16x32_bf16 v[16:19], v[180:183], v[204:207], v[16:19]
	v_mfma_f32_16x16x32_bf16 v[4:7], v[172:175], v[212:215], v[4:7]
	v_mfma_f32_16x16x32_bf16 v[0:3], v[180:183], v[212:215], v[0:3]
	s_setprio 0
	s_barrier
	s_add_i32 s3, 0, 0x18000
	s_add_i32 s44, 0, 0x1c000
	v_add_u32_e32 v164, s3, v155
	v_add_u32_e32 v180, s44, v155
	ds_read_b128 v[144:147], v164
	ds_read_b128 v[148:151], v164 offset:1024
	ds_read_b128 v[160:163], v164 offset:2048
	ds_read_b128 v[164:167], v164 offset:3072
	ds_read_b128 v[168:171], v180
	ds_read_b128 v[172:175], v180 offset:1024
	ds_read_b128 v[176:179], v180 offset:2048
	ds_read_b128 v[180:183], v180 offset:3072
	s_add_u32 s42, s90, 0x20000
	s_addc_u32 s43, s91, 0
	s_mov_b32 m0, s30
	ds_read_b128 v[184:187], v159 offset:32768
	ds_read_b128 v[188:191], v159 offset:33792
	ds_read_b128 v[192:195], v159 offset:34816
	ds_read_b128 v[196:199], v159 offset:35840
	ds_read_b128 v[200:203], v159 offset:36864
	ds_read_b128 v[204:207], v159 offset:37888
	ds_read_b128 v[208:211], v159 offset:38912
	ds_read_b128 v[212:215], v159 offset:39936
	global_load_lds_dwordx4 v128, s[42:43]
	v_lshl_add_u64 v[222:223], s[42:43], 0, v[132:133]
	s_mov_b32 m0, s31
	s_nop 0
	global_load_lds_dwordx4 v[222:223], off
	s_waitcnt vmcnt(8)
	s_waitcnt lgkmcnt(0)
	s_barrier
	s_setprio 1
	s_waitcnt lgkmcnt(0)
	v_mfma_f32_16x16x32_bf16 v[124:127], v[144:147], v[184:187], v[124:127]
	v_mfma_f32_16x16x32_bf16 v[120:123], v[160:163], v[184:187], v[120:123]
	v_mfma_f32_16x16x32_bf16 v[108:111], v[144:147], v[192:195], v[108:111]
	v_mfma_f32_16x16x32_bf16 v[104:107], v[160:163], v[192:195], v[104:107]
	v_mfma_f32_16x16x32_bf16 v[92:95], v[144:147], v[200:203], v[92:95]
	v_mfma_f32_16x16x32_bf16 v[88:91], v[160:163], v[200:203], v[88:91]
	v_mfma_f32_16x16x32_bf16 v[76:79], v[144:147], v[208:211], v[76:79]
	v_mfma_f32_16x16x32_bf16 v[72:75], v[160:163], v[208:211], v[72:75]
	v_mfma_f32_16x16x32_bf16 v[124:127], v[148:151], v[188:191], v[124:127]
	v_mfma_f32_16x16x32_bf16 v[120:123], v[164:167], v[188:191], v[120:123]
	v_mfma_f32_16x16x32_bf16 v[108:111], v[148:151], v[196:199], v[108:111]
	v_mfma_f32_16x16x32_bf16 v[104:107], v[164:167], v[196:199], v[104:107]
	v_mfma_f32_16x16x32_bf16 v[92:95], v[148:151], v[204:207], v[92:95]
	v_mfma_f32_16x16x32_bf16 v[88:91], v[164:167], v[204:207], v[88:91]
	v_mfma_f32_16x16x32_bf16 v[76:79], v[148:151], v[212:215], v[76:79]
	v_mfma_f32_16x16x32_bf16 v[72:75], v[164:167], v[212:215], v[72:75]
	s_setprio 0
	s_setprio 1
	v_mfma_f32_16x16x32_bf16 v[116:119], v[168:171], v[184:187], v[116:119]
	v_mfma_f32_16x16x32_bf16 v[112:115], v[176:179], v[184:187], v[112:115]
	v_mfma_f32_16x16x32_bf16 v[100:103], v[168:171], v[192:195], v[100:103]
	v_mfma_f32_16x16x32_bf16 v[96:99], v[176:179], v[192:195], v[96:99]
	v_mfma_f32_16x16x32_bf16 v[84:87], v[168:171], v[200:203], v[84:87]
	v_mfma_f32_16x16x32_bf16 v[80:83], v[176:179], v[200:203], v[80:83]
	v_mfma_f32_16x16x32_bf16 v[68:71], v[168:171], v[208:211], v[68:71]
	v_mfma_f32_16x16x32_bf16 v[64:67], v[176:179], v[208:211], v[64:67]
	v_mfma_f32_16x16x32_bf16 v[116:119], v[172:175], v[188:191], v[116:119]
	v_mfma_f32_16x16x32_bf16 v[112:115], v[180:183], v[188:191], v[112:115]
	v_mfma_f32_16x16x32_bf16 v[100:103], v[172:175], v[196:199], v[100:103]
	v_mfma_f32_16x16x32_bf16 v[96:99], v[180:183], v[196:199], v[96:99]
	v_mfma_f32_16x16x32_bf16 v[84:87], v[172:175], v[204:207], v[84:87]
	v_mfma_f32_16x16x32_bf16 v[80:83], v[180:183], v[204:207], v[80:83]
	v_mfma_f32_16x16x32_bf16 v[68:71], v[172:175], v[212:215], v[68:71]
	v_mfma_f32_16x16x32_bf16 v[64:67], v[180:183], v[212:215], v[64:67]
	s_setprio 0
	s_barrier
	s_add_i32 s3, s3, s18
	v_lshl_add_u64 v[152:153], v[152:153], 0, s[12:13]
	s_mov_b32 m0, s3
	ds_read_b128 v[184:187], v159 offset:49152
	ds_read_b128 v[188:191], v159 offset:50176
	ds_read_b128 v[192:195], v159 offset:51200
	ds_read_b128 v[196:199], v159 offset:52224
	ds_read_b128 v[200:203], v159 offset:53248
	ds_read_b128 v[204:207], v159 offset:54272
	ds_read_b128 v[208:211], v159 offset:55296
	ds_read_b128 v[212:215], v159 offset:56320
	global_load_lds_dwordx4 v[152:153], off
	s_add_i32 m0, s3, 0x2000
	s_add_u32 s42, s88, 0x20080
	v_lshl_add_u64 v[152:153], v[216:217], 0, s[12:13]
	s_addc_u32 s43, s89, 0
	s_add_i32 s3, s44, s18
	global_load_lds_dwordx4 v[152:153], off
	s_mov_b32 m0, s3
	s_nop 0
	global_load_lds_dwordx4 v130, s[42:43]
	s_add_i32 m0, s3, 0x2000
	s_nop 0
	global_load_lds_dwordx4 v134, s[42:43]
	v_lshl_add_u64 v[152:153], v[218:219], 0, s[12:13]
	s_mov_b32 m0, s58
	s_nop 0
	global_load_lds_dwordx4 v[152:153], off
	v_lshl_add_u64 v[152:153], v[220:221], 0, s[12:13]
	s_mov_b32 m0, s59
	s_nop 0
	global_load_lds_dwordx4 v[152:153], off
	s_waitcnt vmcnt(8)
	s_waitcnt lgkmcnt(0)
	s_barrier
	s_setprio 1
	s_waitcnt lgkmcnt(0)
	v_mfma_f32_16x16x32_bf16 v[60:63], v[144:147], v[184:187], v[60:63]
	v_mfma_f32_16x16x32_bf16 v[56:59], v[160:163], v[184:187], v[56:59]
	v_mfma_f32_16x16x32_bf16 v[44:47], v[144:147], v[192:195], v[44:47]
	v_mfma_f32_16x16x32_bf16 v[40:43], v[160:163], v[192:195], v[40:43]
	v_mfma_f32_16x16x32_bf16 v[28:31], v[144:147], v[200:203], v[28:31]
	v_mfma_f32_16x16x32_bf16 v[24:27], v[160:163], v[200:203], v[24:27]
	v_mfma_f32_16x16x32_bf16 v[12:15], v[144:147], v[208:211], v[12:15]
	v_mfma_f32_16x16x32_bf16 v[8:11], v[160:163], v[208:211], v[8:11]
	v_mfma_f32_16x16x32_bf16 v[60:63], v[148:151], v[188:191], v[60:63]
	v_mfma_f32_16x16x32_bf16 v[56:59], v[164:167], v[188:191], v[56:59]
	v_mfma_f32_16x16x32_bf16 v[44:47], v[148:151], v[196:199], v[44:47]
	v_mfma_f32_16x16x32_bf16 v[40:43], v[164:167], v[196:199], v[40:43]
	v_mfma_f32_16x16x32_bf16 v[28:31], v[148:151], v[204:207], v[28:31]
	v_mfma_f32_16x16x32_bf16 v[24:27], v[164:167], v[204:207], v[24:27]
	v_mfma_f32_16x16x32_bf16 v[12:15], v[148:151], v[212:215], v[12:15]
	v_mfma_f32_16x16x32_bf16 v[8:11], v[164:167], v[212:215], v[8:11]
	s_setprio 0
	s_setprio 1
	v_mfma_f32_16x16x32_bf16 v[52:55], v[168:171], v[184:187], v[52:55]
	v_mfma_f32_16x16x32_bf16 v[48:51], v[176:179], v[184:187], v[48:51]
	v_mfma_f32_16x16x32_bf16 v[36:39], v[168:171], v[192:195], v[36:39]
	v_mfma_f32_16x16x32_bf16 v[32:35], v[176:179], v[192:195], v[32:35]
	v_mfma_f32_16x16x32_bf16 v[20:23], v[168:171], v[200:203], v[20:23]
	v_mfma_f32_16x16x32_bf16 v[16:19], v[176:179], v[200:203], v[16:19]
	v_mfma_f32_16x16x32_bf16 v[4:7], v[168:171], v[208:211], v[4:7]
	v_mfma_f32_16x16x32_bf16 v[0:3], v[176:179], v[208:211], v[0:3]
	v_mfma_f32_16x16x32_bf16 v[52:55], v[172:175], v[188:191], v[52:55]
	v_mfma_f32_16x16x32_bf16 v[48:51], v[180:183], v[188:191], v[48:51]
	v_mfma_f32_16x16x32_bf16 v[36:39], v[172:175], v[196:199], v[36:39]
	v_mfma_f32_16x16x32_bf16 v[32:35], v[180:183], v[196:199], v[32:35]
	v_mfma_f32_16x16x32_bf16 v[20:23], v[172:175], v[204:207], v[20:23]
	v_mfma_f32_16x16x32_bf16 v[16:19], v[180:183], v[204:207], v[16:19]
	v_mfma_f32_16x16x32_bf16 v[4:7], v[172:175], v[212:215], v[4:7]
	v_mfma_f32_16x16x32_bf16 v[0:3], v[180:183], v[212:215], v[0:3]
	s_setprio 0
	s_barrier
	s_add_i32 s37, s37, 2
	s_add_u32 s34, s34, 0x100
	s_addc_u32 s35, s35, 0
	s_add_u32 s33, s33, 0x100
	s_addc_u32 s36, s36, 0
	s_cmp_gt_u32 s37, 5
	s_cbranch_scc0 .LBB0_563
	s_and_b64 vcc, exec, s[14:15]
	s_cbranch_vccz .LBB0_566
	s_barrier

.LBB0_629:
	v_bfe_u32 v16, v14, 4, 2
	v_and_b32_e32 v15, 15, v14
	v_lshlrev_b32_e32 v17, 4, v16
	v_lshlrev_b32_e32 v14, 2, v14
	v_lshl_or_b32 v146, s0, 6, v15
	v_lshl_or_b32 v15, v15, 6, v17
	s_lshl_b32 s0, s0, 13
	v_and_b32_e32 v14, 32, v14
	v_bitop3_b32 v17, v15, s0, v14 bitop3:0xde
	s_lshl_b32 s0, s1, 5
	s_mov_b64 s[10:11], 0x80
	s_sext_i32_i8 s18, s8
	s_and_b32 s8, s0, 0x60
	s_add_i32 m0, s30, 0x18000
	v_lshl_add_u64 v[6:7], v[6:7], 0, s[10:11]
	s_lshl_b32 s0, s8, 7
	s_waitcnt vmcnt(2)
	s_barrier
	global_load_lds_dwordx4 v[6:7], off
	v_lshl_add_u64 v[4:5], v[4:5], 0, s[10:11]
	s_add_i32 m0, s30, 0x1a000
	s_add_i32 s57, s30, 0x8000
	s_add_i32 s58, s30, 0xa000
	v_bitop3_b32 v147, v15, s0, v14 bitop3:0xde
	global_load_lds_dwordx4 v[4:5], off
	v_lshl_add_u64 v[0:1], v[0:1], 0, s[10:11]
	s_mov_b32 m0, s57
	s_add_u32 s0, s88, 0x80080
	global_load_lds_dwordx4 v[0:1], off
	v_lshl_add_u64 v[0:1], v[2:3], 0, s[10:11]
	s_mov_b32 m0, s58
	s_addc_u32 s1, s89, 0
	global_load_lds_dwordx4 v[0:1], off
	s_add_i32 m0, s30, 0x1c000
	s_nop 0
	global_load_lds_dwordx4 v128, s[0:1]
	s_add_i32 m0, s30, 0x1e000
	s_cmpk_lt_u32 s3, 0x100
	global_load_lds_dwordx4 v130, s[0:1]
	v_lshlrev_b32_e32 v0, 15, v8
	v_and_b32_e32 v0, 0xffff0000, v0
	v_lshl_add_u32 v0, v9, 12, v0
	v_and_b32_e32 v1, 1, v8
	v_lshl_or_b32 v0, v1, 6, v0
	v_lshl_add_u32 v132, v10, 1, v0
	v_lshlrev_b32_e32 v0, 15, v11
	v_and_b32_e32 v0, 0xffff0000, v0
	s_waitcnt vmcnt(6)
	v_lshl_add_u32 v0, v12, 12, v0
	v_and_b32_e32 v1, 1, v11
	s_cselect_b64 s[12:13], -1, 0
	v_lshl_or_b32 v0, v1, 6, v0
	s_add_i32 s59, 0, 0x10000
	s_add_i32 s68, 0, 0x14000
	v_lshl_or_b32 v148, v16, 2, s8
	v_mov_b32_e32 v133, v129
	v_lshl_add_u32 v134, v13, 1, v0
	v_mov_b32_e32 v135, v129
	v_mov_b64_e32 v[136:137], 0x200
	v_mov_b64_e32 v[138:139], 0x1ff
	v_add_u32_e32 v149, s59, v147
	v_add_u32_e32 v150, s68, v147
	v_add_u32_e32 v151, 0, v17
	s_barrier
	s_branch .LBB0_632

.LBB0_639:
	ds_read_b128 v[140:143], v149
	ds_read_b128 v[152:155], v149 offset:1024
	ds_read_b128 v[156:159], v149 offset:2048
	ds_read_b128 v[160:163], v149 offset:3072
	ds_read_b128 v[164:167], v150
	ds_read_b128 v[168:171], v150 offset:1024
	ds_read_b128 v[172:175], v150 offset:2048
	ds_read_b128 v[176:179], v150 offset:3072
	s_add_u32 s3, s86, 0xfff80080
	s_addc_u32 s33, s87, -1
	s_cmp_eq_u32 s27, 28
	s_cselect_b32 s91, s0, s33
	s_cselect_b32 s90, s1, s3
	s_cselect_b32 s89, s15, s24
	s_cselect_b32 s88, s17, s19
	s_add_i32 m0, s30, 0xc000
	ds_read_b128 v[180:183], v151
	ds_read_b128 v[184:187], v151 offset:1024
	ds_read_b128 v[188:191], v151 offset:2048
	ds_read_b128 v[192:195], v151 offset:3072
	ds_read_b128 v[196:199], v151 offset:4096
	ds_read_b128 v[200:203], v151 offset:5120
	ds_read_b128 v[204:207], v151 offset:6144
	ds_read_b128 v[208:211], v151 offset:7168
	global_load_lds_dwordx4 v132, s[86:87]
	s_add_i32 m0, s30, 0xe000
	s_nop 0
	global_load_lds_dwordx4 v134, s[86:87]
	s_waitcnt vmcnt(8)
	s_waitcnt lgkmcnt(0)
	s_barrier
	s_setprio 1
	s_waitcnt lgkmcnt(0)
	v_mfma_f32_16x16x32_bf16 v[124:127], v[140:143], v[180:183], v[124:127]
	v_mfma_f32_16x16x32_bf16 v[120:123], v[156:159], v[180:183], v[120:123]
	v_mfma_f32_16x16x32_bf16 v[108:111], v[140:143], v[188:191], v[108:111]
	v_mfma_f32_16x16x32_bf16 v[104:107], v[156:159], v[188:191], v[104:107]
	v_mfma_f32_16x16x32_bf16 v[92:95], v[140:143], v[196:199], v[92:95]
	v_mfma_f32_16x16x32_bf16 v[88:91], v[156:159], v[196:199], v[88:91]
	v_mfma_f32_16x16x32_bf16 v[76:79], v[140:143], v[204:207], v[76:79]
	v_mfma_f32_16x16x32_bf16 v[72:75], v[156:159], v[204:207], v[72:75]
	v_mfma_f32_16x16x32_bf16 v[124:127], v[152:155], v[184:187], v[124:127]
	v_mfma_f32_16x16x32_bf16 v[120:123], v[160:163], v[184:187], v[120:123]
	v_mfma_f32_16x16x32_bf16 v[108:111], v[152:155], v[192:195], v[108:111]
	v_mfma_f32_16x16x32_bf16 v[104:107], v[160:163], v[192:195], v[104:107]
	v_mfma_f32_16x16x32_bf16 v[92:95], v[152:155], v[200:203], v[92:95]
	v_mfma_f32_16x16x32_bf16 v[88:91], v[160:163], v[200:203], v[88:91]
	v_mfma_f32_16x16x32_bf16 v[76:79], v[152:155], v[208:211], v[76:79]
	v_mfma_f32_16x16x32_bf16 v[72:75], v[160:163], v[208:211], v[72:75]
	s_setprio 0
	s_setprio 1
	v_mfma_f32_16x16x32_bf16 v[116:119], v[164:167], v[180:183], v[116:119]
	v_mfma_f32_16x16x32_bf16 v[112:115], v[172:175], v[180:183], v[112:115]
	v_mfma_f32_16x16x32_bf16 v[100:103], v[164:167], v[188:191], v[100:103]
	v_mfma_f32_16x16x32_bf16 v[96:99], v[172:175], v[188:191], v[96:99]
	v_mfma_f32_16x16x32_bf16 v[84:87], v[164:167], v[196:199], v[84:87]
	v_mfma_f32_16x16x32_bf16 v[80:83], v[172:175], v[196:199], v[80:83]
	v_mfma_f32_16x16x32_bf16 v[68:71], v[164:167], v[204:207], v[68:71]
	v_mfma_f32_16x16x32_bf16 v[64:67], v[172:175], v[204:207], v[64:67]
	v_mfma_f32_16x16x32_bf16 v[116:119], v[168:171], v[184:187], v[116:119]
	v_mfma_f32_16x16x32_bf16 v[112:115], v[176:179], v[184:187], v[112:115]
	v_mfma_f32_16x16x32_bf16 v[100:103], v[168:171], v[192:195], v[100:103]
	v_mfma_f32_16x16x32_bf16 v[96:99], v[176:179], v[192:195], v[96:99]
	v_mfma_f32_16x16x32_bf16 v[84:87], v[168:171], v[200:203], v[84:87]
	v_mfma_f32_16x16x32_bf16 v[80:83], v[176:179], v[200:203], v[80:83]
	v_mfma_f32_16x16x32_bf16 v[68:71], v[168:171], v[208:211], v[68:71]
	v_mfma_f32_16x16x32_bf16 v[64:67], v[176:179], v[208:211], v[64:67]
	s_setprio 0
	s_barrier
	s_add_i32 s3, s59, s25
	v_lshl_add_u64 v[144:145], s[88:89], 0, v[128:129]
	s_mov_b32 m0, s3
	ds_read_b128 v[180:183], v151 offset:16384
	ds_read_b128 v[184:187], v151 offset:17408
	ds_read_b128 v[188:191], v151 offset:18432
	ds_read_b128 v[192:195], v151 offset:19456
	ds_read_b128 v[196:199], v151 offset:20480
	ds_read_b128 v[200:203], v151 offset:21504
	ds_read_b128 v[204:207], v151 offset:22528
	ds_read_b128 v[208:211], v151 offset:23552
	global_load_lds_dwordx4 v[144:145], off
	s_add_i32 m0, s3, 0x2000
	s_add_u32 s36, s88, 0x80000
	v_lshl_add_u64 v[212:213], s[88:89], 0, v[130:131]
	s_addc_u32 s37, s89, 0
	s_add_i32 s3, s68, s25
	global_load_lds_dwordx4 v[212:213], off
	s_mov_b32 m0, s3
	v_lshl_add_u64 v[216:217], s[90:91], 0, v[130:131]
	global_load_lds_dwordx4 v128, s[36:37]
	s_add_i32 m0, s3, 0x2000
	s_nop 0
	global_load_lds_dwordx4 v130, s[36:37]
	v_lshl_add_u64 v[214:215], s[90:91], 0, v[128:129]
	s_mov_b32 m0, s30
	s_nop 0
	global_load_lds_dwordx4 v[214:215], off
	s_mov_b32 m0, s31
	s_nop 0
	global_load_lds_dwordx4 v[216:217], off
	s_waitcnt vmcnt(8)
	s_waitcnt lgkmcnt(0)
	s_barrier
	s_setprio 1
	s_waitcnt lgkmcnt(0)
	v_mfma_f32_16x16x32_bf16 v[60:63], v[140:143], v[180:183], v[60:63]
	v_mfma_f32_16x16x32_bf16 v[56:59], v[156:159], v[180:183], v[56:59]
	v_mfma_f32_16x16x32_bf16 v[44:47], v[140:143], v[188:191], v[44:47]
	v_mfma_f32_16x16x32_bf16 v[40:43], v[156:159], v[188:191], v[40:43]
	v_mfma_f32_16x16x32_bf16 v[28:31], v[140:143], v[196:199], v[28:31]
	v_mfma_f32_16x16x32_bf16 v[24:27], v[156:159], v[196:199], v[24:27]
	v_mfma_f32_16x16x32_bf16 v[12:15], v[140:143], v[204:207], v[12:15]
	v_mfma_f32_16x16x32_bf16 v[8:11], v[156:159], v[204:207], v[8:11]
	v_mfma_f32_16x16x32_bf16 v[60:63], v[152:155], v[184:187], v[60:63]
	v_mfma_f32_16x16x32_bf16 v[56:59], v[160:163], v[184:187], v[56:59]
	v_mfma_f32_16x16x32_bf16 v[44:47], v[152:155], v[192:195], v[44:47]
	v_mfma_f32_16x16x32_bf16 v[40:43], v[160:163], v[192:195], v[40:43]
	v_mfma_f32_16x16x32_bf16 v[28:31], v[152:155], v[200:203], v[28:31]
	v_mfma_f32_16x16x32_bf16 v[24:27], v[160:163], v[200:203], v[24:27]
	v_mfma_f32_16x16x32_bf16 v[12:15], v[152:155], v[208:211], v[12:15]
	v_mfma_f32_16x16x32_bf16 v[8:11], v[160:163], v[208:211], v[8:11]
	s_setprio 0
	s_setprio 1
	v_mfma_f32_16x16x32_bf16 v[52:55], v[164:167], v[180:183], v[52:55]
	v_mfma_f32_16x16x32_bf16 v[48:51], v[172:175], v[180:183], v[48:51]
	v_mfma_f32_16x16x32_bf16 v[36:39], v[164:167], v[188:191], v[36:39]
	v_mfma_f32_16x16x32_bf16 v[32:35], v[172:175], v[188:191], v[32:35]
	v_mfma_f32_16x16x32_bf16 v[20:23], v[164:167], v[196:199], v[20:23]
	v_mfma_f32_16x16x32_bf16 v[16:19], v[172:175], v[196:199], v[16:19]
	v_mfma_f32_16x16x32_bf16 v[4:7], v[164:167], v[204:207], v[4:7]
	v_mfma_f32_16x16x32_bf16 v[0:3], v[172:175], v[204:207], v[0:3]
	v_mfma_f32_16x16x32_bf16 v[52:55], v[168:171], v[184:187], v[52:55]
	v_mfma_f32_16x16x32_bf16 v[48:51], v[176:179], v[184:187], v[48:51]
	v_mfma_f32_16x16x32_bf16 v[36:39], v[168:171], v[192:195], v[36:39]
	v_mfma_f32_16x16x32_bf16 v[32:35], v[176:179], v[192:195], v[32:35]
	v_mfma_f32_16x16x32_bf16 v[20:23], v[168:171], v[200:203], v[20:23]
	v_mfma_f32_16x16x32_bf16 v[16:19], v[176:179], v[200:203], v[16:19]
	v_mfma_f32_16x16x32_bf16 v[4:7], v[168:171], v[208:211], v[4:7]
	v_mfma_f32_16x16x32_bf16 v[0:3], v[176:179], v[208:211], v[0:3]
	s_setprio 0
	s_barrier
	s_add_i32 s3, 0, 0x18000
	s_add_i32 s33, 0, 0x1c000
	v_add_u32_e32 v160, s3, v147
	v_add_u32_e32 v176, s33, v147
	ds_read_b128 v[140:143], v160
	ds_read_b128 v[152:155], v160 offset:1024
	ds_read_b128 v[156:159], v160 offset:2048
	ds_read_b128 v[160:163], v160 offset:3072
	ds_read_b128 v[164:167], v176
	ds_read_b128 v[168:171], v176 offset:1024
	ds_read_b128 v[172:175], v176 offset:2048
	ds_read_b128 v[176:179], v176 offset:3072
	s_add_u32 s36, s90, 0x80000
	s_addc_u32 s37, s91, 0
	s_mov_b32 m0, s48
	ds_read_b128 v[180:183], v151 offset:32768
	ds_read_b128 v[184:187], v151 offset:33792
	ds_read_b128 v[188:191], v151 offset:34816
	ds_read_b128 v[192:195], v151 offset:35840
	ds_read_b128 v[196:199], v151 offset:36864
	ds_read_b128 v[200:203], v151 offset:37888
	ds_read_b128 v[204:207], v151 offset:38912
	ds_read_b128 v[208:211], v151 offset:39936
	global_load_lds_dwordx4 v128, s[36:37]
	v_lshl_add_u64 v[218:219], s[36:37], 0, v[130:131]
	s_mov_b32 m0, s49
	s_nop 0
	global_load_lds_dwordx4 v[218:219], off
	s_waitcnt vmcnt(8)
	s_waitcnt lgkmcnt(0)
	s_barrier
	s_setprio 1
	s_waitcnt lgkmcnt(0)
	v_mfma_f32_16x16x32_bf16 v[124:127], v[140:143], v[180:183], v[124:127]
	v_mfma_f32_16x16x32_bf16 v[120:123], v[156:159], v[180:183], v[120:123]
	v_mfma_f32_16x16x32_bf16 v[108:111], v[140:143], v[188:191], v[108:111]
	v_mfma_f32_16x16x32_bf16 v[104:107], v[156:159], v[188:191], v[104:107]
	v_mfma_f32_16x16x32_bf16 v[92:95], v[140:143], v[196:199], v[92:95]
	v_mfma_f32_16x16x32_bf16 v[88:91], v[156:159], v[196:199], v[88:91]
	v_mfma_f32_16x16x32_bf16 v[76:79], v[140:143], v[204:207], v[76:79]
	v_mfma_f32_16x16x32_bf16 v[72:75], v[156:159], v[204:207], v[72:75]
	v_mfma_f32_16x16x32_bf16 v[124:127], v[152:155], v[184:187], v[124:127]
	v_mfma_f32_16x16x32_bf16 v[120:123], v[160:163], v[184:187], v[120:123]
	v_mfma_f32_16x16x32_bf16 v[108:111], v[152:155], v[192:195], v[108:111]
	v_mfma_f32_16x16x32_bf16 v[104:107], v[160:163], v[192:195], v[104:107]
	v_mfma_f32_16x16x32_bf16 v[92:95], v[152:155], v[200:203], v[92:95]
	v_mfma_f32_16x16x32_bf16 v[88:91], v[160:163], v[200:203], v[88:91]
	v_mfma_f32_16x16x32_bf16 v[76:79], v[152:155], v[208:211], v[76:79]
	v_mfma_f32_16x16x32_bf16 v[72:75], v[160:163], v[208:211], v[72:75]
	s_setprio 0
	s_setprio 1
	v_mfma_f32_16x16x32_bf16 v[116:119], v[164:167], v[180:183], v[116:119]
	v_mfma_f32_16x16x32_bf16 v[112:115], v[172:175], v[180:183], v[112:115]
	v_mfma_f32_16x16x32_bf16 v[100:103], v[164:167], v[188:191], v[100:103]
	v_mfma_f32_16x16x32_bf16 v[96:99], v[172:175], v[188:191], v[96:99]
	v_mfma_f32_16x16x32_bf16 v[84:87], v[164:167], v[196:199], v[84:87]
	v_mfma_f32_16x16x32_bf16 v[80:83], v[172:175], v[196:199], v[80:83]
	v_mfma_f32_16x16x32_bf16 v[68:71], v[164:167], v[204:207], v[68:71]
	v_mfma_f32_16x16x32_bf16 v[64:67], v[172:175], v[204:207], v[64:67]
	v_mfma_f32_16x16x32_bf16 v[116:119], v[168:171], v[184:187], v[116:119]
	v_mfma_f32_16x16x32_bf16 v[112:115], v[176:179], v[184:187], v[112:115]
	v_mfma_f32_16x16x32_bf16 v[100:103], v[168:171], v[192:195], v[100:103]
	v_mfma_f32_16x16x32_bf16 v[96:99], v[176:179], v[192:195], v[96:99]
	v_mfma_f32_16x16x32_bf16 v[84:87], v[168:171], v[200:203], v[84:87]
	v_mfma_f32_16x16x32_bf16 v[80:83], v[176:179], v[200:203], v[80:83]
	v_mfma_f32_16x16x32_bf16 v[68:71], v[168:171], v[208:211], v[68:71]
	v_mfma_f32_16x16x32_bf16 v[64:67], v[176:179], v[208:211], v[64:67]
	s_setprio 0
	s_barrier
	s_add_i32 s3, s3, s25
	v_lshl_add_u64 v[144:145], v[144:145], 0, s[10:11]
	s_mov_b32 m0, s3
	ds_read_b128 v[180:183], v151 offset:49152
	ds_read_b128 v[184:187], v151 offset:50176
	ds_read_b128 v[188:191], v151 offset:51200
	ds_read_b128 v[192:195], v151 offset:52224
	ds_read_b128 v[196:199], v151 offset:53248
	ds_read_b128 v[200:203], v151 offset:54272
	ds_read_b128 v[204:207], v151 offset:55296
	ds_read_b128 v[208:211], v151 offset:56320
	global_load_lds_dwordx4 v[144:145], off
	s_add_i32 m0, s3, 0x2000
	s_add_u32 s36, s88, 0x80080
	v_lshl_add_u64 v[144:145], v[212:213], 0, s[10:11]
	s_addc_u32 s37, s89, 0
	s_add_i32 s3, s33, s25
	global_load_lds_dwordx4 v[144:145], off
	s_mov_b32 m0, s3
	s_nop 0
	global_load_lds_dwordx4 v128, s[36:37]
	s_add_i32 m0, s3, 0x2000
	s_nop 0
	global_load_lds_dwordx4 v130, s[36:37]
	v_lshl_add_u64 v[144:145], v[214:215], 0, s[10:11]
	s_mov_b32 m0, s57
	s_nop 0
	global_load_lds_dwordx4 v[144:145], off
	v_lshl_add_u64 v[144:145], v[216:217], 0, s[10:11]
	s_mov_b32 m0, s58
	s_nop 0
	global_load_lds_dwordx4 v[144:145], off
	s_waitcnt vmcnt(8)
	s_waitcnt lgkmcnt(0)
	s_barrier
	s_setprio 1
	s_waitcnt lgkmcnt(0)
	v_mfma_f32_16x16x32_bf16 v[60:63], v[140:143], v[180:183], v[60:63]
	v_mfma_f32_16x16x32_bf16 v[56:59], v[156:159], v[180:183], v[56:59]
	v_mfma_f32_16x16x32_bf16 v[44:47], v[140:143], v[188:191], v[44:47]
	v_mfma_f32_16x16x32_bf16 v[40:43], v[156:159], v[188:191], v[40:43]
	v_mfma_f32_16x16x32_bf16 v[28:31], v[140:143], v[196:199], v[28:31]
	v_mfma_f32_16x16x32_bf16 v[24:27], v[156:159], v[196:199], v[24:27]
	v_mfma_f32_16x16x32_bf16 v[12:15], v[140:143], v[204:207], v[12:15]
	v_mfma_f32_16x16x32_bf16 v[8:11], v[156:159], v[204:207], v[8:11]
	v_mfma_f32_16x16x32_bf16 v[60:63], v[152:155], v[184:187], v[60:63]
	v_mfma_f32_16x16x32_bf16 v[56:59], v[160:163], v[184:187], v[56:59]
	v_mfma_f32_16x16x32_bf16 v[44:47], v[152:155], v[192:195], v[44:47]
	v_mfma_f32_16x16x32_bf16 v[40:43], v[160:163], v[192:195], v[40:43]
	v_mfma_f32_16x16x32_bf16 v[28:31], v[152:155], v[200:203], v[28:31]
	v_mfma_f32_16x16x32_bf16 v[24:27], v[160:163], v[200:203], v[24:27]
	v_mfma_f32_16x16x32_bf16 v[12:15], v[152:155], v[208:211], v[12:15]
	v_mfma_f32_16x16x32_bf16 v[8:11], v[160:163], v[208:211], v[8:11]
	s_setprio 0
	s_setprio 1
	v_mfma_f32_16x16x32_bf16 v[52:55], v[164:167], v[180:183], v[52:55]
	v_mfma_f32_16x16x32_bf16 v[48:51], v[172:175], v[180:183], v[48:51]
	v_mfma_f32_16x16x32_bf16 v[36:39], v[164:167], v[188:191], v[36:39]
	v_mfma_f32_16x16x32_bf16 v[32:35], v[172:175], v[188:191], v[32:35]
	v_mfma_f32_16x16x32_bf16 v[20:23], v[164:167], v[196:199], v[20:23]
	v_mfma_f32_16x16x32_bf16 v[16:19], v[172:175], v[196:199], v[16:19]
	v_mfma_f32_16x16x32_bf16 v[4:7], v[164:167], v[204:207], v[4:7]
	v_mfma_f32_16x16x32_bf16 v[0:3], v[172:175], v[204:207], v[0:3]
	v_mfma_f32_16x16x32_bf16 v[52:55], v[168:171], v[184:187], v[52:55]
	v_mfma_f32_16x16x32_bf16 v[48:51], v[176:179], v[184:187], v[48:51]
	v_mfma_f32_16x16x32_bf16 v[36:39], v[168:171], v[192:195], v[36:39]
	v_mfma_f32_16x16x32_bf16 v[32:35], v[176:179], v[192:195], v[32:35]
	v_mfma_f32_16x16x32_bf16 v[20:23], v[168:171], v[200:203], v[20:23]
	v_mfma_f32_16x16x32_bf16 v[16:19], v[176:179], v[200:203], v[16:19]
	v_mfma_f32_16x16x32_bf16 v[4:7], v[168:171], v[208:211], v[4:7]
	v_mfma_f32_16x16x32_bf16 v[0:3], v[176:179], v[208:211], v[0:3]
	s_setprio 0
	s_barrier
	s_add_i32 s27, s27, 2
	s_add_u32 s86, s86, 0x100
	s_addc_u32 s87, s87, 0
	s_add_u32 s19, s19, 0x100
	s_addc_u32 s24, s24, 0
	s_cmp_gt_u32 s27, 29
	s_cbranch_scc0 .LBB0_639
	s_and_b64 vcc, exec, s[12:13]
	s_cbranch_vccz .LBB0_642
	s_barrier

.LBB0_760:
	s_lshl_b32 s1, s1, 5
	s_mov_b64 s[12:13], 0x80
	s_and_b32 s1, s1, 0x60
	s_add_i32 m0, s19, 0x18000
	v_lshl_add_u64 v[6:7], v[6:7], 0, s[12:13]
	s_lshl_b32 s14, s0, 13
	s_lshl_b32 s15, s1, 7
	s_waitcnt vmcnt(2)
	s_barrier
	global_load_lds_dwordx4 v[6:7], off
	v_lshl_add_u64 v[4:5], v[4:5], 0, s[12:13]
	s_add_i32 m0, s19, 0x1a000
	s_add_i32 s48, s19, 0x8000
	s_add_i32 s49, s19, 0xa000
	global_load_lds_dwordx4 v[4:5], off
	v_lshl_add_u64 v[0:1], v[0:1], 0, s[12:13]
	s_mov_b32 m0, s48
	s_add_u32 s8, s80, 0x80080
	global_load_lds_dwordx4 v[0:1], off
	v_lshl_add_u64 v[0:1], v[2:3], 0, s[12:13]
	s_mov_b32 m0, s49
	s_addc_u32 s9, s81, 0
	global_load_lds_dwordx4 v[0:1], off
	s_add_i32 m0, s19, 0x1c000
	s_nop 0
	global_load_lds_dwordx4 v130, s[8:9]
	s_add_i32 m0, s19, 0x1e000
	s_cmpk_lt_u32 s3, 0x100
	global_load_lds_dwordx4 v134, s[8:9]
	v_lshrrev_b32_e32 v0, 1, v8
	v_and_b32_e32 v0, 24, v0
	v_and_b32_e32 v1, 15, v8
	v_lshlrev_b32_e32 v2, 1, v0
	v_lshl_or_b32 v148, s0, 6, v1
	v_lshl_or_b32 v1, v1, 6, v2
	v_lshlrev_b32_e32 v2, 2, v8
	v_and_b32_e32 v2, 32, v2
	v_bitop3_b32 v3, v1, s14, v2 bitop3:0xde
	v_bitop3_b32 v149, v1, s15, v2 bitop3:0xde
	v_lshlrev_b32_e32 v1, 15, v9
	v_and_b32_e32 v1, 0xffff0000, v1
	v_lshl_add_u32 v1, v10, 12, v1
	v_and_b32_e32 v2, 1, v9
	v_lshl_or_b32 v1, v2, 6, v1
	v_lshl_add_u32 v138, v11, 1, v1
	v_lshlrev_b32_e32 v1, 15, v12
	v_and_b32_e32 v1, 0xffff0000, v1
	s_waitcnt vmcnt(6)
	v_lshl_add_u32 v1, v13, 12, v1
	v_and_b32_e32 v2, 1, v12
	s_cselect_b64 s[14:15], -1, 0
	v_lshl_or_b32 v1, v2, 6, v1
	s_add_i32 s56, 0, 0x10000
	s_add_i32 s57, 0, 0x14000
	s_sext_i32_i8 s24, s6
	v_mov_b32_e32 v139, v137
	v_lshl_add_u32 v140, v14, 1, v1
	v_mov_b32_e32 v141, v137
	v_mov_b64_e32 v[142:143], 0x800
	v_mov_b64_e32 v[144:145], 0x7ff
	v_add_u32_e32 v150, s56, v149
	v_add_u32_e32 v151, s57, v149
	v_add_u32_e32 v152, 0, v3
	s_lshl_b32 s6, s1, 1
	v_lshlrev_b32_e32 v136, 1, v0
	s_mov_b32 s58, s7
	s_barrier
	s_branch .LBB0_763

.LBB0_770:
	ds_read_b128 v[154:157], v150
	ds_read_b128 v[158:161], v150 offset:1024
	ds_read_b128 v[162:165], v150 offset:2048
	ds_read_b128 v[166:169], v150 offset:3072
	ds_read_b128 v[170:173], v151
	ds_read_b128 v[174:177], v151 offset:1024
	ds_read_b128 v[178:181], v151 offset:2048
	ds_read_b128 v[182:185], v151 offset:3072
	s_add_u32 s3, s88, 0xfff80080
	s_addc_u32 s37, s89, -1
	s_cmp_eq_u32 s36, 28
	s_cselect_b32 s91, s0, s37
	s_cselect_b32 s90, s1, s3
	s_cselect_b32 s81, s17, s35
	s_cselect_b32 s80, s27, s33
	s_add_i32 m0, s19, 0xc000
	ds_read_b128 v[186:189], v152
	ds_read_b128 v[190:193], v152 offset:1024
	ds_read_b128 v[194:197], v152 offset:2048
	ds_read_b128 v[198:201], v152 offset:3072
	ds_read_b128 v[202:205], v152 offset:4096
	ds_read_b128 v[206:209], v152 offset:5120
	ds_read_b128 v[210:213], v152 offset:6144
	ds_read_b128 v[214:217], v152 offset:7168
	global_load_lds_dwordx4 v138, s[88:89]
	s_add_i32 m0, s19, 0xe000
	s_nop 0
	global_load_lds_dwordx4 v140, s[88:89]
	s_waitcnt vmcnt(8)
	s_waitcnt lgkmcnt(0)
	s_barrier
	s_setprio 1
	s_waitcnt lgkmcnt(0)
	v_mfma_f32_16x16x32_bf16 v[124:127], v[154:157], v[186:189], v[124:127]
	v_mfma_f32_16x16x32_bf16 v[120:123], v[162:165], v[186:189], v[120:123]
	v_mfma_f32_16x16x32_bf16 v[108:111], v[154:157], v[194:197], v[108:111]
	v_mfma_f32_16x16x32_bf16 v[104:107], v[162:165], v[194:197], v[104:107]
	v_mfma_f32_16x16x32_bf16 v[92:95], v[154:157], v[202:205], v[92:95]
	v_mfma_f32_16x16x32_bf16 v[88:91], v[162:165], v[202:205], v[88:91]
	v_mfma_f32_16x16x32_bf16 v[76:79], v[154:157], v[210:213], v[76:79]
	v_mfma_f32_16x16x32_bf16 v[72:75], v[162:165], v[210:213], v[72:75]
	v_mfma_f32_16x16x32_bf16 v[124:127], v[158:161], v[190:193], v[124:127]
	v_mfma_f32_16x16x32_bf16 v[120:123], v[166:169], v[190:193], v[120:123]
	v_mfma_f32_16x16x32_bf16 v[108:111], v[158:161], v[198:201], v[108:111]
	v_mfma_f32_16x16x32_bf16 v[104:107], v[166:169], v[198:201], v[104:107]
	v_mfma_f32_16x16x32_bf16 v[92:95], v[158:161], v[206:209], v[92:95]
	v_mfma_f32_16x16x32_bf16 v[88:91], v[166:169], v[206:209], v[88:91]
	v_mfma_f32_16x16x32_bf16 v[76:79], v[158:161], v[214:217], v[76:79]
	v_mfma_f32_16x16x32_bf16 v[72:75], v[166:169], v[214:217], v[72:75]
	s_setprio 0
	s_setprio 1
	v_mfma_f32_16x16x32_bf16 v[116:119], v[170:173], v[186:189], v[116:119]
	v_mfma_f32_16x16x32_bf16 v[112:115], v[178:181], v[186:189], v[112:115]
	v_mfma_f32_16x16x32_bf16 v[100:103], v[170:173], v[194:197], v[100:103]
	v_mfma_f32_16x16x32_bf16 v[96:99], v[178:181], v[194:197], v[96:99]
	v_mfma_f32_16x16x32_bf16 v[84:87], v[170:173], v[202:205], v[84:87]
	v_mfma_f32_16x16x32_bf16 v[80:83], v[178:181], v[202:205], v[80:83]
	v_mfma_f32_16x16x32_bf16 v[68:71], v[170:173], v[210:213], v[68:71]
	v_mfma_f32_16x16x32_bf16 v[64:67], v[178:181], v[210:213], v[64:67]
	v_mfma_f32_16x16x32_bf16 v[116:119], v[174:177], v[190:193], v[116:119]
	v_mfma_f32_16x16x32_bf16 v[112:115], v[182:185], v[190:193], v[112:115]
	v_mfma_f32_16x16x32_bf16 v[100:103], v[174:177], v[198:201], v[100:103]
	v_mfma_f32_16x16x32_bf16 v[96:99], v[182:185], v[198:201], v[96:99]
	v_mfma_f32_16x16x32_bf16 v[84:87], v[174:177], v[206:209], v[84:87]
	v_mfma_f32_16x16x32_bf16 v[80:83], v[182:185], v[206:209], v[80:83]
	v_mfma_f32_16x16x32_bf16 v[68:71], v[174:177], v[214:217], v[68:71]
	v_mfma_f32_16x16x32_bf16 v[64:67], v[182:185], v[214:217], v[64:67]
	s_setprio 0
	s_barrier
	s_add_i32 s3, s56, s18
	v_lshl_add_u64 v[146:147], s[80:81], 0, v[130:131]
	s_mov_b32 m0, s3
	ds_read_b128 v[186:189], v152 offset:16384
	ds_read_b128 v[190:193], v152 offset:17408
	ds_read_b128 v[194:197], v152 offset:18432
	ds_read_b128 v[198:201], v152 offset:19456
	ds_read_b128 v[202:205], v152 offset:20480
	ds_read_b128 v[206:209], v152 offset:21504
	ds_read_b128 v[210:213], v152 offset:22528
	ds_read_b128 v[214:217], v152 offset:23552
	global_load_lds_dwordx4 v[146:147], off
	s_add_i32 m0, s3, 0x2000
	s_add_u32 s42, s80, 0x80000
	v_lshl_add_u64 v[218:219], s[80:81], 0, v[134:135]
	s_addc_u32 s43, s81, 0
	s_add_i32 s3, s57, s18
	global_load_lds_dwordx4 v[218:219], off
	s_mov_b32 m0, s3
	v_lshl_add_u64 v[222:223], s[90:91], 0, v[132:133]
	global_load_lds_dwordx4 v130, s[42:43]
	s_add_i32 m0, s3, 0x2000
	s_nop 0
	global_load_lds_dwordx4 v134, s[42:43]
	v_lshl_add_u64 v[220:221], s[90:91], 0, v[128:129]
	s_mov_b32 m0, s19
	s_nop 0
	global_load_lds_dwordx4 v[220:221], off
	s_mov_b32 m0, s25
	s_nop 0
	global_load_lds_dwordx4 v[222:223], off
	s_waitcnt vmcnt(8)
	s_waitcnt lgkmcnt(0)
	s_barrier
	s_setprio 1
	s_waitcnt lgkmcnt(0)
	v_mfma_f32_16x16x32_bf16 v[60:63], v[154:157], v[186:189], v[60:63]
	v_mfma_f32_16x16x32_bf16 v[56:59], v[162:165], v[186:189], v[56:59]
	v_mfma_f32_16x16x32_bf16 v[44:47], v[154:157], v[194:197], v[44:47]
	v_mfma_f32_16x16x32_bf16 v[40:43], v[162:165], v[194:197], v[40:43]
	v_mfma_f32_16x16x32_bf16 v[28:31], v[154:157], v[202:205], v[28:31]
	v_mfma_f32_16x16x32_bf16 v[24:27], v[162:165], v[202:205], v[24:27]
	v_mfma_f32_16x16x32_bf16 v[12:15], v[154:157], v[210:213], v[12:15]
	v_mfma_f32_16x16x32_bf16 v[8:11], v[162:165], v[210:213], v[8:11]
	v_mfma_f32_16x16x32_bf16 v[60:63], v[158:161], v[190:193], v[60:63]
	v_mfma_f32_16x16x32_bf16 v[56:59], v[166:169], v[190:193], v[56:59]
	v_mfma_f32_16x16x32_bf16 v[44:47], v[158:161], v[198:201], v[44:47]
	v_mfma_f32_16x16x32_bf16 v[40:43], v[166:169], v[198:201], v[40:43]
	v_mfma_f32_16x16x32_bf16 v[28:31], v[158:161], v[206:209], v[28:31]
	v_mfma_f32_16x16x32_bf16 v[24:27], v[166:169], v[206:209], v[24:27]
	v_mfma_f32_16x16x32_bf16 v[12:15], v[158:161], v[214:217], v[12:15]
	v_mfma_f32_16x16x32_bf16 v[8:11], v[166:169], v[214:217], v[8:11]
	s_setprio 0
	s_setprio 1
	v_mfma_f32_16x16x32_bf16 v[52:55], v[170:173], v[186:189], v[52:55]
	v_mfma_f32_16x16x32_bf16 v[48:51], v[178:181], v[186:189], v[48:51]
	v_mfma_f32_16x16x32_bf16 v[36:39], v[170:173], v[194:197], v[36:39]
	v_mfma_f32_16x16x32_bf16 v[32:35], v[178:181], v[194:197], v[32:35]
	v_mfma_f32_16x16x32_bf16 v[20:23], v[170:173], v[202:205], v[20:23]
	v_mfma_f32_16x16x32_bf16 v[16:19], v[178:181], v[202:205], v[16:19]
	v_mfma_f32_16x16x32_bf16 v[4:7], v[170:173], v[210:213], v[4:7]
	v_mfma_f32_16x16x32_bf16 v[0:3], v[178:181], v[210:213], v[0:3]
	v_mfma_f32_16x16x32_bf16 v[52:55], v[174:177], v[190:193], v[52:55]
	v_mfma_f32_16x16x32_bf16 v[48:51], v[182:185], v[190:193], v[48:51]
	v_mfma_f32_16x16x32_bf16 v[36:39], v[174:177], v[198:201], v[36:39]
	v_mfma_f32_16x16x32_bf16 v[32:35], v[182:185], v[198:201], v[32:35]
	v_mfma_f32_16x16x32_bf16 v[20:23], v[174:177], v[206:209], v[20:23]
	v_mfma_f32_16x16x32_bf16 v[16:19], v[182:185], v[206:209], v[16:19]
	v_mfma_f32_16x16x32_bf16 v[4:7], v[174:177], v[214:217], v[4:7]
	v_mfma_f32_16x16x32_bf16 v[0:3], v[182:185], v[214:217], v[0:3]
	s_setprio 0
	s_barrier
	s_add_i32 s3, 0, 0x18000
	v_add_u32_e32 v153, s3, v149
	s_add_i32 s37, 0, 0x1c000
	ds_read_b128 v[154:157], v153
	ds_read_b128 v[158:161], v153 offset:1024
	ds_read_b128 v[162:165], v153 offset:2048
	ds_read_b128 v[166:169], v153 offset:3072
	v_add_u32_e32 v153, s37, v149
	ds_read_b128 v[170:173], v153
	ds_read_b128 v[174:177], v153 offset:1024
	ds_read_b128 v[178:181], v153 offset:2048
	ds_read_b128 v[182:185], v153 offset:3072
	s_add_u32 s42, s90, 0x80000
	s_addc_u32 s43, s91, 0
	s_mov_b32 m0, s30
	ds_read_b128 v[186:189], v152 offset:32768
	ds_read_b128 v[190:193], v152 offset:33792
	ds_read_b128 v[194:197], v152 offset:34816
	ds_read_b128 v[198:201], v152 offset:35840
	ds_read_b128 v[202:205], v152 offset:36864
	ds_read_b128 v[206:209], v152 offset:37888
	ds_read_b128 v[210:213], v152 offset:38912
	ds_read_b128 v[214:217], v152 offset:39936
	global_load_lds_dwordx4 v128, s[42:43]
	v_lshl_add_u64 v[224:225], s[42:43], 0, v[132:133]
	s_mov_b32 m0, s31
	s_nop 0
	global_load_lds_dwordx4 v[224:225], off
	s_waitcnt vmcnt(8)
	s_waitcnt lgkmcnt(0)
	s_barrier
	s_setprio 1
	s_waitcnt lgkmcnt(0)
	v_mfma_f32_16x16x32_bf16 v[124:127], v[154:157], v[186:189], v[124:127]
	v_mfma_f32_16x16x32_bf16 v[120:123], v[162:165], v[186:189], v[120:123]
	v_mfma_f32_16x16x32_bf16 v[108:111], v[154:157], v[194:197], v[108:111]
	v_mfma_f32_16x16x32_bf16 v[104:107], v[162:165], v[194:197], v[104:107]
	v_mfma_f32_16x16x32_bf16 v[92:95], v[154:157], v[202:205], v[92:95]
	v_mfma_f32_16x16x32_bf16 v[88:91], v[162:165], v[202:205], v[88:91]
	v_mfma_f32_16x16x32_bf16 v[76:79], v[154:157], v[210:213], v[76:79]
	v_mfma_f32_16x16x32_bf16 v[72:75], v[162:165], v[210:213], v[72:75]
	v_mfma_f32_16x16x32_bf16 v[124:127], v[158:161], v[190:193], v[124:127]
	v_mfma_f32_16x16x32_bf16 v[120:123], v[166:169], v[190:193], v[120:123]
	v_mfma_f32_16x16x32_bf16 v[108:111], v[158:161], v[198:201], v[108:111]
	v_mfma_f32_16x16x32_bf16 v[104:107], v[166:169], v[198:201], v[104:107]
	v_mfma_f32_16x16x32_bf16 v[92:95], v[158:161], v[206:209], v[92:95]
	v_mfma_f32_16x16x32_bf16 v[88:91], v[166:169], v[206:209], v[88:91]
	v_mfma_f32_16x16x32_bf16 v[76:79], v[158:161], v[214:217], v[76:79]
	v_mfma_f32_16x16x32_bf16 v[72:75], v[166:169], v[214:217], v[72:75]
	s_setprio 0
	s_setprio 1
	v_mfma_f32_16x16x32_bf16 v[116:119], v[170:173], v[186:189], v[116:119]
	v_mfma_f32_16x16x32_bf16 v[112:115], v[178:181], v[186:189], v[112:115]
	v_mfma_f32_16x16x32_bf16 v[100:103], v[170:173], v[194:197], v[100:103]
	v_mfma_f32_16x16x32_bf16 v[96:99], v[178:181], v[194:197], v[96:99]
	v_mfma_f32_16x16x32_bf16 v[84:87], v[170:173], v[202:205], v[84:87]
	v_mfma_f32_16x16x32_bf16 v[80:83], v[178:181], v[202:205], v[80:83]
	v_mfma_f32_16x16x32_bf16 v[68:71], v[170:173], v[210:213], v[68:71]
	v_mfma_f32_16x16x32_bf16 v[64:67], v[178:181], v[210:213], v[64:67]
	v_mfma_f32_16x16x32_bf16 v[116:119], v[174:177], v[190:193], v[116:119]
	v_mfma_f32_16x16x32_bf16 v[112:115], v[182:185], v[190:193], v[112:115]
	v_mfma_f32_16x16x32_bf16 v[100:103], v[174:177], v[198:201], v[100:103]
	v_mfma_f32_16x16x32_bf16 v[96:99], v[182:185], v[198:201], v[96:99]
	v_mfma_f32_16x16x32_bf16 v[84:87], v[174:177], v[206:209], v[84:87]
	v_mfma_f32_16x16x32_bf16 v[80:83], v[182:185], v[206:209], v[80:83]
	v_mfma_f32_16x16x32_bf16 v[68:71], v[174:177], v[214:217], v[68:71]
	v_mfma_f32_16x16x32_bf16 v[64:67], v[182:185], v[214:217], v[64:67]
	s_setprio 0
	s_barrier
	s_add_i32 s3, s3, s18
	v_lshl_add_u64 v[146:147], v[146:147], 0, s[12:13]
	s_mov_b32 m0, s3
	ds_read_b128 v[186:189], v152 offset:49152
	ds_read_b128 v[190:193], v152 offset:50176
	ds_read_b128 v[194:197], v152 offset:51200
	ds_read_b128 v[198:201], v152 offset:52224
	ds_read_b128 v[202:205], v152 offset:53248
	ds_read_b128 v[206:209], v152 offset:54272
	ds_read_b128 v[210:213], v152 offset:55296
	ds_read_b128 v[214:217], v152 offset:56320
	global_load_lds_dwordx4 v[146:147], off
	s_add_i32 m0, s3, 0x2000
	s_add_u32 s42, s80, 0x80080
	v_lshl_add_u64 v[146:147], v[218:219], 0, s[12:13]
	s_addc_u32 s43, s81, 0
	s_add_i32 s3, s37, s18
	global_load_lds_dwordx4 v[146:147], off
	s_mov_b32 m0, s3
	s_nop 0
	global_load_lds_dwordx4 v130, s[42:43]
	s_add_i32 m0, s3, 0x2000
	s_nop 0
	global_load_lds_dwordx4 v134, s[42:43]
	v_lshl_add_u64 v[146:147], v[220:221], 0, s[12:13]
	s_mov_b32 m0, s48
	s_nop 0
	global_load_lds_dwordx4 v[146:147], off
	v_lshl_add_u64 v[146:147], v[222:223], 0, s[12:13]
	s_mov_b32 m0, s49
	s_nop 0
	global_load_lds_dwordx4 v[146:147], off
	s_waitcnt vmcnt(8)
	s_waitcnt lgkmcnt(0)
	s_barrier
	s_setprio 1
	s_waitcnt lgkmcnt(0)
	v_mfma_f32_16x16x32_bf16 v[60:63], v[154:157], v[186:189], v[60:63]
	v_mfma_f32_16x16x32_bf16 v[56:59], v[162:165], v[186:189], v[56:59]
	v_mfma_f32_16x16x32_bf16 v[44:47], v[154:157], v[194:197], v[44:47]
	v_mfma_f32_16x16x32_bf16 v[40:43], v[162:165], v[194:197], v[40:43]
	v_mfma_f32_16x16x32_bf16 v[28:31], v[154:157], v[202:205], v[28:31]
	v_mfma_f32_16x16x32_bf16 v[24:27], v[162:165], v[202:205], v[24:27]
	v_mfma_f32_16x16x32_bf16 v[12:15], v[154:157], v[210:213], v[12:15]
	v_mfma_f32_16x16x32_bf16 v[8:11], v[162:165], v[210:213], v[8:11]
	v_mfma_f32_16x16x32_bf16 v[60:63], v[158:161], v[190:193], v[60:63]
	v_mfma_f32_16x16x32_bf16 v[56:59], v[166:169], v[190:193], v[56:59]
	v_mfma_f32_16x16x32_bf16 v[44:47], v[158:161], v[198:201], v[44:47]
	v_mfma_f32_16x16x32_bf16 v[40:43], v[166:169], v[198:201], v[40:43]
	v_mfma_f32_16x16x32_bf16 v[28:31], v[158:161], v[206:209], v[28:31]
	v_mfma_f32_16x16x32_bf16 v[24:27], v[166:169], v[206:209], v[24:27]
	v_mfma_f32_16x16x32_bf16 v[12:15], v[158:161], v[214:217], v[12:15]
	v_mfma_f32_16x16x32_bf16 v[8:11], v[166:169], v[214:217], v[8:11]
	s_setprio 0
	s_setprio 1
	v_mfma_f32_16x16x32_bf16 v[52:55], v[170:173], v[186:189], v[52:55]
	v_mfma_f32_16x16x32_bf16 v[48:51], v[178:181], v[186:189], v[48:51]
	v_mfma_f32_16x16x32_bf16 v[36:39], v[170:173], v[194:197], v[36:39]
	v_mfma_f32_16x16x32_bf16 v[32:35], v[178:181], v[194:197], v[32:35]
	v_mfma_f32_16x16x32_bf16 v[20:23], v[170:173], v[202:205], v[20:23]
	v_mfma_f32_16x16x32_bf16 v[16:19], v[178:181], v[202:205], v[16:19]
	v_mfma_f32_16x16x32_bf16 v[4:7], v[170:173], v[210:213], v[4:7]
	v_mfma_f32_16x16x32_bf16 v[0:3], v[178:181], v[210:213], v[0:3]
	v_mfma_f32_16x16x32_bf16 v[52:55], v[174:177], v[190:193], v[52:55]
	v_mfma_f32_16x16x32_bf16 v[48:51], v[182:185], v[190:193], v[48:51]
	v_mfma_f32_16x16x32_bf16 v[36:39], v[174:177], v[198:201], v[36:39]
	v_mfma_f32_16x16x32_bf16 v[32:35], v[182:185], v[198:201], v[32:35]
	v_mfma_f32_16x16x32_bf16 v[20:23], v[174:177], v[206:209], v[20:23]
	v_mfma_f32_16x16x32_bf16 v[16:19], v[182:185], v[206:209], v[16:19]
	v_mfma_f32_16x16x32_bf16 v[4:7], v[174:177], v[214:217], v[4:7]
	v_mfma_f32_16x16x32_bf16 v[0:3], v[182:185], v[214:217], v[0:3]
	s_setprio 0
	s_barrier
	s_add_i32 s36, s36, 2
	s_add_u32 s88, s88, 0x100
	s_addc_u32 s89, s89, 0
	s_add_u32 s33, s33, 0x100
	s_addc_u32 s35, s35, 0
	s_cmp_gt_u32 s36, 29
	s_cbranch_scc0 .LBB0_770
	s_and_b64 vcc, exec, s[14:15]
	s_cbranch_vccz .LBB0_773
	s_barrier

.LBB0_836:
	v_bfe_u32 v16, v14, 4, 2
	v_and_b32_e32 v15, 15, v14
	v_lshlrev_b32_e32 v17, 4, v16
	v_lshlrev_b32_e32 v14, 2, v14
	v_lshl_or_b32 v146, s0, 6, v15
	v_lshl_or_b32 v15, v15, 6, v17
	s_lshl_b32 s0, s0, 13
	v_and_b32_e32 v14, 32, v14
	v_bitop3_b32 v17, v15, s0, v14 bitop3:0xde
	s_lshl_b32 s0, s1, 5
	s_mov_b64 s[10:11], 0x80
	s_sext_i32_i8 s24, s8
	s_and_b32 s8, s0, 0x60
	s_add_i32 m0, s19, 0x18000
	v_lshl_add_u64 v[6:7], v[6:7], 0, s[10:11]
	s_lshl_b32 s0, s8, 7
	s_waitcnt vmcnt(2)
	s_barrier
	global_load_lds_dwordx4 v[6:7], off
	v_lshl_add_u64 v[4:5], v[4:5], 0, s[10:11]
	s_add_i32 m0, s19, 0x1a000
	s_add_i32 s49, s19, 0x8000
	s_add_i32 s56, s19, 0xa000
	v_bitop3_b32 v147, v15, s0, v14 bitop3:0xde
	global_load_lds_dwordx4 v[4:5], off
	v_lshl_add_u64 v[0:1], v[0:1], 0, s[10:11]
	s_mov_b32 m0, s49
	s_add_u32 s0, s86, 0x200080
	global_load_lds_dwordx4 v[0:1], off
	v_lshl_add_u64 v[0:1], v[2:3], 0, s[10:11]
	s_mov_b32 m0, s56
	s_addc_u32 s1, s87, 0
	global_load_lds_dwordx4 v[0:1], off
	s_add_i32 m0, s19, 0x1c000
	s_nop 0
	global_load_lds_dwordx4 v128, s[0:1]
	s_add_i32 m0, s19, 0x1e000
	s_cmpk_lt_u32 s3, 0x100
	global_load_lds_dwordx4 v130, s[0:1]
	v_lshlrev_b32_e32 v0, 17, v8
	v_and_b32_e32 v0, 0xfffc0000, v0
	v_lshl_add_u32 v0, v9, 14, v0
	v_and_b32_e32 v1, 1, v8
	v_lshl_or_b32 v0, v1, 6, v0
	v_lshl_add_u32 v132, v10, 1, v0
	v_lshlrev_b32_e32 v0, 17, v11
	v_and_b32_e32 v0, 0xfffc0000, v0
	s_waitcnt vmcnt(6)
	v_lshl_add_u32 v0, v12, 14, v0
	v_and_b32_e32 v1, 1, v11
	s_cselect_b64 s[12:13], -1, 0
	v_lshl_or_b32 v0, v1, 6, v0
	s_add_i32 s57, 0, 0x10000
	s_add_i32 s58, 0, 0x14000
	v_lshl_or_b32 v148, v16, 2, s8
	v_mov_b32_e32 v133, v129
	v_lshl_add_u32 v134, v13, 1, v0
	v_mov_b32_e32 v135, v129
	v_mov_b64_e32 v[136:137], 0x200
	v_mov_b64_e32 v[138:139], 0x1ff
	v_add_u32_e32 v149, s57, v147
	v_add_u32_e32 v150, s58, v147
	v_add_u32_e32 v151, 0, v17
	s_barrier
	s_branch .LBB0_839

.LBB0_846:
	ds_read_b128 v[140:143], v149
	ds_read_b128 v[152:155], v149 offset:1024
	ds_read_b128 v[156:159], v149 offset:2048
	ds_read_b128 v[160:163], v149 offset:3072
	ds_read_b128 v[164:167], v150
	ds_read_b128 v[168:171], v150 offset:1024
	ds_read_b128 v[172:175], v150 offset:2048
	ds_read_b128 v[176:179], v150 offset:3072
	s_add_u32 s3, s84, 0xffe00080
	s_addc_u32 s37, s85, -1
	s_cmpk_eq_i32 s36, 0x7c
	s_cselect_b32 s87, s0, s37
	s_cselect_b32 s86, s1, s3
	s_cselect_b32 s81, s15, s33
	s_cselect_b32 s80, s17, s27
	s_add_i32 m0, s19, 0xc000
	ds_read_b128 v[180:183], v151
	ds_read_b128 v[184:187], v151 offset:1024
	ds_read_b128 v[188:191], v151 offset:2048
	ds_read_b128 v[192:195], v151 offset:3072
	ds_read_b128 v[196:199], v151 offset:4096
	ds_read_b128 v[200:203], v151 offset:5120
	ds_read_b128 v[204:207], v151 offset:6144
	ds_read_b128 v[208:211], v151 offset:7168
	global_load_lds_dwordx4 v132, s[84:85]
	s_add_i32 m0, s19, 0xe000
	s_nop 0
	global_load_lds_dwordx4 v134, s[84:85]
	s_waitcnt vmcnt(8)
	s_waitcnt lgkmcnt(0)
	s_barrier
	s_setprio 1
	s_waitcnt lgkmcnt(0)
	v_mfma_f32_16x16x32_bf16 v[124:127], v[140:143], v[180:183], v[124:127]
	v_mfma_f32_16x16x32_bf16 v[120:123], v[156:159], v[180:183], v[120:123]
	v_mfma_f32_16x16x32_bf16 v[112:115], v[140:143], v[188:191], v[112:115]
	v_mfma_f32_16x16x32_bf16 v[104:107], v[156:159], v[188:191], v[104:107]
	v_mfma_f32_16x16x32_bf16 v[96:99], v[140:143], v[196:199], v[96:99]
	v_mfma_f32_16x16x32_bf16 v[88:91], v[156:159], v[196:199], v[88:91]
	v_mfma_f32_16x16x32_bf16 v[80:83], v[140:143], v[204:207], v[80:83]
	v_mfma_f32_16x16x32_bf16 v[72:75], v[156:159], v[204:207], v[72:75]
	v_mfma_f32_16x16x32_bf16 v[124:127], v[152:155], v[184:187], v[124:127]
	v_mfma_f32_16x16x32_bf16 v[120:123], v[160:163], v[184:187], v[120:123]
	v_mfma_f32_16x16x32_bf16 v[112:115], v[152:155], v[192:195], v[112:115]
	v_mfma_f32_16x16x32_bf16 v[104:107], v[160:163], v[192:195], v[104:107]
	v_mfma_f32_16x16x32_bf16 v[96:99], v[152:155], v[200:203], v[96:99]
	v_mfma_f32_16x16x32_bf16 v[88:91], v[160:163], v[200:203], v[88:91]
	v_mfma_f32_16x16x32_bf16 v[80:83], v[152:155], v[208:211], v[80:83]
	v_mfma_f32_16x16x32_bf16 v[72:75], v[160:163], v[208:211], v[72:75]
	s_setprio 0
	s_setprio 1
	v_mfma_f32_16x16x32_bf16 v[116:119], v[164:167], v[180:183], v[116:119]
	v_mfma_f32_16x16x32_bf16 v[108:111], v[172:175], v[180:183], v[108:111]
	v_mfma_f32_16x16x32_bf16 v[100:103], v[164:167], v[188:191], v[100:103]
	v_mfma_f32_16x16x32_bf16 v[92:95], v[172:175], v[188:191], v[92:95]
	v_mfma_f32_16x16x32_bf16 v[84:87], v[164:167], v[196:199], v[84:87]
	v_mfma_f32_16x16x32_bf16 v[76:79], v[172:175], v[196:199], v[76:79]
	v_mfma_f32_16x16x32_bf16 v[68:71], v[164:167], v[204:207], v[68:71]
	v_mfma_f32_16x16x32_bf16 v[64:67], v[172:175], v[204:207], v[64:67]
	v_mfma_f32_16x16x32_bf16 v[116:119], v[168:171], v[184:187], v[116:119]
	v_mfma_f32_16x16x32_bf16 v[108:111], v[176:179], v[184:187], v[108:111]
	v_mfma_f32_16x16x32_bf16 v[100:103], v[168:171], v[192:195], v[100:103]
	v_mfma_f32_16x16x32_bf16 v[92:95], v[176:179], v[192:195], v[92:95]
	v_mfma_f32_16x16x32_bf16 v[84:87], v[168:171], v[200:203], v[84:87]
	v_mfma_f32_16x16x32_bf16 v[76:79], v[176:179], v[200:203], v[76:79]
	v_mfma_f32_16x16x32_bf16 v[68:71], v[168:171], v[208:211], v[68:71]
	v_mfma_f32_16x16x32_bf16 v[64:67], v[176:179], v[208:211], v[64:67]
	s_setprio 0
	s_barrier
	s_add_i32 s3, s57, s18
	v_lshl_add_u64 v[144:145], s[80:81], 0, v[128:129]
	s_mov_b32 m0, s3
	ds_read_b128 v[180:183], v151 offset:16384
	ds_read_b128 v[184:187], v151 offset:17408
	ds_read_b128 v[188:191], v151 offset:18432
	ds_read_b128 v[192:195], v151 offset:19456
	ds_read_b128 v[196:199], v151 offset:20480
	ds_read_b128 v[200:203], v151 offset:21504
	ds_read_b128 v[204:207], v151 offset:22528
	ds_read_b128 v[208:211], v151 offset:23552
	global_load_lds_dwordx4 v[144:145], off
	s_add_i32 m0, s3, 0x2000
	s_add_u32 s42, s80, 0x200000
	v_lshl_add_u64 v[212:213], s[80:81], 0, v[130:131]
	s_addc_u32 s43, s81, 0
	s_add_i32 s3, s58, s18
	global_load_lds_dwordx4 v[212:213], off
	s_mov_b32 m0, s3
	v_lshl_add_u64 v[216:217], s[86:87], 0, v[130:131]
	global_load_lds_dwordx4 v128, s[42:43]
	s_add_i32 m0, s3, 0x2000
	s_nop 0
	global_load_lds_dwordx4 v130, s[42:43]
	v_lshl_add_u64 v[214:215], s[86:87], 0, v[128:129]
	s_mov_b32 m0, s19
	s_nop 0
	global_load_lds_dwordx4 v[214:215], off
	s_mov_b32 m0, s25
	s_nop 0
	global_load_lds_dwordx4 v[216:217], off
	s_waitcnt vmcnt(8)
	s_waitcnt lgkmcnt(0)
	s_barrier
	s_setprio 1
	s_waitcnt lgkmcnt(0)
	v_mfma_f32_16x16x32_bf16 v[60:63], v[140:143], v[180:183], v[60:63]
	v_mfma_f32_16x16x32_bf16 v[56:59], v[156:159], v[180:183], v[56:59]
	v_mfma_f32_16x16x32_bf16 v[48:51], v[140:143], v[188:191], v[48:51]
	v_mfma_f32_16x16x32_bf16 v[40:43], v[156:159], v[188:191], v[40:43]
	v_mfma_f32_16x16x32_bf16 v[32:35], v[140:143], v[196:199], v[32:35]
	v_mfma_f32_16x16x32_bf16 v[24:27], v[156:159], v[196:199], v[24:27]
	v_mfma_f32_16x16x32_bf16 v[16:19], v[140:143], v[204:207], v[16:19]
	v_mfma_f32_16x16x32_bf16 v[8:11], v[156:159], v[204:207], v[8:11]
	v_mfma_f32_16x16x32_bf16 v[60:63], v[152:155], v[184:187], v[60:63]
	v_mfma_f32_16x16x32_bf16 v[56:59], v[160:163], v[184:187], v[56:59]
	v_mfma_f32_16x16x32_bf16 v[48:51], v[152:155], v[192:195], v[48:51]
	v_mfma_f32_16x16x32_bf16 v[40:43], v[160:163], v[192:195], v[40:43]
	v_mfma_f32_16x16x32_bf16 v[32:35], v[152:155], v[200:203], v[32:35]
	v_mfma_f32_16x16x32_bf16 v[24:27], v[160:163], v[200:203], v[24:27]
	v_mfma_f32_16x16x32_bf16 v[16:19], v[152:155], v[208:211], v[16:19]
	v_mfma_f32_16x16x32_bf16 v[8:11], v[160:163], v[208:211], v[8:11]
	s_setprio 0
	s_setprio 1
	v_mfma_f32_16x16x32_bf16 v[52:55], v[164:167], v[180:183], v[52:55]
	v_mfma_f32_16x16x32_bf16 v[44:47], v[172:175], v[180:183], v[44:47]
	v_mfma_f32_16x16x32_bf16 v[36:39], v[164:167], v[188:191], v[36:39]
	v_mfma_f32_16x16x32_bf16 v[28:31], v[172:175], v[188:191], v[28:31]
	v_mfma_f32_16x16x32_bf16 v[20:23], v[164:167], v[196:199], v[20:23]
	v_mfma_f32_16x16x32_bf16 v[12:15], v[172:175], v[196:199], v[12:15]
	v_mfma_f32_16x16x32_bf16 v[4:7], v[164:167], v[204:207], v[4:7]
	v_mfma_f32_16x16x32_bf16 v[0:3], v[172:175], v[204:207], v[0:3]
	v_mfma_f32_16x16x32_bf16 v[52:55], v[168:171], v[184:187], v[52:55]
	v_mfma_f32_16x16x32_bf16 v[44:47], v[176:179], v[184:187], v[44:47]
	v_mfma_f32_16x16x32_bf16 v[36:39], v[168:171], v[192:195], v[36:39]
	v_mfma_f32_16x16x32_bf16 v[28:31], v[176:179], v[192:195], v[28:31]
	v_mfma_f32_16x16x32_bf16 v[20:23], v[168:171], v[200:203], v[20:23]
	v_mfma_f32_16x16x32_bf16 v[12:15], v[176:179], v[200:203], v[12:15]
	v_mfma_f32_16x16x32_bf16 v[4:7], v[168:171], v[208:211], v[4:7]
	v_mfma_f32_16x16x32_bf16 v[0:3], v[176:179], v[208:211], v[0:3]
	s_setprio 0
	s_barrier
	s_add_i32 s3, 0, 0x18000
	s_add_i32 s37, 0, 0x1c000
	v_add_u32_e32 v160, s3, v147
	v_add_u32_e32 v176, s37, v147
	ds_read_b128 v[140:143], v160
	ds_read_b128 v[152:155], v160 offset:1024
	ds_read_b128 v[156:159], v160 offset:2048
	ds_read_b128 v[160:163], v160 offset:3072
	ds_read_b128 v[164:167], v176
	ds_read_b128 v[168:171], v176 offset:1024
	ds_read_b128 v[172:175], v176 offset:2048
	ds_read_b128 v[176:179], v176 offset:3072
	s_add_u32 s42, s86, 0x200000
	s_addc_u32 s43, s87, 0
	s_mov_b32 m0, s30
	ds_read_b128 v[180:183], v151 offset:32768
	ds_read_b128 v[184:187], v151 offset:33792
	ds_read_b128 v[188:191], v151 offset:34816
	ds_read_b128 v[192:195], v151 offset:35840
	ds_read_b128 v[196:199], v151 offset:36864
	ds_read_b128 v[200:203], v151 offset:37888
	ds_read_b128 v[204:207], v151 offset:38912
	ds_read_b128 v[208:211], v151 offset:39936
	global_load_lds_dwordx4 v128, s[42:43]
	v_lshl_add_u64 v[218:219], s[42:43], 0, v[130:131]
	s_mov_b32 m0, s31
	s_nop 0
	global_load_lds_dwordx4 v[218:219], off
	s_waitcnt vmcnt(8)
	s_waitcnt lgkmcnt(0)
	s_barrier
	s_setprio 1
	s_waitcnt lgkmcnt(0)
	v_mfma_f32_16x16x32_bf16 v[124:127], v[140:143], v[180:183], v[124:127]
	v_mfma_f32_16x16x32_bf16 v[120:123], v[156:159], v[180:183], v[120:123]
	v_mfma_f32_16x16x32_bf16 v[112:115], v[140:143], v[188:191], v[112:115]
	v_mfma_f32_16x16x32_bf16 v[104:107], v[156:159], v[188:191], v[104:107]
	v_mfma_f32_16x16x32_bf16 v[96:99], v[140:143], v[196:199], v[96:99]
	v_mfma_f32_16x16x32_bf16 v[88:91], v[156:159], v[196:199], v[88:91]
	v_mfma_f32_16x16x32_bf16 v[80:83], v[140:143], v[204:207], v[80:83]
	v_mfma_f32_16x16x32_bf16 v[72:75], v[156:159], v[204:207], v[72:75]
	v_mfma_f32_16x16x32_bf16 v[124:127], v[152:155], v[184:187], v[124:127]
	v_mfma_f32_16x16x32_bf16 v[120:123], v[160:163], v[184:187], v[120:123]
	v_mfma_f32_16x16x32_bf16 v[112:115], v[152:155], v[192:195], v[112:115]
	v_mfma_f32_16x16x32_bf16 v[104:107], v[160:163], v[192:195], v[104:107]
	v_mfma_f32_16x16x32_bf16 v[96:99], v[152:155], v[200:203], v[96:99]
	v_mfma_f32_16x16x32_bf16 v[88:91], v[160:163], v[200:203], v[88:91]
	v_mfma_f32_16x16x32_bf16 v[80:83], v[152:155], v[208:211], v[80:83]
	v_mfma_f32_16x16x32_bf16 v[72:75], v[160:163], v[208:211], v[72:75]
	s_setprio 0
	s_setprio 1
	v_mfma_f32_16x16x32_bf16 v[116:119], v[164:167], v[180:183], v[116:119]
	v_mfma_f32_16x16x32_bf16 v[108:111], v[172:175], v[180:183], v[108:111]
	v_mfma_f32_16x16x32_bf16 v[100:103], v[164:167], v[188:191], v[100:103]
	v_mfma_f32_16x16x32_bf16 v[92:95], v[172:175], v[188:191], v[92:95]
	v_mfma_f32_16x16x32_bf16 v[84:87], v[164:167], v[196:199], v[84:87]
	v_mfma_f32_16x16x32_bf16 v[76:79], v[172:175], v[196:199], v[76:79]
	v_mfma_f32_16x16x32_bf16 v[68:71], v[164:167], v[204:207], v[68:71]
	v_mfma_f32_16x16x32_bf16 v[64:67], v[172:175], v[204:207], v[64:67]
	v_mfma_f32_16x16x32_bf16 v[116:119], v[168:171], v[184:187], v[116:119]
	v_mfma_f32_16x16x32_bf16 v[108:111], v[176:179], v[184:187], v[108:111]
	v_mfma_f32_16x16x32_bf16 v[100:103], v[168:171], v[192:195], v[100:103]
	v_mfma_f32_16x16x32_bf16 v[92:95], v[176:179], v[192:195], v[92:95]
	v_mfma_f32_16x16x32_bf16 v[84:87], v[168:171], v[200:203], v[84:87]
	v_mfma_f32_16x16x32_bf16 v[76:79], v[176:179], v[200:203], v[76:79]
	v_mfma_f32_16x16x32_bf16 v[68:71], v[168:171], v[208:211], v[68:71]
	v_mfma_f32_16x16x32_bf16 v[64:67], v[176:179], v[208:211], v[64:67]
	s_setprio 0
	s_barrier
	s_add_i32 s3, s3, s18
	v_lshl_add_u64 v[144:145], v[144:145], 0, s[10:11]
	s_mov_b32 m0, s3
	ds_read_b128 v[180:183], v151 offset:49152
	ds_read_b128 v[184:187], v151 offset:50176
	ds_read_b128 v[188:191], v151 offset:51200
	ds_read_b128 v[192:195], v151 offset:52224
	ds_read_b128 v[196:199], v151 offset:53248
	ds_read_b128 v[200:203], v151 offset:54272
	ds_read_b128 v[204:207], v151 offset:55296
	ds_read_b128 v[208:211], v151 offset:56320
	global_load_lds_dwordx4 v[144:145], off
	s_add_i32 m0, s3, 0x2000
	s_add_u32 s42, s80, 0x200080
	v_lshl_add_u64 v[144:145], v[212:213], 0, s[10:11]
	s_addc_u32 s43, s81, 0
	s_add_i32 s3, s37, s18
	global_load_lds_dwordx4 v[144:145], off
	s_mov_b32 m0, s3
	s_nop 0
	global_load_lds_dwordx4 v128, s[42:43]
	s_add_i32 m0, s3, 0x2000
	s_nop 0
	global_load_lds_dwordx4 v130, s[42:43]
	v_lshl_add_u64 v[144:145], v[214:215], 0, s[10:11]
	s_mov_b32 m0, s49
	s_nop 0
	global_load_lds_dwordx4 v[144:145], off
	v_lshl_add_u64 v[144:145], v[216:217], 0, s[10:11]
	s_mov_b32 m0, s56
	s_nop 0
	global_load_lds_dwordx4 v[144:145], off
	s_waitcnt vmcnt(8)
	s_waitcnt lgkmcnt(0)
	s_barrier
	s_setprio 1
	s_waitcnt lgkmcnt(0)
	v_mfma_f32_16x16x32_bf16 v[60:63], v[140:143], v[180:183], v[60:63]
	v_mfma_f32_16x16x32_bf16 v[56:59], v[156:159], v[180:183], v[56:59]
	v_mfma_f32_16x16x32_bf16 v[48:51], v[140:143], v[188:191], v[48:51]
	v_mfma_f32_16x16x32_bf16 v[40:43], v[156:159], v[188:191], v[40:43]
	v_mfma_f32_16x16x32_bf16 v[32:35], v[140:143], v[196:199], v[32:35]
	v_mfma_f32_16x16x32_bf16 v[24:27], v[156:159], v[196:199], v[24:27]
	v_mfma_f32_16x16x32_bf16 v[16:19], v[140:143], v[204:207], v[16:19]
	v_mfma_f32_16x16x32_bf16 v[8:11], v[156:159], v[204:207], v[8:11]
	v_mfma_f32_16x16x32_bf16 v[60:63], v[152:155], v[184:187], v[60:63]
	v_mfma_f32_16x16x32_bf16 v[56:59], v[160:163], v[184:187], v[56:59]
	v_mfma_f32_16x16x32_bf16 v[48:51], v[152:155], v[192:195], v[48:51]
	v_mfma_f32_16x16x32_bf16 v[40:43], v[160:163], v[192:195], v[40:43]
	v_mfma_f32_16x16x32_bf16 v[32:35], v[152:155], v[200:203], v[32:35]
	v_mfma_f32_16x16x32_bf16 v[24:27], v[160:163], v[200:203], v[24:27]
	v_mfma_f32_16x16x32_bf16 v[16:19], v[152:155], v[208:211], v[16:19]
	v_mfma_f32_16x16x32_bf16 v[8:11], v[160:163], v[208:211], v[8:11]
	s_setprio 0
	s_setprio 1
	v_mfma_f32_16x16x32_bf16 v[52:55], v[164:167], v[180:183], v[52:55]
	v_mfma_f32_16x16x32_bf16 v[44:47], v[172:175], v[180:183], v[44:47]
	v_mfma_f32_16x16x32_bf16 v[36:39], v[164:167], v[188:191], v[36:39]
	v_mfma_f32_16x16x32_bf16 v[28:31], v[172:175], v[188:191], v[28:31]
	v_mfma_f32_16x16x32_bf16 v[20:23], v[164:167], v[196:199], v[20:23]
	v_mfma_f32_16x16x32_bf16 v[12:15], v[172:175], v[196:199], v[12:15]
	v_mfma_f32_16x16x32_bf16 v[4:7], v[164:167], v[204:207], v[4:7]
	v_mfma_f32_16x16x32_bf16 v[0:3], v[172:175], v[204:207], v[0:3]
	v_mfma_f32_16x16x32_bf16 v[52:55], v[168:171], v[184:187], v[52:55]
	v_mfma_f32_16x16x32_bf16 v[44:47], v[176:179], v[184:187], v[44:47]
	v_mfma_f32_16x16x32_bf16 v[36:39], v[168:171], v[192:195], v[36:39]
	v_mfma_f32_16x16x32_bf16 v[28:31], v[176:179], v[192:195], v[28:31]
	v_mfma_f32_16x16x32_bf16 v[20:23], v[168:171], v[200:203], v[20:23]
	v_mfma_f32_16x16x32_bf16 v[12:15], v[176:179], v[200:203], v[12:15]
	v_mfma_f32_16x16x32_bf16 v[4:7], v[168:171], v[208:211], v[4:7]
	v_mfma_f32_16x16x32_bf16 v[0:3], v[176:179], v[208:211], v[0:3]
	s_setprio 0
	s_barrier
	s_add_i32 s36, s36, 2
	s_add_u32 s84, s84, 0x100
	s_addc_u32 s85, s85, 0
	s_add_u32 s27, s27, 0x100
	s_addc_u32 s33, s33, 0
	s_cmpk_gt_u32 s36, 0x7d
	s_cbranch_scc0 .LBB0_846
	s_and_b64 vcc, exec, s[12:13]
	s_cbranch_vccz .LBB0_849
	s_barrier

.LBB0_913:
	s_mov_b64 s[84:85], 0x80
	s_and_b32 s1, s1, 3
	s_add_i32 m0, s30, 0x18000
	v_lshl_add_u64 v[6:7], v[6:7], 0, s[84:85]
	s_lshl_b32 s8, s3, 13
	s_lshl_b32 s12, s1, 5
	s_lshl_b32 s9, s1, 12
	s_waitcnt vmcnt(2)
	s_barrier
	global_load_lds_dwordx4 v[6:7], off
	v_lshl_add_u64 v[4:5], v[4:5], 0, s[84:85]
	s_add_i32 m0, s30, 0x1a000
	s_add_i32 s78, s30, 0x8000
	s_add_i32 s56, s30, 0xa000
	global_load_lds_dwordx4 v[4:5], off
	v_lshl_add_u64 v[0:1], v[0:1], 0, s[84:85]
	s_mov_b32 m0, s78
	s_add_u32 s6, s80, 0x80080
	global_load_lds_dwordx4 v[0:1], off
	v_lshl_add_u64 v[0:1], v[2:3], 0, s[84:85]
	s_mov_b32 m0, s56
	s_addc_u32 s7, s81, 0
	global_load_lds_dwordx4 v[0:1], off
	s_add_i32 m0, s30, 0x1c000
	s_nop 0
	global_load_lds_dwordx4 v138, s[6:7]
	s_add_i32 m0, s30, 0x1e000
	v_bfe_u32 v2, v8, 4, 2
	global_load_lds_dwordx4 v142, s[6:7]
	v_and_b32_e32 v1, 15, v8
	v_lshlrev_b32_e32 v3, 4, v2
	v_lshl_or_b32 v164, s3, 6, v1
	v_lshl_or_b32 v1, v1, 6, v3
	v_lshlrev_b32_e32 v3, 2, v8
	v_and_b32_e32 v3, 32, v3
	v_bitop3_b32 v4, v1, s8, v3 bitop3:0xde
	v_bitop3_b32 v165, v1, s9, v3 bitop3:0xde
	v_lshlrev_b32_e32 v1, 1, v8
	v_and_b32_e32 v144, 32, v1
	v_lshlrev_b32_e32 v1, 15, v9
	v_and_b32_e32 v1, 0xffff0000, v1
	v_lshlrev_b32_e32 v0, 3, v2
	v_cmp_gt_u32_e64 s[8:9], 2, v2
	v_cmp_eq_u32_e64 s[10:11], 0, v2
	v_lshl_add_u32 v1, v10, 12, v1
	v_and_b32_e32 v2, 1, v9
	v_lshl_or_b32 v1, v2, 6, v1
	s_cmpk_lt_u32 s0, 0x100
	v_lshl_add_u32 v148, v11, 1, v1
	v_lshlrev_b32_e32 v1, 15, v12
	s_cselect_b64 s[86:87], -1, 0
	s_bitcmp0_b32 s0, 6
	v_and_b32_e32 v1, 0xffff0000, v1
	s_waitcnt vmcnt(6)
	s_cselect_b64 s[88:89], -1, 0
	s_cmp_eq_u32 s1, 0
	v_readlane_b32 s0, v249, 33
	v_lshl_add_u32 v1, v13, 12, v1
	v_and_b32_e32 v2, 1, v12
	s_cselect_b64 s[90:91], -1, 0
	v_readlane_b32 s1, v249, 34
	v_lshl_or_b32 v1, v2, 6, v1
	s_add_i32 s57, 0, 0x10000
	s_add_i32 s76, 0, 0x14000
	v_or_b32_e32 v166, 16, v164
	v_or_b32_e32 v167, 32, v164
	v_or_b32_e32 v168, 48, v164
	v_add_u32_e32 v169, 0x80, v164
	v_add_u32_e32 v170, 0x90, v164
	v_add_u32_e32 v171, 0xa0, v164
	v_add_u32_e32 v172, 0xb0, v164
	v_lshl_add_u64 v[146:147], s[0:1], 0, v[144:145]
	v_mov_b32_e32 v149, v145
	v_lshl_add_u32 v150, v14, 1, v1
	v_mov_b32_e32 v151, v145
	v_mov_b64_e32 v[152:153], 0xb80
	v_mov_b64_e32 v[154:155], 0xb7f
	v_add_u32_e32 v173, s57, v165
	v_add_u32_e32 v174, s76, v165
	v_add_u32_e32 v175, 0, v4
	s_movk_i32 s77, 0x5c00
	s_lshl_b32 s52, s12, 1
	v_lshlrev_b32_e32 v156, 1, v0
	v_mov_b32_e32 v176, 0x3e0293ee
	v_mov_b32_e32 v177, 0x3e38aa3b
	s_mov_b32 s68, s53
	s_barrier
	s_branch .LBB0_916

.LBB0_919:
	ds_read_b128 v[128:131], v173
	ds_read_b128 v[132:135], v173 offset:1024
	ds_read_b128 v[158:161], v173 offset:2048
	ds_read_b128 v[178:181], v173 offset:3072
	ds_read_b128 v[182:185], v174
	ds_read_b128 v[186:189], v174 offset:1024
	ds_read_b128 v[190:193], v174 offset:2048
	ds_read_b128 v[194:197], v174 offset:3072
	s_add_u32 s3, s34, 0xfff80080
	s_addc_u32 s27, s35, -1
	s_cmp_eq_u32 s24, 28
	s_cselect_b32 vcc_hi, s0, s27
	s_cselect_b32 vcc_lo, s1, s3
	s_cselect_b32 s81, s15, s19
	s_cselect_b32 s80, s17, s18
	s_add_i32 m0, s30, 0xc000
	ds_read_b128 v[198:201], v175
	ds_read_b128 v[202:205], v175 offset:1024
	ds_read_b128 v[206:209], v175 offset:2048
	ds_read_b128 v[210:213], v175 offset:3072
	ds_read_b128 v[214:217], v175 offset:4096
	ds_read_b128 v[218:221], v175 offset:5120
	ds_read_b128 v[222:225], v175 offset:6144
	ds_read_b128 v[230:233], v175 offset:7168
	global_load_lds_dwordx4 v148, s[34:35]
	s_add_i32 m0, s30, 0xe000
	s_nop 0
	global_load_lds_dwordx4 v150, s[34:35]
	s_waitcnt vmcnt(8)
	s_waitcnt lgkmcnt(0)
	s_barrier
	s_setprio 1
	s_waitcnt lgkmcnt(0)
	v_mfma_f32_16x16x32_bf16 v[124:127], v[128:131], v[198:201], v[124:127]
	v_mfma_f32_16x16x32_bf16 v[120:123], v[158:161], v[198:201], v[120:123]
	v_mfma_f32_16x16x32_bf16 v[108:111], v[128:131], v[206:209], v[108:111]
	v_mfma_f32_16x16x32_bf16 v[104:107], v[158:161], v[206:209], v[104:107]
	v_mfma_f32_16x16x32_bf16 v[92:95], v[128:131], v[214:217], v[92:95]
	v_mfma_f32_16x16x32_bf16 v[88:91], v[158:161], v[214:217], v[88:91]
	v_mfma_f32_16x16x32_bf16 v[76:79], v[128:131], v[222:225], v[76:79]
	v_mfma_f32_16x16x32_bf16 v[72:75], v[158:161], v[222:225], v[72:75]
	v_mfma_f32_16x16x32_bf16 v[124:127], v[132:135], v[202:205], v[124:127]
	v_mfma_f32_16x16x32_bf16 v[120:123], v[178:181], v[202:205], v[120:123]
	v_mfma_f32_16x16x32_bf16 v[108:111], v[132:135], v[210:213], v[108:111]
	v_mfma_f32_16x16x32_bf16 v[104:107], v[178:181], v[210:213], v[104:107]
	v_mfma_f32_16x16x32_bf16 v[92:95], v[132:135], v[218:221], v[92:95]
	v_mfma_f32_16x16x32_bf16 v[88:91], v[178:181], v[218:221], v[88:91]
	v_mfma_f32_16x16x32_bf16 v[76:79], v[132:135], v[230:233], v[76:79]
	v_mfma_f32_16x16x32_bf16 v[72:75], v[178:181], v[230:233], v[72:75]
	s_setprio 0
	s_setprio 1
	v_mfma_f32_16x16x32_bf16 v[116:119], v[182:185], v[198:201], v[116:119]
	v_mfma_f32_16x16x32_bf16 v[112:115], v[190:193], v[198:201], v[112:115]
	v_mfma_f32_16x16x32_bf16 v[100:103], v[182:185], v[206:209], v[100:103]
	v_mfma_f32_16x16x32_bf16 v[96:99], v[190:193], v[206:209], v[96:99]
	v_mfma_f32_16x16x32_bf16 v[84:87], v[182:185], v[214:217], v[84:87]
	v_mfma_f32_16x16x32_bf16 v[80:83], v[190:193], v[214:217], v[80:83]
	v_mfma_f32_16x16x32_bf16 v[68:71], v[182:185], v[222:225], v[68:71]
	v_mfma_f32_16x16x32_bf16 v[64:67], v[190:193], v[222:225], v[64:67]
	v_mfma_f32_16x16x32_bf16 v[116:119], v[186:189], v[202:205], v[116:119]
	v_mfma_f32_16x16x32_bf16 v[112:115], v[194:197], v[202:205], v[112:115]
	v_mfma_f32_16x16x32_bf16 v[100:103], v[186:189], v[210:213], v[100:103]
	v_mfma_f32_16x16x32_bf16 v[96:99], v[194:197], v[210:213], v[96:99]
	v_mfma_f32_16x16x32_bf16 v[84:87], v[186:189], v[218:221], v[84:87]
	v_mfma_f32_16x16x32_bf16 v[80:83], v[194:197], v[218:221], v[80:83]
	v_mfma_f32_16x16x32_bf16 v[68:71], v[186:189], v[230:233], v[68:71]
	v_mfma_f32_16x16x32_bf16 v[64:67], v[194:197], v[230:233], v[64:67]
	s_setprio 0
	s_barrier
	s_add_i32 s3, s57, s25
	v_lshl_add_u64 v[162:163], s[80:81], 0, v[138:139]
	s_mov_b32 m0, s3
	ds_read_b128 v[198:201], v175 offset:16384
	ds_read_b128 v[202:205], v175 offset:17408
	ds_read_b128 v[206:209], v175 offset:18432
	ds_read_b128 v[210:213], v175 offset:19456
	ds_read_b128 v[214:217], v175 offset:20480
	ds_read_b128 v[218:221], v175 offset:21504
	ds_read_b128 v[222:225], v175 offset:22528
	ds_read_b128 v[230:233], v175 offset:23552
	global_load_lds_dwordx4 v[162:163], off
	s_add_i32 m0, s3, 0x2000
	s_add_u32 s36, s80, 0x80000
	v_lshl_add_u64 v[226:227], s[80:81], 0, v[142:143]
	s_addc_u32 s37, s81, 0
	s_add_i32 s3, s76, s25
	global_load_lds_dwordx4 v[226:227], off
	s_mov_b32 m0, s3
	v_lshl_add_u64 v[236:237], vcc, 0, v[140:141]
	global_load_lds_dwordx4 v138, s[36:37]
	s_add_i32 m0, s3, 0x2000
	s_nop 0
	global_load_lds_dwordx4 v142, s[36:37]
	v_lshl_add_u64 v[234:235], vcc, 0, v[136:137]
	s_mov_b32 m0, s30
	s_nop 0
	global_load_lds_dwordx4 v[234:235], off
	s_mov_b32 m0, s31
	s_nop 0
	global_load_lds_dwordx4 v[236:237], off
	s_waitcnt vmcnt(8)
	s_waitcnt lgkmcnt(0)
	s_barrier
	s_setprio 1
	s_waitcnt lgkmcnt(0)
	v_mfma_f32_16x16x32_bf16 v[60:63], v[128:131], v[198:201], v[60:63]
	v_mfma_f32_16x16x32_bf16 v[56:59], v[158:161], v[198:201], v[56:59]
	v_mfma_f32_16x16x32_bf16 v[44:47], v[128:131], v[206:209], v[44:47]
	v_mfma_f32_16x16x32_bf16 v[40:43], v[158:161], v[206:209], v[40:43]
	v_mfma_f32_16x16x32_bf16 v[28:31], v[128:131], v[214:217], v[28:31]
	v_mfma_f32_16x16x32_bf16 v[24:27], v[158:161], v[214:217], v[24:27]
	v_mfma_f32_16x16x32_bf16 v[12:15], v[128:131], v[222:225], v[12:15]
	v_mfma_f32_16x16x32_bf16 v[8:11], v[158:161], v[222:225], v[8:11]
	v_mfma_f32_16x16x32_bf16 v[60:63], v[132:135], v[202:205], v[60:63]
	v_mfma_f32_16x16x32_bf16 v[56:59], v[178:181], v[202:205], v[56:59]
	v_mfma_f32_16x16x32_bf16 v[44:47], v[132:135], v[210:213], v[44:47]
	v_mfma_f32_16x16x32_bf16 v[40:43], v[178:181], v[210:213], v[40:43]
	v_mfma_f32_16x16x32_bf16 v[28:31], v[132:135], v[218:221], v[28:31]
	v_mfma_f32_16x16x32_bf16 v[24:27], v[178:181], v[218:221], v[24:27]
	v_mfma_f32_16x16x32_bf16 v[12:15], v[132:135], v[230:233], v[12:15]
	v_mfma_f32_16x16x32_bf16 v[8:11], v[178:181], v[230:233], v[8:11]
	s_setprio 0
	s_setprio 1
	v_mfma_f32_16x16x32_bf16 v[52:55], v[182:185], v[198:201], v[52:55]
	v_mfma_f32_16x16x32_bf16 v[48:51], v[190:193], v[198:201], v[48:51]
	v_mfma_f32_16x16x32_bf16 v[36:39], v[182:185], v[206:209], v[36:39]
	v_mfma_f32_16x16x32_bf16 v[32:35], v[190:193], v[206:209], v[32:35]
	v_mfma_f32_16x16x32_bf16 v[20:23], v[182:185], v[214:217], v[20:23]
	v_mfma_f32_16x16x32_bf16 v[16:19], v[190:193], v[214:217], v[16:19]
	v_mfma_f32_16x16x32_bf16 v[4:7], v[182:185], v[222:225], v[4:7]
	v_mfma_f32_16x16x32_bf16 v[0:3], v[190:193], v[222:225], v[0:3]
	v_mfma_f32_16x16x32_bf16 v[52:55], v[186:189], v[202:205], v[52:55]
	v_mfma_f32_16x16x32_bf16 v[48:51], v[194:197], v[202:205], v[48:51]
	v_mfma_f32_16x16x32_bf16 v[36:39], v[186:189], v[210:213], v[36:39]
	v_mfma_f32_16x16x32_bf16 v[32:35], v[194:197], v[210:213], v[32:35]
	v_mfma_f32_16x16x32_bf16 v[20:23], v[186:189], v[218:221], v[20:23]
	v_mfma_f32_16x16x32_bf16 v[16:19], v[194:197], v[218:221], v[16:19]
	v_mfma_f32_16x16x32_bf16 v[4:7], v[186:189], v[230:233], v[4:7]
	v_mfma_f32_16x16x32_bf16 v[0:3], v[194:197], v[230:233], v[0:3]
	s_setprio 0
	s_barrier
	s_add_i32 s3, 0, 0x18000
	v_add_u32_e32 v144, s3, v165
	s_add_i32 s27, 0, 0x1c000
	ds_read_b128 v[128:131], v144
	ds_read_b128 v[132:135], v144 offset:1024
	ds_read_b128 v[158:161], v144 offset:2048
	ds_read_b128 v[178:181], v144 offset:3072
	v_add_u32_e32 v144, s27, v165
	ds_read_b128 v[182:185], v144
	ds_read_b128 v[186:189], v144 offset:1024
	ds_read_b128 v[190:193], v144 offset:2048
	ds_read_b128 v[194:197], v144 offset:3072
	s_add_u32 s36, vcc_lo, 0x80000
	s_addc_u32 s37, vcc_hi, 0
	s_mov_b32 m0, s58
	ds_read_b128 v[198:201], v175 offset:32768
	ds_read_b128 v[202:205], v175 offset:33792
	ds_read_b128 v[206:209], v175 offset:34816
	ds_read_b128 v[210:213], v175 offset:35840
	ds_read_b128 v[214:217], v175 offset:36864
	ds_read_b128 v[218:221], v175 offset:37888
	ds_read_b128 v[222:225], v175 offset:38912
	ds_read_b128 v[230:233], v175 offset:39936
	global_load_lds_dwordx4 v136, s[36:37]
	s_mov_b32 m0, s59
	s_nop 0
	global_load_lds_dwordx4 v140, s[36:37]
	s_waitcnt vmcnt(8)
	s_waitcnt lgkmcnt(0)
	s_barrier
	s_setprio 1
	s_waitcnt lgkmcnt(0)
	v_mfma_f32_16x16x32_bf16 v[124:127], v[128:131], v[198:201], v[124:127]
	v_mfma_f32_16x16x32_bf16 v[120:123], v[158:161], v[198:201], v[120:123]
	v_mfma_f32_16x16x32_bf16 v[108:111], v[128:131], v[206:209], v[108:111]
	v_mfma_f32_16x16x32_bf16 v[104:107], v[158:161], v[206:209], v[104:107]
	v_mfma_f32_16x16x32_bf16 v[92:95], v[128:131], v[214:217], v[92:95]
	v_mfma_f32_16x16x32_bf16 v[88:91], v[158:161], v[214:217], v[88:91]
	v_mfma_f32_16x16x32_bf16 v[76:79], v[128:131], v[222:225], v[76:79]
	v_mfma_f32_16x16x32_bf16 v[72:75], v[158:161], v[222:225], v[72:75]
	v_mfma_f32_16x16x32_bf16 v[124:127], v[132:135], v[202:205], v[124:127]
	v_mfma_f32_16x16x32_bf16 v[120:123], v[178:181], v[202:205], v[120:123]
	v_mfma_f32_16x16x32_bf16 v[108:111], v[132:135], v[210:213], v[108:111]
	v_mfma_f32_16x16x32_bf16 v[104:107], v[178:181], v[210:213], v[104:107]
	v_mfma_f32_16x16x32_bf16 v[92:95], v[132:135], v[218:221], v[92:95]
	v_mfma_f32_16x16x32_bf16 v[88:91], v[178:181], v[218:221], v[88:91]
	v_mfma_f32_16x16x32_bf16 v[76:79], v[132:135], v[230:233], v[76:79]
	v_mfma_f32_16x16x32_bf16 v[72:75], v[178:181], v[230:233], v[72:75]
	s_setprio 0
	s_setprio 1
	v_mfma_f32_16x16x32_bf16 v[116:119], v[182:185], v[198:201], v[116:119]
	v_mfma_f32_16x16x32_bf16 v[112:115], v[190:193], v[198:201], v[112:115]
	v_mfma_f32_16x16x32_bf16 v[100:103], v[182:185], v[206:209], v[100:103]
	v_mfma_f32_16x16x32_bf16 v[96:99], v[190:193], v[206:209], v[96:99]
	v_mfma_f32_16x16x32_bf16 v[84:87], v[182:185], v[214:217], v[84:87]
	v_mfma_f32_16x16x32_bf16 v[80:83], v[190:193], v[214:217], v[80:83]
	v_mfma_f32_16x16x32_bf16 v[68:71], v[182:185], v[222:225], v[68:71]
	v_mfma_f32_16x16x32_bf16 v[64:67], v[190:193], v[222:225], v[64:67]
	v_mfma_f32_16x16x32_bf16 v[116:119], v[186:189], v[202:205], v[116:119]
	v_mfma_f32_16x16x32_bf16 v[112:115], v[194:197], v[202:205], v[112:115]
	v_mfma_f32_16x16x32_bf16 v[100:103], v[186:189], v[210:213], v[100:103]
	v_mfma_f32_16x16x32_bf16 v[96:99], v[194:197], v[210:213], v[96:99]
	v_mfma_f32_16x16x32_bf16 v[84:87], v[186:189], v[218:221], v[84:87]
	v_mfma_f32_16x16x32_bf16 v[80:83], v[194:197], v[218:221], v[80:83]
	v_mfma_f32_16x16x32_bf16 v[68:71], v[186:189], v[230:233], v[68:71]
	v_mfma_f32_16x16x32_bf16 v[64:67], v[194:197], v[230:233], v[64:67]
	s_setprio 0
	s_barrier
	s_add_i32 s3, s3, s25
	v_lshl_add_u64 v[162:163], v[162:163], 0, s[84:85]
	s_mov_b32 m0, s3
	ds_read_b128 v[198:201], v175 offset:49152
	ds_read_b128 v[202:205], v175 offset:50176
	ds_read_b128 v[206:209], v175 offset:51200
	ds_read_b128 v[210:213], v175 offset:52224
	ds_read_b128 v[214:217], v175 offset:53248
	ds_read_b128 v[218:221], v175 offset:54272
	ds_read_b128 v[222:225], v175 offset:55296
	ds_read_b128 v[230:233], v175 offset:56320
	global_load_lds_dwordx4 v[162:163], off
	s_add_i32 m0, s3, 0x2000
	s_add_u32 s36, s80, 0x80080
	v_lshl_add_u64 v[162:163], v[226:227], 0, s[84:85]
	s_addc_u32 s37, s81, 0
	s_add_i32 s3, s27, s25
	global_load_lds_dwordx4 v[162:163], off
	s_mov_b32 m0, s3
	s_nop 0
	global_load_lds_dwordx4 v138, s[36:37]
	s_add_i32 m0, s3, 0x2000
	s_nop 0
	global_load_lds_dwordx4 v142, s[36:37]
	v_lshl_add_u64 v[162:163], v[234:235], 0, s[84:85]
	s_mov_b32 m0, s78
	s_nop 0
	global_load_lds_dwordx4 v[162:163], off
	v_lshl_add_u64 v[162:163], v[236:237], 0, s[84:85]
	s_mov_b32 m0, s56
	s_nop 0
	global_load_lds_dwordx4 v[162:163], off
	s_waitcnt vmcnt(8)
	s_waitcnt lgkmcnt(0)
	s_barrier
	s_setprio 1
	s_waitcnt lgkmcnt(0)
	v_mfma_f32_16x16x32_bf16 v[60:63], v[128:131], v[198:201], v[60:63]
	v_mfma_f32_16x16x32_bf16 v[56:59], v[158:161], v[198:201], v[56:59]
	v_mfma_f32_16x16x32_bf16 v[44:47], v[128:131], v[206:209], v[44:47]
	v_mfma_f32_16x16x32_bf16 v[40:43], v[158:161], v[206:209], v[40:43]
	v_mfma_f32_16x16x32_bf16 v[28:31], v[128:131], v[214:217], v[28:31]
	v_mfma_f32_16x16x32_bf16 v[24:27], v[158:161], v[214:217], v[24:27]
	v_mfma_f32_16x16x32_bf16 v[12:15], v[128:131], v[222:225], v[12:15]
	v_mfma_f32_16x16x32_bf16 v[8:11], v[158:161], v[222:225], v[8:11]
	v_mfma_f32_16x16x32_bf16 v[60:63], v[132:135], v[202:205], v[60:63]
	v_mfma_f32_16x16x32_bf16 v[56:59], v[178:181], v[202:205], v[56:59]
	v_mfma_f32_16x16x32_bf16 v[44:47], v[132:135], v[210:213], v[44:47]
	v_mfma_f32_16x16x32_bf16 v[40:43], v[178:181], v[210:213], v[40:43]
	v_mfma_f32_16x16x32_bf16 v[28:31], v[132:135], v[218:221], v[28:31]
	v_mfma_f32_16x16x32_bf16 v[24:27], v[178:181], v[218:221], v[24:27]
	v_mfma_f32_16x16x32_bf16 v[12:15], v[132:135], v[230:233], v[12:15]
	v_mfma_f32_16x16x32_bf16 v[8:11], v[178:181], v[230:233], v[8:11]
	s_setprio 0
	s_setprio 1
	v_mfma_f32_16x16x32_bf16 v[52:55], v[182:185], v[198:201], v[52:55]
	v_mfma_f32_16x16x32_bf16 v[48:51], v[190:193], v[198:201], v[48:51]
	v_mfma_f32_16x16x32_bf16 v[36:39], v[182:185], v[206:209], v[36:39]
	v_mfma_f32_16x16x32_bf16 v[32:35], v[190:193], v[206:209], v[32:35]
	v_mfma_f32_16x16x32_bf16 v[20:23], v[182:185], v[214:217], v[20:23]
	v_mfma_f32_16x16x32_bf16 v[16:19], v[190:193], v[214:217], v[16:19]
	v_mfma_f32_16x16x32_bf16 v[4:7], v[182:185], v[222:225], v[4:7]
	v_mfma_f32_16x16x32_bf16 v[0:3], v[190:193], v[222:225], v[0:3]
	v_mfma_f32_16x16x32_bf16 v[52:55], v[186:189], v[202:205], v[52:55]
	v_mfma_f32_16x16x32_bf16 v[48:51], v[194:197], v[202:205], v[48:51]
	v_mfma_f32_16x16x32_bf16 v[36:39], v[186:189], v[210:213], v[36:39]
	v_mfma_f32_16x16x32_bf16 v[32:35], v[194:197], v[210:213], v[32:35]
	v_mfma_f32_16x16x32_bf16 v[20:23], v[186:189], v[218:221], v[20:23]
	v_mfma_f32_16x16x32_bf16 v[16:19], v[194:197], v[218:221], v[16:19]
	v_mfma_f32_16x16x32_bf16 v[4:7], v[186:189], v[230:233], v[4:7]
	v_mfma_f32_16x16x32_bf16 v[0:3], v[194:197], v[230:233], v[0:3]
	s_setprio 0
	s_barrier
	s_add_i32 s24, s24, 2
	s_add_u32 s34, s34, 0x100
	s_addc_u32 s35, s35, 0
	s_add_u32 s18, s18, 0x100
	s_addc_u32 s19, s19, 0
	s_cmp_gt_u32 s24, 29
	s_cbranch_scc0 .LBB0_919
	s_and_b64 vcc, exec, s[86:87]
	s_cbranch_vccz .LBB0_922
	s_barrier

.LBB0_1249:
	s_cmp_eq_u32 s86, 0
	s_cselect_b64 s[0:1], -1, 0
	s_or_b64 s[0:1], s[88:89], s[0:1]
	s_and_b64 vcc, exec, s[0:1]
	s_cbranch_vccnz .Lfz1_c1
	s_add_i32 s0, s77, 0xc000
	s_and_b32 s0, s0, 0xc000
	v_add_u32_e32 v0, s0, v234
	ds_read_b64_tr_b16 v[160:161], v0 offset:0x2000
	ds_read_b64_tr_b16 v[162:163], v0 offset:0x2100
	ds_read_b64_tr_b16 v[164:165], v0 offset:0x3000
	ds_read_b64_tr_b16 v[166:167], v0 offset:0x3100
	s_waitcnt lgkmcnt(2)
	s_nop 0
	v_mfma_f32_32x32x16_bf16 v[128:143], v[6:9], v[160:163], v[128:143]
	ds_read_b64_tr_b16 v[168:169], v0 offset:0x2200
	v_mfma_f32_32x32x16_bf16 v[96:111], v[2:5], v[160:163], v[96:111]
	ds_read_b64_tr_b16 v[170:171], v0 offset:0x2300
	s_waitcnt lgkmcnt(2)
	v_mfma_f32_32x32x16_bf16 v[128:143], v[208:211], v[164:167], v[128:143]
	ds_read_b64_tr_b16 v[172:173], v0 offset:0x3200
	v_mfma_f32_32x32x16_bf16 v[96:111], v[10:13], v[164:167], v[96:111]
	ds_read_b64_tr_b16 v[174:175], v0 offset:0x3300
	s_waitcnt lgkmcnt(2)
	v_mfma_f32_32x32x16_bf16 v[112:127], v[6:9], v[168:171], v[112:127]
	ds_read_b64_tr_b16 v[160:161], v0 offset:0x2400
	v_mfma_f32_32x32x16_bf16 v[80:95], v[2:5], v[168:171], v[80:95]
	ds_read_b64_tr_b16 v[162:163], v0 offset:0x2500
	s_waitcnt lgkmcnt(2)
	v_mfma_f32_32x32x16_bf16 v[112:127], v[208:211], v[172:175], v[112:127]
	ds_read_b64_tr_b16 v[164:165], v0 offset:0x3400
	v_mfma_f32_32x32x16_bf16 v[80:95], v[10:13], v[172:175], v[80:95]
	ds_read_b64_tr_b16 v[166:167], v0 offset:0x3500
	s_waitcnt lgkmcnt(2)
	v_mfma_f32_32x32x16_bf16 v[64:79], v[6:9], v[160:163], v[64:79]
	ds_read_b64_tr_b16 v[168:169], v0 offset:0x2600
	v_mfma_f32_32x32x16_bf16 v[48:63], v[2:5], v[160:163], v[48:63]
	ds_read_b64_tr_b16 v[170:171], v0 offset:0x2700
	s_waitcnt lgkmcnt(2)
	v_mfma_f32_32x32x16_bf16 v[64:79], v[208:211], v[164:167], v[64:79]
	ds_read_b64_tr_b16 v[172:173], v0 offset:0x3600
	v_mfma_f32_32x32x16_bf16 v[48:63], v[10:13], v[164:167], v[48:63]
	ds_read_b64_tr_b16 v[174:175], v0 offset:0x3700
	s_waitcnt lgkmcnt(2)
	v_mfma_f32_32x32x16_bf16 v[32:47], v[6:9], v[168:171], v[32:47]
	v_mfma_f32_32x32x16_bf16 v[16:31], v[2:5], v[168:171], v[16:31]
	s_waitcnt lgkmcnt(0)
	v_mfma_f32_32x32x16_bf16 v[32:47], v[208:211], v[172:175], v[32:47]
	v_mfma_f32_32x32x16_bf16 v[16:31], v[10:13], v[172:175], v[16:31]
.Lfz1_c1:
	s_and_b32 s27, s77, 0xc000
	v_add_u32_e32 v241, s27, v233
	ds_read_b128 v[144:147], v241 offset:0
	v_xor_b32_e32 v240, 32, v241
	ds_read_b128 v[148:151], v240 offset:0
	v_xor_b32_e32 v239, 64, v241
	ds_read_b128 v[152:155], v239 offset:0
	v_xor_b32_e32 v0, 0x60, v241
	ds_read_b128 v[156:159], v0 offset:0
	s_waitcnt lgkmcnt(0)
	v_mfma_f32_32x32x16_bf16 v[212:227], v[144:147], v[176:179], 0
	v_mfma_f32_32x32x16_bf16 v[212:227], v[148:151], v[180:183], v[212:227]
	v_mfma_f32_32x32x16_bf16 v[212:227], v[152:155], v[184:187], v[212:227]
	v_mfma_f32_32x32x16_bf16 v[212:227], v[156:159], v[188:191], v[212:227]
	ds_read_b128 v[144:147], v241 offset:0x80
	ds_read_b128 v[148:151], v240 offset:0x80
	ds_read_b128 v[152:155], v239 offset:0x80
	ds_read_b128 v[156:159], v0 offset:0x80
	v_cmp_eq_f32_e32 vcc, 0, v238
	v_cmp_eq_f32_e64 s[10:11], 0, v237
	s_and_b64 s[0:1], vcc, s[10:11]
	s_cmp_eq_u64 s[0:1], exec
	s_waitcnt lgkmcnt(0)
	v_mfma_f32_32x32x16_bf16 v[160:175], v[144:147], v[192:195], 0
	v_mfma_f32_32x32x16_bf16 v[160:175], v[148:151], v[196:199], v[160:175]
	v_mfma_f32_32x32x16_bf16 v[160:175], v[152:155], v[200:203], v[160:175]
	v_mfma_f32_32x32x16_bf16 v[160:175], v[156:159], v[204:207], v[160:175]
	s_cbranch_scc0 .LBB0_1251
	v_exp_f32_e32 v144, v212
	v_exp_f32_e32 v145, v213
	v_exp_f32_e32 v146, v214
	v_exp_f32_e32 v147, v215
	v_exp_f32_e32 v148, v216
	v_exp_f32_e32 v149, v217
	v_exp_f32_e32 v150, v218
	v_exp_f32_e32 v151, v219
	v_exp_f32_e32 v152, v220
	v_exp_f32_e32 v153, v221
	v_exp_f32_e32 v154, v222
	v_exp_f32_e32 v155, v223
	v_exp_f32_e32 v156, v224
	v_exp_f32_e32 v157, v225
	v_exp_f32_e32 v158, v226
	v_exp_f32_e32 v159, v227
	v_pk_add_f32 v[252:253], v[144:145], v[146:147]
	v_pk_add_f32 v[254:255], v[148:149], v[150:151]
	v_pk_add_f32 v[252:253], v[152:153], v[252:253]
	v_pk_add_f32 v[254:255], v[154:155], v[254:255]
	v_pk_add_f32 v[252:253], v[156:157], v[252:253]
	v_pk_add_f32 v[254:255], v[158:159], v[254:255]
	v_cvt_pk_bf16_f32 v216, v144, v145
	v_cvt_pk_bf16_f32 v217, v146, v147
	v_cvt_pk_bf16_f32 v218, v148, v149
	v_pk_add_f32 v[252:253], v[252:253], v[254:255]
	v_cvt_pk_bf16_f32 v219, v150, v151
	v_cvt_pk_bf16_f32 v224, v152, v153
	v_cvt_pk_bf16_f32 v225, v154, v155
	v_pk_add_f32 v[252:253], v[252:253], v[252:253] op_sel:[0,1] op_sel_hi:[1,0]
	v_cvt_pk_bf16_f32 v226, v156, v157
	v_cvt_pk_bf16_f32 v227, v158, v159
	v_cmp_lt_f32_e32 vcc, s52, v252
	v_cmp_gt_f32_e64 s[10:11], s53, v252
	s_and_b64 s[0:1], vcc, s[10:11]
	s_cmp_lg_u64 s[0:1], exec
	s_cbranch_scc1 .LBB0_1286
	v_add_f32_e32 v15, v15, v252
	v_exp_f32_e32 v144, v160
	v_exp_f32_e32 v145, v161
	v_exp_f32_e32 v146, v162
	v_exp_f32_e32 v147, v163
	v_exp_f32_e32 v148, v164
	v_exp_f32_e32 v149, v165
	v_exp_f32_e32 v150, v166
	v_exp_f32_e32 v151, v167
	v_exp_f32_e32 v152, v168
	v_exp_f32_e32 v153, v169
	v_exp_f32_e32 v154, v170
	v_exp_f32_e32 v155, v171
	v_exp_f32_e32 v156, v172
	v_exp_f32_e32 v157, v173
	v_exp_f32_e32 v158, v174
	v_exp_f32_e32 v159, v175
	v_pk_add_f32 v[252:253], v[144:145], v[146:147]
	v_pk_add_f32 v[254:255], v[148:149], v[150:151]
	v_pk_add_f32 v[252:253], v[152:153], v[252:253]
	v_pk_add_f32 v[254:255], v[154:155], v[254:255]
	v_pk_add_f32 v[252:253], v[156:157], v[252:253]
	v_pk_add_f32 v[254:255], v[158:159], v[254:255]
	v_cvt_pk_bf16_f32 v212, v144, v145
	v_cvt_pk_bf16_f32 v213, v146, v147
	v_cvt_pk_bf16_f32 v214, v148, v149
	v_pk_add_f32 v[252:253], v[252:253], v[254:255]
	v_cvt_pk_bf16_f32 v215, v150, v151
	v_cvt_pk_bf16_f32 v220, v152, v153
	v_cvt_pk_bf16_f32 v221, v154, v155
	v_pk_add_f32 v[252:253], v[252:253], v[252:253] op_sel:[0,1] op_sel_hi:[1,0]
	v_cvt_pk_bf16_f32 v222, v156, v157
	v_cvt_pk_bf16_f32 v223, v158, v159
	v_cmp_lt_f32_e32 vcc, s52, v252
	v_cmp_gt_f32_e64 s[10:11], s53, v252
	s_and_b64 s[0:1], vcc, s[10:11]
	s_cmp_lg_u64 s[0:1], exec
	s_cbranch_scc1 .Lfzsb1_c1
	v_add_f32_e32 v14, v14, v252
	s_branch .LBB0_1267

.LBB0_1267:
	v_add_u32_e32 v242, s27, v234
	ds_read_b64_tr_b16 v[160:161], v242 offset:0x0
	ds_read_b64_tr_b16 v[162:163], v242 offset:0x100
	ds_read_b64_tr_b16 v[164:165], v242 offset:0x1000
	ds_read_b64_tr_b16 v[166:167], v242 offset:0x1100
	s_waitcnt lgkmcnt(2)
	s_nop 0
	v_mfma_f32_32x32x16_bf16 v[128:143], v[216:219], v[160:163], v[128:143]
	ds_read_b64_tr_b16 v[168:169], v242 offset:0x200
	v_mfma_f32_32x32x16_bf16 v[96:111], v[212:215], v[160:163], v[96:111]
	ds_read_b64_tr_b16 v[170:171], v242 offset:0x300
	s_waitcnt lgkmcnt(2)
	v_mfma_f32_32x32x16_bf16 v[128:143], v[224:227], v[164:167], v[128:143]
	ds_read_b64_tr_b16 v[172:173], v242 offset:0x1200
	v_mfma_f32_32x32x16_bf16 v[96:111], v[220:223], v[164:167], v[96:111]
	ds_read_b64_tr_b16 v[174:175], v242 offset:0x1300
	s_waitcnt lgkmcnt(2)
	v_mfma_f32_32x32x16_bf16 v[112:127], v[216:219], v[168:171], v[112:127]
	ds_read_b64_tr_b16 v[160:161], v242 offset:0x400
	v_mfma_f32_32x32x16_bf16 v[80:95], v[212:215], v[168:171], v[80:95]
	ds_read_b64_tr_b16 v[162:163], v242 offset:0x500
	s_waitcnt lgkmcnt(2)
	v_mfma_f32_32x32x16_bf16 v[112:127], v[224:227], v[172:175], v[112:127]
	ds_read_b64_tr_b16 v[164:165], v242 offset:0x1400
	v_mfma_f32_32x32x16_bf16 v[80:95], v[220:223], v[172:175], v[80:95]
	ds_read_b64_tr_b16 v[166:167], v242 offset:0x1500
	ds_read_b128 v[144:147], v241 offset:0x2000
	ds_read_b128 v[148:151], v240 offset:0x2000
	ds_read_b128 v[152:155], v239 offset:0x2000
	ds_read_b128 v[156:159], v0 offset:0x2000
	s_waitcnt lgkmcnt(6)
	v_mfma_f32_32x32x16_bf16 v[64:79], v[216:219], v[160:163], v[64:79]
	ds_read_b64_tr_b16 v[168:169], v242 offset:0x600
	v_mfma_f32_32x32x16_bf16 v[48:63], v[212:215], v[160:163], v[48:63]
	ds_read_b64_tr_b16 v[170:171], v242 offset:0x700
	s_waitcnt lgkmcnt(6)
	v_mfma_f32_32x32x16_bf16 v[64:79], v[224:227], v[164:167], v[64:79]
	ds_read_b64_tr_b16 v[172:173], v242 offset:0x1600
	v_mfma_f32_32x32x16_bf16 v[48:63], v[220:223], v[164:167], v[48:63]
	ds_read_b64_tr_b16 v[174:175], v242 offset:0x1700
	s_waitcnt lgkmcnt(2)
	v_mfma_f32_32x32x16_bf16 v[32:47], v[216:219], v[168:171], v[32:47]
	v_mfma_f32_32x32x16_bf16 v[16:31], v[212:215], v[168:171], v[16:31]
	s_waitcnt lgkmcnt(0)
	v_mfma_f32_32x32x16_bf16 v[32:47], v[224:227], v[172:175], v[32:47]
	v_mfma_f32_32x32x16_bf16 v[16:31], v[220:223], v[172:175], v[16:31]
	s_waitcnt lgkmcnt(0)
	v_mfma_f32_32x32x16_bf16 v[212:227], v[144:147], v[176:179], 0
	v_mfma_f32_32x32x16_bf16 v[212:227], v[148:151], v[180:183], v[212:227]
	v_mfma_f32_32x32x16_bf16 v[212:227], v[152:155], v[184:187], v[212:227]
	v_mfma_f32_32x32x16_bf16 v[212:227], v[156:159], v[188:191], v[212:227]
	ds_read_b128 v[144:147], v241 offset:0x2080
	ds_read_b128 v[148:151], v240 offset:0x2080
	ds_read_b128 v[152:155], v239 offset:0x2080
	ds_read_b128 v[156:159], v0 offset:0x2080
	v_cmp_eq_f32_e32 vcc, 0, v238
	v_cmp_eq_f32_e64 s[10:11], 0, v237
	s_and_b64 s[0:1], vcc, s[10:11]
	s_cmp_eq_u64 s[0:1], exec
	s_waitcnt lgkmcnt(0)
	v_mfma_f32_32x32x16_bf16 v[160:175], v[144:147], v[192:195], 0
	v_mfma_f32_32x32x16_bf16 v[160:175], v[148:151], v[196:199], v[160:175]
	v_mfma_f32_32x32x16_bf16 v[160:175], v[152:155], v[200:203], v[160:175]
	v_mfma_f32_32x32x16_bf16 v[160:175], v[156:159], v[204:207], v[160:175]
	s_cbranch_scc0 .Lfz2o_c1
	v_exp_f32_e32 v144, v212
	v_exp_f32_e32 v145, v213
	v_exp_f32_e32 v146, v214
	v_exp_f32_e32 v147, v215
	v_exp_f32_e32 v148, v216
	v_exp_f32_e32 v149, v217
	v_exp_f32_e32 v150, v218
	v_exp_f32_e32 v151, v219
	v_exp_f32_e32 v152, v220
	v_exp_f32_e32 v153, v221
	v_exp_f32_e32 v154, v222
	v_exp_f32_e32 v155, v223
	v_exp_f32_e32 v156, v224
	v_exp_f32_e32 v157, v225
	v_exp_f32_e32 v158, v226
	v_exp_f32_e32 v159, v227
	v_pk_add_f32 v[252:253], v[144:145], v[146:147]
	v_pk_add_f32 v[254:255], v[148:149], v[150:151]
	v_pk_add_f32 v[252:253], v[152:153], v[252:253]
	v_pk_add_f32 v[254:255], v[154:155], v[254:255]
	v_pk_add_f32 v[252:253], v[156:157], v[252:253]
	v_pk_add_f32 v[254:255], v[158:159], v[254:255]
	v_cvt_pk_bf16_f32 v6, v144, v145
	v_cvt_pk_bf16_f32 v7, v146, v147
	v_cvt_pk_bf16_f32 v8, v148, v149
	v_pk_add_f32 v[252:253], v[252:253], v[254:255]
	v_cvt_pk_bf16_f32 v9, v150, v151
	v_cvt_pk_bf16_f32 v208, v152, v153
	v_cvt_pk_bf16_f32 v209, v154, v155
	v_pk_add_f32 v[252:253], v[252:253], v[252:253] op_sel:[0,1] op_sel_hi:[1,0]
	v_cvt_pk_bf16_f32 v210, v156, v157
	v_cvt_pk_bf16_f32 v211, v158, v159
	v_cmp_lt_f32_e32 vcc, s52, v252
	v_cmp_gt_f32_e64 s[10:11], s53, v252
	s_and_b64 s[0:1], vcc, s[10:11]
	s_cmp_lg_u64 s[0:1], exec
	s_cbranch_scc1 .LBB0_1298
	v_add_f32_e32 v15, v15, v252
	v_exp_f32_e32 v144, v160
	v_exp_f32_e32 v145, v161
	v_exp_f32_e32 v146, v162
	v_exp_f32_e32 v147, v163
	v_exp_f32_e32 v148, v164
	v_exp_f32_e32 v149, v165
	v_exp_f32_e32 v150, v166
	v_exp_f32_e32 v151, v167
	v_exp_f32_e32 v152, v168
	v_exp_f32_e32 v153, v169
	v_exp_f32_e32 v154, v170
	v_exp_f32_e32 v155, v171
	v_exp_f32_e32 v156, v172
	v_exp_f32_e32 v157, v173
	v_exp_f32_e32 v158, v174
	v_exp_f32_e32 v159, v175
	v_pk_add_f32 v[252:253], v[144:145], v[146:147]
	v_pk_add_f32 v[254:255], v[148:149], v[150:151]
	v_pk_add_f32 v[252:253], v[152:153], v[252:253]
	v_pk_add_f32 v[254:255], v[154:155], v[254:255]
	v_pk_add_f32 v[252:253], v[156:157], v[252:253]
	v_pk_add_f32 v[254:255], v[158:159], v[254:255]
	v_cvt_pk_bf16_f32 v2, v144, v145
	v_cvt_pk_bf16_f32 v3, v146, v147
	v_cvt_pk_bf16_f32 v4, v148, v149
	v_pk_add_f32 v[252:253], v[252:253], v[254:255]
	v_cvt_pk_bf16_f32 v5, v150, v151
	v_cvt_pk_bf16_f32 v10, v152, v153
	v_cvt_pk_bf16_f32 v11, v154, v155
	v_pk_add_f32 v[252:253], v[252:253], v[252:253] op_sel:[0,1] op_sel_hi:[1,0]
	v_cvt_pk_bf16_f32 v12, v156, v157
	v_cvt_pk_bf16_f32 v13, v158, v159
	v_cmp_lt_f32_e32 vcc, s52, v252
	v_cmp_gt_f32_e64 s[10:11], s53, v252
	s_and_b64 s[0:1], vcc, s[10:11]
	s_cmp_lg_u64 s[0:1], exec
	s_cbranch_scc1 .Lfzsb2_c1
	v_add_f32_e32 v14, v14, v252
	s_branch .LBB0_1283

.LBB0_1283:
	s_andn2_b64 vcc, exec, s[84:85]
	s_cbranch_vccnz .LBB0_1242
	ds_read_b64_tr_b16 v[160:161], v242 offset:0x2000
	ds_read_b64_tr_b16 v[162:163], v242 offset:0x2100
	ds_read_b64_tr_b16 v[164:165], v242 offset:0x3000
	ds_read_b64_tr_b16 v[166:167], v242 offset:0x3100
	s_waitcnt lgkmcnt(2)
	s_nop 0
	v_mfma_f32_32x32x16_bf16 v[128:143], v[6:9], v[160:163], v[128:143]
	ds_read_b64_tr_b16 v[168:169], v242 offset:0x2200
	v_mfma_f32_32x32x16_bf16 v[96:111], v[2:5], v[160:163], v[96:111]
	ds_read_b64_tr_b16 v[170:171], v242 offset:0x2300
	s_waitcnt lgkmcnt(2)
	v_mfma_f32_32x32x16_bf16 v[128:143], v[208:211], v[164:167], v[128:143]
	ds_read_b64_tr_b16 v[172:173], v242 offset:0x3200
	v_mfma_f32_32x32x16_bf16 v[96:111], v[10:13], v[164:167], v[96:111]
	ds_read_b64_tr_b16 v[174:175], v242 offset:0x3300
	s_waitcnt lgkmcnt(2)
	v_mfma_f32_32x32x16_bf16 v[112:127], v[6:9], v[168:171], v[112:127]
	ds_read_b64_tr_b16 v[160:161], v242 offset:0x2400
	v_mfma_f32_32x32x16_bf16 v[80:95], v[2:5], v[168:171], v[80:95]
	ds_read_b64_tr_b16 v[162:163], v242 offset:0x2500
	s_waitcnt lgkmcnt(2)
	v_mfma_f32_32x32x16_bf16 v[112:127], v[208:211], v[172:175], v[112:127]
	ds_read_b64_tr_b16 v[164:165], v242 offset:0x3400
	v_mfma_f32_32x32x16_bf16 v[80:95], v[10:13], v[172:175], v[80:95]
	ds_read_b64_tr_b16 v[166:167], v242 offset:0x3500
	s_waitcnt lgkmcnt(2)
	v_mfma_f32_32x32x16_bf16 v[64:79], v[6:9], v[160:163], v[64:79]
	ds_read_b64_tr_b16 v[168:169], v242 offset:0x2600
	v_mfma_f32_32x32x16_bf16 v[48:63], v[2:5], v[160:163], v[48:63]
	ds_read_b64_tr_b16 v[170:171], v242 offset:0x2700
	s_waitcnt lgkmcnt(2)
	v_mfma_f32_32x32x16_bf16 v[64:79], v[208:211], v[164:167], v[64:79]
	ds_read_b64_tr_b16 v[172:173], v242 offset:0x3600
	v_mfma_f32_32x32x16_bf16 v[48:63], v[10:13], v[164:167], v[48:63]
	ds_read_b64_tr_b16 v[174:175], v242 offset:0x3700
	s_waitcnt lgkmcnt(2)
	v_mfma_f32_32x32x16_bf16 v[32:47], v[6:9], v[168:171], v[32:47]
	v_mfma_f32_32x32x16_bf16 v[16:31], v[2:5], v[168:171], v[16:31]
	s_waitcnt lgkmcnt(0)
	v_mfma_f32_32x32x16_bf16 v[32:47], v[208:211], v[172:175], v[32:47]
	v_mfma_f32_32x32x16_bf16 v[16:31], v[10:13], v[172:175], v[16:31]
	s_branch .LBB0_1242

.LBB0_1317:
	s_and_b64 vcc, exec, s[34:35]
	s_cbranch_vccz .LBB0_1319
	s_cmp_lg_u32 0, -1
	s_cselect_b32 s0, 0, 0
	s_add_i32 s0, s0, 0xc000
	v_add_u32_e32 v0, s0, v232
	ds_read_b64_tr_b16 v[160:161], v0 offset:0x2000
	ds_read_b64_tr_b16 v[162:163], v0 offset:0x2100
	ds_read_b64_tr_b16 v[164:165], v0 offset:0x3000
	ds_read_b64_tr_b16 v[166:167], v0 offset:0x3100
	s_waitcnt lgkmcnt(2)
	s_nop 0
	v_mfma_f32_32x32x16_bf16 v[128:143], v[6:9], v[160:163], v[128:143]
	ds_read_b64_tr_b16 v[168:169], v0 offset:0x2200
	v_mfma_f32_32x32x16_bf16 v[96:111], v[2:5], v[160:163], v[96:111]
	ds_read_b64_tr_b16 v[170:171], v0 offset:0x2300
	s_waitcnt lgkmcnt(2)
	v_mfma_f32_32x32x16_bf16 v[128:143], v[208:211], v[164:167], v[128:143]
	ds_read_b64_tr_b16 v[172:173], v0 offset:0x3200
	v_mfma_f32_32x32x16_bf16 v[96:111], v[10:13], v[164:167], v[96:111]
	ds_read_b64_tr_b16 v[174:175], v0 offset:0x3300
	s_waitcnt lgkmcnt(2)
	v_mfma_f32_32x32x16_bf16 v[112:127], v[6:9], v[168:171], v[112:127]
	ds_read_b64_tr_b16 v[160:161], v0 offset:0x2400
	v_mfma_f32_32x32x16_bf16 v[80:95], v[2:5], v[168:171], v[80:95]
	ds_read_b64_tr_b16 v[162:163], v0 offset:0x2500
	s_waitcnt lgkmcnt(2)
	v_mfma_f32_32x32x16_bf16 v[112:127], v[208:211], v[172:175], v[112:127]
	ds_read_b64_tr_b16 v[164:165], v0 offset:0x3400
	v_mfma_f32_32x32x16_bf16 v[80:95], v[10:13], v[172:175], v[80:95]
	ds_read_b64_tr_b16 v[166:167], v0 offset:0x3500
	s_waitcnt lgkmcnt(2)
	v_mfma_f32_32x32x16_bf16 v[64:79], v[6:9], v[160:163], v[64:79]
	ds_read_b64_tr_b16 v[168:169], v0 offset:0x2600
	v_mfma_f32_32x32x16_bf16 v[48:63], v[2:5], v[160:163], v[48:63]
	ds_read_b64_tr_b16 v[170:171], v0 offset:0x2700
	s_waitcnt lgkmcnt(2)
	v_mfma_f32_32x32x16_bf16 v[64:79], v[208:211], v[164:167], v[64:79]
	ds_read_b64_tr_b16 v[172:173], v0 offset:0x3600
	v_mfma_f32_32x32x16_bf16 v[48:63], v[10:13], v[164:167], v[48:63]
	ds_read_b64_tr_b16 v[174:175], v0 offset:0x3700
	s_waitcnt lgkmcnt(2)
	v_mfma_f32_32x32x16_bf16 v[32:47], v[6:9], v[168:171], v[32:47]
	v_mfma_f32_32x32x16_bf16 v[16:31], v[2:5], v[168:171], v[16:31]
	s_waitcnt lgkmcnt(0)
	v_mfma_f32_32x32x16_bf16 v[32:47], v[208:211], v[172:175], v[32:47]
	v_mfma_f32_32x32x16_bf16 v[16:31], v[10:13], v[172:175], v[16:31]

.LBB0_1383:
	v_lshrrev_b32_e32 v16, 1, v14
	v_and_b32_e32 v16, 24, v16
	v_and_b32_e32 v15, 15, v14
	v_lshlrev_b32_e32 v17, 1, v16
	v_lshlrev_b32_e32 v14, 2, v14
	v_lshl_or_b32 v150, s0, 6, v15
	v_lshl_or_b32 v15, v15, 6, v17
	s_lshl_b32 s0, s0, 13
	v_and_b32_e32 v14, 32, v14
	v_bitop3_b32 v17, v15, s0, v14 bitop3:0xde
	s_lshl_b32 s0, s1, 5
	s_mov_b64 s[10:11], 0x80
	s_sext_i32_i8 s24, s8
	s_and_b32 s8, s0, 0x60
	s_add_i32 m0, s19, 0x18000
	v_lshl_add_u64 v[6:7], v[6:7], 0, s[10:11]
	s_lshl_b32 s0, s8, 7
	s_waitcnt vmcnt(2)
	s_barrier
	global_load_lds_dwordx4 v[6:7], off
	v_lshl_add_u64 v[4:5], v[4:5], 0, s[10:11]
	s_add_i32 m0, s19, 0x1a000
	s_add_i32 s53, s19, 0x8000
	s_add_i32 s56, s19, 0xa000
	v_bitop3_b32 v151, v15, s0, v14 bitop3:0xde
	global_load_lds_dwordx4 v[4:5], off
	v_lshl_add_u64 v[0:1], v[0:1], 0, s[10:11]
	s_mov_b32 m0, s53
	s_add_u32 s0, s90, 0x40080
	global_load_lds_dwordx4 v[0:1], off
	v_lshl_add_u64 v[0:1], v[2:3], 0, s[10:11]
	s_mov_b32 m0, s56
	s_addc_u32 s1, s91, 0
	global_load_lds_dwordx4 v[0:1], off
	s_add_i32 m0, s19, 0x1c000
	s_nop 0
	global_load_lds_dwordx4 v130, s[0:1]
	s_add_i32 m0, s19, 0x1e000
	s_cmpk_lt_u32 s3, 0x100
	global_load_lds_dwordx4 v134, s[0:1]
	v_lshlrev_b32_e32 v0, 14, v8
	v_and_b32_e32 v0, 0xffff8000, v0
	v_lshl_add_u32 v0, v9, 11, v0
	v_and_b32_e32 v1, 1, v8
	v_lshl_or_b32 v0, v1, 6, v0
	v_lshl_add_u32 v136, v10, 1, v0
	v_lshlrev_b32_e32 v0, 14, v11
	v_and_b32_e32 v0, 0xffff8000, v0
	s_waitcnt vmcnt(6)
	v_lshl_add_u32 v0, v12, 11, v0
	v_and_b32_e32 v1, 1, v11
	s_cselect_b64 s[12:13], -1, 0
	v_lshl_or_b32 v0, v1, 6, v0
	s_add_i32 s57, 0, 0x10000
	s_add_i32 s58, 0, 0x14000
	v_or_b32_e32 v152, s8, v16
	v_mov_b32_e32 v137, v131
	v_lshl_add_u32 v138, v13, 1, v0
	v_mov_b32_e32 v139, v131
	v_mov_b64_e32 v[140:141], 0x200
	v_mov_b64_e32 v[142:143], 0x1ff
	v_add_u32_e32 v153, s57, v151
	v_add_u32_e32 v154, s58, v151
	v_add_u32_e32 v155, 0, v17
	s_movk_i32 s59, 0x5c00
	s_mov_b64 s[14:15], 0x3c00
	s_movk_i32 s68, 0x3000
	s_barrier
	s_branch .LBB0_1386

.LBB0_1393:
	ds_read_b128 v[144:147], v153
	ds_read_b128 v[156:159], v153 offset:1024
	ds_read_b128 v[160:163], v153 offset:2048
	ds_read_b128 v[164:167], v153 offset:3072
	ds_read_b128 v[168:171], v154
	ds_read_b128 v[172:175], v154 offset:1024
	ds_read_b128 v[176:179], v154 offset:2048
	ds_read_b128 v[180:183], v154 offset:3072
	s_add_u32 s3, s88, 0xfffc0080
	s_addc_u32 s37, s89, -1
	s_cmp_eq_u32 s36, 12
	s_cselect_b32 s91, s0, s37
	s_cselect_b32 s90, s1, s3
	s_cselect_b32 s81, s17, s35
	s_cselect_b32 s80, s27, s33
	s_add_i32 m0, s19, 0xc000
	ds_read_b128 v[184:187], v155
	ds_read_b128 v[188:191], v155 offset:1024
	ds_read_b128 v[192:195], v155 offset:2048
	ds_read_b128 v[196:199], v155 offset:3072
	ds_read_b128 v[200:203], v155 offset:4096
	ds_read_b128 v[204:207], v155 offset:5120
	ds_read_b128 v[208:211], v155 offset:6144
	ds_read_b128 v[212:215], v155 offset:7168
	global_load_lds_dwordx4 v136, s[88:89]
	s_add_i32 m0, s19, 0xe000
	s_nop 0
	global_load_lds_dwordx4 v138, s[88:89]
	s_waitcnt vmcnt(8)
	s_waitcnt lgkmcnt(0)
	s_barrier
	s_setprio 1
	s_waitcnt lgkmcnt(0)
	v_mfma_f32_16x16x32_bf16 v[124:127], v[144:147], v[184:187], v[124:127]
	v_mfma_f32_16x16x32_bf16 v[120:123], v[160:163], v[184:187], v[120:123]
	v_mfma_f32_16x16x32_bf16 v[108:111], v[144:147], v[192:195], v[108:111]
	v_mfma_f32_16x16x32_bf16 v[104:107], v[160:163], v[192:195], v[104:107]
	v_mfma_f32_16x16x32_bf16 v[92:95], v[144:147], v[200:203], v[92:95]
	v_mfma_f32_16x16x32_bf16 v[88:91], v[160:163], v[200:203], v[88:91]
	v_mfma_f32_16x16x32_bf16 v[76:79], v[144:147], v[208:211], v[76:79]
	v_mfma_f32_16x16x32_bf16 v[72:75], v[160:163], v[208:211], v[72:75]
	v_mfma_f32_16x16x32_bf16 v[124:127], v[156:159], v[188:191], v[124:127]
	v_mfma_f32_16x16x32_bf16 v[120:123], v[164:167], v[188:191], v[120:123]
	v_mfma_f32_16x16x32_bf16 v[108:111], v[156:159], v[196:199], v[108:111]
	v_mfma_f32_16x16x32_bf16 v[104:107], v[164:167], v[196:199], v[104:107]
	v_mfma_f32_16x16x32_bf16 v[92:95], v[156:159], v[204:207], v[92:95]
	v_mfma_f32_16x16x32_bf16 v[88:91], v[164:167], v[204:207], v[88:91]
	v_mfma_f32_16x16x32_bf16 v[76:79], v[156:159], v[212:215], v[76:79]
	v_mfma_f32_16x16x32_bf16 v[72:75], v[164:167], v[212:215], v[72:75]
	s_setprio 0
	s_setprio 1
	v_mfma_f32_16x16x32_bf16 v[116:119], v[168:171], v[184:187], v[116:119]
	v_mfma_f32_16x16x32_bf16 v[112:115], v[176:179], v[184:187], v[112:115]
	v_mfma_f32_16x16x32_bf16 v[100:103], v[168:171], v[192:195], v[100:103]
	v_mfma_f32_16x16x32_bf16 v[96:99], v[176:179], v[192:195], v[96:99]
	v_mfma_f32_16x16x32_bf16 v[84:87], v[168:171], v[200:203], v[84:87]
	v_mfma_f32_16x16x32_bf16 v[80:83], v[176:179], v[200:203], v[80:83]
	v_mfma_f32_16x16x32_bf16 v[68:71], v[168:171], v[208:211], v[68:71]
	v_mfma_f32_16x16x32_bf16 v[64:67], v[176:179], v[208:211], v[64:67]
	v_mfma_f32_16x16x32_bf16 v[116:119], v[172:175], v[188:191], v[116:119]
	v_mfma_f32_16x16x32_bf16 v[112:115], v[180:183], v[188:191], v[112:115]
	v_mfma_f32_16x16x32_bf16 v[100:103], v[172:175], v[196:199], v[100:103]
	v_mfma_f32_16x16x32_bf16 v[96:99], v[180:183], v[196:199], v[96:99]
	v_mfma_f32_16x16x32_bf16 v[84:87], v[172:175], v[204:207], v[84:87]
	v_mfma_f32_16x16x32_bf16 v[80:83], v[180:183], v[204:207], v[80:83]
	v_mfma_f32_16x16x32_bf16 v[68:71], v[172:175], v[212:215], v[68:71]
	v_mfma_f32_16x16x32_bf16 v[64:67], v[180:183], v[212:215], v[64:67]
	s_setprio 0
	s_barrier
	s_add_i32 s3, s57, s18
	v_lshl_add_u64 v[148:149], s[80:81], 0, v[130:131]
	s_mov_b32 m0, s3
	ds_read_b128 v[184:187], v155 offset:16384
	ds_read_b128 v[188:191], v155 offset:17408
	ds_read_b128 v[192:195], v155 offset:18432
	ds_read_b128 v[196:199], v155 offset:19456
	ds_read_b128 v[200:203], v155 offset:20480
	ds_read_b128 v[204:207], v155 offset:21504
	ds_read_b128 v[208:211], v155 offset:22528
	ds_read_b128 v[212:215], v155 offset:23552
	global_load_lds_dwordx4 v[148:149], off
	s_add_i32 m0, s3, 0x2000
	s_add_u32 s42, s80, 0x40000
	v_lshl_add_u64 v[216:217], s[80:81], 0, v[134:135]
	s_addc_u32 s43, s81, 0
	s_add_i32 s3, s58, s18
	global_load_lds_dwordx4 v[216:217], off
	s_mov_b32 m0, s3
	v_lshl_add_u64 v[220:221], s[90:91], 0, v[132:133]
	global_load_lds_dwordx4 v130, s[42:43]
	s_add_i32 m0, s3, 0x2000
	s_nop 0
	global_load_lds_dwordx4 v134, s[42:43]
	v_lshl_add_u64 v[218:219], s[90:91], 0, v[128:129]
	s_mov_b32 m0, s19
	s_nop 0
	global_load_lds_dwordx4 v[218:219], off
	s_mov_b32 m0, s25
	s_nop 0
	global_load_lds_dwordx4 v[220:221], off
	s_waitcnt vmcnt(8)
	s_waitcnt lgkmcnt(0)
	s_barrier
	s_setprio 1
	s_waitcnt lgkmcnt(0)
	v_mfma_f32_16x16x32_bf16 v[60:63], v[144:147], v[184:187], v[60:63]
	v_mfma_f32_16x16x32_bf16 v[56:59], v[160:163], v[184:187], v[56:59]
	v_mfma_f32_16x16x32_bf16 v[44:47], v[144:147], v[192:195], v[44:47]
	v_mfma_f32_16x16x32_bf16 v[40:43], v[160:163], v[192:195], v[40:43]
	v_mfma_f32_16x16x32_bf16 v[28:31], v[144:147], v[200:203], v[28:31]
	v_mfma_f32_16x16x32_bf16 v[24:27], v[160:163], v[200:203], v[24:27]
	v_mfma_f32_16x16x32_bf16 v[12:15], v[144:147], v[208:211], v[12:15]
	v_mfma_f32_16x16x32_bf16 v[8:11], v[160:163], v[208:211], v[8:11]
	v_mfma_f32_16x16x32_bf16 v[60:63], v[156:159], v[188:191], v[60:63]
	v_mfma_f32_16x16x32_bf16 v[56:59], v[164:167], v[188:191], v[56:59]
	v_mfma_f32_16x16x32_bf16 v[44:47], v[156:159], v[196:199], v[44:47]
	v_mfma_f32_16x16x32_bf16 v[40:43], v[164:167], v[196:199], v[40:43]
	v_mfma_f32_16x16x32_bf16 v[28:31], v[156:159], v[204:207], v[28:31]
	v_mfma_f32_16x16x32_bf16 v[24:27], v[164:167], v[204:207], v[24:27]
	v_mfma_f32_16x16x32_bf16 v[12:15], v[156:159], v[212:215], v[12:15]
	v_mfma_f32_16x16x32_bf16 v[8:11], v[164:167], v[212:215], v[8:11]
	s_setprio 0
	s_setprio 1
	v_mfma_f32_16x16x32_bf16 v[52:55], v[168:171], v[184:187], v[52:55]
	v_mfma_f32_16x16x32_bf16 v[48:51], v[176:179], v[184:187], v[48:51]
	v_mfma_f32_16x16x32_bf16 v[36:39], v[168:171], v[192:195], v[36:39]
	v_mfma_f32_16x16x32_bf16 v[32:35], v[176:179], v[192:195], v[32:35]
	v_mfma_f32_16x16x32_bf16 v[20:23], v[168:171], v[200:203], v[20:23]
	v_mfma_f32_16x16x32_bf16 v[16:19], v[176:179], v[200:203], v[16:19]
	v_mfma_f32_16x16x32_bf16 v[4:7], v[168:171], v[208:211], v[4:7]
	v_mfma_f32_16x16x32_bf16 v[0:3], v[176:179], v[208:211], v[0:3]
	v_mfma_f32_16x16x32_bf16 v[52:55], v[172:175], v[188:191], v[52:55]
	v_mfma_f32_16x16x32_bf16 v[48:51], v[180:183], v[188:191], v[48:51]
	v_mfma_f32_16x16x32_bf16 v[36:39], v[172:175], v[196:199], v[36:39]
	v_mfma_f32_16x16x32_bf16 v[32:35], v[180:183], v[196:199], v[32:35]
	v_mfma_f32_16x16x32_bf16 v[20:23], v[172:175], v[204:207], v[20:23]
	v_mfma_f32_16x16x32_bf16 v[16:19], v[180:183], v[204:207], v[16:19]
	v_mfma_f32_16x16x32_bf16 v[4:7], v[172:175], v[212:215], v[4:7]
	v_mfma_f32_16x16x32_bf16 v[0:3], v[180:183], v[212:215], v[0:3]
	s_setprio 0
	s_barrier
	s_add_i32 s3, 0, 0x18000
	s_add_i32 s37, 0, 0x1c000
	v_add_u32_e32 v164, s3, v151
	v_add_u32_e32 v180, s37, v151
	ds_read_b128 v[144:147], v164
	ds_read_b128 v[156:159], v164 offset:1024
	ds_read_b128 v[160:163], v164 offset:2048
	ds_read_b128 v[164:167], v164 offset:3072
	ds_read_b128 v[168:171], v180
	ds_read_b128 v[172:175], v180 offset:1024
	ds_read_b128 v[176:179], v180 offset:2048
	ds_read_b128 v[180:183], v180 offset:3072
	s_add_u32 s42, s90, 0x40000
	s_addc_u32 s43, s91, 0
	s_mov_b32 m0, s30
	ds_read_b128 v[184:187], v155 offset:32768
	ds_read_b128 v[188:191], v155 offset:33792
	ds_read_b128 v[192:195], v155 offset:34816
	ds_read_b128 v[196:199], v155 offset:35840
	ds_read_b128 v[200:203], v155 offset:36864
	ds_read_b128 v[204:207], v155 offset:37888
	ds_read_b128 v[208:211], v155 offset:38912
	ds_read_b128 v[212:215], v155 offset:39936
	global_load_lds_dwordx4 v128, s[42:43]
	v_lshl_add_u64 v[222:223], s[42:43], 0, v[132:133]
	s_mov_b32 m0, s31
	s_nop 0
	global_load_lds_dwordx4 v[222:223], off
	s_waitcnt vmcnt(8)
	s_waitcnt lgkmcnt(0)
	s_barrier
	s_setprio 1
	s_waitcnt lgkmcnt(0)
	v_mfma_f32_16x16x32_bf16 v[124:127], v[144:147], v[184:187], v[124:127]
	v_mfma_f32_16x16x32_bf16 v[120:123], v[160:163], v[184:187], v[120:123]
	v_mfma_f32_16x16x32_bf16 v[108:111], v[144:147], v[192:195], v[108:111]
	v_mfma_f32_16x16x32_bf16 v[104:107], v[160:163], v[192:195], v[104:107]
	v_mfma_f32_16x16x32_bf16 v[92:95], v[144:147], v[200:203], v[92:95]
	v_mfma_f32_16x16x32_bf16 v[88:91], v[160:163], v[200:203], v[88:91]
	v_mfma_f32_16x16x32_bf16 v[76:79], v[144:147], v[208:211], v[76:79]
	v_mfma_f32_16x16x32_bf16 v[72:75], v[160:163], v[208:211], v[72:75]
	v_mfma_f32_16x16x32_bf16 v[124:127], v[156:159], v[188:191], v[124:127]
	v_mfma_f32_16x16x32_bf16 v[120:123], v[164:167], v[188:191], v[120:123]
	v_mfma_f32_16x16x32_bf16 v[108:111], v[156:159], v[196:199], v[108:111]
	v_mfma_f32_16x16x32_bf16 v[104:107], v[164:167], v[196:199], v[104:107]
	v_mfma_f32_16x16x32_bf16 v[92:95], v[156:159], v[204:207], v[92:95]
	v_mfma_f32_16x16x32_bf16 v[88:91], v[164:167], v[204:207], v[88:91]
	v_mfma_f32_16x16x32_bf16 v[76:79], v[156:159], v[212:215], v[76:79]
	v_mfma_f32_16x16x32_bf16 v[72:75], v[164:167], v[212:215], v[72:75]
	s_setprio 0
	s_setprio 1
	v_mfma_f32_16x16x32_bf16 v[116:119], v[168:171], v[184:187], v[116:119]
	v_mfma_f32_16x16x32_bf16 v[112:115], v[176:179], v[184:187], v[112:115]
	v_mfma_f32_16x16x32_bf16 v[100:103], v[168:171], v[192:195], v[100:103]
	v_mfma_f32_16x16x32_bf16 v[96:99], v[176:179], v[192:195], v[96:99]
	v_mfma_f32_16x16x32_bf16 v[84:87], v[168:171], v[200:203], v[84:87]
	v_mfma_f32_16x16x32_bf16 v[80:83], v[176:179], v[200:203], v[80:83]
	v_mfma_f32_16x16x32_bf16 v[68:71], v[168:171], v[208:211], v[68:71]
	v_mfma_f32_16x16x32_bf16 v[64:67], v[176:179], v[208:211], v[64:67]
	v_mfma_f32_16x16x32_bf16 v[116:119], v[172:175], v[188:191], v[116:119]
	v_mfma_f32_16x16x32_bf16 v[112:115], v[180:183], v[188:191], v[112:115]
	v_mfma_f32_16x16x32_bf16 v[100:103], v[172:175], v[196:199], v[100:103]
	v_mfma_f32_16x16x32_bf16 v[96:99], v[180:183], v[196:199], v[96:99]
	v_mfma_f32_16x16x32_bf16 v[84:87], v[172:175], v[204:207], v[84:87]
	v_mfma_f32_16x16x32_bf16 v[80:83], v[180:183], v[204:207], v[80:83]
	v_mfma_f32_16x16x32_bf16 v[68:71], v[172:175], v[212:215], v[68:71]
	v_mfma_f32_16x16x32_bf16 v[64:67], v[180:183], v[212:215], v[64:67]
	s_setprio 0
	s_barrier
	s_add_i32 s3, s3, s18
	v_lshl_add_u64 v[148:149], v[148:149], 0, s[10:11]
	s_mov_b32 m0, s3
	ds_read_b128 v[184:187], v155 offset:49152
	ds_read_b128 v[188:191], v155 offset:50176
	ds_read_b128 v[192:195], v155 offset:51200
	ds_read_b128 v[196:199], v155 offset:52224
	ds_read_b128 v[200:203], v155 offset:53248
	ds_read_b128 v[204:207], v155 offset:54272
	ds_read_b128 v[208:211], v155 offset:55296
	ds_read_b128 v[212:215], v155 offset:56320
	global_load_lds_dwordx4 v[148:149], off
	s_add_i32 m0, s3, 0x2000
	s_add_u32 s42, s80, 0x40080
	v_lshl_add_u64 v[148:149], v[216:217], 0, s[10:11]
	s_addc_u32 s43, s81, 0
	s_add_i32 s3, s37, s18
	global_load_lds_dwordx4 v[148:149], off
	s_mov_b32 m0, s3
	s_nop 0
	global_load_lds_dwordx4 v130, s[42:43]
	s_add_i32 m0, s3, 0x2000
	s_nop 0
	global_load_lds_dwordx4 v134, s[42:43]
	v_lshl_add_u64 v[148:149], v[218:219], 0, s[10:11]
	s_mov_b32 m0, s53
	s_nop 0
	global_load_lds_dwordx4 v[148:149], off
	v_lshl_add_u64 v[148:149], v[220:221], 0, s[10:11]
	s_mov_b32 m0, s56
	s_nop 0
	global_load_lds_dwordx4 v[148:149], off
	s_waitcnt vmcnt(8)
	s_waitcnt lgkmcnt(0)
	s_barrier
	s_setprio 1
	s_waitcnt lgkmcnt(0)
	v_mfma_f32_16x16x32_bf16 v[60:63], v[144:147], v[184:187], v[60:63]
	v_mfma_f32_16x16x32_bf16 v[56:59], v[160:163], v[184:187], v[56:59]
	v_mfma_f32_16x16x32_bf16 v[44:47], v[144:147], v[192:195], v[44:47]
	v_mfma_f32_16x16x32_bf16 v[40:43], v[160:163], v[192:195], v[40:43]
	v_mfma_f32_16x16x32_bf16 v[28:31], v[144:147], v[200:203], v[28:31]
	v_mfma_f32_16x16x32_bf16 v[24:27], v[160:163], v[200:203], v[24:27]
	v_mfma_f32_16x16x32_bf16 v[12:15], v[144:147], v[208:211], v[12:15]
	v_mfma_f32_16x16x32_bf16 v[8:11], v[160:163], v[208:211], v[8:11]
	v_mfma_f32_16x16x32_bf16 v[60:63], v[156:159], v[188:191], v[60:63]
	v_mfma_f32_16x16x32_bf16 v[56:59], v[164:167], v[188:191], v[56:59]
	v_mfma_f32_16x16x32_bf16 v[44:47], v[156:159], v[196:199], v[44:47]
	v_mfma_f32_16x16x32_bf16 v[40:43], v[164:167], v[196:199], v[40:43]
	v_mfma_f32_16x16x32_bf16 v[28:31], v[156:159], v[204:207], v[28:31]
	v_mfma_f32_16x16x32_bf16 v[24:27], v[164:167], v[204:207], v[24:27]
	v_mfma_f32_16x16x32_bf16 v[12:15], v[156:159], v[212:215], v[12:15]
	v_mfma_f32_16x16x32_bf16 v[8:11], v[164:167], v[212:215], v[8:11]
	s_setprio 0
	s_setprio 1
	v_mfma_f32_16x16x32_bf16 v[52:55], v[168:171], v[184:187], v[52:55]
	v_mfma_f32_16x16x32_bf16 v[48:51], v[176:179], v[184:187], v[48:51]
	v_mfma_f32_16x16x32_bf16 v[36:39], v[168:171], v[192:195], v[36:39]
	v_mfma_f32_16x16x32_bf16 v[32:35], v[176:179], v[192:195], v[32:35]
	v_mfma_f32_16x16x32_bf16 v[20:23], v[168:171], v[200:203], v[20:23]
	v_mfma_f32_16x16x32_bf16 v[16:19], v[176:179], v[200:203], v[16:19]
	v_mfma_f32_16x16x32_bf16 v[4:7], v[168:171], v[208:211], v[4:7]
	v_mfma_f32_16x16x32_bf16 v[0:3], v[176:179], v[208:211], v[0:3]
	v_mfma_f32_16x16x32_bf16 v[52:55], v[172:175], v[188:191], v[52:55]
	v_mfma_f32_16x16x32_bf16 v[48:51], v[180:183], v[188:191], v[48:51]
	v_mfma_f32_16x16x32_bf16 v[36:39], v[172:175], v[196:199], v[36:39]
	v_mfma_f32_16x16x32_bf16 v[32:35], v[180:183], v[196:199], v[32:35]
	v_mfma_f32_16x16x32_bf16 v[20:23], v[172:175], v[204:207], v[20:23]
	v_mfma_f32_16x16x32_bf16 v[16:19], v[180:183], v[204:207], v[16:19]
	v_mfma_f32_16x16x32_bf16 v[4:7], v[172:175], v[212:215], v[4:7]
	v_mfma_f32_16x16x32_bf16 v[0:3], v[180:183], v[212:215], v[0:3]
	s_setprio 0
	s_barrier
	s_add_i32 s36, s36, 2
	s_add_u32 s88, s88, 0x100
	s_addc_u32 s89, s89, 0
	s_add_u32 s33, s33, 0x100
	s_addc_u32 s35, s35, 0
	s_cmp_gt_u32 s36, 13
	s_cbranch_scc0 .LBB0_1393
	s_and_b64 vcc, exec, s[12:13]
	s_cbranch_vccz .LBB0_1396
	s_barrier

.LBB0_1407:
	v_lshrrev_b32_e32 v16, 1, v14
	v_and_b32_e32 v16, 24, v16
	v_and_b32_e32 v15, 15, v14
	v_lshlrev_b32_e32 v17, 1, v16
	v_lshlrev_b32_e32 v14, 2, v14
	v_lshl_or_b32 v154, s0, 6, v15
	v_lshl_or_b32 v15, v15, 6, v17
	s_lshl_b32 s0, s0, 13
	v_and_b32_e32 v14, 32, v14
	v_bitop3_b32 v17, v15, s0, v14 bitop3:0xde
	s_lshl_b32 s0, s1, 5
	s_mov_b64 s[12:13], 0x80
	s_sext_i32_i8 s7, s8
	s_and_b32 s8, s0, 0x60
	s_add_i32 m0, s19, 0x18000
	v_lshl_add_u64 v[6:7], v[6:7], 0, s[12:13]
	s_lshl_b32 s0, s8, 7
	s_waitcnt vmcnt(2)
	s_barrier
	global_load_lds_dwordx4 v[6:7], off
	v_lshl_add_u64 v[4:5], v[4:5], 0, s[12:13]
	s_add_i32 m0, s19, 0x1a000
	s_add_i32 s58, s19, 0x8000
	s_add_i32 s59, s19, 0xa000
	v_bitop3_b32 v155, v15, s0, v14 bitop3:0xde
	global_load_lds_dwordx4 v[4:5], off
	v_lshl_add_u64 v[2:3], v[2:3], 0, s[12:13]
	s_mov_b32 m0, s58
	s_add_u32 s0, s90, 0x20080
	global_load_lds_dwordx4 v[2:3], off
	v_lshl_add_u64 v[0:1], v[0:1], 0, s[12:13]
	s_mov_b32 m0, s59
	s_addc_u32 s1, s91, 0
	global_load_lds_dwordx4 v[0:1], off
	s_add_i32 m0, s19, 0x1c000
	s_nop 0
	global_load_lds_dwordx4 v130, s[0:1]
	s_add_i32 m0, s19, 0x1e000
	s_cmpk_lt_u32 s3, 0x100
	global_load_lds_dwordx4 v134, s[0:1]
	v_lshlrev_b32_e32 v0, 13, v8
	v_and_b32_e32 v0, 0xffffc000, v0
	v_lshl_add_u32 v0, v9, 10, v0
	v_and_b32_e32 v1, 1, v8
	v_lshl_or_b32 v0, v1, 6, v0
	v_lshl_add_u32 v136, v10, 1, v0
	v_lshlrev_b32_e32 v0, 13, v11
	v_and_b32_e32 v0, 0xffffc000, v0
	s_waitcnt vmcnt(6)
	v_lshl_add_u32 v0, v12, 10, v0
	v_and_b32_e32 v1, 1, v11
	s_cselect_b64 s[14:15], -1, 0
	v_lshl_or_b32 v0, v1, 6, v0
	s_add_i32 s78, 0, 0x10000
	s_add_i32 s79, 0, 0x14000
	v_or_b32_e32 v156, s8, v16
	v_mov_b32_e32 v137, v131
	v_lshl_add_u32 v138, v13, 1, v0
	v_mov_b32_e32 v139, v131
	v_mov_b64_e32 v[140:141], 0x200
	v_mov_b64_e32 v[142:143], 0x1ff
	v_add_u32_e32 v157, s78, v155
	v_add_u32_e32 v158, s79, v155
	v_add_u32_e32 v159, 0, v17
	s_movk_i32 s92, 0x5c00
	s_mov_b64 s[16:17], 0x4c00
	s_barrier
	s_branch .LBB0_1410

.LBB0_1417:
	ds_read_b128 v[144:147], v157
	ds_read_b128 v[148:151], v157 offset:1024
	ds_read_b128 v[160:163], v157 offset:2048
	ds_read_b128 v[164:167], v157 offset:3072
	ds_read_b128 v[168:171], v158
	ds_read_b128 v[172:175], v158 offset:1024
	ds_read_b128 v[176:179], v158 offset:2048
	ds_read_b128 v[180:183], v158 offset:3072
	s_add_u32 s3, s34, 0xfffe0080
	s_addc_u32 s42, s35, -1
	s_cmp_eq_u32 s37, 4
	s_cselect_b32 s91, s0, s42
	s_cselect_b32 s90, s1, s3
	s_cselect_b32 s81, s24, s36
	s_cselect_b32 s80, s27, s33
	s_add_i32 m0, s19, 0xc000
	ds_read_b128 v[184:187], v159
	ds_read_b128 v[188:191], v159 offset:1024
	ds_read_b128 v[192:195], v159 offset:2048
	ds_read_b128 v[196:199], v159 offset:3072
	ds_read_b128 v[200:203], v159 offset:4096
	ds_read_b128 v[204:207], v159 offset:5120
	ds_read_b128 v[208:211], v159 offset:6144
	ds_read_b128 v[212:215], v159 offset:7168
	global_load_lds_dwordx4 v136, s[34:35]
	s_add_i32 m0, s19, 0xe000
	s_nop 0
	global_load_lds_dwordx4 v138, s[34:35]
	s_waitcnt vmcnt(8)
	s_waitcnt lgkmcnt(0)
	s_barrier
	s_setprio 1
	s_waitcnt lgkmcnt(0)
	v_mfma_f32_16x16x32_bf16 v[124:127], v[144:147], v[184:187], v[124:127]
	v_mfma_f32_16x16x32_bf16 v[120:123], v[160:163], v[184:187], v[120:123]
	v_mfma_f32_16x16x32_bf16 v[108:111], v[144:147], v[192:195], v[108:111]
	v_mfma_f32_16x16x32_bf16 v[104:107], v[160:163], v[192:195], v[104:107]
	v_mfma_f32_16x16x32_bf16 v[92:95], v[144:147], v[200:203], v[92:95]
	v_mfma_f32_16x16x32_bf16 v[88:91], v[160:163], v[200:203], v[88:91]
	v_mfma_f32_16x16x32_bf16 v[76:79], v[144:147], v[208:211], v[76:79]
	v_mfma_f32_16x16x32_bf16 v[72:75], v[160:163], v[208:211], v[72:75]
	v_mfma_f32_16x16x32_bf16 v[124:127], v[148:151], v[188:191], v[124:127]
	v_mfma_f32_16x16x32_bf16 v[120:123], v[164:167], v[188:191], v[120:123]
	v_mfma_f32_16x16x32_bf16 v[108:111], v[148:151], v[196:199], v[108:111]
	v_mfma_f32_16x16x32_bf16 v[104:107], v[164:167], v[196:199], v[104:107]
	v_mfma_f32_16x16x32_bf16 v[92:95], v[148:151], v[204:207], v[92:95]
	v_mfma_f32_16x16x32_bf16 v[88:91], v[164:167], v[204:207], v[88:91]
	v_mfma_f32_16x16x32_bf16 v[76:79], v[148:151], v[212:215], v[76:79]
	v_mfma_f32_16x16x32_bf16 v[72:75], v[164:167], v[212:215], v[72:75]
	s_setprio 0
	s_setprio 1
	v_mfma_f32_16x16x32_bf16 v[116:119], v[168:171], v[184:187], v[116:119]
	v_mfma_f32_16x16x32_bf16 v[112:115], v[176:179], v[184:187], v[112:115]
	v_mfma_f32_16x16x32_bf16 v[100:103], v[168:171], v[192:195], v[100:103]
	v_mfma_f32_16x16x32_bf16 v[96:99], v[176:179], v[192:195], v[96:99]
	v_mfma_f32_16x16x32_bf16 v[84:87], v[168:171], v[200:203], v[84:87]
	v_mfma_f32_16x16x32_bf16 v[80:83], v[176:179], v[200:203], v[80:83]
	v_mfma_f32_16x16x32_bf16 v[68:71], v[168:171], v[208:211], v[68:71]
	v_mfma_f32_16x16x32_bf16 v[64:67], v[176:179], v[208:211], v[64:67]
	v_mfma_f32_16x16x32_bf16 v[116:119], v[172:175], v[188:191], v[116:119]
	v_mfma_f32_16x16x32_bf16 v[112:115], v[180:183], v[188:191], v[112:115]
	v_mfma_f32_16x16x32_bf16 v[100:103], v[172:175], v[196:199], v[100:103]
	v_mfma_f32_16x16x32_bf16 v[96:99], v[180:183], v[196:199], v[96:99]
	v_mfma_f32_16x16x32_bf16 v[84:87], v[172:175], v[204:207], v[84:87]
	v_mfma_f32_16x16x32_bf16 v[80:83], v[180:183], v[204:207], v[80:83]
	v_mfma_f32_16x16x32_bf16 v[68:71], v[172:175], v[212:215], v[68:71]
	v_mfma_f32_16x16x32_bf16 v[64:67], v[180:183], v[212:215], v[64:67]
	s_setprio 0
	s_barrier
	s_add_i32 s3, s78, s18
	v_lshl_add_u64 v[152:153], s[80:81], 0, v[130:131]
	s_mov_b32 m0, s3
	ds_read_b128 v[184:187], v159 offset:16384
	ds_read_b128 v[188:191], v159 offset:17408
	ds_read_b128 v[192:195], v159 offset:18432
	ds_read_b128 v[196:199], v159 offset:19456
	ds_read_b128 v[200:203], v159 offset:20480
	ds_read_b128 v[204:207], v159 offset:21504
	ds_read_b128 v[208:211], v159 offset:22528
	ds_read_b128 v[212:215], v159 offset:23552
	global_load_lds_dwordx4 v[152:153], off
	s_add_i32 m0, s3, 0x2000
	s_add_u32 s42, s80, 0x20000
	v_lshl_add_u64 v[216:217], s[80:81], 0, v[134:135]
	s_addc_u32 s43, s81, 0
	s_add_i32 s3, s79, s18
	global_load_lds_dwordx4 v[216:217], off
	s_mov_b32 m0, s3
	v_lshl_add_u64 v[220:221], s[90:91], 0, v[132:133]
	global_load_lds_dwordx4 v130, s[42:43]
	s_add_i32 m0, s3, 0x2000
	s_nop 0
	global_load_lds_dwordx4 v134, s[42:43]
	v_lshl_add_u64 v[218:219], s[90:91], 0, v[128:129]
	s_mov_b32 m0, s19
	s_nop 0
	global_load_lds_dwordx4 v[218:219], off
	s_mov_b32 m0, s25
	s_nop 0
	global_load_lds_dwordx4 v[220:221], off
	s_waitcnt vmcnt(8)
	s_waitcnt lgkmcnt(0)
	s_barrier
	s_setprio 1
	s_waitcnt lgkmcnt(0)
	v_mfma_f32_16x16x32_bf16 v[60:63], v[144:147], v[184:187], v[60:63]
	v_mfma_f32_16x16x32_bf16 v[56:59], v[160:163], v[184:187], v[56:59]
	v_mfma_f32_16x16x32_bf16 v[44:47], v[144:147], v[192:195], v[44:47]
	v_mfma_f32_16x16x32_bf16 v[40:43], v[160:163], v[192:195], v[40:43]
	v_mfma_f32_16x16x32_bf16 v[28:31], v[144:147], v[200:203], v[28:31]
	v_mfma_f32_16x16x32_bf16 v[24:27], v[160:163], v[200:203], v[24:27]
	v_mfma_f32_16x16x32_bf16 v[12:15], v[144:147], v[208:211], v[12:15]
	v_mfma_f32_16x16x32_bf16 v[8:11], v[160:163], v[208:211], v[8:11]
	v_mfma_f32_16x16x32_bf16 v[60:63], v[148:151], v[188:191], v[60:63]
	v_mfma_f32_16x16x32_bf16 v[56:59], v[164:167], v[188:191], v[56:59]
	v_mfma_f32_16x16x32_bf16 v[44:47], v[148:151], v[196:199], v[44:47]
	v_mfma_f32_16x16x32_bf16 v[40:43], v[164:167], v[196:199], v[40:43]
	v_mfma_f32_16x16x32_bf16 v[28:31], v[148:151], v[204:207], v[28:31]
	v_mfma_f32_16x16x32_bf16 v[24:27], v[164:167], v[204:207], v[24:27]
	v_mfma_f32_16x16x32_bf16 v[12:15], v[148:151], v[212:215], v[12:15]
	v_mfma_f32_16x16x32_bf16 v[8:11], v[164:167], v[212:215], v[8:11]
	s_setprio 0
	s_setprio 1
	v_mfma_f32_16x16x32_bf16 v[52:55], v[168:171], v[184:187], v[52:55]
	v_mfma_f32_16x16x32_bf16 v[48:51], v[176:179], v[184:187], v[48:51]
	v_mfma_f32_16x16x32_bf16 v[36:39], v[168:171], v[192:195], v[36:39]
	v_mfma_f32_16x16x32_bf16 v[32:35], v[176:179], v[192:195], v[32:35]
	v_mfma_f32_16x16x32_bf16 v[20:23], v[168:171], v[200:203], v[20:23]
	v_mfma_f32_16x16x32_bf16 v[16:19], v[176:179], v[200:203], v[16:19]
	v_mfma_f32_16x16x32_bf16 v[4:7], v[168:171], v[208:211], v[4:7]
	v_mfma_f32_16x16x32_bf16 v[0:3], v[176:179], v[208:211], v[0:3]
	v_mfma_f32_16x16x32_bf16 v[52:55], v[172:175], v[188:191], v[52:55]
	v_mfma_f32_16x16x32_bf16 v[48:51], v[180:183], v[188:191], v[48:51]
	v_mfma_f32_16x16x32_bf16 v[36:39], v[172:175], v[196:199], v[36:39]
	v_mfma_f32_16x16x32_bf16 v[32:35], v[180:183], v[196:199], v[32:35]
	v_mfma_f32_16x16x32_bf16 v[20:23], v[172:175], v[204:207], v[20:23]
	v_mfma_f32_16x16x32_bf16 v[16:19], v[180:183], v[204:207], v[16:19]
	v_mfma_f32_16x16x32_bf16 v[4:7], v[172:175], v[212:215], v[4:7]
	v_mfma_f32_16x16x32_bf16 v[0:3], v[180:183], v[212:215], v[0:3]
	s_setprio 0
	s_barrier
	s_add_i32 s3, 0, 0x18000
	s_add_i32 s44, 0, 0x1c000
	v_add_u32_e32 v164, s3, v155
	v_add_u32_e32 v180, s44, v155
	ds_read_b128 v[144:147], v164
	ds_read_b128 v[148:151], v164 offset:1024
	ds_read_b128 v[160:163], v164 offset:2048
	ds_read_b128 v[164:167], v164 offset:3072
	ds_read_b128 v[168:171], v180
	ds_read_b128 v[172:175], v180 offset:1024
	ds_read_b128 v[176:179], v180 offset:2048
	ds_read_b128 v[180:183], v180 offset:3072
	s_add_u32 s42, s90, 0x20000
	s_addc_u32 s43, s91, 0
	s_mov_b32 m0, s30
	ds_read_b128 v[184:187], v159 offset:32768
	ds_read_b128 v[188:191], v159 offset:33792
	ds_read_b128 v[192:195], v159 offset:34816
	ds_read_b128 v[196:199], v159 offset:35840
	ds_read_b128 v[200:203], v159 offset:36864
	ds_read_b128 v[204:207], v159 offset:37888
	ds_read_b128 v[208:211], v159 offset:38912
	ds_read_b128 v[212:215], v159 offset:39936
	global_load_lds_dwordx4 v128, s[42:43]
	v_lshl_add_u64 v[222:223], s[42:43], 0, v[132:133]
	s_mov_b32 m0, s31
	s_nop 0
	global_load_lds_dwordx4 v[222:223], off
	s_waitcnt vmcnt(8)
	s_waitcnt lgkmcnt(0)
	s_barrier
	s_setprio 1
	s_waitcnt lgkmcnt(0)
	v_mfma_f32_16x16x32_bf16 v[124:127], v[144:147], v[184:187], v[124:127]
	v_mfma_f32_16x16x32_bf16 v[120:123], v[160:163], v[184:187], v[120:123]
	v_mfma_f32_16x16x32_bf16 v[108:111], v[144:147], v[192:195], v[108:111]
	v_mfma_f32_16x16x32_bf16 v[104:107], v[160:163], v[192:195], v[104:107]
	v_mfma_f32_16x16x32_bf16 v[92:95], v[144:147], v[200:203], v[92:95]
	v_mfma_f32_16x16x32_bf16 v[88:91], v[160:163], v[200:203], v[88:91]
	v_mfma_f32_16x16x32_bf16 v[76:79], v[144:147], v[208:211], v[76:79]
	v_mfma_f32_16x16x32_bf16 v[72:75], v[160:163], v[208:211], v[72:75]
	v_mfma_f32_16x16x32_bf16 v[124:127], v[148:151], v[188:191], v[124:127]
	v_mfma_f32_16x16x32_bf16 v[120:123], v[164:167], v[188:191], v[120:123]
	v_mfma_f32_16x16x32_bf16 v[108:111], v[148:151], v[196:199], v[108:111]
	v_mfma_f32_16x16x32_bf16 v[104:107], v[164:167], v[196:199], v[104:107]
	v_mfma_f32_16x16x32_bf16 v[92:95], v[148:151], v[204:207], v[92:95]
	v_mfma_f32_16x16x32_bf16 v[88:91], v[164:167], v[204:207], v[88:91]
	v_mfma_f32_16x16x32_bf16 v[76:79], v[148:151], v[212:215], v[76:79]
	v_mfma_f32_16x16x32_bf16 v[72:75], v[164:167], v[212:215], v[72:75]
	s_setprio 0
	s_setprio 1
	v_mfma_f32_16x16x32_bf16 v[116:119], v[168:171], v[184:187], v[116:119]
	v_mfma_f32_16x16x32_bf16 v[112:115], v[176:179], v[184:187], v[112:115]
	v_mfma_f32_16x16x32_bf16 v[100:103], v[168:171], v[192:195], v[100:103]
	v_mfma_f32_16x16x32_bf16 v[96:99], v[176:179], v[192:195], v[96:99]
	v_mfma_f32_16x16x32_bf16 v[84:87], v[168:171], v[200:203], v[84:87]
	v_mfma_f32_16x16x32_bf16 v[80:83], v[176:179], v[200:203], v[80:83]
	v_mfma_f32_16x16x32_bf16 v[68:71], v[168:171], v[208:211], v[68:71]
	v_mfma_f32_16x16x32_bf16 v[64:67], v[176:179], v[208:211], v[64:67]
	v_mfma_f32_16x16x32_bf16 v[116:119], v[172:175], v[188:191], v[116:119]
	v_mfma_f32_16x16x32_bf16 v[112:115], v[180:183], v[188:191], v[112:115]
	v_mfma_f32_16x16x32_bf16 v[100:103], v[172:175], v[196:199], v[100:103]
	v_mfma_f32_16x16x32_bf16 v[96:99], v[180:183], v[196:199], v[96:99]
	v_mfma_f32_16x16x32_bf16 v[84:87], v[172:175], v[204:207], v[84:87]
	v_mfma_f32_16x16x32_bf16 v[80:83], v[180:183], v[204:207], v[80:83]
	v_mfma_f32_16x16x32_bf16 v[68:71], v[172:175], v[212:215], v[68:71]
	v_mfma_f32_16x16x32_bf16 v[64:67], v[180:183], v[212:215], v[64:67]
	s_setprio 0
	s_barrier
	s_add_i32 s3, s3, s18
	v_lshl_add_u64 v[152:153], v[152:153], 0, s[12:13]
	s_mov_b32 m0, s3
	ds_read_b128 v[184:187], v159 offset:49152
	ds_read_b128 v[188:191], v159 offset:50176
	ds_read_b128 v[192:195], v159 offset:51200
	ds_read_b128 v[196:199], v159 offset:52224
	ds_read_b128 v[200:203], v159 offset:53248
	ds_read_b128 v[204:207], v159 offset:54272
	ds_read_b128 v[208:211], v159 offset:55296
	ds_read_b128 v[212:215], v159 offset:56320
	global_load_lds_dwordx4 v[152:153], off
	s_add_i32 m0, s3, 0x2000
	s_add_u32 s42, s80, 0x20080
	v_lshl_add_u64 v[152:153], v[216:217], 0, s[12:13]
	s_addc_u32 s43, s81, 0
	s_add_i32 s3, s44, s18
	global_load_lds_dwordx4 v[152:153], off
	s_mov_b32 m0, s3
	s_nop 0
	global_load_lds_dwordx4 v130, s[42:43]
	s_add_i32 m0, s3, 0x2000
	s_nop 0
	global_load_lds_dwordx4 v134, s[42:43]
	v_lshl_add_u64 v[152:153], v[218:219], 0, s[12:13]
	s_mov_b32 m0, s58
	s_nop 0
	global_load_lds_dwordx4 v[152:153], off
	v_lshl_add_u64 v[152:153], v[220:221], 0, s[12:13]
	s_mov_b32 m0, s59
	s_nop 0
	global_load_lds_dwordx4 v[152:153], off
	s_waitcnt vmcnt(8)
	s_waitcnt lgkmcnt(0)
	s_barrier
	s_setprio 1
	s_waitcnt lgkmcnt(0)
	v_mfma_f32_16x16x32_bf16 v[60:63], v[144:147], v[184:187], v[60:63]
	v_mfma_f32_16x16x32_bf16 v[56:59], v[160:163], v[184:187], v[56:59]
	v_mfma_f32_16x16x32_bf16 v[44:47], v[144:147], v[192:195], v[44:47]
	v_mfma_f32_16x16x32_bf16 v[40:43], v[160:163], v[192:195], v[40:43]
	v_mfma_f32_16x16x32_bf16 v[28:31], v[144:147], v[200:203], v[28:31]
	v_mfma_f32_16x16x32_bf16 v[24:27], v[160:163], v[200:203], v[24:27]
	v_mfma_f32_16x16x32_bf16 v[12:15], v[144:147], v[208:211], v[12:15]
	v_mfma_f32_16x16x32_bf16 v[8:11], v[160:163], v[208:211], v[8:11]
	v_mfma_f32_16x16x32_bf16 v[60:63], v[148:151], v[188:191], v[60:63]
	v_mfma_f32_16x16x32_bf16 v[56:59], v[164:167], v[188:191], v[56:59]
	v_mfma_f32_16x16x32_bf16 v[44:47], v[148:151], v[196:199], v[44:47]
	v_mfma_f32_16x16x32_bf16 v[40:43], v[164:167], v[196:199], v[40:43]
	v_mfma_f32_16x16x32_bf16 v[28:31], v[148:151], v[204:207], v[28:31]
	v_mfma_f32_16x16x32_bf16 v[24:27], v[164:167], v[204:207], v[24:27]
	v_mfma_f32_16x16x32_bf16 v[12:15], v[148:151], v[212:215], v[12:15]
	v_mfma_f32_16x16x32_bf16 v[8:11], v[164:167], v[212:215], v[8:11]
	s_setprio 0
	s_setprio 1
	v_mfma_f32_16x16x32_bf16 v[52:55], v[168:171], v[184:187], v[52:55]
	v_mfma_f32_16x16x32_bf16 v[48:51], v[176:179], v[184:187], v[48:51]
	v_mfma_f32_16x16x32_bf16 v[36:39], v[168:171], v[192:195], v[36:39]
	v_mfma_f32_16x16x32_bf16 v[32:35], v[176:179], v[192:195], v[32:35]
	v_mfma_f32_16x16x32_bf16 v[20:23], v[168:171], v[200:203], v[20:23]
	v_mfma_f32_16x16x32_bf16 v[16:19], v[176:179], v[200:203], v[16:19]
	v_mfma_f32_16x16x32_bf16 v[4:7], v[168:171], v[208:211], v[4:7]
	v_mfma_f32_16x16x32_bf16 v[0:3], v[176:179], v[208:211], v[0:3]
	v_mfma_f32_16x16x32_bf16 v[52:55], v[172:175], v[188:191], v[52:55]
	v_mfma_f32_16x16x32_bf16 v[48:51], v[180:183], v[188:191], v[48:51]
	v_mfma_f32_16x16x32_bf16 v[36:39], v[172:175], v[196:199], v[36:39]
	v_mfma_f32_16x16x32_bf16 v[32:35], v[180:183], v[196:199], v[32:35]
	v_mfma_f32_16x16x32_bf16 v[20:23], v[172:175], v[204:207], v[20:23]
	v_mfma_f32_16x16x32_bf16 v[16:19], v[180:183], v[204:207], v[16:19]
	v_mfma_f32_16x16x32_bf16 v[4:7], v[172:175], v[212:215], v[4:7]
	v_mfma_f32_16x16x32_bf16 v[0:3], v[180:183], v[212:215], v[0:3]
	s_setprio 0
	s_barrier
	s_add_i32 s37, s37, 2
	s_add_u32 s34, s34, 0x100
	s_addc_u32 s35, s35, 0
	s_add_u32 s33, s33, 0x100
	s_addc_u32 s36, s36, 0
	s_cmp_gt_u32 s37, 5
	s_cbranch_scc0 .LBB0_1417
	s_and_b64 vcc, exec, s[14:15]
	s_cbranch_vccz .LBB0_1420
	s_barrier

.LBB0_1493:
	ds_read_b128 v[140:143], v149
	ds_read_b128 v[152:155], v149 offset:1024
	ds_read_b128 v[156:159], v149 offset:2048
	ds_read_b128 v[160:163], v149 offset:3072
	ds_read_b128 v[164:167], v150
	ds_read_b128 v[168:171], v150 offset:1024
	ds_read_b128 v[172:175], v150 offset:2048
	ds_read_b128 v[176:179], v150 offset:3072
	s_add_u32 s3, s86, 0xfff80080
	s_addc_u32 s33, s87, -1
	s_cmp_eq_u32 s27, 28
	s_cselect_b32 s89, s0, s33
	s_cselect_b32 s88, s1, s3
	s_cselect_b32 s81, s15, s24
	s_cselect_b32 s80, s17, s19
	s_add_i32 m0, s30, 0xc000
	ds_read_b128 v[180:183], v151
	ds_read_b128 v[184:187], v151 offset:1024
	ds_read_b128 v[188:191], v151 offset:2048
	ds_read_b128 v[192:195], v151 offset:3072
	ds_read_b128 v[196:199], v151 offset:4096
	ds_read_b128 v[200:203], v151 offset:5120
	ds_read_b128 v[204:207], v151 offset:6144
	ds_read_b128 v[208:211], v151 offset:7168
	global_load_lds_dwordx4 v132, s[86:87]
	s_add_i32 m0, s30, 0xe000
	s_nop 0
	global_load_lds_dwordx4 v134, s[86:87]
	s_waitcnt vmcnt(8)
	s_waitcnt lgkmcnt(0)
	s_barrier
	s_setprio 1
	s_waitcnt lgkmcnt(0)
	v_mfma_f32_16x16x32_bf16 v[124:127], v[140:143], v[180:183], v[124:127]
	v_mfma_f32_16x16x32_bf16 v[120:123], v[156:159], v[180:183], v[120:123]
	v_mfma_f32_16x16x32_bf16 v[108:111], v[140:143], v[188:191], v[108:111]
	v_mfma_f32_16x16x32_bf16 v[104:107], v[156:159], v[188:191], v[104:107]
	v_mfma_f32_16x16x32_bf16 v[92:95], v[140:143], v[196:199], v[92:95]
	v_mfma_f32_16x16x32_bf16 v[88:91], v[156:159], v[196:199], v[88:91]
	v_mfma_f32_16x16x32_bf16 v[76:79], v[140:143], v[204:207], v[76:79]
	v_mfma_f32_16x16x32_bf16 v[72:75], v[156:159], v[204:207], v[72:75]
	v_mfma_f32_16x16x32_bf16 v[124:127], v[152:155], v[184:187], v[124:127]
	v_mfma_f32_16x16x32_bf16 v[120:123], v[160:163], v[184:187], v[120:123]
	v_mfma_f32_16x16x32_bf16 v[108:111], v[152:155], v[192:195], v[108:111]
	v_mfma_f32_16x16x32_bf16 v[104:107], v[160:163], v[192:195], v[104:107]
	v_mfma_f32_16x16x32_bf16 v[92:95], v[152:155], v[200:203], v[92:95]
	v_mfma_f32_16x16x32_bf16 v[88:91], v[160:163], v[200:203], v[88:91]
	v_mfma_f32_16x16x32_bf16 v[76:79], v[152:155], v[208:211], v[76:79]
	v_mfma_f32_16x16x32_bf16 v[72:75], v[160:163], v[208:211], v[72:75]
	s_setprio 0
	s_setprio 1
	v_mfma_f32_16x16x32_bf16 v[116:119], v[164:167], v[180:183], v[116:119]
	v_mfma_f32_16x16x32_bf16 v[112:115], v[172:175], v[180:183], v[112:115]
	v_mfma_f32_16x16x32_bf16 v[100:103], v[164:167], v[188:191], v[100:103]
	v_mfma_f32_16x16x32_bf16 v[96:99], v[172:175], v[188:191], v[96:99]
	v_mfma_f32_16x16x32_bf16 v[84:87], v[164:167], v[196:199], v[84:87]
	v_mfma_f32_16x16x32_bf16 v[80:83], v[172:175], v[196:199], v[80:83]
	v_mfma_f32_16x16x32_bf16 v[68:71], v[164:167], v[204:207], v[68:71]
	v_mfma_f32_16x16x32_bf16 v[64:67], v[172:175], v[204:207], v[64:67]
	v_mfma_f32_16x16x32_bf16 v[116:119], v[168:171], v[184:187], v[116:119]
	v_mfma_f32_16x16x32_bf16 v[112:115], v[176:179], v[184:187], v[112:115]
	v_mfma_f32_16x16x32_bf16 v[100:103], v[168:171], v[192:195], v[100:103]
	v_mfma_f32_16x16x32_bf16 v[96:99], v[176:179], v[192:195], v[96:99]
	v_mfma_f32_16x16x32_bf16 v[84:87], v[168:171], v[200:203], v[84:87]
	v_mfma_f32_16x16x32_bf16 v[80:83], v[176:179], v[200:203], v[80:83]
	v_mfma_f32_16x16x32_bf16 v[68:71], v[168:171], v[208:211], v[68:71]
	v_mfma_f32_16x16x32_bf16 v[64:67], v[176:179], v[208:211], v[64:67]
	s_setprio 0
	s_barrier
	s_add_i32 s3, s59, s25
	v_lshl_add_u64 v[144:145], s[80:81], 0, v[128:129]
	s_mov_b32 m0, s3
	ds_read_b128 v[180:183], v151 offset:16384
	ds_read_b128 v[184:187], v151 offset:17408
	ds_read_b128 v[188:191], v151 offset:18432
	ds_read_b128 v[192:195], v151 offset:19456
	ds_read_b128 v[196:199], v151 offset:20480
	ds_read_b128 v[200:203], v151 offset:21504
	ds_read_b128 v[204:207], v151 offset:22528
	ds_read_b128 v[208:211], v151 offset:23552
	global_load_lds_dwordx4 v[144:145], off
	s_add_i32 m0, s3, 0x2000
	s_add_u32 s36, s80, 0x80000
	v_lshl_add_u64 v[212:213], s[80:81], 0, v[130:131]
	s_addc_u32 s37, s81, 0
	s_add_i32 s3, s68, s25
	global_load_lds_dwordx4 v[212:213], off
	s_mov_b32 m0, s3
	v_lshl_add_u64 v[216:217], s[88:89], 0, v[130:131]
	global_load_lds_dwordx4 v128, s[36:37]
	s_add_i32 m0, s3, 0x2000
	s_nop 0
	global_load_lds_dwordx4 v130, s[36:37]
	v_lshl_add_u64 v[214:215], s[88:89], 0, v[128:129]
	s_mov_b32 m0, s30
	s_nop 0
	global_load_lds_dwordx4 v[214:215], off
	s_mov_b32 m0, s31
	s_nop 0
	global_load_lds_dwordx4 v[216:217], off
	s_waitcnt vmcnt(8)
	s_waitcnt lgkmcnt(0)
	s_barrier
	s_setprio 1
	s_waitcnt lgkmcnt(0)
	v_mfma_f32_16x16x32_bf16 v[60:63], v[140:143], v[180:183], v[60:63]
	v_mfma_f32_16x16x32_bf16 v[56:59], v[156:159], v[180:183], v[56:59]
	v_mfma_f32_16x16x32_bf16 v[44:47], v[140:143], v[188:191], v[44:47]
	v_mfma_f32_16x16x32_bf16 v[40:43], v[156:159], v[188:191], v[40:43]
	v_mfma_f32_16x16x32_bf16 v[28:31], v[140:143], v[196:199], v[28:31]
	v_mfma_f32_16x16x32_bf16 v[24:27], v[156:159], v[196:199], v[24:27]
	v_mfma_f32_16x16x32_bf16 v[12:15], v[140:143], v[204:207], v[12:15]
	v_mfma_f32_16x16x32_bf16 v[8:11], v[156:159], v[204:207], v[8:11]
	v_mfma_f32_16x16x32_bf16 v[60:63], v[152:155], v[184:187], v[60:63]
	v_mfma_f32_16x16x32_bf16 v[56:59], v[160:163], v[184:187], v[56:59]
	v_mfma_f32_16x16x32_bf16 v[44:47], v[152:155], v[192:195], v[44:47]
	v_mfma_f32_16x16x32_bf16 v[40:43], v[160:163], v[192:195], v[40:43]
	v_mfma_f32_16x16x32_bf16 v[28:31], v[152:155], v[200:203], v[28:31]
	v_mfma_f32_16x16x32_bf16 v[24:27], v[160:163], v[200:203], v[24:27]
	v_mfma_f32_16x16x32_bf16 v[12:15], v[152:155], v[208:211], v[12:15]
	v_mfma_f32_16x16x32_bf16 v[8:11], v[160:163], v[208:211], v[8:11]
	s_setprio 0
	s_setprio 1
	v_mfma_f32_16x16x32_bf16 v[52:55], v[164:167], v[180:183], v[52:55]
	v_mfma_f32_16x16x32_bf16 v[48:51], v[172:175], v[180:183], v[48:51]
	v_mfma_f32_16x16x32_bf16 v[36:39], v[164:167], v[188:191], v[36:39]
	v_mfma_f32_16x16x32_bf16 v[32:35], v[172:175], v[188:191], v[32:35]
	v_mfma_f32_16x16x32_bf16 v[20:23], v[164:167], v[196:199], v[20:23]
	v_mfma_f32_16x16x32_bf16 v[16:19], v[172:175], v[196:199], v[16:19]
	v_mfma_f32_16x16x32_bf16 v[4:7], v[164:167], v[204:207], v[4:7]
	v_mfma_f32_16x16x32_bf16 v[0:3], v[172:175], v[204:207], v[0:3]
	v_mfma_f32_16x16x32_bf16 v[52:55], v[168:171], v[184:187], v[52:55]
	v_mfma_f32_16x16x32_bf16 v[48:51], v[176:179], v[184:187], v[48:51]
	v_mfma_f32_16x16x32_bf16 v[36:39], v[168:171], v[192:195], v[36:39]
	v_mfma_f32_16x16x32_bf16 v[32:35], v[176:179], v[192:195], v[32:35]
	v_mfma_f32_16x16x32_bf16 v[20:23], v[168:171], v[200:203], v[20:23]
	v_mfma_f32_16x16x32_bf16 v[16:19], v[176:179], v[200:203], v[16:19]
	v_mfma_f32_16x16x32_bf16 v[4:7], v[168:171], v[208:211], v[4:7]
	v_mfma_f32_16x16x32_bf16 v[0:3], v[176:179], v[208:211], v[0:3]
	s_setprio 0
	s_barrier
	s_add_i32 s3, 0, 0x18000
	s_add_i32 s33, 0, 0x1c000
	v_add_u32_e32 v160, s3, v147
	v_add_u32_e32 v176, s33, v147
	ds_read_b128 v[140:143], v160
	ds_read_b128 v[152:155], v160 offset:1024
	ds_read_b128 v[156:159], v160 offset:2048
	ds_read_b128 v[160:163], v160 offset:3072
	ds_read_b128 v[164:167], v176
	ds_read_b128 v[168:171], v176 offset:1024
	ds_read_b128 v[172:175], v176 offset:2048
	ds_read_b128 v[176:179], v176 offset:3072
	s_add_u32 s36, s88, 0x80000
	s_addc_u32 s37, s89, 0
	s_mov_b32 m0, s52
	ds_read_b128 v[180:183], v151 offset:32768
	ds_read_b128 v[184:187], v151 offset:33792
	ds_read_b128 v[188:191], v151 offset:34816
	ds_read_b128 v[192:195], v151 offset:35840
	ds_read_b128 v[196:199], v151 offset:36864
	ds_read_b128 v[200:203], v151 offset:37888
	ds_read_b128 v[204:207], v151 offset:38912
	ds_read_b128 v[208:211], v151 offset:39936
	global_load_lds_dwordx4 v128, s[36:37]
	v_lshl_add_u64 v[218:219], s[36:37], 0, v[130:131]
	s_mov_b32 m0, s53
	s_nop 0
	global_load_lds_dwordx4 v[218:219], off
	s_waitcnt vmcnt(8)
	s_waitcnt lgkmcnt(0)
	s_barrier
	s_setprio 1
	s_waitcnt lgkmcnt(0)
	v_mfma_f32_16x16x32_bf16 v[124:127], v[140:143], v[180:183], v[124:127]
	v_mfma_f32_16x16x32_bf16 v[120:123], v[156:159], v[180:183], v[120:123]
	v_mfma_f32_16x16x32_bf16 v[108:111], v[140:143], v[188:191], v[108:111]
	v_mfma_f32_16x16x32_bf16 v[104:107], v[156:159], v[188:191], v[104:107]
	v_mfma_f32_16x16x32_bf16 v[92:95], v[140:143], v[196:199], v[92:95]
	v_mfma_f32_16x16x32_bf16 v[88:91], v[156:159], v[196:199], v[88:91]
	v_mfma_f32_16x16x32_bf16 v[76:79], v[140:143], v[204:207], v[76:79]
	v_mfma_f32_16x16x32_bf16 v[72:75], v[156:159], v[204:207], v[72:75]
	v_mfma_f32_16x16x32_bf16 v[124:127], v[152:155], v[184:187], v[124:127]
	v_mfma_f32_16x16x32_bf16 v[120:123], v[160:163], v[184:187], v[120:123]
	v_mfma_f32_16x16x32_bf16 v[108:111], v[152:155], v[192:195], v[108:111]
	v_mfma_f32_16x16x32_bf16 v[104:107], v[160:163], v[192:195], v[104:107]
	v_mfma_f32_16x16x32_bf16 v[92:95], v[152:155], v[200:203], v[92:95]
	v_mfma_f32_16x16x32_bf16 v[88:91], v[160:163], v[200:203], v[88:91]
	v_mfma_f32_16x16x32_bf16 v[76:79], v[152:155], v[208:211], v[76:79]
	v_mfma_f32_16x16x32_bf16 v[72:75], v[160:163], v[208:211], v[72:75]
	s_setprio 0
	s_setprio 1
	v_mfma_f32_16x16x32_bf16 v[116:119], v[164:167], v[180:183], v[116:119]
	v_mfma_f32_16x16x32_bf16 v[112:115], v[172:175], v[180:183], v[112:115]
	v_mfma_f32_16x16x32_bf16 v[100:103], v[164:167], v[188:191], v[100:103]
	v_mfma_f32_16x16x32_bf16 v[96:99], v[172:175], v[188:191], v[96:99]
	v_mfma_f32_16x16x32_bf16 v[84:87], v[164:167], v[196:199], v[84:87]
	v_mfma_f32_16x16x32_bf16 v[80:83], v[172:175], v[196:199], v[80:83]
	v_mfma_f32_16x16x32_bf16 v[68:71], v[164:167], v[204:207], v[68:71]
	v_mfma_f32_16x16x32_bf16 v[64:67], v[172:175], v[204:207], v[64:67]
	v_mfma_f32_16x16x32_bf16 v[116:119], v[168:171], v[184:187], v[116:119]
	v_mfma_f32_16x16x32_bf16 v[112:115], v[176:179], v[184:187], v[112:115]
	v_mfma_f32_16x16x32_bf16 v[100:103], v[168:171], v[192:195], v[100:103]
	v_mfma_f32_16x16x32_bf16 v[96:99], v[176:179], v[192:195], v[96:99]
	v_mfma_f32_16x16x32_bf16 v[84:87], v[168:171], v[200:203], v[84:87]
	v_mfma_f32_16x16x32_bf16 v[80:83], v[176:179], v[200:203], v[80:83]
	v_mfma_f32_16x16x32_bf16 v[68:71], v[168:171], v[208:211], v[68:71]
	v_mfma_f32_16x16x32_bf16 v[64:67], v[176:179], v[208:211], v[64:67]
	s_setprio 0
	s_barrier
	s_add_i32 s3, s3, s25
	v_lshl_add_u64 v[144:145], v[144:145], 0, s[10:11]
	s_mov_b32 m0, s3
	ds_read_b128 v[180:183], v151 offset:49152
	ds_read_b128 v[184:187], v151 offset:50176
	ds_read_b128 v[188:191], v151 offset:51200
	ds_read_b128 v[192:195], v151 offset:52224
	ds_read_b128 v[196:199], v151 offset:53248
	ds_read_b128 v[200:203], v151 offset:54272
	ds_read_b128 v[204:207], v151 offset:55296
	ds_read_b128 v[208:211], v151 offset:56320
	global_load_lds_dwordx4 v[144:145], off
	s_add_i32 m0, s3, 0x2000
	s_add_u32 s36, s80, 0x80080
	v_lshl_add_u64 v[144:145], v[212:213], 0, s[10:11]
	s_addc_u32 s37, s81, 0
	s_add_i32 s3, s33, s25
	global_load_lds_dwordx4 v[144:145], off
	s_mov_b32 m0, s3
	s_nop 0
	global_load_lds_dwordx4 v128, s[36:37]
	s_add_i32 m0, s3, 0x2000
	s_nop 0
	global_load_lds_dwordx4 v130, s[36:37]
	v_lshl_add_u64 v[144:145], v[214:215], 0, s[10:11]
	s_mov_b32 m0, s57
	s_nop 0
	global_load_lds_dwordx4 v[144:145], off
	v_lshl_add_u64 v[144:145], v[216:217], 0, s[10:11]
	s_mov_b32 m0, s58
	s_nop 0
	global_load_lds_dwordx4 v[144:145], off
	s_waitcnt vmcnt(8)
	s_waitcnt lgkmcnt(0)
	s_barrier
	s_setprio 1
	s_waitcnt lgkmcnt(0)
	v_mfma_f32_16x16x32_bf16 v[60:63], v[140:143], v[180:183], v[60:63]
	v_mfma_f32_16x16x32_bf16 v[56:59], v[156:159], v[180:183], v[56:59]
	v_mfma_f32_16x16x32_bf16 v[44:47], v[140:143], v[188:191], v[44:47]
	v_mfma_f32_16x16x32_bf16 v[40:43], v[156:159], v[188:191], v[40:43]
	v_mfma_f32_16x16x32_bf16 v[28:31], v[140:143], v[196:199], v[28:31]
	v_mfma_f32_16x16x32_bf16 v[24:27], v[156:159], v[196:199], v[24:27]
	v_mfma_f32_16x16x32_bf16 v[12:15], v[140:143], v[204:207], v[12:15]
	v_mfma_f32_16x16x32_bf16 v[8:11], v[156:159], v[204:207], v[8:11]
	v_mfma_f32_16x16x32_bf16 v[60:63], v[152:155], v[184:187], v[60:63]
	v_mfma_f32_16x16x32_bf16 v[56:59], v[160:163], v[184:187], v[56:59]
	v_mfma_f32_16x16x32_bf16 v[44:47], v[152:155], v[192:195], v[44:47]
	v_mfma_f32_16x16x32_bf16 v[40:43], v[160:163], v[192:195], v[40:43]
	v_mfma_f32_16x16x32_bf16 v[28:31], v[152:155], v[200:203], v[28:31]
	v_mfma_f32_16x16x32_bf16 v[24:27], v[160:163], v[200:203], v[24:27]
	v_mfma_f32_16x16x32_bf16 v[12:15], v[152:155], v[208:211], v[12:15]
	v_mfma_f32_16x16x32_bf16 v[8:11], v[160:163], v[208:211], v[8:11]
	s_setprio 0
	s_setprio 1
	v_mfma_f32_16x16x32_bf16 v[52:55], v[164:167], v[180:183], v[52:55]
	v_mfma_f32_16x16x32_bf16 v[48:51], v[172:175], v[180:183], v[48:51]
	v_mfma_f32_16x16x32_bf16 v[36:39], v[164:167], v[188:191], v[36:39]
	v_mfma_f32_16x16x32_bf16 v[32:35], v[172:175], v[188:191], v[32:35]
	v_mfma_f32_16x16x32_bf16 v[20:23], v[164:167], v[196:199], v[20:23]
	v_mfma_f32_16x16x32_bf16 v[16:19], v[172:175], v[196:199], v[16:19]
	v_mfma_f32_16x16x32_bf16 v[4:7], v[164:167], v[204:207], v[4:7]
	v_mfma_f32_16x16x32_bf16 v[0:3], v[172:175], v[204:207], v[0:3]
	v_mfma_f32_16x16x32_bf16 v[52:55], v[168:171], v[184:187], v[52:55]
	v_mfma_f32_16x16x32_bf16 v[48:51], v[176:179], v[184:187], v[48:51]
	v_mfma_f32_16x16x32_bf16 v[36:39], v[168:171], v[192:195], v[36:39]
	v_mfma_f32_16x16x32_bf16 v[32:35], v[176:179], v[192:195], v[32:35]
	v_mfma_f32_16x16x32_bf16 v[20:23], v[168:171], v[200:203], v[20:23]
	v_mfma_f32_16x16x32_bf16 v[16:19], v[176:179], v[200:203], v[16:19]
	v_mfma_f32_16x16x32_bf16 v[4:7], v[168:171], v[208:211], v[4:7]
	v_mfma_f32_16x16x32_bf16 v[0:3], v[176:179], v[208:211], v[0:3]
	s_setprio 0
	s_barrier
	s_add_i32 s27, s27, 2
	s_add_u32 s86, s86, 0x100
	s_addc_u32 s87, s87, 0
	s_add_u32 s19, s19, 0x100
	s_addc_u32 s24, s24, 0
	s_cmp_gt_u32 s27, 29
	s_cbranch_scc0 .LBB0_1493
	s_and_b64 vcc, exec, s[12:13]
	s_cbranch_vccz .LBB0_1496
	s_barrier

.LBB0_1614:
	s_lshl_b32 s1, s1, 5
	s_mov_b64 s[14:15], 0x80
	s_and_b32 s1, s1, 0x60
	s_add_i32 m0, s9, 0x18000
	v_lshl_add_u64 v[6:7], v[6:7], 0, s[14:15]
	s_lshl_b32 s16, s0, 13
	s_lshl_b32 s17, s1, 7
	s_waitcnt vmcnt(2)
	s_barrier
	global_load_lds_dwordx4 v[6:7], off
	v_lshl_add_u64 v[4:5], v[4:5], 0, s[14:15]
	s_add_i32 m0, s9, 0x1a000
	s_add_i32 s30, s9, 0x8000
	s_add_i32 s31, s9, 0xa000
	global_load_lds_dwordx4 v[4:5], off
	v_lshl_add_u64 v[0:1], v[0:1], 0, s[14:15]
	s_mov_b32 m0, s30
	s_add_u32 s10, s90, 0x80080
	global_load_lds_dwordx4 v[0:1], off
	v_lshl_add_u64 v[0:1], v[2:3], 0, s[14:15]
	s_mov_b32 m0, s31
	s_addc_u32 s11, s91, 0
	global_load_lds_dwordx4 v[0:1], off
	s_add_i32 m0, s9, 0x1c000
	s_nop 0
	global_load_lds_dwordx4 v130, s[10:11]
	s_add_i32 m0, s9, 0x1e000
	s_cmpk_lt_u32 s3, 0x100
	global_load_lds_dwordx4 v134, s[10:11]
	v_lshrrev_b32_e32 v0, 1, v8
	v_and_b32_e32 v0, 24, v0
	v_and_b32_e32 v1, 15, v8
	v_lshlrev_b32_e32 v2, 1, v0
	v_lshl_or_b32 v148, s0, 6, v1
	v_lshl_or_b32 v1, v1, 6, v2
	v_lshlrev_b32_e32 v2, 2, v8
	v_and_b32_e32 v2, 32, v2
	v_bitop3_b32 v3, v1, s16, v2 bitop3:0xde
	v_bitop3_b32 v149, v1, s17, v2 bitop3:0xde
	v_lshlrev_b32_e32 v1, 15, v9
	v_and_b32_e32 v1, 0xffff0000, v1
	v_lshl_add_u32 v1, v10, 12, v1
	v_and_b32_e32 v2, 1, v9
	v_lshl_or_b32 v1, v2, 6, v1
	v_lshl_add_u32 v138, v11, 1, v1
	v_lshlrev_b32_e32 v1, 15, v12
	v_and_b32_e32 v1, 0xffff0000, v1
	s_waitcnt vmcnt(6)
	v_lshl_add_u32 v1, v13, 12, v1
	v_and_b32_e32 v2, 1, v12
	s_cselect_b64 s[16:17], -1, 0
	v_lshl_or_b32 v1, v2, 6, v1
	s_add_i32 s48, 0, 0x10000
	s_add_i32 s49, 0, 0x14000
	s_sext_i32_i8 s24, s6
	v_mov_b32_e32 v139, v137
	v_lshl_add_u32 v140, v14, 1, v1
	v_mov_b32_e32 v141, v137
	v_mov_b64_e32 v[142:143], 0x800
	v_mov_b64_e32 v[144:145], 0x7ff
	v_add_u32_e32 v150, s48, v149
	v_add_u32_e32 v151, s49, v149
	v_add_u32_e32 v152, 0, v3
	s_lshl_b32 s6, s1, 1
	v_lshlrev_b32_e32 v136, 1, v0
	s_mov_b32 s52, s7
	s_barrier
	s_branch .LBB0_1617

.LBB0_1624:
	ds_read_b128 v[154:157], v150
	ds_read_b128 v[158:161], v150 offset:1024
	ds_read_b128 v[162:165], v150 offset:2048
	ds_read_b128 v[166:169], v150 offset:3072
	ds_read_b128 v[170:173], v151
	ds_read_b128 v[174:177], v151 offset:1024
	ds_read_b128 v[178:181], v151 offset:2048
	ds_read_b128 v[182:185], v151 offset:3072
	s_add_u32 s3, s88, 0xfff80080
	s_addc_u32 s42, s89, -1
	s_cmp_eq_u32 s37, 28
	s_cselect_b32 s93, s0, s42
	s_cselect_b32 s92, s1, s3
	s_cselect_b32 s91, s27, s36
	s_cselect_b32 s90, s33, s35
	s_add_i32 m0, s9, 0xc000
	ds_read_b128 v[186:189], v152
	ds_read_b128 v[190:193], v152 offset:1024
	ds_read_b128 v[194:197], v152 offset:2048
	ds_read_b128 v[198:201], v152 offset:3072
	ds_read_b128 v[202:205], v152 offset:4096
	ds_read_b128 v[206:209], v152 offset:5120
	ds_read_b128 v[210:213], v152 offset:6144
	ds_read_b128 v[214:217], v152 offset:7168
	global_load_lds_dwordx4 v138, s[88:89]
	s_add_i32 m0, s9, 0xe000
	s_nop 0
	global_load_lds_dwordx4 v140, s[88:89]
	s_waitcnt vmcnt(8)
	s_waitcnt lgkmcnt(0)
	s_barrier
	s_setprio 1
	s_waitcnt lgkmcnt(0)
	v_mfma_f32_16x16x32_bf16 v[124:127], v[154:157], v[186:189], v[124:127]
	v_mfma_f32_16x16x32_bf16 v[120:123], v[162:165], v[186:189], v[120:123]
	v_mfma_f32_16x16x32_bf16 v[108:111], v[154:157], v[194:197], v[108:111]
	v_mfma_f32_16x16x32_bf16 v[104:107], v[162:165], v[194:197], v[104:107]
	v_mfma_f32_16x16x32_bf16 v[92:95], v[154:157], v[202:205], v[92:95]
	v_mfma_f32_16x16x32_bf16 v[88:91], v[162:165], v[202:205], v[88:91]
	v_mfma_f32_16x16x32_bf16 v[76:79], v[154:157], v[210:213], v[76:79]
	v_mfma_f32_16x16x32_bf16 v[72:75], v[162:165], v[210:213], v[72:75]
	v_mfma_f32_16x16x32_bf16 v[124:127], v[158:161], v[190:193], v[124:127]
	v_mfma_f32_16x16x32_bf16 v[120:123], v[166:169], v[190:193], v[120:123]
	v_mfma_f32_16x16x32_bf16 v[108:111], v[158:161], v[198:201], v[108:111]
	v_mfma_f32_16x16x32_bf16 v[104:107], v[166:169], v[198:201], v[104:107]
	v_mfma_f32_16x16x32_bf16 v[92:95], v[158:161], v[206:209], v[92:95]
	v_mfma_f32_16x16x32_bf16 v[88:91], v[166:169], v[206:209], v[88:91]
	v_mfma_f32_16x16x32_bf16 v[76:79], v[158:161], v[214:217], v[76:79]
	v_mfma_f32_16x16x32_bf16 v[72:75], v[166:169], v[214:217], v[72:75]
	s_setprio 0
	s_setprio 1
	v_mfma_f32_16x16x32_bf16 v[116:119], v[170:173], v[186:189], v[116:119]
	v_mfma_f32_16x16x32_bf16 v[112:115], v[178:181], v[186:189], v[112:115]
	v_mfma_f32_16x16x32_bf16 v[100:103], v[170:173], v[194:197], v[100:103]
	v_mfma_f32_16x16x32_bf16 v[96:99], v[178:181], v[194:197], v[96:99]
	v_mfma_f32_16x16x32_bf16 v[84:87], v[170:173], v[202:205], v[84:87]
	v_mfma_f32_16x16x32_bf16 v[80:83], v[178:181], v[202:205], v[80:83]
	v_mfma_f32_16x16x32_bf16 v[68:71], v[170:173], v[210:213], v[68:71]
	v_mfma_f32_16x16x32_bf16 v[64:67], v[178:181], v[210:213], v[64:67]
	v_mfma_f32_16x16x32_bf16 v[116:119], v[174:177], v[190:193], v[116:119]
	v_mfma_f32_16x16x32_bf16 v[112:115], v[182:185], v[190:193], v[112:115]
	v_mfma_f32_16x16x32_bf16 v[100:103], v[174:177], v[198:201], v[100:103]
	v_mfma_f32_16x16x32_bf16 v[96:99], v[182:185], v[198:201], v[96:99]
	v_mfma_f32_16x16x32_bf16 v[84:87], v[174:177], v[206:209], v[84:87]
	v_mfma_f32_16x16x32_bf16 v[80:83], v[182:185], v[206:209], v[80:83]
	v_mfma_f32_16x16x32_bf16 v[68:71], v[174:177], v[214:217], v[68:71]
	v_mfma_f32_16x16x32_bf16 v[64:67], v[182:185], v[214:217], v[64:67]
	s_setprio 0
	s_barrier
	s_add_i32 s3, s48, s8
	v_lshl_add_u64 v[146:147], s[90:91], 0, v[130:131]
	s_mov_b32 m0, s3
	ds_read_b128 v[186:189], v152 offset:16384
	ds_read_b128 v[190:193], v152 offset:17408
	ds_read_b128 v[194:197], v152 offset:18432
	ds_read_b128 v[198:201], v152 offset:19456
	ds_read_b128 v[202:205], v152 offset:20480
	ds_read_b128 v[206:209], v152 offset:21504
	ds_read_b128 v[210:213], v152 offset:22528
	ds_read_b128 v[214:217], v152 offset:23552
	global_load_lds_dwordx4 v[146:147], off
	s_add_i32 m0, s3, 0x2000
	s_add_u32 s42, s90, 0x80000
	v_lshl_add_u64 v[218:219], s[90:91], 0, v[134:135]
	s_addc_u32 s43, s91, 0
	s_add_i32 s3, s49, s8
	global_load_lds_dwordx4 v[218:219], off
	s_mov_b32 m0, s3
	v_lshl_add_u64 v[222:223], s[92:93], 0, v[132:133]
	global_load_lds_dwordx4 v130, s[42:43]
	s_add_i32 m0, s3, 0x2000
	s_nop 0
	global_load_lds_dwordx4 v134, s[42:43]
	v_lshl_add_u64 v[220:221], s[92:93], 0, v[128:129]
	s_mov_b32 m0, s9
	s_nop 0
	global_load_lds_dwordx4 v[220:221], off
	s_mov_b32 m0, s18
	s_nop 0
	global_load_lds_dwordx4 v[222:223], off
	s_waitcnt vmcnt(8)
	s_waitcnt lgkmcnt(0)
	s_barrier
	s_setprio 1
	s_waitcnt lgkmcnt(0)
	v_mfma_f32_16x16x32_bf16 v[60:63], v[154:157], v[186:189], v[60:63]
	v_mfma_f32_16x16x32_bf16 v[56:59], v[162:165], v[186:189], v[56:59]
	v_mfma_f32_16x16x32_bf16 v[44:47], v[154:157], v[194:197], v[44:47]
	v_mfma_f32_16x16x32_bf16 v[40:43], v[162:165], v[194:197], v[40:43]
	v_mfma_f32_16x16x32_bf16 v[28:31], v[154:157], v[202:205], v[28:31]
	v_mfma_f32_16x16x32_bf16 v[24:27], v[162:165], v[202:205], v[24:27]
	v_mfma_f32_16x16x32_bf16 v[12:15], v[154:157], v[210:213], v[12:15]
	v_mfma_f32_16x16x32_bf16 v[8:11], v[162:165], v[210:213], v[8:11]
	v_mfma_f32_16x16x32_bf16 v[60:63], v[158:161], v[190:193], v[60:63]
	v_mfma_f32_16x16x32_bf16 v[56:59], v[166:169], v[190:193], v[56:59]
	v_mfma_f32_16x16x32_bf16 v[44:47], v[158:161], v[198:201], v[44:47]
	v_mfma_f32_16x16x32_bf16 v[40:43], v[166:169], v[198:201], v[40:43]
	v_mfma_f32_16x16x32_bf16 v[28:31], v[158:161], v[206:209], v[28:31]
	v_mfma_f32_16x16x32_bf16 v[24:27], v[166:169], v[206:209], v[24:27]
	v_mfma_f32_16x16x32_bf16 v[12:15], v[158:161], v[214:217], v[12:15]
	v_mfma_f32_16x16x32_bf16 v[8:11], v[166:169], v[214:217], v[8:11]
	s_setprio 0
	s_setprio 1
	v_mfma_f32_16x16x32_bf16 v[52:55], v[170:173], v[186:189], v[52:55]
	v_mfma_f32_16x16x32_bf16 v[48:51], v[178:181], v[186:189], v[48:51]
	v_mfma_f32_16x16x32_bf16 v[36:39], v[170:173], v[194:197], v[36:39]
	v_mfma_f32_16x16x32_bf16 v[32:35], v[178:181], v[194:197], v[32:35]
	v_mfma_f32_16x16x32_bf16 v[20:23], v[170:173], v[202:205], v[20:23]
	v_mfma_f32_16x16x32_bf16 v[16:19], v[178:181], v[202:205], v[16:19]
	v_mfma_f32_16x16x32_bf16 v[4:7], v[170:173], v[210:213], v[4:7]
	v_mfma_f32_16x16x32_bf16 v[0:3], v[178:181], v[210:213], v[0:3]
	v_mfma_f32_16x16x32_bf16 v[52:55], v[174:177], v[190:193], v[52:55]
	v_mfma_f32_16x16x32_bf16 v[48:51], v[182:185], v[190:193], v[48:51]
	v_mfma_f32_16x16x32_bf16 v[36:39], v[174:177], v[198:201], v[36:39]
	v_mfma_f32_16x16x32_bf16 v[32:35], v[182:185], v[198:201], v[32:35]
	v_mfma_f32_16x16x32_bf16 v[20:23], v[174:177], v[206:209], v[20:23]
	v_mfma_f32_16x16x32_bf16 v[16:19], v[182:185], v[206:209], v[16:19]
	v_mfma_f32_16x16x32_bf16 v[4:7], v[174:177], v[214:217], v[4:7]
	v_mfma_f32_16x16x32_bf16 v[0:3], v[182:185], v[214:217], v[0:3]
	s_setprio 0
	s_barrier
	s_add_i32 s3, 0, 0x18000
	v_add_u32_e32 v153, s3, v149
	s_add_i32 s44, 0, 0x1c000
	ds_read_b128 v[154:157], v153
	ds_read_b128 v[158:161], v153 offset:1024
	ds_read_b128 v[162:165], v153 offset:2048
	ds_read_b128 v[166:169], v153 offset:3072
	v_add_u32_e32 v153, s44, v149
	ds_read_b128 v[170:173], v153
	ds_read_b128 v[174:177], v153 offset:1024
	ds_read_b128 v[178:181], v153 offset:2048
	ds_read_b128 v[182:185], v153 offset:3072
	s_add_u32 s42, s92, 0x80000
	s_addc_u32 s43, s93, 0
	s_mov_b32 m0, s19
	ds_read_b128 v[186:189], v152 offset:32768
	ds_read_b128 v[190:193], v152 offset:33792
	ds_read_b128 v[194:197], v152 offset:34816
	ds_read_b128 v[198:201], v152 offset:35840
	ds_read_b128 v[202:205], v152 offset:36864
	ds_read_b128 v[206:209], v152 offset:37888
	ds_read_b128 v[210:213], v152 offset:38912
	ds_read_b128 v[214:217], v152 offset:39936
	global_load_lds_dwordx4 v128, s[42:43]
	v_lshl_add_u64 v[224:225], s[42:43], 0, v[132:133]
	s_mov_b32 m0, s25
	s_nop 0
	global_load_lds_dwordx4 v[224:225], off
	s_waitcnt vmcnt(8)
	s_waitcnt lgkmcnt(0)
	s_barrier
	s_setprio 1
	s_waitcnt lgkmcnt(0)
	v_mfma_f32_16x16x32_bf16 v[124:127], v[154:157], v[186:189], v[124:127]
	v_mfma_f32_16x16x32_bf16 v[120:123], v[162:165], v[186:189], v[120:123]
	v_mfma_f32_16x16x32_bf16 v[108:111], v[154:157], v[194:197], v[108:111]
	v_mfma_f32_16x16x32_bf16 v[104:107], v[162:165], v[194:197], v[104:107]
	v_mfma_f32_16x16x32_bf16 v[92:95], v[154:157], v[202:205], v[92:95]
	v_mfma_f32_16x16x32_bf16 v[88:91], v[162:165], v[202:205], v[88:91]
	v_mfma_f32_16x16x32_bf16 v[76:79], v[154:157], v[210:213], v[76:79]
	v_mfma_f32_16x16x32_bf16 v[72:75], v[162:165], v[210:213], v[72:75]
	v_mfma_f32_16x16x32_bf16 v[124:127], v[158:161], v[190:193], v[124:127]
	v_mfma_f32_16x16x32_bf16 v[120:123], v[166:169], v[190:193], v[120:123]
	v_mfma_f32_16x16x32_bf16 v[108:111], v[158:161], v[198:201], v[108:111]
	v_mfma_f32_16x16x32_bf16 v[104:107], v[166:169], v[198:201], v[104:107]
	v_mfma_f32_16x16x32_bf16 v[92:95], v[158:161], v[206:209], v[92:95]
	v_mfma_f32_16x16x32_bf16 v[88:91], v[166:169], v[206:209], v[88:91]
	v_mfma_f32_16x16x32_bf16 v[76:79], v[158:161], v[214:217], v[76:79]
	v_mfma_f32_16x16x32_bf16 v[72:75], v[166:169], v[214:217], v[72:75]
	s_setprio 0
	s_setprio 1
	v_mfma_f32_16x16x32_bf16 v[116:119], v[170:173], v[186:189], v[116:119]
	v_mfma_f32_16x16x32_bf16 v[112:115], v[178:181], v[186:189], v[112:115]
	v_mfma_f32_16x16x32_bf16 v[100:103], v[170:173], v[194:197], v[100:103]
	v_mfma_f32_16x16x32_bf16 v[96:99], v[178:181], v[194:197], v[96:99]
	v_mfma_f32_16x16x32_bf16 v[84:87], v[170:173], v[202:205], v[84:87]
	v_mfma_f32_16x16x32_bf16 v[80:83], v[178:181], v[202:205], v[80:83]
	v_mfma_f32_16x16x32_bf16 v[68:71], v[170:173], v[210:213], v[68:71]
	v_mfma_f32_16x16x32_bf16 v[64:67], v[178:181], v[210:213], v[64:67]
	v_mfma_f32_16x16x32_bf16 v[116:119], v[174:177], v[190:193], v[116:119]
	v_mfma_f32_16x16x32_bf16 v[112:115], v[182:185], v[190:193], v[112:115]
	v_mfma_f32_16x16x32_bf16 v[100:103], v[174:177], v[198:201], v[100:103]
	v_mfma_f32_16x16x32_bf16 v[96:99], v[182:185], v[198:201], v[96:99]
	v_mfma_f32_16x16x32_bf16 v[84:87], v[174:177], v[206:209], v[84:87]
	v_mfma_f32_16x16x32_bf16 v[80:83], v[182:185], v[206:209], v[80:83]
	v_mfma_f32_16x16x32_bf16 v[68:71], v[174:177], v[214:217], v[68:71]
	v_mfma_f32_16x16x32_bf16 v[64:67], v[182:185], v[214:217], v[64:67]
	s_setprio 0
	s_barrier
	s_add_i32 s3, s3, s8
	v_lshl_add_u64 v[146:147], v[146:147], 0, s[14:15]
	s_mov_b32 m0, s3
	ds_read_b128 v[186:189], v152 offset:49152
	ds_read_b128 v[190:193], v152 offset:50176
	ds_read_b128 v[194:197], v152 offset:51200
	ds_read_b128 v[198:201], v152 offset:52224
	ds_read_b128 v[202:205], v152 offset:53248
	ds_read_b128 v[206:209], v152 offset:54272
	ds_read_b128 v[210:213], v152 offset:55296
	ds_read_b128 v[214:217], v152 offset:56320
	global_load_lds_dwordx4 v[146:147], off
	s_add_i32 m0, s3, 0x2000
	s_add_u32 s42, s90, 0x80080
	v_lshl_add_u64 v[146:147], v[218:219], 0, s[14:15]
	s_addc_u32 s43, s91, 0
	s_add_i32 s3, s44, s8
	global_load_lds_dwordx4 v[146:147], off
	s_mov_b32 m0, s3
	s_nop 0
	global_load_lds_dwordx4 v130, s[42:43]
	s_add_i32 m0, s3, 0x2000
	s_nop 0
	global_load_lds_dwordx4 v134, s[42:43]
	v_lshl_add_u64 v[146:147], v[220:221], 0, s[14:15]
	s_mov_b32 m0, s30
	s_nop 0
	global_load_lds_dwordx4 v[146:147], off
	v_lshl_add_u64 v[146:147], v[222:223], 0, s[14:15]
	s_mov_b32 m0, s31
	s_nop 0
	global_load_lds_dwordx4 v[146:147], off
	s_waitcnt vmcnt(8)
	s_waitcnt lgkmcnt(0)
	s_barrier
	s_setprio 1
	s_waitcnt lgkmcnt(0)
	v_mfma_f32_16x16x32_bf16 v[60:63], v[154:157], v[186:189], v[60:63]
	v_mfma_f32_16x16x32_bf16 v[56:59], v[162:165], v[186:189], v[56:59]
	v_mfma_f32_16x16x32_bf16 v[44:47], v[154:157], v[194:197], v[44:47]
	v_mfma_f32_16x16x32_bf16 v[40:43], v[162:165], v[194:197], v[40:43]
	v_mfma_f32_16x16x32_bf16 v[28:31], v[154:157], v[202:205], v[28:31]
	v_mfma_f32_16x16x32_bf16 v[24:27], v[162:165], v[202:205], v[24:27]
	v_mfma_f32_16x16x32_bf16 v[12:15], v[154:157], v[210:213], v[12:15]
	v_mfma_f32_16x16x32_bf16 v[8:11], v[162:165], v[210:213], v[8:11]
	v_mfma_f32_16x16x32_bf16 v[60:63], v[158:161], v[190:193], v[60:63]
	v_mfma_f32_16x16x32_bf16 v[56:59], v[166:169], v[190:193], v[56:59]
	v_mfma_f32_16x16x32_bf16 v[44:47], v[158:161], v[198:201], v[44:47]
	v_mfma_f32_16x16x32_bf16 v[40:43], v[166:169], v[198:201], v[40:43]
	v_mfma_f32_16x16x32_bf16 v[28:31], v[158:161], v[206:209], v[28:31]
	v_mfma_f32_16x16x32_bf16 v[24:27], v[166:169], v[206:209], v[24:27]
	v_mfma_f32_16x16x32_bf16 v[12:15], v[158:161], v[214:217], v[12:15]
	v_mfma_f32_16x16x32_bf16 v[8:11], v[166:169], v[214:217], v[8:11]
	s_setprio 0
	s_setprio 1
	v_mfma_f32_16x16x32_bf16 v[52:55], v[170:173], v[186:189], v[52:55]
	v_mfma_f32_16x16x32_bf16 v[48:51], v[178:181], v[186:189], v[48:51]
	v_mfma_f32_16x16x32_bf16 v[36:39], v[170:173], v[194:197], v[36:39]
	v_mfma_f32_16x16x32_bf16 v[32:35], v[178:181], v[194:197], v[32:35]
	v_mfma_f32_16x16x32_bf16 v[20:23], v[170:173], v[202:205], v[20:23]
	v_mfma_f32_16x16x32_bf16 v[16:19], v[178:181], v[202:205], v[16:19]
	v_mfma_f32_16x16x32_bf16 v[4:7], v[170:173], v[210:213], v[4:7]
	v_mfma_f32_16x16x32_bf16 v[0:3], v[178:181], v[210:213], v[0:3]
	v_mfma_f32_16x16x32_bf16 v[52:55], v[174:177], v[190:193], v[52:55]
	v_mfma_f32_16x16x32_bf16 v[48:51], v[182:185], v[190:193], v[48:51]
	v_mfma_f32_16x16x32_bf16 v[36:39], v[174:177], v[198:201], v[36:39]
	v_mfma_f32_16x16x32_bf16 v[32:35], v[182:185], v[198:201], v[32:35]
	v_mfma_f32_16x16x32_bf16 v[20:23], v[174:177], v[206:209], v[20:23]
	v_mfma_f32_16x16x32_bf16 v[16:19], v[182:185], v[206:209], v[16:19]
	v_mfma_f32_16x16x32_bf16 v[4:7], v[174:177], v[214:217], v[4:7]
	v_mfma_f32_16x16x32_bf16 v[0:3], v[182:185], v[214:217], v[0:3]
	s_setprio 0
	s_barrier
	s_add_i32 s37, s37, 2
	s_add_u32 s88, s88, 0x100
	s_addc_u32 s89, s89, 0
	s_add_u32 s35, s35, 0x100
	s_addc_u32 s36, s36, 0
	s_cmp_gt_u32 s37, 29
	s_cbranch_scc0 .LBB0_1624
	s_and_b64 vcc, exec, s[16:17]
	s_cbranch_vccz .LBB0_1627
	s_barrier

.LBB0_1690:
	v_bfe_u32 v16, v14, 4, 2
	v_and_b32_e32 v15, 15, v14
	v_lshlrev_b32_e32 v17, 4, v16
	v_lshlrev_b32_e32 v14, 2, v14
	v_lshl_or_b32 v146, s0, 6, v15
	v_lshl_or_b32 v15, v15, 6, v17
	s_lshl_b32 s0, s0, 13
	v_and_b32_e32 v14, 32, v14
	v_bitop3_b32 v17, v15, s0, v14 bitop3:0xde
	s_lshl_b32 s0, s1, 5
	s_mov_b64 s[12:13], 0x80
	s_and_b32 s10, s0, 0x60
	s_add_i32 m0, s18, 0x18000
	v_lshl_add_u64 v[6:7], v[6:7], 0, s[12:13]
	s_sext_i32_i8 s24, s8
	s_lshl_b32 s0, s10, 7
	s_waitcnt vmcnt(2)
	s_barrier
	global_load_lds_dwordx4 v[6:7], off
	v_lshl_add_u64 v[4:5], v[4:5], 0, s[12:13]
	s_add_i32 m0, s18, 0x1a000
	s_add_i32 s8, s18, 0x8000
	s_add_i32 s48, s18, 0xa000
	v_bitop3_b32 v147, v15, s0, v14 bitop3:0xde
	global_load_lds_dwordx4 v[4:5], off
	v_lshl_add_u64 v[0:1], v[0:1], 0, s[12:13]
	s_mov_b32 m0, s8
	s_add_u32 s0, s88, 0x200080
	global_load_lds_dwordx4 v[0:1], off
	v_lshl_add_u64 v[0:1], v[2:3], 0, s[12:13]
	s_mov_b32 m0, s48
	s_addc_u32 s1, s89, 0
	global_load_lds_dwordx4 v[0:1], off
	s_add_i32 m0, s18, 0x1c000
	s_nop 0
	global_load_lds_dwordx4 v128, s[0:1]
	s_add_i32 m0, s18, 0x1e000
	s_cmpk_lt_u32 s3, 0x100
	global_load_lds_dwordx4 v130, s[0:1]
	v_lshlrev_b32_e32 v0, 17, v8
	v_and_b32_e32 v0, 0xfffc0000, v0
	v_lshl_add_u32 v0, v9, 14, v0
	v_and_b32_e32 v1, 1, v8
	v_lshl_or_b32 v0, v1, 6, v0
	v_lshl_add_u32 v132, v10, 1, v0
	v_lshlrev_b32_e32 v0, 17, v11
	v_and_b32_e32 v0, 0xfffc0000, v0
	s_waitcnt vmcnt(6)
	v_lshl_add_u32 v0, v12, 14, v0
	v_and_b32_e32 v1, 1, v11
	s_cselect_b64 s[14:15], -1, 0
	v_lshl_or_b32 v0, v1, 6, v0
	s_add_i32 s49, 0, 0x10000
	s_add_i32 s52, 0, 0x14000
	v_lshl_or_b32 v148, v16, 2, s10
	v_mov_b32_e32 v133, v129
	v_lshl_add_u32 v134, v13, 1, v0
	v_mov_b32_e32 v135, v129
	v_mov_b64_e32 v[136:137], 0x200
	v_mov_b64_e32 v[138:139], 0x1ff
	v_add_u32_e32 v149, s49, v147
	v_add_u32_e32 v150, s52, v147
	v_add_u32_e32 v151, 0, v17
	s_barrier
	s_branch .LBB0_1693

.LBB0_1700:
	ds_read_b128 v[140:143], v149
	ds_read_b128 v[152:155], v149 offset:1024
	ds_read_b128 v[156:159], v149 offset:2048
	ds_read_b128 v[160:163], v149 offset:3072
	ds_read_b128 v[164:167], v150
	ds_read_b128 v[168:171], v150 offset:1024
	ds_read_b128 v[172:175], v150 offset:2048
	ds_read_b128 v[176:179], v150 offset:3072
	s_add_u32 s3, s86, 0xffe00080
	s_addc_u32 s37, s87, -1
	s_cmpk_eq_i32 s36, 0x7c
	s_cselect_b32 s91, s0, s37
	s_cselect_b32 s90, s1, s3
	s_cselect_b32 s89, s17, s35
	s_cselect_b32 s88, s27, s33
	s_add_i32 m0, s18, 0xc000
	ds_read_b128 v[180:183], v151
	ds_read_b128 v[184:187], v151 offset:1024
	ds_read_b128 v[188:191], v151 offset:2048
	ds_read_b128 v[192:195], v151 offset:3072
	ds_read_b128 v[196:199], v151 offset:4096
	ds_read_b128 v[200:203], v151 offset:5120
	ds_read_b128 v[204:207], v151 offset:6144
	ds_read_b128 v[208:211], v151 offset:7168
	global_load_lds_dwordx4 v132, s[86:87]
	s_add_i32 m0, s18, 0xe000
	s_nop 0
	global_load_lds_dwordx4 v134, s[86:87]
	s_waitcnt vmcnt(8)
	s_waitcnt lgkmcnt(0)
	s_barrier
	s_setprio 1
	s_waitcnt lgkmcnt(0)
	v_mfma_f32_16x16x32_bf16 v[124:127], v[140:143], v[180:183], v[124:127]
	v_mfma_f32_16x16x32_bf16 v[120:123], v[156:159], v[180:183], v[120:123]
	v_mfma_f32_16x16x32_bf16 v[112:115], v[140:143], v[188:191], v[112:115]
	v_mfma_f32_16x16x32_bf16 v[104:107], v[156:159], v[188:191], v[104:107]
	v_mfma_f32_16x16x32_bf16 v[96:99], v[140:143], v[196:199], v[96:99]
	v_mfma_f32_16x16x32_bf16 v[88:91], v[156:159], v[196:199], v[88:91]
	v_mfma_f32_16x16x32_bf16 v[80:83], v[140:143], v[204:207], v[80:83]
	v_mfma_f32_16x16x32_bf16 v[72:75], v[156:159], v[204:207], v[72:75]
	v_mfma_f32_16x16x32_bf16 v[124:127], v[152:155], v[184:187], v[124:127]
	v_mfma_f32_16x16x32_bf16 v[120:123], v[160:163], v[184:187], v[120:123]
	v_mfma_f32_16x16x32_bf16 v[112:115], v[152:155], v[192:195], v[112:115]
	v_mfma_f32_16x16x32_bf16 v[104:107], v[160:163], v[192:195], v[104:107]
	v_mfma_f32_16x16x32_bf16 v[96:99], v[152:155], v[200:203], v[96:99]
	v_mfma_f32_16x16x32_bf16 v[88:91], v[160:163], v[200:203], v[88:91]
	v_mfma_f32_16x16x32_bf16 v[80:83], v[152:155], v[208:211], v[80:83]
	v_mfma_f32_16x16x32_bf16 v[72:75], v[160:163], v[208:211], v[72:75]
	s_setprio 0
	s_setprio 1
	v_mfma_f32_16x16x32_bf16 v[116:119], v[164:167], v[180:183], v[116:119]
	v_mfma_f32_16x16x32_bf16 v[108:111], v[172:175], v[180:183], v[108:111]
	v_mfma_f32_16x16x32_bf16 v[100:103], v[164:167], v[188:191], v[100:103]
	v_mfma_f32_16x16x32_bf16 v[92:95], v[172:175], v[188:191], v[92:95]
	v_mfma_f32_16x16x32_bf16 v[84:87], v[164:167], v[196:199], v[84:87]
	v_mfma_f32_16x16x32_bf16 v[76:79], v[172:175], v[196:199], v[76:79]
	v_mfma_f32_16x16x32_bf16 v[68:71], v[164:167], v[204:207], v[68:71]
	v_mfma_f32_16x16x32_bf16 v[64:67], v[172:175], v[204:207], v[64:67]
	v_mfma_f32_16x16x32_bf16 v[116:119], v[168:171], v[184:187], v[116:119]
	v_mfma_f32_16x16x32_bf16 v[108:111], v[176:179], v[184:187], v[108:111]
	v_mfma_f32_16x16x32_bf16 v[100:103], v[168:171], v[192:195], v[100:103]
	v_mfma_f32_16x16x32_bf16 v[92:95], v[176:179], v[192:195], v[92:95]
	v_mfma_f32_16x16x32_bf16 v[84:87], v[168:171], v[200:203], v[84:87]
	v_mfma_f32_16x16x32_bf16 v[76:79], v[176:179], v[200:203], v[76:79]
	v_mfma_f32_16x16x32_bf16 v[68:71], v[168:171], v[208:211], v[68:71]
	v_mfma_f32_16x16x32_bf16 v[64:67], v[176:179], v[208:211], v[64:67]
	s_setprio 0
	s_barrier
	s_add_i32 s3, s49, s9
	v_lshl_add_u64 v[144:145], s[88:89], 0, v[128:129]
	s_mov_b32 m0, s3
	ds_read_b128 v[180:183], v151 offset:16384
	ds_read_b128 v[184:187], v151 offset:17408
	ds_read_b128 v[188:191], v151 offset:18432
	ds_read_b128 v[192:195], v151 offset:19456
	ds_read_b128 v[196:199], v151 offset:20480
	ds_read_b128 v[200:203], v151 offset:21504
	ds_read_b128 v[204:207], v151 offset:22528
	ds_read_b128 v[208:211], v151 offset:23552
	global_load_lds_dwordx4 v[144:145], off
	s_add_i32 m0, s3, 0x2000
	s_add_u32 s42, s88, 0x200000
	v_lshl_add_u64 v[212:213], s[88:89], 0, v[130:131]
	s_addc_u32 s43, s89, 0
	s_add_i32 s3, s52, s9
	global_load_lds_dwordx4 v[212:213], off
	s_mov_b32 m0, s3
	v_lshl_add_u64 v[216:217], s[90:91], 0, v[130:131]
	global_load_lds_dwordx4 v128, s[42:43]
	s_add_i32 m0, s3, 0x2000
	s_nop 0
	global_load_lds_dwordx4 v130, s[42:43]
	v_lshl_add_u64 v[214:215], s[90:91], 0, v[128:129]
	s_mov_b32 m0, s18
	s_nop 0
	global_load_lds_dwordx4 v[214:215], off
	s_mov_b32 m0, s19
	s_nop 0
	global_load_lds_dwordx4 v[216:217], off
	s_waitcnt vmcnt(8)
	s_waitcnt lgkmcnt(0)
	s_barrier
	s_setprio 1
	s_waitcnt lgkmcnt(0)
	v_mfma_f32_16x16x32_bf16 v[60:63], v[140:143], v[180:183], v[60:63]
	v_mfma_f32_16x16x32_bf16 v[56:59], v[156:159], v[180:183], v[56:59]
	v_mfma_f32_16x16x32_bf16 v[48:51], v[140:143], v[188:191], v[48:51]
	v_mfma_f32_16x16x32_bf16 v[40:43], v[156:159], v[188:191], v[40:43]
	v_mfma_f32_16x16x32_bf16 v[32:35], v[140:143], v[196:199], v[32:35]
	v_mfma_f32_16x16x32_bf16 v[24:27], v[156:159], v[196:199], v[24:27]
	v_mfma_f32_16x16x32_bf16 v[16:19], v[140:143], v[204:207], v[16:19]
	v_mfma_f32_16x16x32_bf16 v[8:11], v[156:159], v[204:207], v[8:11]
	v_mfma_f32_16x16x32_bf16 v[60:63], v[152:155], v[184:187], v[60:63]
	v_mfma_f32_16x16x32_bf16 v[56:59], v[160:163], v[184:187], v[56:59]
	v_mfma_f32_16x16x32_bf16 v[48:51], v[152:155], v[192:195], v[48:51]
	v_mfma_f32_16x16x32_bf16 v[40:43], v[160:163], v[192:195], v[40:43]
	v_mfma_f32_16x16x32_bf16 v[32:35], v[152:155], v[200:203], v[32:35]
	v_mfma_f32_16x16x32_bf16 v[24:27], v[160:163], v[200:203], v[24:27]
	v_mfma_f32_16x16x32_bf16 v[16:19], v[152:155], v[208:211], v[16:19]
	v_mfma_f32_16x16x32_bf16 v[8:11], v[160:163], v[208:211], v[8:11]
	s_setprio 0
	s_setprio 1
	v_mfma_f32_16x16x32_bf16 v[52:55], v[164:167], v[180:183], v[52:55]
	v_mfma_f32_16x16x32_bf16 v[44:47], v[172:175], v[180:183], v[44:47]
	v_mfma_f32_16x16x32_bf16 v[36:39], v[164:167], v[188:191], v[36:39]
	v_mfma_f32_16x16x32_bf16 v[28:31], v[172:175], v[188:191], v[28:31]
	v_mfma_f32_16x16x32_bf16 v[20:23], v[164:167], v[196:199], v[20:23]
	v_mfma_f32_16x16x32_bf16 v[12:15], v[172:175], v[196:199], v[12:15]
	v_mfma_f32_16x16x32_bf16 v[4:7], v[164:167], v[204:207], v[4:7]
	v_mfma_f32_16x16x32_bf16 v[0:3], v[172:175], v[204:207], v[0:3]
	v_mfma_f32_16x16x32_bf16 v[52:55], v[168:171], v[184:187], v[52:55]
	v_mfma_f32_16x16x32_bf16 v[44:47], v[176:179], v[184:187], v[44:47]
	v_mfma_f32_16x16x32_bf16 v[36:39], v[168:171], v[192:195], v[36:39]
	v_mfma_f32_16x16x32_bf16 v[28:31], v[176:179], v[192:195], v[28:31]
	v_mfma_f32_16x16x32_bf16 v[20:23], v[168:171], v[200:203], v[20:23]
	v_mfma_f32_16x16x32_bf16 v[12:15], v[176:179], v[200:203], v[12:15]
	v_mfma_f32_16x16x32_bf16 v[4:7], v[168:171], v[208:211], v[4:7]
	v_mfma_f32_16x16x32_bf16 v[0:3], v[176:179], v[208:211], v[0:3]
	s_setprio 0
	s_barrier
	s_add_i32 s3, 0, 0x18000
	s_add_i32 s37, 0, 0x1c000
	v_add_u32_e32 v160, s3, v147
	v_add_u32_e32 v176, s37, v147
	ds_read_b128 v[140:143], v160
	ds_read_b128 v[152:155], v160 offset:1024
	ds_read_b128 v[156:159], v160 offset:2048
	ds_read_b128 v[160:163], v160 offset:3072
	ds_read_b128 v[164:167], v176
	ds_read_b128 v[168:171], v176 offset:1024
	ds_read_b128 v[172:175], v176 offset:2048
	ds_read_b128 v[176:179], v176 offset:3072
	s_add_u32 s42, s90, 0x200000
	s_addc_u32 s43, s91, 0
	s_mov_b32 m0, s25
	ds_read_b128 v[180:183], v151 offset:32768
	ds_read_b128 v[184:187], v151 offset:33792
	ds_read_b128 v[188:191], v151 offset:34816
	ds_read_b128 v[192:195], v151 offset:35840
	ds_read_b128 v[196:199], v151 offset:36864
	ds_read_b128 v[200:203], v151 offset:37888
	ds_read_b128 v[204:207], v151 offset:38912
	ds_read_b128 v[208:211], v151 offset:39936
	global_load_lds_dwordx4 v128, s[42:43]
	v_lshl_add_u64 v[218:219], s[42:43], 0, v[130:131]
	s_mov_b32 m0, s30
	s_nop 0
	global_load_lds_dwordx4 v[218:219], off
	s_waitcnt vmcnt(8)
	s_waitcnt lgkmcnt(0)
	s_barrier
	s_setprio 1
	s_waitcnt lgkmcnt(0)
	v_mfma_f32_16x16x32_bf16 v[124:127], v[140:143], v[180:183], v[124:127]
	v_mfma_f32_16x16x32_bf16 v[120:123], v[156:159], v[180:183], v[120:123]
	v_mfma_f32_16x16x32_bf16 v[112:115], v[140:143], v[188:191], v[112:115]
	v_mfma_f32_16x16x32_bf16 v[104:107], v[156:159], v[188:191], v[104:107]
	v_mfma_f32_16x16x32_bf16 v[96:99], v[140:143], v[196:199], v[96:99]
	v_mfma_f32_16x16x32_bf16 v[88:91], v[156:159], v[196:199], v[88:91]
	v_mfma_f32_16x16x32_bf16 v[80:83], v[140:143], v[204:207], v[80:83]
	v_mfma_f32_16x16x32_bf16 v[72:75], v[156:159], v[204:207], v[72:75]
	v_mfma_f32_16x16x32_bf16 v[124:127], v[152:155], v[184:187], v[124:127]
	v_mfma_f32_16x16x32_bf16 v[120:123], v[160:163], v[184:187], v[120:123]
	v_mfma_f32_16x16x32_bf16 v[112:115], v[152:155], v[192:195], v[112:115]
	v_mfma_f32_16x16x32_bf16 v[104:107], v[160:163], v[192:195], v[104:107]
	v_mfma_f32_16x16x32_bf16 v[96:99], v[152:155], v[200:203], v[96:99]
	v_mfma_f32_16x16x32_bf16 v[88:91], v[160:163], v[200:203], v[88:91]
	v_mfma_f32_16x16x32_bf16 v[80:83], v[152:155], v[208:211], v[80:83]
	v_mfma_f32_16x16x32_bf16 v[72:75], v[160:163], v[208:211], v[72:75]
	s_setprio 0
	s_setprio 1
	v_mfma_f32_16x16x32_bf16 v[116:119], v[164:167], v[180:183], v[116:119]
	v_mfma_f32_16x16x32_bf16 v[108:111], v[172:175], v[180:183], v[108:111]
	v_mfma_f32_16x16x32_bf16 v[100:103], v[164:167], v[188:191], v[100:103]
	v_mfma_f32_16x16x32_bf16 v[92:95], v[172:175], v[188:191], v[92:95]
	v_mfma_f32_16x16x32_bf16 v[84:87], v[164:167], v[196:199], v[84:87]
	v_mfma_f32_16x16x32_bf16 v[76:79], v[172:175], v[196:199], v[76:79]
	v_mfma_f32_16x16x32_bf16 v[68:71], v[164:167], v[204:207], v[68:71]
	v_mfma_f32_16x16x32_bf16 v[64:67], v[172:175], v[204:207], v[64:67]
	v_mfma_f32_16x16x32_bf16 v[116:119], v[168:171], v[184:187], v[116:119]
	v_mfma_f32_16x16x32_bf16 v[108:111], v[176:179], v[184:187], v[108:111]
	v_mfma_f32_16x16x32_bf16 v[100:103], v[168:171], v[192:195], v[100:103]
	v_mfma_f32_16x16x32_bf16 v[92:95], v[176:179], v[192:195], v[92:95]
	v_mfma_f32_16x16x32_bf16 v[84:87], v[168:171], v[200:203], v[84:87]
	v_mfma_f32_16x16x32_bf16 v[76:79], v[176:179], v[200:203], v[76:79]
	v_mfma_f32_16x16x32_bf16 v[68:71], v[168:171], v[208:211], v[68:71]
	v_mfma_f32_16x16x32_bf16 v[64:67], v[176:179], v[208:211], v[64:67]
	s_setprio 0
	s_barrier
	s_add_i32 s3, s3, s9
	v_lshl_add_u64 v[144:145], v[144:145], 0, s[12:13]
	s_mov_b32 m0, s3
	ds_read_b128 v[180:183], v151 offset:49152
	ds_read_b128 v[184:187], v151 offset:50176
	ds_read_b128 v[188:191], v151 offset:51200
	ds_read_b128 v[192:195], v151 offset:52224
	ds_read_b128 v[196:199], v151 offset:53248
	ds_read_b128 v[200:203], v151 offset:54272
	ds_read_b128 v[204:207], v151 offset:55296
	ds_read_b128 v[208:211], v151 offset:56320
	global_load_lds_dwordx4 v[144:145], off
	s_add_i32 m0, s3, 0x2000
	s_add_u32 s42, s88, 0x200080
	v_lshl_add_u64 v[144:145], v[212:213], 0, s[12:13]
	s_addc_u32 s43, s89, 0
	s_add_i32 s3, s37, s9
	global_load_lds_dwordx4 v[144:145], off
	s_mov_b32 m0, s3
	s_nop 0
	global_load_lds_dwordx4 v128, s[42:43]
	s_add_i32 m0, s3, 0x2000
	s_nop 0
	global_load_lds_dwordx4 v130, s[42:43]
	v_lshl_add_u64 v[144:145], v[214:215], 0, s[12:13]
	s_mov_b32 m0, s8
	s_nop 0
	global_load_lds_dwordx4 v[144:145], off
	v_lshl_add_u64 v[144:145], v[216:217], 0, s[12:13]
	s_mov_b32 m0, s48
	s_nop 0
	global_load_lds_dwordx4 v[144:145], off
	s_waitcnt vmcnt(8)
	s_waitcnt lgkmcnt(0)
	s_barrier
	s_setprio 1
	s_waitcnt lgkmcnt(0)
	v_mfma_f32_16x16x32_bf16 v[60:63], v[140:143], v[180:183], v[60:63]
	v_mfma_f32_16x16x32_bf16 v[56:59], v[156:159], v[180:183], v[56:59]
	v_mfma_f32_16x16x32_bf16 v[48:51], v[140:143], v[188:191], v[48:51]
	v_mfma_f32_16x16x32_bf16 v[40:43], v[156:159], v[188:191], v[40:43]
	v_mfma_f32_16x16x32_bf16 v[32:35], v[140:143], v[196:199], v[32:35]
	v_mfma_f32_16x16x32_bf16 v[24:27], v[156:159], v[196:199], v[24:27]
	v_mfma_f32_16x16x32_bf16 v[16:19], v[140:143], v[204:207], v[16:19]
	v_mfma_f32_16x16x32_bf16 v[8:11], v[156:159], v[204:207], v[8:11]
	v_mfma_f32_16x16x32_bf16 v[60:63], v[152:155], v[184:187], v[60:63]
	v_mfma_f32_16x16x32_bf16 v[56:59], v[160:163], v[184:187], v[56:59]
	v_mfma_f32_16x16x32_bf16 v[48:51], v[152:155], v[192:195], v[48:51]
	v_mfma_f32_16x16x32_bf16 v[40:43], v[160:163], v[192:195], v[40:43]
	v_mfma_f32_16x16x32_bf16 v[32:35], v[152:155], v[200:203], v[32:35]
	v_mfma_f32_16x16x32_bf16 v[24:27], v[160:163], v[200:203], v[24:27]
	v_mfma_f32_16x16x32_bf16 v[16:19], v[152:155], v[208:211], v[16:19]
	v_mfma_f32_16x16x32_bf16 v[8:11], v[160:163], v[208:211], v[8:11]
	s_setprio 0
	s_setprio 1
	v_mfma_f32_16x16x32_bf16 v[52:55], v[164:167], v[180:183], v[52:55]
	v_mfma_f32_16x16x32_bf16 v[44:47], v[172:175], v[180:183], v[44:47]
	v_mfma_f32_16x16x32_bf16 v[36:39], v[164:167], v[188:191], v[36:39]
	v_mfma_f32_16x16x32_bf16 v[28:31], v[172:175], v[188:191], v[28:31]
	v_mfma_f32_16x16x32_bf16 v[20:23], v[164:167], v[196:199], v[20:23]
	v_mfma_f32_16x16x32_bf16 v[12:15], v[172:175], v[196:199], v[12:15]
	v_mfma_f32_16x16x32_bf16 v[4:7], v[164:167], v[204:207], v[4:7]
	v_mfma_f32_16x16x32_bf16 v[0:3], v[172:175], v[204:207], v[0:3]
	v_mfma_f32_16x16x32_bf16 v[52:55], v[168:171], v[184:187], v[52:55]
	v_mfma_f32_16x16x32_bf16 v[44:47], v[176:179], v[184:187], v[44:47]
	v_mfma_f32_16x16x32_bf16 v[36:39], v[168:171], v[192:195], v[36:39]
	v_mfma_f32_16x16x32_bf16 v[28:31], v[176:179], v[192:195], v[28:31]
	v_mfma_f32_16x16x32_bf16 v[20:23], v[168:171], v[200:203], v[20:23]
	v_mfma_f32_16x16x32_bf16 v[12:15], v[176:179], v[200:203], v[12:15]
	v_mfma_f32_16x16x32_bf16 v[4:7], v[168:171], v[208:211], v[4:7]
	v_mfma_f32_16x16x32_bf16 v[0:3], v[176:179], v[208:211], v[0:3]
	s_setprio 0
	s_barrier
	s_add_i32 s36, s36, 2
	s_add_u32 s86, s86, 0x100
	s_addc_u32 s87, s87, 0
	s_add_u32 s33, s33, 0x100
	s_addc_u32 s35, s35, 0
	s_cmpk_gt_u32 s36, 0x7d
	s_cbranch_scc0 .LBB0_1700
	s_and_b64 vcc, exec, s[14:15]
	s_cbranch_vccz .LBB0_1703
	s_barrier

.LBB0_1767:
	s_mov_b64 s[82:83], 0x80
	s_and_b32 s1, s1, 3
	s_add_i32 m0, s48, 0x18000
	v_lshl_add_u64 v[6:7], v[6:7], 0, s[82:83]
	s_lshl_b32 s8, s3, 13
	s_lshl_b32 s9, s1, 5
	s_lshl_b32 s10, s1, 12
	s_waitcnt vmcnt(2)
	s_barrier
	global_load_lds_dwordx4 v[6:7], off
	v_lshl_add_u64 v[4:5], v[4:5], 0, s[82:83]
	s_add_i32 m0, s48, 0x1a000
	s_add_i32 s56, s48, 0x8000
	s_add_i32 s57, s48, 0xa000
	global_load_lds_dwordx4 v[4:5], off
	v_lshl_add_u64 v[0:1], v[0:1], 0, s[82:83]
	s_mov_b32 m0, s56
	s_add_u32 s6, s96, 0x80080
	global_load_lds_dwordx4 v[0:1], off
	v_lshl_add_u64 v[0:1], v[2:3], 0, s[82:83]
	s_mov_b32 m0, s57
	s_addc_u32 s7, s97, 0
	global_load_lds_dwordx4 v[0:1], off
	s_add_i32 m0, s48, 0x1c000
	s_nop 0
	global_load_lds_dwordx4 v138, s[6:7]
	s_add_i32 m0, s48, 0x1e000
	v_bfe_u32 v2, v8, 4, 2
	global_load_lds_dwordx4 v142, s[6:7]
	v_and_b32_e32 v1, 15, v8
	v_lshlrev_b32_e32 v3, 4, v2
	v_lshl_or_b32 v164, s3, 6, v1
	v_lshl_or_b32 v1, v1, 6, v3
	v_lshlrev_b32_e32 v3, 2, v8
	v_and_b32_e32 v3, 32, v3
	v_bitop3_b32 v4, v1, s8, v3 bitop3:0xde
	v_bitop3_b32 v165, v1, s10, v3 bitop3:0xde
	v_lshlrev_b32_e32 v1, 1, v8
	v_and_b32_e32 v144, 32, v1
	v_lshlrev_b32_e32 v1, 15, v9
	v_and_b32_e32 v1, 0xffff0000, v1
	v_lshlrev_b32_e32 v0, 3, v2
	v_cmp_gt_u32_e64 s[6:7], 2, v2
	v_cmp_eq_u32_e64 s[10:11], 0, v2
	v_lshl_add_u32 v1, v10, 12, v1
	v_and_b32_e32 v2, 1, v9
	v_lshl_or_b32 v1, v2, 6, v1
	s_cmpk_lt_u32 s0, 0x100
	v_lshl_add_u32 v148, v11, 1, v1
	v_lshlrev_b32_e32 v1, 15, v12
	s_cselect_b64 s[84:85], -1, 0
	s_bitcmp0_b32 s0, 6
	v_and_b32_e32 v1, 0xffff0000, v1
	s_waitcnt vmcnt(6)
	s_cselect_b64 s[86:87], -1, 0
	s_cmp_eq_u32 s1, 0
	v_readlane_b32 s0, v249, 33
	v_lshl_add_u32 v1, v13, 12, v1
	v_and_b32_e32 v2, 1, v12
	s_cselect_b64 s[88:89], -1, 0
	v_readlane_b32 s1, v249, 34
	v_lshl_or_b32 v1, v2, 6, v1
	s_add_i32 s76, 0, 0x10000
	s_add_i32 s77, 0, 0x14000
	v_or_b32_e32 v166, 16, v164
	v_or_b32_e32 v167, 32, v164
	v_or_b32_e32 v168, 48, v164
	v_add_u32_e32 v169, 0x80, v164
	v_add_u32_e32 v170, 0x90, v164
	v_add_u32_e32 v171, 0xa0, v164
	v_add_u32_e32 v172, 0xb0, v164
	v_lshl_add_u64 v[146:147], s[0:1], 0, v[144:145]
	v_mov_b32_e32 v149, v145
	v_lshl_add_u32 v150, v14, 1, v1
	v_mov_b32_e32 v151, v145
	v_mov_b64_e32 v[152:153], 0xb80
	v_mov_b64_e32 v[154:155], 0xb7f
	v_add_u32_e32 v173, s76, v165
	v_add_u32_e32 v174, s77, v165
	v_add_u32_e32 v175, 0, v4
	s_movk_i32 s68, 0x5c00
	s_lshl_b32 s78, s9, 1
	v_lshlrev_b32_e32 v156, 1, v0
	v_mov_b32_e32 v176, 0x3e0293ee
	v_mov_b32_e32 v177, 0x3e38aa3b
	s_mov_b32 s69, s79
	s_barrier
	s_branch .LBB0_1770

.LBB0_1773:
	ds_read_b128 v[128:131], v173
	ds_read_b128 v[132:135], v173 offset:1024
	ds_read_b128 v[158:161], v173 offset:2048
	ds_read_b128 v[178:181], v173 offset:3072
	ds_read_b128 v[182:185], v174
	ds_read_b128 v[186:189], v174 offset:1024
	ds_read_b128 v[190:193], v174 offset:2048
	ds_read_b128 v[194:197], v174 offset:3072
	s_add_u32 s3, s34, 0xfff80080
	s_addc_u32 s19, s35, -1
	s_cmp_eq_u32 s18, 28
	s_cselect_b32 vcc_hi, s0, s19
	s_cselect_b32 vcc_lo, s1, s3
	s_cselect_b32 s97, s8, s17
	s_cselect_b32 s96, s9, s15
	s_add_i32 m0, s48, 0xc000
	ds_read_b128 v[198:201], v175
	ds_read_b128 v[202:205], v175 offset:1024
	ds_read_b128 v[206:209], v175 offset:2048
	ds_read_b128 v[210:213], v175 offset:3072
	ds_read_b128 v[214:217], v175 offset:4096
	ds_read_b128 v[218:221], v175 offset:5120
	ds_read_b128 v[222:225], v175 offset:6144
	ds_read_b128 v[230:233], v175 offset:7168
	global_load_lds_dwordx4 v148, s[34:35]
	s_add_i32 m0, s48, 0xe000
	s_nop 0
	global_load_lds_dwordx4 v150, s[34:35]
	s_waitcnt vmcnt(8)
	s_waitcnt lgkmcnt(0)
	s_barrier
	s_setprio 1
	s_waitcnt lgkmcnt(0)
	v_mfma_f32_16x16x32_bf16 v[124:127], v[128:131], v[198:201], v[124:127]
	v_mfma_f32_16x16x32_bf16 v[120:123], v[158:161], v[198:201], v[120:123]
	v_mfma_f32_16x16x32_bf16 v[108:111], v[128:131], v[206:209], v[108:111]
	v_mfma_f32_16x16x32_bf16 v[104:107], v[158:161], v[206:209], v[104:107]
	v_mfma_f32_16x16x32_bf16 v[92:95], v[128:131], v[214:217], v[92:95]
	v_mfma_f32_16x16x32_bf16 v[88:91], v[158:161], v[214:217], v[88:91]
	v_mfma_f32_16x16x32_bf16 v[76:79], v[128:131], v[222:225], v[76:79]
	v_mfma_f32_16x16x32_bf16 v[72:75], v[158:161], v[222:225], v[72:75]
	v_mfma_f32_16x16x32_bf16 v[124:127], v[132:135], v[202:205], v[124:127]
	v_mfma_f32_16x16x32_bf16 v[120:123], v[178:181], v[202:205], v[120:123]
	v_mfma_f32_16x16x32_bf16 v[108:111], v[132:135], v[210:213], v[108:111]
	v_mfma_f32_16x16x32_bf16 v[104:107], v[178:181], v[210:213], v[104:107]
	v_mfma_f32_16x16x32_bf16 v[92:95], v[132:135], v[218:221], v[92:95]
	v_mfma_f32_16x16x32_bf16 v[88:91], v[178:181], v[218:221], v[88:91]
	v_mfma_f32_16x16x32_bf16 v[76:79], v[132:135], v[230:233], v[76:79]
	v_mfma_f32_16x16x32_bf16 v[72:75], v[178:181], v[230:233], v[72:75]
	s_setprio 0
	s_setprio 1
	v_mfma_f32_16x16x32_bf16 v[116:119], v[182:185], v[198:201], v[116:119]
	v_mfma_f32_16x16x32_bf16 v[112:115], v[190:193], v[198:201], v[112:115]
	v_mfma_f32_16x16x32_bf16 v[100:103], v[182:185], v[206:209], v[100:103]
	v_mfma_f32_16x16x32_bf16 v[96:99], v[190:193], v[206:209], v[96:99]
	v_mfma_f32_16x16x32_bf16 v[84:87], v[182:185], v[214:217], v[84:87]
	v_mfma_f32_16x16x32_bf16 v[80:83], v[190:193], v[214:217], v[80:83]
	v_mfma_f32_16x16x32_bf16 v[68:71], v[182:185], v[222:225], v[68:71]
	v_mfma_f32_16x16x32_bf16 v[64:67], v[190:193], v[222:225], v[64:67]
	v_mfma_f32_16x16x32_bf16 v[116:119], v[186:189], v[202:205], v[116:119]
	v_mfma_f32_16x16x32_bf16 v[112:115], v[194:197], v[202:205], v[112:115]
	v_mfma_f32_16x16x32_bf16 v[100:103], v[186:189], v[210:213], v[100:103]
	v_mfma_f32_16x16x32_bf16 v[96:99], v[194:197], v[210:213], v[96:99]
	v_mfma_f32_16x16x32_bf16 v[84:87], v[186:189], v[218:221], v[84:87]
	v_mfma_f32_16x16x32_bf16 v[80:83], v[194:197], v[218:221], v[80:83]
	v_mfma_f32_16x16x32_bf16 v[68:71], v[186:189], v[230:233], v[68:71]
	v_mfma_f32_16x16x32_bf16 v[64:67], v[194:197], v[230:233], v[64:67]
	s_setprio 0
	s_barrier
	s_add_i32 s3, s76, s25
	v_lshl_add_u64 v[162:163], s[96:97], 0, v[138:139]
	s_mov_b32 m0, s3
	ds_read_b128 v[198:201], v175 offset:16384
	ds_read_b128 v[202:205], v175 offset:17408
	ds_read_b128 v[206:209], v175 offset:18432
	ds_read_b128 v[210:213], v175 offset:19456
	ds_read_b128 v[214:217], v175 offset:20480
	ds_read_b128 v[218:221], v175 offset:21504
	ds_read_b128 v[222:225], v175 offset:22528
	ds_read_b128 v[230:233], v175 offset:23552
	global_load_lds_dwordx4 v[162:163], off
	s_add_i32 m0, s3, 0x2000
	s_add_u32 s36, s96, 0x80000
	v_lshl_add_u64 v[226:227], s[96:97], 0, v[142:143]
	s_addc_u32 s37, s97, 0
	s_add_i32 s3, s77, s25
	global_load_lds_dwordx4 v[226:227], off
	s_mov_b32 m0, s3
	v_lshl_add_u64 v[236:237], vcc, 0, v[140:141]
	global_load_lds_dwordx4 v138, s[36:37]
	s_add_i32 m0, s3, 0x2000
	s_nop 0
	global_load_lds_dwordx4 v142, s[36:37]
	v_lshl_add_u64 v[234:235], vcc, 0, v[136:137]
	s_mov_b32 m0, s48
	s_nop 0
	global_load_lds_dwordx4 v[234:235], off
	s_mov_b32 m0, s49
	s_nop 0
	global_load_lds_dwordx4 v[236:237], off
	s_waitcnt vmcnt(8)
	s_waitcnt lgkmcnt(0)
	s_barrier
	s_setprio 1
	s_waitcnt lgkmcnt(0)
	v_mfma_f32_16x16x32_bf16 v[60:63], v[128:131], v[198:201], v[60:63]
	v_mfma_f32_16x16x32_bf16 v[56:59], v[158:161], v[198:201], v[56:59]
	v_mfma_f32_16x16x32_bf16 v[44:47], v[128:131], v[206:209], v[44:47]
	v_mfma_f32_16x16x32_bf16 v[40:43], v[158:161], v[206:209], v[40:43]
	v_mfma_f32_16x16x32_bf16 v[28:31], v[128:131], v[214:217], v[28:31]
	v_mfma_f32_16x16x32_bf16 v[24:27], v[158:161], v[214:217], v[24:27]
	v_mfma_f32_16x16x32_bf16 v[12:15], v[128:131], v[222:225], v[12:15]
	v_mfma_f32_16x16x32_bf16 v[8:11], v[158:161], v[222:225], v[8:11]
	v_mfma_f32_16x16x32_bf16 v[60:63], v[132:135], v[202:205], v[60:63]
	v_mfma_f32_16x16x32_bf16 v[56:59], v[178:181], v[202:205], v[56:59]
	v_mfma_f32_16x16x32_bf16 v[44:47], v[132:135], v[210:213], v[44:47]
	v_mfma_f32_16x16x32_bf16 v[40:43], v[178:181], v[210:213], v[40:43]
	v_mfma_f32_16x16x32_bf16 v[28:31], v[132:135], v[218:221], v[28:31]
	v_mfma_f32_16x16x32_bf16 v[24:27], v[178:181], v[218:221], v[24:27]
	v_mfma_f32_16x16x32_bf16 v[12:15], v[132:135], v[230:233], v[12:15]
	v_mfma_f32_16x16x32_bf16 v[8:11], v[178:181], v[230:233], v[8:11]
	s_setprio 0
	s_setprio 1
	v_mfma_f32_16x16x32_bf16 v[52:55], v[182:185], v[198:201], v[52:55]
	v_mfma_f32_16x16x32_bf16 v[48:51], v[190:193], v[198:201], v[48:51]
	v_mfma_f32_16x16x32_bf16 v[36:39], v[182:185], v[206:209], v[36:39]
	v_mfma_f32_16x16x32_bf16 v[32:35], v[190:193], v[206:209], v[32:35]
	v_mfma_f32_16x16x32_bf16 v[20:23], v[182:185], v[214:217], v[20:23]
	v_mfma_f32_16x16x32_bf16 v[16:19], v[190:193], v[214:217], v[16:19]
	v_mfma_f32_16x16x32_bf16 v[4:7], v[182:185], v[222:225], v[4:7]
	v_mfma_f32_16x16x32_bf16 v[0:3], v[190:193], v[222:225], v[0:3]
	v_mfma_f32_16x16x32_bf16 v[52:55], v[186:189], v[202:205], v[52:55]
	v_mfma_f32_16x16x32_bf16 v[48:51], v[194:197], v[202:205], v[48:51]
	v_mfma_f32_16x16x32_bf16 v[36:39], v[186:189], v[210:213], v[36:39]
	v_mfma_f32_16x16x32_bf16 v[32:35], v[194:197], v[210:213], v[32:35]
	v_mfma_f32_16x16x32_bf16 v[20:23], v[186:189], v[218:221], v[20:23]
	v_mfma_f32_16x16x32_bf16 v[16:19], v[194:197], v[218:221], v[16:19]
	v_mfma_f32_16x16x32_bf16 v[4:7], v[186:189], v[230:233], v[4:7]
	v_mfma_f32_16x16x32_bf16 v[0:3], v[194:197], v[230:233], v[0:3]
	s_setprio 0
	s_barrier
	s_add_i32 s3, 0, 0x18000
	v_add_u32_e32 v144, s3, v165
	s_add_i32 s19, 0, 0x1c000
	ds_read_b128 v[128:131], v144
	ds_read_b128 v[132:135], v144 offset:1024
	ds_read_b128 v[158:161], v144 offset:2048
	ds_read_b128 v[178:181], v144 offset:3072
	v_add_u32_e32 v144, s19, v165
	ds_read_b128 v[182:185], v144
	ds_read_b128 v[186:189], v144 offset:1024
	ds_read_b128 v[190:193], v144 offset:2048
	ds_read_b128 v[194:197], v144 offset:3072
	s_add_u32 s36, vcc_lo, 0x80000
	s_addc_u32 s37, vcc_hi, 0
	s_mov_b32 m0, s52
	ds_read_b128 v[198:201], v175 offset:32768
	ds_read_b128 v[202:205], v175 offset:33792
	ds_read_b128 v[206:209], v175 offset:34816
	ds_read_b128 v[210:213], v175 offset:35840
	ds_read_b128 v[214:217], v175 offset:36864
	ds_read_b128 v[218:221], v175 offset:37888
	ds_read_b128 v[222:225], v175 offset:38912
	ds_read_b128 v[230:233], v175 offset:39936
	global_load_lds_dwordx4 v136, s[36:37]
	s_mov_b32 m0, s53
	s_nop 0
	global_load_lds_dwordx4 v140, s[36:37]
	s_waitcnt vmcnt(8)
	s_waitcnt lgkmcnt(0)
	s_barrier
	s_setprio 1
	s_waitcnt lgkmcnt(0)
	v_mfma_f32_16x16x32_bf16 v[124:127], v[128:131], v[198:201], v[124:127]
	v_mfma_f32_16x16x32_bf16 v[120:123], v[158:161], v[198:201], v[120:123]
	v_mfma_f32_16x16x32_bf16 v[108:111], v[128:131], v[206:209], v[108:111]
	v_mfma_f32_16x16x32_bf16 v[104:107], v[158:161], v[206:209], v[104:107]
	v_mfma_f32_16x16x32_bf16 v[92:95], v[128:131], v[214:217], v[92:95]
	v_mfma_f32_16x16x32_bf16 v[88:91], v[158:161], v[214:217], v[88:91]
	v_mfma_f32_16x16x32_bf16 v[76:79], v[128:131], v[222:225], v[76:79]
	v_mfma_f32_16x16x32_bf16 v[72:75], v[158:161], v[222:225], v[72:75]
	v_mfma_f32_16x16x32_bf16 v[124:127], v[132:135], v[202:205], v[124:127]
	v_mfma_f32_16x16x32_bf16 v[120:123], v[178:181], v[202:205], v[120:123]
	v_mfma_f32_16x16x32_bf16 v[108:111], v[132:135], v[210:213], v[108:111]
	v_mfma_f32_16x16x32_bf16 v[104:107], v[178:181], v[210:213], v[104:107]
	v_mfma_f32_16x16x32_bf16 v[92:95], v[132:135], v[218:221], v[92:95]
	v_mfma_f32_16x16x32_bf16 v[88:91], v[178:181], v[218:221], v[88:91]
	v_mfma_f32_16x16x32_bf16 v[76:79], v[132:135], v[230:233], v[76:79]
	v_mfma_f32_16x16x32_bf16 v[72:75], v[178:181], v[230:233], v[72:75]
	s_setprio 0
	s_setprio 1
	v_mfma_f32_16x16x32_bf16 v[116:119], v[182:185], v[198:201], v[116:119]
	v_mfma_f32_16x16x32_bf16 v[112:115], v[190:193], v[198:201], v[112:115]
	v_mfma_f32_16x16x32_bf16 v[100:103], v[182:185], v[206:209], v[100:103]
	v_mfma_f32_16x16x32_bf16 v[96:99], v[190:193], v[206:209], v[96:99]
	v_mfma_f32_16x16x32_bf16 v[84:87], v[182:185], v[214:217], v[84:87]
	v_mfma_f32_16x16x32_bf16 v[80:83], v[190:193], v[214:217], v[80:83]
	v_mfma_f32_16x16x32_bf16 v[68:71], v[182:185], v[222:225], v[68:71]
	v_mfma_f32_16x16x32_bf16 v[64:67], v[190:193], v[222:225], v[64:67]
	v_mfma_f32_16x16x32_bf16 v[116:119], v[186:189], v[202:205], v[116:119]
	v_mfma_f32_16x16x32_bf16 v[112:115], v[194:197], v[202:205], v[112:115]
	v_mfma_f32_16x16x32_bf16 v[100:103], v[186:189], v[210:213], v[100:103]
	v_mfma_f32_16x16x32_bf16 v[96:99], v[194:197], v[210:213], v[96:99]
	v_mfma_f32_16x16x32_bf16 v[84:87], v[186:189], v[218:221], v[84:87]
	v_mfma_f32_16x16x32_bf16 v[80:83], v[194:197], v[218:221], v[80:83]
	v_mfma_f32_16x16x32_bf16 v[68:71], v[186:189], v[230:233], v[68:71]
	v_mfma_f32_16x16x32_bf16 v[64:67], v[194:197], v[230:233], v[64:67]
	s_setprio 0
	s_barrier
	s_add_i32 s3, s3, s25
	v_lshl_add_u64 v[162:163], v[162:163], 0, s[82:83]
	s_mov_b32 m0, s3
	ds_read_b128 v[198:201], v175 offset:49152
	ds_read_b128 v[202:205], v175 offset:50176
	ds_read_b128 v[206:209], v175 offset:51200
	ds_read_b128 v[210:213], v175 offset:52224
	ds_read_b128 v[214:217], v175 offset:53248
	ds_read_b128 v[218:221], v175 offset:54272
	ds_read_b128 v[222:225], v175 offset:55296
	ds_read_b128 v[230:233], v175 offset:56320
	global_load_lds_dwordx4 v[162:163], off
	s_add_i32 m0, s3, 0x2000
	s_add_u32 s36, s96, 0x80080
	v_lshl_add_u64 v[162:163], v[226:227], 0, s[82:83]
	s_addc_u32 s37, s97, 0
	s_add_i32 s3, s19, s25
	global_load_lds_dwordx4 v[162:163], off
	s_mov_b32 m0, s3
	s_nop 0
	global_load_lds_dwordx4 v138, s[36:37]
	s_add_i32 m0, s3, 0x2000
	s_nop 0
	global_load_lds_dwordx4 v142, s[36:37]
	v_lshl_add_u64 v[162:163], v[234:235], 0, s[82:83]
	s_mov_b32 m0, s56
	s_nop 0
	global_load_lds_dwordx4 v[162:163], off
	v_lshl_add_u64 v[162:163], v[236:237], 0, s[82:83]
	s_mov_b32 m0, s57
	s_nop 0
	global_load_lds_dwordx4 v[162:163], off
	s_waitcnt vmcnt(8)
	s_waitcnt lgkmcnt(0)
	s_barrier
	s_setprio 1
	s_waitcnt lgkmcnt(0)
	v_mfma_f32_16x16x32_bf16 v[60:63], v[128:131], v[198:201], v[60:63]
	v_mfma_f32_16x16x32_bf16 v[56:59], v[158:161], v[198:201], v[56:59]
	v_mfma_f32_16x16x32_bf16 v[44:47], v[128:131], v[206:209], v[44:47]
	v_mfma_f32_16x16x32_bf16 v[40:43], v[158:161], v[206:209], v[40:43]
	v_mfma_f32_16x16x32_bf16 v[28:31], v[128:131], v[214:217], v[28:31]
	v_mfma_f32_16x16x32_bf16 v[24:27], v[158:161], v[214:217], v[24:27]
	v_mfma_f32_16x16x32_bf16 v[12:15], v[128:131], v[222:225], v[12:15]
	v_mfma_f32_16x16x32_bf16 v[8:11], v[158:161], v[222:225], v[8:11]
	v_mfma_f32_16x16x32_bf16 v[60:63], v[132:135], v[202:205], v[60:63]
	v_mfma_f32_16x16x32_bf16 v[56:59], v[178:181], v[202:205], v[56:59]
	v_mfma_f32_16x16x32_bf16 v[44:47], v[132:135], v[210:213], v[44:47]
	v_mfma_f32_16x16x32_bf16 v[40:43], v[178:181], v[210:213], v[40:43]
	v_mfma_f32_16x16x32_bf16 v[28:31], v[132:135], v[218:221], v[28:31]
	v_mfma_f32_16x16x32_bf16 v[24:27], v[178:181], v[218:221], v[24:27]
	v_mfma_f32_16x16x32_bf16 v[12:15], v[132:135], v[230:233], v[12:15]
	v_mfma_f32_16x16x32_bf16 v[8:11], v[178:181], v[230:233], v[8:11]
	s_setprio 0
	s_setprio 1
	v_mfma_f32_16x16x32_bf16 v[52:55], v[182:185], v[198:201], v[52:55]
	v_mfma_f32_16x16x32_bf16 v[48:51], v[190:193], v[198:201], v[48:51]
	v_mfma_f32_16x16x32_bf16 v[36:39], v[182:185], v[206:209], v[36:39]
	v_mfma_f32_16x16x32_bf16 v[32:35], v[190:193], v[206:209], v[32:35]
	v_mfma_f32_16x16x32_bf16 v[20:23], v[182:185], v[214:217], v[20:23]
	v_mfma_f32_16x16x32_bf16 v[16:19], v[190:193], v[214:217], v[16:19]
	v_mfma_f32_16x16x32_bf16 v[4:7], v[182:185], v[222:225], v[4:7]
	v_mfma_f32_16x16x32_bf16 v[0:3], v[190:193], v[222:225], v[0:3]
	v_mfma_f32_16x16x32_bf16 v[52:55], v[186:189], v[202:205], v[52:55]
	v_mfma_f32_16x16x32_bf16 v[48:51], v[194:197], v[202:205], v[48:51]
	v_mfma_f32_16x16x32_bf16 v[36:39], v[186:189], v[210:213], v[36:39]
	v_mfma_f32_16x16x32_bf16 v[32:35], v[194:197], v[210:213], v[32:35]
	v_mfma_f32_16x16x32_bf16 v[20:23], v[186:189], v[218:221], v[20:23]
	v_mfma_f32_16x16x32_bf16 v[16:19], v[194:197], v[218:221], v[16:19]
	v_mfma_f32_16x16x32_bf16 v[4:7], v[186:189], v[230:233], v[4:7]
	v_mfma_f32_16x16x32_bf16 v[0:3], v[194:197], v[230:233], v[0:3]
	s_setprio 0
	s_barrier
	s_add_i32 s18, s18, 2
	s_add_u32 s34, s34, 0x100
	s_addc_u32 s35, s35, 0
	s_add_u32 s15, s15, 0x100
	s_addc_u32 s17, s17, 0
	s_cmp_gt_u32 s18, 29
	s_cbranch_scc0 .LBB0_1773
	s_and_b64 vcc, exec, s[84:85]
	s_cbranch_vccz .LBB0_1776
	s_barrier

.LBB0_2103:
	s_cmp_eq_u32 s58, 0
	s_cselect_b64 s[0:1], -1, 0
	s_or_b64 s[0:1], s[60:61], s[0:1]
	s_and_b64 vcc, exec, s[0:1]
	s_cbranch_vccnz .Lfz1_c2
	s_add_i32 s0, s68, 0xc000
	s_and_b32 s0, s0, 0xc000
	v_add_u32_e32 v0, s0, v234
	ds_read_b64_tr_b16 v[160:161], v0 offset:0x2000
	ds_read_b64_tr_b16 v[162:163], v0 offset:0x2100
	ds_read_b64_tr_b16 v[164:165], v0 offset:0x3000
	ds_read_b64_tr_b16 v[166:167], v0 offset:0x3100
	s_waitcnt lgkmcnt(2)
	s_nop 0
	v_mfma_f32_32x32x16_bf16 v[128:143], v[6:9], v[160:163], v[128:143]
	ds_read_b64_tr_b16 v[168:169], v0 offset:0x2200
	v_mfma_f32_32x32x16_bf16 v[96:111], v[2:5], v[160:163], v[96:111]
	ds_read_b64_tr_b16 v[170:171], v0 offset:0x2300
	s_waitcnt lgkmcnt(2)
	v_mfma_f32_32x32x16_bf16 v[128:143], v[208:211], v[164:167], v[128:143]
	ds_read_b64_tr_b16 v[172:173], v0 offset:0x3200
	v_mfma_f32_32x32x16_bf16 v[96:111], v[10:13], v[164:167], v[96:111]
	ds_read_b64_tr_b16 v[174:175], v0 offset:0x3300
	s_waitcnt lgkmcnt(2)
	v_mfma_f32_32x32x16_bf16 v[112:127], v[6:9], v[168:171], v[112:127]
	ds_read_b64_tr_b16 v[160:161], v0 offset:0x2400
	v_mfma_f32_32x32x16_bf16 v[80:95], v[2:5], v[168:171], v[80:95]
	ds_read_b64_tr_b16 v[162:163], v0 offset:0x2500
	s_waitcnt lgkmcnt(2)
	v_mfma_f32_32x32x16_bf16 v[112:127], v[208:211], v[172:175], v[112:127]
	ds_read_b64_tr_b16 v[164:165], v0 offset:0x3400
	v_mfma_f32_32x32x16_bf16 v[80:95], v[10:13], v[172:175], v[80:95]
	ds_read_b64_tr_b16 v[166:167], v0 offset:0x3500
	s_waitcnt lgkmcnt(2)
	v_mfma_f32_32x32x16_bf16 v[64:79], v[6:9], v[160:163], v[64:79]
	ds_read_b64_tr_b16 v[168:169], v0 offset:0x2600
	v_mfma_f32_32x32x16_bf16 v[32:47], v[2:5], v[160:163], v[32:47]
	ds_read_b64_tr_b16 v[170:171], v0 offset:0x2700
	s_waitcnt lgkmcnt(2)
	v_mfma_f32_32x32x16_bf16 v[64:79], v[208:211], v[164:167], v[64:79]
	ds_read_b64_tr_b16 v[172:173], v0 offset:0x3600
	v_mfma_f32_32x32x16_bf16 v[32:47], v[10:13], v[164:167], v[32:47]
	ds_read_b64_tr_b16 v[174:175], v0 offset:0x3700
	s_waitcnt lgkmcnt(2)
	v_mfma_f32_32x32x16_bf16 v[48:63], v[6:9], v[168:171], v[48:63]
	v_mfma_f32_32x32x16_bf16 v[16:31], v[2:5], v[168:171], v[16:31]
	s_waitcnt lgkmcnt(0)
	v_mfma_f32_32x32x16_bf16 v[48:63], v[208:211], v[172:175], v[48:63]
	v_mfma_f32_32x32x16_bf16 v[16:31], v[10:13], v[172:175], v[16:31]
.Lfz1_c2:
	s_and_b32 s27, s68, 0xc000
	v_add_u32_e32 v241, s27, v233
	ds_read_b128 v[144:147], v241 offset:0
	v_xor_b32_e32 v240, 32, v241
	ds_read_b128 v[148:151], v240 offset:0
	v_xor_b32_e32 v239, 64, v241
	ds_read_b128 v[152:155], v239 offset:0
	v_xor_b32_e32 v0, 0x60, v241
	ds_read_b128 v[156:159], v0 offset:0
	s_waitcnt lgkmcnt(0)
	v_mfma_f32_32x32x16_bf16 v[212:227], v[144:147], v[176:179], 0
	v_mfma_f32_32x32x16_bf16 v[212:227], v[148:151], v[180:183], v[212:227]
	v_mfma_f32_32x32x16_bf16 v[212:227], v[152:155], v[184:187], v[212:227]
	v_mfma_f32_32x32x16_bf16 v[212:227], v[156:159], v[188:191], v[212:227]
	ds_read_b128 v[144:147], v241 offset:0x80
	ds_read_b128 v[148:151], v240 offset:0x80
	ds_read_b128 v[152:155], v239 offset:0x80
	ds_read_b128 v[156:159], v0 offset:0x80
	v_cmp_eq_f32_e32 vcc, 0, v238
	v_cmp_eq_f32_e64 s[6:7], 0, v237
	s_and_b64 s[0:1], vcc, s[6:7]
	s_cmp_eq_u64 s[0:1], exec
	s_waitcnt lgkmcnt(0)
	v_mfma_f32_32x32x16_bf16 v[160:175], v[144:147], v[192:195], 0
	v_mfma_f32_32x32x16_bf16 v[160:175], v[148:151], v[196:199], v[160:175]
	v_mfma_f32_32x32x16_bf16 v[160:175], v[152:155], v[200:203], v[160:175]
	v_mfma_f32_32x32x16_bf16 v[160:175], v[156:159], v[204:207], v[160:175]
	s_cbranch_scc0 .LBB0_2105
	v_exp_f32_e32 v144, v212
	v_exp_f32_e32 v145, v213
	v_exp_f32_e32 v146, v214
	v_exp_f32_e32 v147, v215
	v_exp_f32_e32 v148, v216
	v_exp_f32_e32 v149, v217
	v_exp_f32_e32 v150, v218
	v_exp_f32_e32 v151, v219
	v_exp_f32_e32 v152, v220
	v_exp_f32_e32 v153, v221
	v_exp_f32_e32 v154, v222
	v_exp_f32_e32 v155, v223
	v_exp_f32_e32 v156, v224
	v_exp_f32_e32 v157, v225
	v_exp_f32_e32 v158, v226
	v_exp_f32_e32 v159, v227
	v_pk_add_f32 v[252:253], v[144:145], v[146:147]
	v_pk_add_f32 v[254:255], v[148:149], v[150:151]
	v_pk_add_f32 v[252:253], v[152:153], v[252:253]
	v_pk_add_f32 v[254:255], v[154:155], v[254:255]
	v_pk_add_f32 v[252:253], v[156:157], v[252:253]
	v_pk_add_f32 v[254:255], v[158:159], v[254:255]
	v_cvt_pk_bf16_f32 v216, v144, v145
	v_cvt_pk_bf16_f32 v217, v146, v147
	v_cvt_pk_bf16_f32 v218, v148, v149
	v_pk_add_f32 v[252:253], v[252:253], v[254:255]
	v_cvt_pk_bf16_f32 v219, v150, v151
	v_cvt_pk_bf16_f32 v224, v152, v153
	v_cvt_pk_bf16_f32 v225, v154, v155
	v_pk_add_f32 v[252:253], v[252:253], v[252:253] op_sel:[0,1] op_sel_hi:[1,0]
	v_cvt_pk_bf16_f32 v226, v156, v157
	v_cvt_pk_bf16_f32 v227, v158, v159
	v_cmp_lt_f32_e32 vcc, s48, v252
	v_cmp_gt_f32_e64 s[6:7], s49, v252
	s_and_b64 s[0:1], vcc, s[6:7]
	s_cmp_lg_u64 s[0:1], exec
	s_cbranch_scc1 .LBB0_2140
	v_add_f32_e32 v15, v15, v252
	v_exp_f32_e32 v144, v160
	v_exp_f32_e32 v145, v161
	v_exp_f32_e32 v146, v162
	v_exp_f32_e32 v147, v163
	v_exp_f32_e32 v148, v164
	v_exp_f32_e32 v149, v165
	v_exp_f32_e32 v150, v166
	v_exp_f32_e32 v151, v167
	v_exp_f32_e32 v152, v168
	v_exp_f32_e32 v153, v169
	v_exp_f32_e32 v154, v170
	v_exp_f32_e32 v155, v171
	v_exp_f32_e32 v156, v172
	v_exp_f32_e32 v157, v173
	v_exp_f32_e32 v158, v174
	v_exp_f32_e32 v159, v175
	v_pk_add_f32 v[252:253], v[144:145], v[146:147]
	v_pk_add_f32 v[254:255], v[148:149], v[150:151]
	v_pk_add_f32 v[252:253], v[152:153], v[252:253]
	v_pk_add_f32 v[254:255], v[154:155], v[254:255]
	v_pk_add_f32 v[252:253], v[156:157], v[252:253]
	v_pk_add_f32 v[254:255], v[158:159], v[254:255]
	v_cvt_pk_bf16_f32 v212, v144, v145
	v_cvt_pk_bf16_f32 v213, v146, v147
	v_cvt_pk_bf16_f32 v214, v148, v149
	v_pk_add_f32 v[252:253], v[252:253], v[254:255]
	v_cvt_pk_bf16_f32 v215, v150, v151
	v_cvt_pk_bf16_f32 v220, v152, v153
	v_cvt_pk_bf16_f32 v221, v154, v155
	v_pk_add_f32 v[252:253], v[252:253], v[252:253] op_sel:[0,1] op_sel_hi:[1,0]
	v_cvt_pk_bf16_f32 v222, v156, v157
	v_cvt_pk_bf16_f32 v223, v158, v159
	v_cmp_lt_f32_e32 vcc, s48, v252
	v_cmp_gt_f32_e64 s[6:7], s49, v252
	s_and_b64 s[0:1], vcc, s[6:7]
	s_cmp_lg_u64 s[0:1], exec
	s_cbranch_scc1 .Lfzsb1_c2
	v_add_f32_e32 v14, v14, v252
	s_branch .LBB0_2121

.LBB0_2121:
	v_add_u32_e32 v242, s27, v234
	ds_read_b64_tr_b16 v[160:161], v242 offset:0x0
	ds_read_b64_tr_b16 v[162:163], v242 offset:0x100
	ds_read_b64_tr_b16 v[164:165], v242 offset:0x1000
	ds_read_b64_tr_b16 v[166:167], v242 offset:0x1100
	s_waitcnt lgkmcnt(2)
	s_nop 0
	v_mfma_f32_32x32x16_bf16 v[128:143], v[216:219], v[160:163], v[128:143]
	ds_read_b64_tr_b16 v[168:169], v242 offset:0x200
	v_mfma_f32_32x32x16_bf16 v[96:111], v[212:215], v[160:163], v[96:111]
	ds_read_b64_tr_b16 v[170:171], v242 offset:0x300
	s_waitcnt lgkmcnt(2)
	v_mfma_f32_32x32x16_bf16 v[128:143], v[224:227], v[164:167], v[128:143]
	ds_read_b64_tr_b16 v[172:173], v242 offset:0x1200
	v_mfma_f32_32x32x16_bf16 v[96:111], v[220:223], v[164:167], v[96:111]
	ds_read_b64_tr_b16 v[174:175], v242 offset:0x1300
	s_waitcnt lgkmcnt(2)
	v_mfma_f32_32x32x16_bf16 v[112:127], v[216:219], v[168:171], v[112:127]
	ds_read_b64_tr_b16 v[160:161], v242 offset:0x400
	v_mfma_f32_32x32x16_bf16 v[80:95], v[212:215], v[168:171], v[80:95]
	ds_read_b64_tr_b16 v[162:163], v242 offset:0x500
	s_waitcnt lgkmcnt(2)
	v_mfma_f32_32x32x16_bf16 v[112:127], v[224:227], v[172:175], v[112:127]
	ds_read_b64_tr_b16 v[164:165], v242 offset:0x1400
	v_mfma_f32_32x32x16_bf16 v[80:95], v[220:223], v[172:175], v[80:95]
	ds_read_b64_tr_b16 v[166:167], v242 offset:0x1500
	ds_read_b128 v[144:147], v241 offset:0x2000
	ds_read_b128 v[148:151], v240 offset:0x2000
	ds_read_b128 v[156:159], v239 offset:0x2000
	ds_read_b128 v[244:247], v0 offset:0x2000
	s_waitcnt lgkmcnt(6)
	v_mfma_f32_32x32x16_bf16 v[64:79], v[216:219], v[160:163], v[64:79]
	ds_read_b64_tr_b16 v[168:169], v242 offset:0x600
	v_mfma_f32_32x32x16_bf16 v[32:47], v[212:215], v[160:163], v[32:47]
	ds_read_b64_tr_b16 v[170:171], v242 offset:0x700
	s_waitcnt lgkmcnt(6)
	v_mfma_f32_32x32x16_bf16 v[64:79], v[224:227], v[164:167], v[64:79]
	ds_read_b64_tr_b16 v[172:173], v242 offset:0x1600
	v_mfma_f32_32x32x16_bf16 v[32:47], v[220:223], v[164:167], v[32:47]
	ds_read_b64_tr_b16 v[174:175], v242 offset:0x1700
	s_waitcnt lgkmcnt(2)
	v_mfma_f32_32x32x16_bf16 v[48:63], v[216:219], v[168:171], v[48:63]
	v_mfma_f32_32x32x16_bf16 v[16:31], v[212:215], v[168:171], v[16:31]
	s_waitcnt lgkmcnt(0)
	v_mfma_f32_32x32x16_bf16 v[48:63], v[224:227], v[172:175], v[48:63]
	v_mfma_f32_32x32x16_bf16 v[16:31], v[220:223], v[172:175], v[16:31]
	s_waitcnt lgkmcnt(0)
	v_mfma_f32_32x32x16_bf16 v[212:227], v[144:147], v[176:179], 0
	v_mfma_f32_32x32x16_bf16 v[212:227], v[148:151], v[180:183], v[212:227]
	v_mfma_f32_32x32x16_bf16 v[212:227], v[156:159], v[184:187], v[212:227]
	v_mfma_f32_32x32x16_bf16 v[212:227], v[244:247], v[188:191], v[212:227]
	ds_read_b128 v[144:147], v241 offset:0x2080
	ds_read_b128 v[148:151], v240 offset:0x2080
	ds_read_b128 v[152:155], v239 offset:0x2080
	ds_read_b128 v[156:159], v0 offset:0x2080
	v_cmp_eq_f32_e32 vcc, 0, v238
	v_cmp_eq_f32_e64 s[6:7], 0, v237
	s_and_b64 s[0:1], vcc, s[6:7]
	s_cmp_eq_u64 s[0:1], exec
	s_waitcnt lgkmcnt(0)
	v_mfma_f32_32x32x16_bf16 v[160:175], v[144:147], v[192:195], 0
	v_mfma_f32_32x32x16_bf16 v[160:175], v[148:151], v[196:199], v[160:175]
	v_mfma_f32_32x32x16_bf16 v[160:175], v[152:155], v[200:203], v[160:175]
	v_mfma_f32_32x32x16_bf16 v[160:175], v[156:159], v[204:207], v[160:175]
	s_cbranch_scc0 .Lfz2o_c2
	v_exp_f32_e32 v144, v212
	v_exp_f32_e32 v145, v213
	v_exp_f32_e32 v146, v214
	v_exp_f32_e32 v147, v215
	v_exp_f32_e32 v148, v216
	v_exp_f32_e32 v149, v217
	v_exp_f32_e32 v150, v218
	v_exp_f32_e32 v151, v219
	v_exp_f32_e32 v152, v220
	v_exp_f32_e32 v153, v221
	v_exp_f32_e32 v154, v222
	v_exp_f32_e32 v155, v223
	v_exp_f32_e32 v156, v224
	v_exp_f32_e32 v157, v225
	v_exp_f32_e32 v158, v226
	v_exp_f32_e32 v159, v227
	v_pk_add_f32 v[252:253], v[144:145], v[146:147]
	v_pk_add_f32 v[254:255], v[148:149], v[150:151]
	v_pk_add_f32 v[252:253], v[152:153], v[252:253]
	v_pk_add_f32 v[254:255], v[154:155], v[254:255]
	v_pk_add_f32 v[252:253], v[156:157], v[252:253]
	v_pk_add_f32 v[254:255], v[158:159], v[254:255]
	v_cvt_pk_bf16_f32 v6, v144, v145
	v_cvt_pk_bf16_f32 v7, v146, v147
	v_cvt_pk_bf16_f32 v8, v148, v149
	v_pk_add_f32 v[252:253], v[252:253], v[254:255]
	v_cvt_pk_bf16_f32 v9, v150, v151
	v_cvt_pk_bf16_f32 v208, v152, v153
	v_cvt_pk_bf16_f32 v209, v154, v155
	v_pk_add_f32 v[252:253], v[252:253], v[252:253] op_sel:[0,1] op_sel_hi:[1,0]
	v_cvt_pk_bf16_f32 v210, v156, v157
	v_cvt_pk_bf16_f32 v211, v158, v159
	v_cmp_lt_f32_e32 vcc, s48, v252
	v_cmp_gt_f32_e64 s[6:7], s49, v252
	s_and_b64 s[0:1], vcc, s[6:7]
	s_cmp_lg_u64 s[0:1], exec
	s_cbranch_scc1 .LBB0_2152
	v_add_f32_e32 v15, v15, v252
	v_exp_f32_e32 v144, v160
	v_exp_f32_e32 v145, v161
	v_exp_f32_e32 v146, v162
	v_exp_f32_e32 v147, v163
	v_exp_f32_e32 v148, v164
	v_exp_f32_e32 v149, v165
	v_exp_f32_e32 v150, v166
	v_exp_f32_e32 v151, v167
	v_exp_f32_e32 v152, v168
	v_exp_f32_e32 v153, v169
	v_exp_f32_e32 v154, v170
	v_exp_f32_e32 v155, v171
	v_exp_f32_e32 v156, v172
	v_exp_f32_e32 v157, v173
	v_exp_f32_e32 v158, v174
	v_exp_f32_e32 v159, v175
	v_pk_add_f32 v[252:253], v[144:145], v[146:147]
	v_pk_add_f32 v[254:255], v[148:149], v[150:151]
	v_pk_add_f32 v[252:253], v[152:153], v[252:253]
	v_pk_add_f32 v[254:255], v[154:155], v[254:255]
	v_pk_add_f32 v[252:253], v[156:157], v[252:253]
	v_pk_add_f32 v[254:255], v[158:159], v[254:255]
	v_cvt_pk_bf16_f32 v2, v144, v145
	v_cvt_pk_bf16_f32 v3, v146, v147
	v_cvt_pk_bf16_f32 v4, v148, v149
	v_pk_add_f32 v[252:253], v[252:253], v[254:255]
	v_cvt_pk_bf16_f32 v5, v150, v151
	v_cvt_pk_bf16_f32 v10, v152, v153
	v_cvt_pk_bf16_f32 v11, v154, v155
	v_pk_add_f32 v[252:253], v[252:253], v[252:253] op_sel:[0,1] op_sel_hi:[1,0]
	v_cvt_pk_bf16_f32 v12, v156, v157
	v_cvt_pk_bf16_f32 v13, v158, v159
	v_cmp_lt_f32_e32 vcc, s48, v252
	v_cmp_gt_f32_e64 s[6:7], s49, v252
	s_and_b64 s[0:1], vcc, s[6:7]
	s_cmp_lg_u64 s[0:1], exec
	s_cbranch_scc1 .Lfzsb2_c2
	v_add_f32_e32 v14, v14, v252
	s_branch .LBB0_2137

.Lfz2o_c2:
	ds_read_b128 v[144:147], v241 offset:0x2000
	ds_read_b128 v[148:151], v240 offset:0x2000
	ds_read_b128 v[156:159], v239 offset:0x2000
	ds_read_b128 v[244:247], v0 offset:0x2000
	v_mfma_f32_32x32x16_bf16 v[160:175], v[144:147], v[176:179], 0
	v_cmp_eq_f32_e32 vcc, 0, v238
	s_cmp_eq_u64 vcc, exec
	v_mfma_f32_32x32x16_bf16 v[160:175], v[148:151], v[180:183], v[160:175]
	v_mfma_f32_32x32x16_bf16 v[160:175], v[156:159], v[184:187], v[160:175]
	v_mfma_f32_32x32x16_bf16 v[160:175], v[244:247], v[188:191], v[160:175]
	s_cbranch_scc0 .LBB0_2151

.LBB0_2137:
	s_andn2_b64 vcc, exec, s[52:53]
	s_cbranch_vccnz .LBB0_2096
	ds_read_b64_tr_b16 v[160:161], v242 offset:0x2000
	ds_read_b64_tr_b16 v[162:163], v242 offset:0x2100
	ds_read_b64_tr_b16 v[164:165], v242 offset:0x3000
	ds_read_b64_tr_b16 v[166:167], v242 offset:0x3100
	s_waitcnt lgkmcnt(2)
	s_nop 0
	v_mfma_f32_32x32x16_bf16 v[128:143], v[6:9], v[160:163], v[128:143]
	ds_read_b64_tr_b16 v[168:169], v242 offset:0x2200
	v_mfma_f32_32x32x16_bf16 v[96:111], v[2:5], v[160:163], v[96:111]
	ds_read_b64_tr_b16 v[170:171], v242 offset:0x2300
	s_waitcnt lgkmcnt(2)
	v_mfma_f32_32x32x16_bf16 v[128:143], v[208:211], v[164:167], v[128:143]
	ds_read_b64_tr_b16 v[172:173], v242 offset:0x3200
	v_mfma_f32_32x32x16_bf16 v[96:111], v[10:13], v[164:167], v[96:111]
	ds_read_b64_tr_b16 v[174:175], v242 offset:0x3300
	s_waitcnt lgkmcnt(2)
	v_mfma_f32_32x32x16_bf16 v[112:127], v[6:9], v[168:171], v[112:127]
	ds_read_b64_tr_b16 v[160:161], v242 offset:0x2400
	v_mfma_f32_32x32x16_bf16 v[80:95], v[2:5], v[168:171], v[80:95]
	ds_read_b64_tr_b16 v[162:163], v242 offset:0x2500
	s_waitcnt lgkmcnt(2)
	v_mfma_f32_32x32x16_bf16 v[112:127], v[208:211], v[172:175], v[112:127]
	ds_read_b64_tr_b16 v[164:165], v242 offset:0x3400
	v_mfma_f32_32x32x16_bf16 v[80:95], v[10:13], v[172:175], v[80:95]
	ds_read_b64_tr_b16 v[166:167], v242 offset:0x3500
	s_waitcnt lgkmcnt(2)
	v_mfma_f32_32x32x16_bf16 v[64:79], v[6:9], v[160:163], v[64:79]
	ds_read_b64_tr_b16 v[168:169], v242 offset:0x2600
	v_mfma_f32_32x32x16_bf16 v[32:47], v[2:5], v[160:163], v[32:47]
	ds_read_b64_tr_b16 v[170:171], v242 offset:0x2700
	s_waitcnt lgkmcnt(2)
	v_mfma_f32_32x32x16_bf16 v[64:79], v[208:211], v[164:167], v[64:79]
	ds_read_b64_tr_b16 v[172:173], v242 offset:0x3600
	v_mfma_f32_32x32x16_bf16 v[32:47], v[10:13], v[164:167], v[32:47]
	ds_read_b64_tr_b16 v[174:175], v242 offset:0x3700
	s_waitcnt lgkmcnt(2)
	v_mfma_f32_32x32x16_bf16 v[48:63], v[6:9], v[168:171], v[48:63]
	v_mfma_f32_32x32x16_bf16 v[16:31], v[2:5], v[168:171], v[16:31]
	s_waitcnt lgkmcnt(0)
	v_mfma_f32_32x32x16_bf16 v[48:63], v[208:211], v[172:175], v[48:63]
	v_mfma_f32_32x32x16_bf16 v[16:31], v[10:13], v[172:175], v[16:31]
	s_branch .LBB0_2096

.LBB0_2171:
	s_and_b64 vcc, exec, s[42:43]
	s_cbranch_vccz .LBB0_2173
	s_cmp_lg_u32 0, -1
	s_cselect_b32 s0, 0, 0
	s_add_i32 s0, s0, 0xc000
	v_add_u32_e32 v0, s0, v232
	ds_read_b64_tr_b16 v[160:161], v0 offset:0x2000
	ds_read_b64_tr_b16 v[162:163], v0 offset:0x2100
	ds_read_b64_tr_b16 v[164:165], v0 offset:0x3000
	ds_read_b64_tr_b16 v[166:167], v0 offset:0x3100
	s_waitcnt lgkmcnt(2)
	s_nop 0
	v_mfma_f32_32x32x16_bf16 v[128:143], v[6:9], v[160:163], v[128:143]
	ds_read_b64_tr_b16 v[168:169], v0 offset:0x2200
	v_mfma_f32_32x32x16_bf16 v[96:111], v[2:5], v[160:163], v[96:111]
	ds_read_b64_tr_b16 v[170:171], v0 offset:0x2300
	s_waitcnt lgkmcnt(2)
	v_mfma_f32_32x32x16_bf16 v[128:143], v[208:211], v[164:167], v[128:143]
	ds_read_b64_tr_b16 v[172:173], v0 offset:0x3200
	v_mfma_f32_32x32x16_bf16 v[96:111], v[10:13], v[164:167], v[96:111]
	ds_read_b64_tr_b16 v[174:175], v0 offset:0x3300
	s_waitcnt lgkmcnt(2)
	v_mfma_f32_32x32x16_bf16 v[112:127], v[6:9], v[168:171], v[112:127]
	ds_read_b64_tr_b16 v[160:161], v0 offset:0x2400
	v_mfma_f32_32x32x16_bf16 v[80:95], v[2:5], v[168:171], v[80:95]
	ds_read_b64_tr_b16 v[162:163], v0 offset:0x2500
	s_waitcnt lgkmcnt(2)
	v_mfma_f32_32x32x16_bf16 v[112:127], v[208:211], v[172:175], v[112:127]
	ds_read_b64_tr_b16 v[164:165], v0 offset:0x3400
	v_mfma_f32_32x32x16_bf16 v[80:95], v[10:13], v[172:175], v[80:95]
	ds_read_b64_tr_b16 v[166:167], v0 offset:0x3500
	s_waitcnt lgkmcnt(2)
	v_mfma_f32_32x32x16_bf16 v[64:79], v[6:9], v[160:163], v[64:79]
	ds_read_b64_tr_b16 v[168:169], v0 offset:0x2600
	v_mfma_f32_32x32x16_bf16 v[32:47], v[2:5], v[160:163], v[32:47]
	ds_read_b64_tr_b16 v[170:171], v0 offset:0x2700
	s_waitcnt lgkmcnt(2)
	v_mfma_f32_32x32x16_bf16 v[64:79], v[208:211], v[164:167], v[64:79]
	ds_read_b64_tr_b16 v[172:173], v0 offset:0x3600
	v_mfma_f32_32x32x16_bf16 v[32:47], v[10:13], v[164:167], v[32:47]
	ds_read_b64_tr_b16 v[174:175], v0 offset:0x3700
	s_waitcnt lgkmcnt(2)
	v_mfma_f32_32x32x16_bf16 v[48:63], v[6:9], v[168:171], v[48:63]
	v_mfma_f32_32x32x16_bf16 v[16:31], v[2:5], v[168:171], v[16:31]
	s_waitcnt lgkmcnt(0)
	v_mfma_f32_32x32x16_bf16 v[48:63], v[208:211], v[172:175], v[48:63]
	v_mfma_f32_32x32x16_bf16 v[16:31], v[10:13], v[172:175], v[16:31]

.LBB0_2238:
	s_lshl_b32 s1, s1, 5
	s_mov_b64 s[10:11], 0x80
	s_and_b32 s1, s1, 0x60
	s_add_i32 m0, s9, 0x18000
	v_lshl_add_u64 v[6:7], v[6:7], 0, s[10:11]
	s_lshl_b32 s5, s0, 13
	s_lshl_b32 s14, s1, 7
	s_waitcnt vmcnt(2)
	s_barrier
	global_load_lds_dwordx4 v[6:7], off
	v_lshl_add_u64 v[4:5], v[4:5], 0, s[10:11]
	s_add_i32 m0, s9, 0x1a000
	s_add_i32 s60, s9, 0x8000
	s_add_i32 s61, s9, 0xa000
	global_load_lds_dwordx4 v[4:5], off
	v_lshl_add_u64 v[0:1], v[0:1], 0, s[10:11]
	s_mov_b32 m0, s60
	s_add_u32 s12, s56, 0x40080
	global_load_lds_dwordx4 v[0:1], off
	v_lshl_add_u64 v[0:1], v[2:3], 0, s[10:11]
	s_mov_b32 m0, s61
	s_addc_u32 s13, s57, 0
	global_load_lds_dwordx4 v[0:1], off
	s_add_i32 m0, s9, 0x1c000
	s_nop 0
	global_load_lds_dwordx4 v130, s[12:13]
	s_add_i32 m0, s9, 0x1e000
	s_cmpk_lt_u32 s3, 0x100
	global_load_lds_dwordx4 v134, s[12:13]
	v_lshrrev_b32_e32 v1, 1, v8
	v_and_b32_e32 v1, 24, v1
	v_and_b32_e32 v0, 15, v8
	v_lshlrev_b32_e32 v2, 1, v1
	v_lshl_or_b32 v150, s0, 6, v0
	v_lshl_or_b32 v0, v0, 6, v2
	v_lshlrev_b32_e32 v2, 2, v8
	v_and_b32_e32 v2, 32, v2
	v_bitop3_b32 v3, v0, s5, v2 bitop3:0xde
	v_bitop3_b32 v151, v0, s14, v2 bitop3:0xde
	v_lshlrev_b32_e32 v0, 14, v9
	v_and_b32_e32 v0, 0xffff8000, v0
	v_or_b32_e32 v152, s1, v1
	v_lshl_add_u32 v0, v10, 11, v0
	v_and_b32_e32 v1, 1, v9
	v_lshl_or_b32 v0, v1, 6, v0
	v_lshl_add_u32 v136, v11, 1, v0
	v_lshlrev_b32_e32 v0, 14, v12
	v_and_b32_e32 v0, 0xffff8000, v0
	s_waitcnt vmcnt(6)
	v_lshl_add_u32 v0, v13, 11, v0
	v_and_b32_e32 v1, 1, v12
	s_cselect_b64 s[12:13], -1, 0
	v_lshl_or_b32 v0, v1, 6, v0
	s_add_i32 s62, 0, 0x10000
	s_add_i32 s63, 0, 0x14000
	s_sext_i32_i8 s24, s4
	v_mov_b32_e32 v137, v131
	v_lshl_add_u32 v138, v14, 1, v0
	v_mov_b32_e32 v139, v131
	v_mov_b64_e32 v[140:141], 0x200
	v_mov_b64_e32 v[142:143], 0x1ff
	v_add_u32_e32 v153, s62, v151
	v_add_u32_e32 v154, s63, v151
	v_add_u32_e32 v155, 0, v3
	s_movk_i32 s64, 0x5c00
	s_mov_b64 s[14:15], 0x3c00
	s_movk_i32 s65, 0x3000
	s_barrier
	s_branch .LBB0_2241

.LBB0_2248:
	ds_read_b128 v[144:147], v153
	ds_read_b128 v[156:159], v153 offset:1024
	ds_read_b128 v[160:163], v153 offset:2048
	ds_read_b128 v[164:167], v153 offset:3072
	ds_read_b128 v[168:171], v154
	ds_read_b128 v[172:175], v154 offset:1024
	ds_read_b128 v[176:179], v154 offset:2048
	ds_read_b128 v[180:183], v154 offset:3072
	s_add_u32 s3, s52, 0xfffc0080
	s_addc_u32 s45, s53, -1
	s_cmp_eq_u32 s44, 12
	s_cselect_b32 s59, s0, s45
	s_cselect_b32 s58, s1, s3
	s_cselect_b32 s57, s17, s35
	s_cselect_b32 s56, s27, s33
	s_add_i32 m0, s9, 0xc000
	ds_read_b128 v[184:187], v155
	ds_read_b128 v[188:191], v155 offset:1024
	ds_read_b128 v[192:195], v155 offset:2048
	ds_read_b128 v[196:199], v155 offset:3072
	ds_read_b128 v[200:203], v155 offset:4096
	ds_read_b128 v[204:207], v155 offset:5120
	ds_read_b128 v[208:211], v155 offset:6144
	ds_read_b128 v[212:215], v155 offset:7168
	global_load_lds_dwordx4 v136, s[52:53]
	s_add_i32 m0, s9, 0xe000
	s_nop 0
	global_load_lds_dwordx4 v138, s[52:53]
	s_waitcnt vmcnt(8)
	s_waitcnt lgkmcnt(0)
	s_barrier
	s_setprio 1
	s_waitcnt lgkmcnt(0)
	v_mfma_f32_16x16x32_bf16 v[124:127], v[144:147], v[184:187], v[124:127]
	v_mfma_f32_16x16x32_bf16 v[120:123], v[160:163], v[184:187], v[120:123]
	v_mfma_f32_16x16x32_bf16 v[108:111], v[144:147], v[192:195], v[108:111]
	v_mfma_f32_16x16x32_bf16 v[104:107], v[160:163], v[192:195], v[104:107]
	v_mfma_f32_16x16x32_bf16 v[92:95], v[144:147], v[200:203], v[92:95]
	v_mfma_f32_16x16x32_bf16 v[88:91], v[160:163], v[200:203], v[88:91]
	v_mfma_f32_16x16x32_bf16 v[76:79], v[144:147], v[208:211], v[76:79]
	v_mfma_f32_16x16x32_bf16 v[72:75], v[160:163], v[208:211], v[72:75]
	v_mfma_f32_16x16x32_bf16 v[124:127], v[156:159], v[188:191], v[124:127]
	v_mfma_f32_16x16x32_bf16 v[120:123], v[164:167], v[188:191], v[120:123]
	v_mfma_f32_16x16x32_bf16 v[108:111], v[156:159], v[196:199], v[108:111]
	v_mfma_f32_16x16x32_bf16 v[104:107], v[164:167], v[196:199], v[104:107]
	v_mfma_f32_16x16x32_bf16 v[92:95], v[156:159], v[204:207], v[92:95]
	v_mfma_f32_16x16x32_bf16 v[88:91], v[164:167], v[204:207], v[88:91]
	v_mfma_f32_16x16x32_bf16 v[76:79], v[156:159], v[212:215], v[76:79]
	v_mfma_f32_16x16x32_bf16 v[72:75], v[164:167], v[212:215], v[72:75]
	s_setprio 0
	s_setprio 1
	v_mfma_f32_16x16x32_bf16 v[116:119], v[168:171], v[184:187], v[116:119]
	v_mfma_f32_16x16x32_bf16 v[112:115], v[176:179], v[184:187], v[112:115]
	v_mfma_f32_16x16x32_bf16 v[100:103], v[168:171], v[192:195], v[100:103]
	v_mfma_f32_16x16x32_bf16 v[96:99], v[176:179], v[192:195], v[96:99]
	v_mfma_f32_16x16x32_bf16 v[84:87], v[168:171], v[200:203], v[84:87]
	v_mfma_f32_16x16x32_bf16 v[80:83], v[176:179], v[200:203], v[80:83]
	v_mfma_f32_16x16x32_bf16 v[68:71], v[168:171], v[208:211], v[68:71]
	v_mfma_f32_16x16x32_bf16 v[64:67], v[176:179], v[208:211], v[64:67]
	v_mfma_f32_16x16x32_bf16 v[116:119], v[172:175], v[188:191], v[116:119]
	v_mfma_f32_16x16x32_bf16 v[112:115], v[180:183], v[188:191], v[112:115]
	v_mfma_f32_16x16x32_bf16 v[100:103], v[172:175], v[196:199], v[100:103]
	v_mfma_f32_16x16x32_bf16 v[96:99], v[180:183], v[196:199], v[96:99]
	v_mfma_f32_16x16x32_bf16 v[84:87], v[172:175], v[204:207], v[84:87]
	v_mfma_f32_16x16x32_bf16 v[80:83], v[180:183], v[204:207], v[80:83]
	v_mfma_f32_16x16x32_bf16 v[68:71], v[172:175], v[212:215], v[68:71]
	v_mfma_f32_16x16x32_bf16 v[64:67], v[180:183], v[212:215], v[64:67]
	s_setprio 0
	s_barrier
	s_add_i32 s3, s62, s8
	v_lshl_add_u64 v[148:149], s[56:57], 0, v[130:131]
	s_mov_b32 m0, s3
	ds_read_b128 v[184:187], v155 offset:16384
	ds_read_b128 v[188:191], v155 offset:17408
	ds_read_b128 v[192:195], v155 offset:18432
	ds_read_b128 v[196:199], v155 offset:19456
	ds_read_b128 v[200:203], v155 offset:20480
	ds_read_b128 v[204:207], v155 offset:21504
	ds_read_b128 v[208:211], v155 offset:22528
	ds_read_b128 v[212:215], v155 offset:23552
	global_load_lds_dwordx4 v[148:149], off
	s_add_i32 m0, s3, 0x2000
	s_add_u32 s50, s56, 0x40000
	v_lshl_add_u64 v[216:217], s[56:57], 0, v[134:135]
	s_addc_u32 s51, s57, 0
	s_add_i32 s3, s63, s8
	global_load_lds_dwordx4 v[216:217], off
	s_mov_b32 m0, s3
	v_lshl_add_u64 v[220:221], s[58:59], 0, v[132:133]
	global_load_lds_dwordx4 v130, s[50:51]
	s_add_i32 m0, s3, 0x2000
	s_nop 0
	global_load_lds_dwordx4 v134, s[50:51]
	v_lshl_add_u64 v[218:219], s[58:59], 0, v[128:129]
	s_mov_b32 m0, s9
	s_nop 0
	global_load_lds_dwordx4 v[218:219], off
	s_mov_b32 m0, s18
	s_nop 0
	global_load_lds_dwordx4 v[220:221], off
	s_waitcnt vmcnt(8)
	s_waitcnt lgkmcnt(0)
	s_barrier
	s_setprio 1
	s_waitcnt lgkmcnt(0)
	v_mfma_f32_16x16x32_bf16 v[60:63], v[144:147], v[184:187], v[60:63]
	v_mfma_f32_16x16x32_bf16 v[56:59], v[160:163], v[184:187], v[56:59]
	v_mfma_f32_16x16x32_bf16 v[44:47], v[144:147], v[192:195], v[44:47]
	v_mfma_f32_16x16x32_bf16 v[40:43], v[160:163], v[192:195], v[40:43]
	v_mfma_f32_16x16x32_bf16 v[28:31], v[144:147], v[200:203], v[28:31]
	v_mfma_f32_16x16x32_bf16 v[24:27], v[160:163], v[200:203], v[24:27]
	v_mfma_f32_16x16x32_bf16 v[12:15], v[144:147], v[208:211], v[12:15]
	v_mfma_f32_16x16x32_bf16 v[8:11], v[160:163], v[208:211], v[8:11]
	v_mfma_f32_16x16x32_bf16 v[60:63], v[156:159], v[188:191], v[60:63]
	v_mfma_f32_16x16x32_bf16 v[56:59], v[164:167], v[188:191], v[56:59]
	v_mfma_f32_16x16x32_bf16 v[44:47], v[156:159], v[196:199], v[44:47]
	v_mfma_f32_16x16x32_bf16 v[40:43], v[164:167], v[196:199], v[40:43]
	v_mfma_f32_16x16x32_bf16 v[28:31], v[156:159], v[204:207], v[28:31]
	v_mfma_f32_16x16x32_bf16 v[24:27], v[164:167], v[204:207], v[24:27]
	v_mfma_f32_16x16x32_bf16 v[12:15], v[156:159], v[212:215], v[12:15]
	v_mfma_f32_16x16x32_bf16 v[8:11], v[164:167], v[212:215], v[8:11]
	s_setprio 0
	s_setprio 1
	v_mfma_f32_16x16x32_bf16 v[52:55], v[168:171], v[184:187], v[52:55]
	v_mfma_f32_16x16x32_bf16 v[48:51], v[176:179], v[184:187], v[48:51]
	v_mfma_f32_16x16x32_bf16 v[36:39], v[168:171], v[192:195], v[36:39]
	v_mfma_f32_16x16x32_bf16 v[32:35], v[176:179], v[192:195], v[32:35]
	v_mfma_f32_16x16x32_bf16 v[20:23], v[168:171], v[200:203], v[20:23]
	v_mfma_f32_16x16x32_bf16 v[16:19], v[176:179], v[200:203], v[16:19]
	v_mfma_f32_16x16x32_bf16 v[4:7], v[168:171], v[208:211], v[4:7]
	v_mfma_f32_16x16x32_bf16 v[0:3], v[176:179], v[208:211], v[0:3]
	v_mfma_f32_16x16x32_bf16 v[52:55], v[172:175], v[188:191], v[52:55]
	v_mfma_f32_16x16x32_bf16 v[48:51], v[180:183], v[188:191], v[48:51]
	v_mfma_f32_16x16x32_bf16 v[36:39], v[172:175], v[196:199], v[36:39]
	v_mfma_f32_16x16x32_bf16 v[32:35], v[180:183], v[196:199], v[32:35]
	v_mfma_f32_16x16x32_bf16 v[20:23], v[172:175], v[204:207], v[20:23]
	v_mfma_f32_16x16x32_bf16 v[16:19], v[180:183], v[204:207], v[16:19]
	v_mfma_f32_16x16x32_bf16 v[4:7], v[172:175], v[212:215], v[4:7]
	v_mfma_f32_16x16x32_bf16 v[0:3], v[180:183], v[212:215], v[0:3]
	s_setprio 0
	s_barrier
	s_add_i32 s3, 0, 0x18000
	s_add_i32 s45, 0, 0x1c000
	v_add_u32_e32 v164, s3, v151
	v_add_u32_e32 v180, s45, v151
	ds_read_b128 v[144:147], v164
	ds_read_b128 v[156:159], v164 offset:1024
	ds_read_b128 v[160:163], v164 offset:2048
	ds_read_b128 v[164:167], v164 offset:3072
	ds_read_b128 v[168:171], v180
	ds_read_b128 v[172:175], v180 offset:1024
	ds_read_b128 v[176:179], v180 offset:2048
	ds_read_b128 v[180:183], v180 offset:3072
	s_add_u32 s50, s58, 0x40000
	s_addc_u32 s51, s59, 0
	s_mov_b32 m0, s19
	ds_read_b128 v[184:187], v155 offset:32768
	ds_read_b128 v[188:191], v155 offset:33792
	ds_read_b128 v[192:195], v155 offset:34816
	ds_read_b128 v[196:199], v155 offset:35840
	ds_read_b128 v[200:203], v155 offset:36864
	ds_read_b128 v[204:207], v155 offset:37888
	ds_read_b128 v[208:211], v155 offset:38912
	ds_read_b128 v[212:215], v155 offset:39936
	global_load_lds_dwordx4 v128, s[50:51]
	s_mov_b32 m0, s25
	s_nop 0
	global_load_lds_dwordx4 v132, s[50:51]
	s_waitcnt vmcnt(8)
	s_waitcnt lgkmcnt(0)
	s_barrier
	s_setprio 1
	s_waitcnt lgkmcnt(0)
	v_mfma_f32_16x16x32_bf16 v[124:127], v[144:147], v[184:187], v[124:127]
	v_mfma_f32_16x16x32_bf16 v[120:123], v[160:163], v[184:187], v[120:123]
	v_mfma_f32_16x16x32_bf16 v[108:111], v[144:147], v[192:195], v[108:111]
	v_mfma_f32_16x16x32_bf16 v[104:107], v[160:163], v[192:195], v[104:107]
	v_mfma_f32_16x16x32_bf16 v[92:95], v[144:147], v[200:203], v[92:95]
	v_mfma_f32_16x16x32_bf16 v[88:91], v[160:163], v[200:203], v[88:91]
	v_mfma_f32_16x16x32_bf16 v[76:79], v[144:147], v[208:211], v[76:79]
	v_mfma_f32_16x16x32_bf16 v[72:75], v[160:163], v[208:211], v[72:75]
	v_mfma_f32_16x16x32_bf16 v[124:127], v[156:159], v[188:191], v[124:127]
	v_mfma_f32_16x16x32_bf16 v[120:123], v[164:167], v[188:191], v[120:123]
	v_mfma_f32_16x16x32_bf16 v[108:111], v[156:159], v[196:199], v[108:111]
	v_mfma_f32_16x16x32_bf16 v[104:107], v[164:167], v[196:199], v[104:107]
	v_mfma_f32_16x16x32_bf16 v[92:95], v[156:159], v[204:207], v[92:95]
	v_mfma_f32_16x16x32_bf16 v[88:91], v[164:167], v[204:207], v[88:91]
	v_mfma_f32_16x16x32_bf16 v[76:79], v[156:159], v[212:215], v[76:79]
	v_mfma_f32_16x16x32_bf16 v[72:75], v[164:167], v[212:215], v[72:75]
	s_setprio 0
	s_setprio 1
	v_mfma_f32_16x16x32_bf16 v[116:119], v[168:171], v[184:187], v[116:119]
	v_mfma_f32_16x16x32_bf16 v[112:115], v[176:179], v[184:187], v[112:115]
	v_mfma_f32_16x16x32_bf16 v[100:103], v[168:171], v[192:195], v[100:103]
	v_mfma_f32_16x16x32_bf16 v[96:99], v[176:179], v[192:195], v[96:99]
	v_mfma_f32_16x16x32_bf16 v[84:87], v[168:171], v[200:203], v[84:87]
	v_mfma_f32_16x16x32_bf16 v[80:83], v[176:179], v[200:203], v[80:83]
	v_mfma_f32_16x16x32_bf16 v[68:71], v[168:171], v[208:211], v[68:71]
	v_mfma_f32_16x16x32_bf16 v[64:67], v[176:179], v[208:211], v[64:67]
	v_mfma_f32_16x16x32_bf16 v[116:119], v[172:175], v[188:191], v[116:119]
	v_mfma_f32_16x16x32_bf16 v[112:115], v[180:183], v[188:191], v[112:115]
	v_mfma_f32_16x16x32_bf16 v[100:103], v[172:175], v[196:199], v[100:103]
	v_mfma_f32_16x16x32_bf16 v[96:99], v[180:183], v[196:199], v[96:99]
	v_mfma_f32_16x16x32_bf16 v[84:87], v[172:175], v[204:207], v[84:87]
	v_mfma_f32_16x16x32_bf16 v[80:83], v[180:183], v[204:207], v[80:83]
	v_mfma_f32_16x16x32_bf16 v[68:71], v[172:175], v[212:215], v[68:71]
	v_mfma_f32_16x16x32_bf16 v[64:67], v[180:183], v[212:215], v[64:67]
	s_setprio 0
	s_barrier
	s_add_i32 s3, s3, s8
	v_lshl_add_u64 v[148:149], v[148:149], 0, s[10:11]
	s_mov_b32 m0, s3
	ds_read_b128 v[184:187], v155 offset:49152
	ds_read_b128 v[188:191], v155 offset:50176
	ds_read_b128 v[192:195], v155 offset:51200
	ds_read_b128 v[196:199], v155 offset:52224
	ds_read_b128 v[200:203], v155 offset:53248
	ds_read_b128 v[204:207], v155 offset:54272
	ds_read_b128 v[208:211], v155 offset:55296
	ds_read_b128 v[212:215], v155 offset:56320
	global_load_lds_dwordx4 v[148:149], off
	s_add_i32 m0, s3, 0x2000
	s_add_u32 s50, s56, 0x40080
	v_lshl_add_u64 v[148:149], v[216:217], 0, s[10:11]
	s_addc_u32 s51, s57, 0
	s_add_i32 s3, s45, s8
	global_load_lds_dwordx4 v[148:149], off
	s_mov_b32 m0, s3
	s_nop 0
	global_load_lds_dwordx4 v130, s[50:51]
	s_add_i32 m0, s3, 0x2000
	s_nop 0
	global_load_lds_dwordx4 v134, s[50:51]
	v_lshl_add_u64 v[148:149], v[218:219], 0, s[10:11]
	s_mov_b32 m0, s60
	s_nop 0
	global_load_lds_dwordx4 v[148:149], off
	v_lshl_add_u64 v[148:149], v[220:221], 0, s[10:11]
	s_mov_b32 m0, s61
	s_nop 0
	global_load_lds_dwordx4 v[148:149], off
	s_waitcnt vmcnt(8)
	s_waitcnt lgkmcnt(0)
	s_barrier
	s_setprio 1
	s_waitcnt lgkmcnt(0)
	v_mfma_f32_16x16x32_bf16 v[60:63], v[144:147], v[184:187], v[60:63]
	v_mfma_f32_16x16x32_bf16 v[56:59], v[160:163], v[184:187], v[56:59]
	v_mfma_f32_16x16x32_bf16 v[44:47], v[144:147], v[192:195], v[44:47]
	v_mfma_f32_16x16x32_bf16 v[40:43], v[160:163], v[192:195], v[40:43]
	v_mfma_f32_16x16x32_bf16 v[28:31], v[144:147], v[200:203], v[28:31]
	v_mfma_f32_16x16x32_bf16 v[24:27], v[160:163], v[200:203], v[24:27]
	v_mfma_f32_16x16x32_bf16 v[12:15], v[144:147], v[208:211], v[12:15]
	v_mfma_f32_16x16x32_bf16 v[8:11], v[160:163], v[208:211], v[8:11]
	v_mfma_f32_16x16x32_bf16 v[60:63], v[156:159], v[188:191], v[60:63]
	v_mfma_f32_16x16x32_bf16 v[56:59], v[164:167], v[188:191], v[56:59]
	v_mfma_f32_16x16x32_bf16 v[44:47], v[156:159], v[196:199], v[44:47]
	v_mfma_f32_16x16x32_bf16 v[40:43], v[164:167], v[196:199], v[40:43]
	v_mfma_f32_16x16x32_bf16 v[28:31], v[156:159], v[204:207], v[28:31]
	v_mfma_f32_16x16x32_bf16 v[24:27], v[164:167], v[204:207], v[24:27]
	v_mfma_f32_16x16x32_bf16 v[12:15], v[156:159], v[212:215], v[12:15]
	v_mfma_f32_16x16x32_bf16 v[8:11], v[164:167], v[212:215], v[8:11]
	s_setprio 0
	s_setprio 1
	v_mfma_f32_16x16x32_bf16 v[52:55], v[168:171], v[184:187], v[52:55]
	v_mfma_f32_16x16x32_bf16 v[48:51], v[176:179], v[184:187], v[48:51]
	v_mfma_f32_16x16x32_bf16 v[36:39], v[168:171], v[192:195], v[36:39]
	v_mfma_f32_16x16x32_bf16 v[32:35], v[176:179], v[192:195], v[32:35]
	v_mfma_f32_16x16x32_bf16 v[20:23], v[168:171], v[200:203], v[20:23]
	v_mfma_f32_16x16x32_bf16 v[16:19], v[176:179], v[200:203], v[16:19]
	v_mfma_f32_16x16x32_bf16 v[4:7], v[168:171], v[208:211], v[4:7]
	v_mfma_f32_16x16x32_bf16 v[0:3], v[176:179], v[208:211], v[0:3]
	v_mfma_f32_16x16x32_bf16 v[52:55], v[172:175], v[188:191], v[52:55]
	v_mfma_f32_16x16x32_bf16 v[48:51], v[180:183], v[188:191], v[48:51]
	v_mfma_f32_16x16x32_bf16 v[36:39], v[172:175], v[196:199], v[36:39]
	v_mfma_f32_16x16x32_bf16 v[32:35], v[180:183], v[196:199], v[32:35]
	v_mfma_f32_16x16x32_bf16 v[20:23], v[172:175], v[204:207], v[20:23]
	v_mfma_f32_16x16x32_bf16 v[16:19], v[180:183], v[204:207], v[16:19]
	v_mfma_f32_16x16x32_bf16 v[4:7], v[172:175], v[212:215], v[4:7]
	v_mfma_f32_16x16x32_bf16 v[0:3], v[180:183], v[212:215], v[0:3]
	s_setprio 0
	s_barrier
	s_add_i32 s44, s44, 2
	s_add_u32 s52, s52, 0x100
	s_addc_u32 s53, s53, 0
	s_add_u32 s33, s33, 0x100
	s_addc_u32 s35, s35, 0
	s_cmp_gt_u32 s44, 13
	s_cbranch_scc0 .LBB0_2248
	s_and_b64 vcc, exec, s[12:13]
	s_cbranch_vccz .LBB0_2251
	s_barrier

.LBB0_2262:
	s_lshl_b32 s1, s1, 5
	s_mov_b64 s[10:11], 0x80
	s_and_b32 s1, s1, 0x60
	s_add_i32 m0, s9, 0x18000
	v_lshl_add_u64 v[6:7], v[6:7], 0, s[10:11]
	s_lshl_b32 s5, s0, 13
	s_lshl_b32 s14, s1, 7
	s_waitcnt vmcnt(2)
	s_barrier
	global_load_lds_dwordx4 v[6:7], off
	v_lshl_add_u64 v[4:5], v[4:5], 0, s[10:11]
	s_add_i32 m0, s9, 0x1a000
	s_add_i32 s49, s9, 0x8000
	s_add_i32 s60, s9, 0xa000
	global_load_lds_dwordx4 v[4:5], off
	v_lshl_add_u64 v[2:3], v[2:3], 0, s[10:11]
	s_mov_b32 m0, s49
	s_add_u32 s12, s56, 0x20080
	global_load_lds_dwordx4 v[2:3], off
	v_lshl_add_u64 v[0:1], v[0:1], 0, s[10:11]
	s_mov_b32 m0, s60
	s_addc_u32 s13, s57, 0
	global_load_lds_dwordx4 v[0:1], off
	s_add_i32 m0, s9, 0x1c000
	s_nop 0
	global_load_lds_dwordx4 v130, s[12:13]
	s_add_i32 m0, s9, 0x1e000
	s_cmpk_lt_u32 s3, 0x100
	global_load_lds_dwordx4 v134, s[12:13]
	v_lshrrev_b32_e32 v1, 1, v8
	v_and_b32_e32 v1, 24, v1
	v_and_b32_e32 v0, 15, v8
	v_lshlrev_b32_e32 v2, 1, v1
	v_lshl_or_b32 v152, s0, 6, v0
	v_lshl_or_b32 v0, v0, 6, v2
	v_lshlrev_b32_e32 v2, 2, v8
	v_and_b32_e32 v2, 32, v2
	v_bitop3_b32 v3, v0, s5, v2 bitop3:0xde
	v_bitop3_b32 v153, v0, s14, v2 bitop3:0xde
	v_lshlrev_b32_e32 v0, 13, v9
	v_and_b32_e32 v0, 0xffffc000, v0
	v_or_b32_e32 v154, s1, v1
	v_lshl_add_u32 v0, v10, 10, v0
	v_and_b32_e32 v1, 1, v9
	v_lshl_or_b32 v0, v1, 6, v0
	v_lshl_add_u32 v136, v11, 1, v0
	v_lshlrev_b32_e32 v0, 13, v12
	v_and_b32_e32 v0, 0xffffc000, v0
	s_waitcnt vmcnt(6)
	v_lshl_add_u32 v0, v13, 10, v0
	v_and_b32_e32 v1, 1, v12
	s_cselect_b64 s[12:13], -1, 0
	v_lshl_or_b32 v0, v1, 6, v0
	s_add_i32 s61, 0, 0x10000
	s_add_i32 s62, 0, 0x14000
	s_sext_i32_i8 s24, s4
	v_mov_b32_e32 v137, v131
	v_lshl_add_u32 v138, v14, 1, v0
	v_mov_b32_e32 v139, v131
	v_mov_b64_e32 v[140:141], 0x200
	v_mov_b64_e32 v[142:143], 0x1ff
	v_add_u32_e32 v155, s61, v153
	v_add_u32_e32 v156, s62, v153
	v_add_u32_e32 v157, 0, v3
	s_movk_i32 s63, 0x5c00
	s_mov_b64 s[14:15], 0x4c00
	s_barrier
	s_branch .LBB0_2265

.LBB0_2272:
	ds_read_b128 v[144:147], v155
	ds_read_b128 v[148:151], v155 offset:1024
	ds_read_b128 v[158:161], v155 offset:2048
	ds_read_b128 v[162:165], v155 offset:3072
	ds_read_b128 v[166:169], v156
	ds_read_b128 v[170:173], v156 offset:1024
	ds_read_b128 v[174:177], v156 offset:2048
	ds_read_b128 v[178:181], v156 offset:3072
	s_add_u32 s3, s52, 0xfffe0080
	s_addc_u32 s51, s53, -1
	s_cmp_eq_u32 s50, 4
	s_cselect_b32 s59, s0, s51
	s_cselect_b32 s58, s1, s3
	s_cselect_b32 s57, s17, s45
	s_cselect_b32 s56, s35, s44
	s_add_i32 m0, s9, 0xc000
	ds_read_b128 v[182:185], v157
	ds_read_b128 v[186:189], v157 offset:1024
	ds_read_b128 v[190:193], v157 offset:2048
	ds_read_b128 v[194:197], v157 offset:3072
	ds_read_b128 v[198:201], v157 offset:4096
	ds_read_b128 v[202:205], v157 offset:5120
	ds_read_b128 v[206:209], v157 offset:6144
	ds_read_b128 v[210:213], v157 offset:7168
	global_load_lds_dwordx4 v136, s[52:53]
	s_add_i32 m0, s9, 0xe000
	s_nop 0
	global_load_lds_dwordx4 v138, s[52:53]
	s_waitcnt vmcnt(8)
	s_waitcnt lgkmcnt(0)
	s_barrier
	s_setprio 1
	s_waitcnt lgkmcnt(0)
	v_mfma_f32_16x16x32_bf16 v[124:127], v[144:147], v[182:185], v[124:127]
	v_mfma_f32_16x16x32_bf16 v[120:123], v[158:161], v[182:185], v[120:123]
	v_mfma_f32_16x16x32_bf16 v[108:111], v[144:147], v[190:193], v[108:111]
	v_mfma_f32_16x16x32_bf16 v[104:107], v[158:161], v[190:193], v[104:107]
	v_mfma_f32_16x16x32_bf16 v[92:95], v[144:147], v[198:201], v[92:95]
	v_mfma_f32_16x16x32_bf16 v[88:91], v[158:161], v[198:201], v[88:91]
	v_mfma_f32_16x16x32_bf16 v[76:79], v[144:147], v[206:209], v[76:79]
	v_mfma_f32_16x16x32_bf16 v[72:75], v[158:161], v[206:209], v[72:75]
	v_mfma_f32_16x16x32_bf16 v[124:127], v[148:151], v[186:189], v[124:127]
	v_mfma_f32_16x16x32_bf16 v[120:123], v[162:165], v[186:189], v[120:123]
	v_mfma_f32_16x16x32_bf16 v[108:111], v[148:151], v[194:197], v[108:111]
	v_mfma_f32_16x16x32_bf16 v[104:107], v[162:165], v[194:197], v[104:107]
	v_mfma_f32_16x16x32_bf16 v[92:95], v[148:151], v[202:205], v[92:95]
	v_mfma_f32_16x16x32_bf16 v[88:91], v[162:165], v[202:205], v[88:91]
	v_mfma_f32_16x16x32_bf16 v[76:79], v[148:151], v[210:213], v[76:79]
	v_mfma_f32_16x16x32_bf16 v[72:75], v[162:165], v[210:213], v[72:75]
	s_setprio 0
	s_setprio 1
	v_mfma_f32_16x16x32_bf16 v[116:119], v[166:169], v[182:185], v[116:119]
	v_mfma_f32_16x16x32_bf16 v[112:115], v[174:177], v[182:185], v[112:115]
	v_mfma_f32_16x16x32_bf16 v[100:103], v[166:169], v[190:193], v[100:103]
	v_mfma_f32_16x16x32_bf16 v[96:99], v[174:177], v[190:193], v[96:99]
	v_mfma_f32_16x16x32_bf16 v[84:87], v[166:169], v[198:201], v[84:87]
	v_mfma_f32_16x16x32_bf16 v[80:83], v[174:177], v[198:201], v[80:83]
	v_mfma_f32_16x16x32_bf16 v[68:71], v[166:169], v[206:209], v[68:71]
	v_mfma_f32_16x16x32_bf16 v[64:67], v[174:177], v[206:209], v[64:67]
	v_mfma_f32_16x16x32_bf16 v[116:119], v[170:173], v[186:189], v[116:119]
	v_mfma_f32_16x16x32_bf16 v[112:115], v[178:181], v[186:189], v[112:115]
	v_mfma_f32_16x16x32_bf16 v[100:103], v[170:173], v[194:197], v[100:103]
	v_mfma_f32_16x16x32_bf16 v[96:99], v[178:181], v[194:197], v[96:99]
	v_mfma_f32_16x16x32_bf16 v[84:87], v[170:173], v[202:205], v[84:87]
	v_mfma_f32_16x16x32_bf16 v[80:83], v[178:181], v[202:205], v[80:83]
	v_mfma_f32_16x16x32_bf16 v[68:71], v[170:173], v[210:213], v[68:71]
	v_mfma_f32_16x16x32_bf16 v[64:67], v[178:181], v[210:213], v[64:67]
	s_setprio 0
	s_barrier
	s_add_i32 s3, s61, s8
	v_lshl_add_u64 v[214:215], s[56:57], 0, v[130:131]
	s_mov_b32 m0, s3
	ds_read_b128 v[182:185], v157 offset:16384
	ds_read_b128 v[186:189], v157 offset:17408
	ds_read_b128 v[190:193], v157 offset:18432
	ds_read_b128 v[194:197], v157 offset:19456
	ds_read_b128 v[198:201], v157 offset:20480
	ds_read_b128 v[202:205], v157 offset:21504
	ds_read_b128 v[206:209], v157 offset:22528
	ds_read_b128 v[210:213], v157 offset:23552
	global_load_lds_dwordx4 v[214:215], off
	s_add_i32 m0, s3, 0x2000
	s_add_u32 s64, s56, 0x20000
	v_lshl_add_u64 v[216:217], s[56:57], 0, v[134:135]
	s_addc_u32 s65, s57, 0
	s_add_i32 s3, s62, s8
	global_load_lds_dwordx4 v[216:217], off
	s_mov_b32 m0, s3
	v_lshl_add_u64 v[220:221], s[58:59], 0, v[132:133]
	global_load_lds_dwordx4 v130, s[64:65]
	s_add_i32 m0, s3, 0x2000
	s_nop 0
	global_load_lds_dwordx4 v134, s[64:65]
	v_lshl_add_u64 v[218:219], s[58:59], 0, v[128:129]
	s_mov_b32 m0, s9
	s_nop 0
	global_load_lds_dwordx4 v[218:219], off
	s_mov_b32 m0, s18
	s_nop 0
	global_load_lds_dwordx4 v[220:221], off
	s_waitcnt vmcnt(8)
	s_waitcnt lgkmcnt(0)
	s_barrier
	s_setprio 1
	s_waitcnt lgkmcnt(0)
	v_mfma_f32_16x16x32_bf16 v[60:63], v[144:147], v[182:185], v[60:63]
	v_mfma_f32_16x16x32_bf16 v[56:59], v[158:161], v[182:185], v[56:59]
	v_mfma_f32_16x16x32_bf16 v[44:47], v[144:147], v[190:193], v[44:47]
	v_mfma_f32_16x16x32_bf16 v[40:43], v[158:161], v[190:193], v[40:43]
	v_mfma_f32_16x16x32_bf16 v[28:31], v[144:147], v[198:201], v[28:31]
	v_mfma_f32_16x16x32_bf16 v[24:27], v[158:161], v[198:201], v[24:27]
	v_mfma_f32_16x16x32_bf16 v[12:15], v[144:147], v[206:209], v[12:15]
	v_mfma_f32_16x16x32_bf16 v[8:11], v[158:161], v[206:209], v[8:11]
	v_mfma_f32_16x16x32_bf16 v[60:63], v[148:151], v[186:189], v[60:63]
	v_mfma_f32_16x16x32_bf16 v[56:59], v[162:165], v[186:189], v[56:59]
	v_mfma_f32_16x16x32_bf16 v[44:47], v[148:151], v[194:197], v[44:47]
	v_mfma_f32_16x16x32_bf16 v[40:43], v[162:165], v[194:197], v[40:43]
	v_mfma_f32_16x16x32_bf16 v[28:31], v[148:151], v[202:205], v[28:31]
	v_mfma_f32_16x16x32_bf16 v[24:27], v[162:165], v[202:205], v[24:27]
	v_mfma_f32_16x16x32_bf16 v[12:15], v[148:151], v[210:213], v[12:15]
	v_mfma_f32_16x16x32_bf16 v[8:11], v[162:165], v[210:213], v[8:11]
	s_setprio 0
	s_setprio 1
	v_mfma_f32_16x16x32_bf16 v[52:55], v[166:169], v[182:185], v[52:55]
	v_mfma_f32_16x16x32_bf16 v[48:51], v[174:177], v[182:185], v[48:51]
	v_mfma_f32_16x16x32_bf16 v[36:39], v[166:169], v[190:193], v[36:39]
	v_mfma_f32_16x16x32_bf16 v[32:35], v[174:177], v[190:193], v[32:35]
	v_mfma_f32_16x16x32_bf16 v[20:23], v[166:169], v[198:201], v[20:23]
	v_mfma_f32_16x16x32_bf16 v[16:19], v[174:177], v[198:201], v[16:19]
	v_mfma_f32_16x16x32_bf16 v[4:7], v[166:169], v[206:209], v[4:7]
	v_mfma_f32_16x16x32_bf16 v[0:3], v[174:177], v[206:209], v[0:3]
	v_mfma_f32_16x16x32_bf16 v[52:55], v[170:173], v[186:189], v[52:55]
	v_mfma_f32_16x16x32_bf16 v[48:51], v[178:181], v[186:189], v[48:51]
	v_mfma_f32_16x16x32_bf16 v[36:39], v[170:173], v[194:197], v[36:39]
	v_mfma_f32_16x16x32_bf16 v[32:35], v[178:181], v[194:197], v[32:35]
	v_mfma_f32_16x16x32_bf16 v[20:23], v[170:173], v[202:205], v[20:23]
	v_mfma_f32_16x16x32_bf16 v[16:19], v[178:181], v[202:205], v[16:19]
	v_mfma_f32_16x16x32_bf16 v[4:7], v[170:173], v[210:213], v[4:7]
	v_mfma_f32_16x16x32_bf16 v[0:3], v[178:181], v[210:213], v[0:3]
	s_setprio 0
	s_barrier
	s_add_i32 s3, 0, 0x18000
	s_add_i32 s51, 0, 0x1c000
	v_add_u32_e32 v162, s3, v153
	v_add_u32_e32 v178, s51, v153
	ds_read_b128 v[144:147], v162
	ds_read_b128 v[148:151], v162 offset:1024
	ds_read_b128 v[158:161], v162 offset:2048
	ds_read_b128 v[162:165], v162 offset:3072
	ds_read_b128 v[166:169], v178
	ds_read_b128 v[170:173], v178 offset:1024
	ds_read_b128 v[174:177], v178 offset:2048
	ds_read_b128 v[178:181], v178 offset:3072
	s_add_u32 s58, s58, 0x20000
	s_addc_u32 s59, s59, 0
	s_mov_b32 m0, s19
	ds_read_b128 v[182:185], v157 offset:32768
	ds_read_b128 v[186:189], v157 offset:33792
	ds_read_b128 v[190:193], v157 offset:34816
	ds_read_b128 v[194:197], v157 offset:35840
	ds_read_b128 v[198:201], v157 offset:36864
	ds_read_b128 v[202:205], v157 offset:37888
	ds_read_b128 v[206:209], v157 offset:38912
	ds_read_b128 v[210:213], v157 offset:39936
	global_load_lds_dwordx4 v128, s[58:59]
	s_mov_b32 m0, s25
	s_nop 0
	global_load_lds_dwordx4 v132, s[58:59]
	s_waitcnt vmcnt(8)
	s_waitcnt lgkmcnt(0)
	s_barrier
	s_setprio 1
	s_waitcnt lgkmcnt(0)
	v_mfma_f32_16x16x32_bf16 v[124:127], v[144:147], v[182:185], v[124:127]
	v_mfma_f32_16x16x32_bf16 v[120:123], v[158:161], v[182:185], v[120:123]
	v_mfma_f32_16x16x32_bf16 v[108:111], v[144:147], v[190:193], v[108:111]
	v_mfma_f32_16x16x32_bf16 v[104:107], v[158:161], v[190:193], v[104:107]
	v_mfma_f32_16x16x32_bf16 v[92:95], v[144:147], v[198:201], v[92:95]
	v_mfma_f32_16x16x32_bf16 v[88:91], v[158:161], v[198:201], v[88:91]
	v_mfma_f32_16x16x32_bf16 v[76:79], v[144:147], v[206:209], v[76:79]
	v_mfma_f32_16x16x32_bf16 v[72:75], v[158:161], v[206:209], v[72:75]
	v_mfma_f32_16x16x32_bf16 v[124:127], v[148:151], v[186:189], v[124:127]
	v_mfma_f32_16x16x32_bf16 v[120:123], v[162:165], v[186:189], v[120:123]
	v_mfma_f32_16x16x32_bf16 v[108:111], v[148:151], v[194:197], v[108:111]
	v_mfma_f32_16x16x32_bf16 v[104:107], v[162:165], v[194:197], v[104:107]
	v_mfma_f32_16x16x32_bf16 v[92:95], v[148:151], v[202:205], v[92:95]
	v_mfma_f32_16x16x32_bf16 v[88:91], v[162:165], v[202:205], v[88:91]
	v_mfma_f32_16x16x32_bf16 v[76:79], v[148:151], v[210:213], v[76:79]
	v_mfma_f32_16x16x32_bf16 v[72:75], v[162:165], v[210:213], v[72:75]
	s_setprio 0
	s_setprio 1
	v_mfma_f32_16x16x32_bf16 v[116:119], v[166:169], v[182:185], v[116:119]
	v_mfma_f32_16x16x32_bf16 v[112:115], v[174:177], v[182:185], v[112:115]
	v_mfma_f32_16x16x32_bf16 v[100:103], v[166:169], v[190:193], v[100:103]
	v_mfma_f32_16x16x32_bf16 v[96:99], v[174:177], v[190:193], v[96:99]
	v_mfma_f32_16x16x32_bf16 v[84:87], v[166:169], v[198:201], v[84:87]
	v_mfma_f32_16x16x32_bf16 v[80:83], v[174:177], v[198:201], v[80:83]
	v_mfma_f32_16x16x32_bf16 v[68:71], v[166:169], v[206:209], v[68:71]
	v_mfma_f32_16x16x32_bf16 v[64:67], v[174:177], v[206:209], v[64:67]
	v_mfma_f32_16x16x32_bf16 v[116:119], v[170:173], v[186:189], v[116:119]
	v_mfma_f32_16x16x32_bf16 v[112:115], v[178:181], v[186:189], v[112:115]
	v_mfma_f32_16x16x32_bf16 v[100:103], v[170:173], v[194:197], v[100:103]
	v_mfma_f32_16x16x32_bf16 v[96:99], v[178:181], v[194:197], v[96:99]
	v_mfma_f32_16x16x32_bf16 v[84:87], v[170:173], v[202:205], v[84:87]
	v_mfma_f32_16x16x32_bf16 v[80:83], v[178:181], v[202:205], v[80:83]
	v_mfma_f32_16x16x32_bf16 v[68:71], v[170:173], v[210:213], v[68:71]
	v_mfma_f32_16x16x32_bf16 v[64:67], v[178:181], v[210:213], v[64:67]
	s_setprio 0
	s_barrier
	s_add_i32 s3, s3, s8
	v_lshl_add_u64 v[214:215], v[214:215], 0, s[10:11]
	s_mov_b32 m0, s3
	ds_read_b128 v[182:185], v157 offset:49152
	ds_read_b128 v[186:189], v157 offset:50176
	ds_read_b128 v[190:193], v157 offset:51200
	ds_read_b128 v[194:197], v157 offset:52224
	ds_read_b128 v[198:201], v157 offset:53248
	ds_read_b128 v[202:205], v157 offset:54272
	ds_read_b128 v[206:209], v157 offset:55296
	ds_read_b128 v[210:213], v157 offset:56320
	global_load_lds_dwordx4 v[214:215], off
	s_add_i32 m0, s3, 0x2000
	s_add_u32 s56, s56, 0x20080
	v_lshl_add_u64 v[214:215], v[216:217], 0, s[10:11]
	s_addc_u32 s57, s57, 0
	s_add_i32 s3, s51, s8
	global_load_lds_dwordx4 v[214:215], off
	s_mov_b32 m0, s3
	s_nop 0
	global_load_lds_dwordx4 v130, s[56:57]
	s_add_i32 m0, s3, 0x2000
	s_nop 0
	global_load_lds_dwordx4 v134, s[56:57]
	v_lshl_add_u64 v[214:215], v[218:219], 0, s[10:11]
	s_mov_b32 m0, s49
	s_nop 0
	global_load_lds_dwordx4 v[214:215], off
	v_lshl_add_u64 v[214:215], v[220:221], 0, s[10:11]
	s_mov_b32 m0, s60
	s_nop 0
	global_load_lds_dwordx4 v[214:215], off
	s_waitcnt vmcnt(8)
	s_waitcnt lgkmcnt(0)
	s_barrier
	s_setprio 1
	s_waitcnt lgkmcnt(0)
	v_mfma_f32_16x16x32_bf16 v[60:63], v[144:147], v[182:185], v[60:63]
	v_mfma_f32_16x16x32_bf16 v[56:59], v[158:161], v[182:185], v[56:59]
	v_mfma_f32_16x16x32_bf16 v[44:47], v[144:147], v[190:193], v[44:47]
	v_mfma_f32_16x16x32_bf16 v[40:43], v[158:161], v[190:193], v[40:43]
	v_mfma_f32_16x16x32_bf16 v[28:31], v[144:147], v[198:201], v[28:31]
	v_mfma_f32_16x16x32_bf16 v[24:27], v[158:161], v[198:201], v[24:27]
	v_mfma_f32_16x16x32_bf16 v[12:15], v[144:147], v[206:209], v[12:15]
	v_mfma_f32_16x16x32_bf16 v[8:11], v[158:161], v[206:209], v[8:11]
	v_mfma_f32_16x16x32_bf16 v[60:63], v[148:151], v[186:189], v[60:63]
	v_mfma_f32_16x16x32_bf16 v[56:59], v[162:165], v[186:189], v[56:59]
	v_mfma_f32_16x16x32_bf16 v[44:47], v[148:151], v[194:197], v[44:47]
	v_mfma_f32_16x16x32_bf16 v[40:43], v[162:165], v[194:197], v[40:43]
	v_mfma_f32_16x16x32_bf16 v[28:31], v[148:151], v[202:205], v[28:31]
	v_mfma_f32_16x16x32_bf16 v[24:27], v[162:165], v[202:205], v[24:27]
	v_mfma_f32_16x16x32_bf16 v[12:15], v[148:151], v[210:213], v[12:15]
	v_mfma_f32_16x16x32_bf16 v[8:11], v[162:165], v[210:213], v[8:11]
	s_setprio 0
	s_setprio 1
	v_mfma_f32_16x16x32_bf16 v[52:55], v[166:169], v[182:185], v[52:55]
	v_mfma_f32_16x16x32_bf16 v[48:51], v[174:177], v[182:185], v[48:51]
	v_mfma_f32_16x16x32_bf16 v[36:39], v[166:169], v[190:193], v[36:39]
	v_mfma_f32_16x16x32_bf16 v[32:35], v[174:177], v[190:193], v[32:35]
	v_mfma_f32_16x16x32_bf16 v[20:23], v[166:169], v[198:201], v[20:23]
	v_mfma_f32_16x16x32_bf16 v[16:19], v[174:177], v[198:201], v[16:19]
	v_mfma_f32_16x16x32_bf16 v[4:7], v[166:169], v[206:209], v[4:7]
	v_mfma_f32_16x16x32_bf16 v[0:3], v[174:177], v[206:209], v[0:3]
	v_mfma_f32_16x16x32_bf16 v[52:55], v[170:173], v[186:189], v[52:55]
	v_mfma_f32_16x16x32_bf16 v[48:51], v[178:181], v[186:189], v[48:51]
	v_mfma_f32_16x16x32_bf16 v[36:39], v[170:173], v[194:197], v[36:39]
	v_mfma_f32_16x16x32_bf16 v[32:35], v[178:181], v[194:197], v[32:35]
	v_mfma_f32_16x16x32_bf16 v[20:23], v[170:173], v[202:205], v[20:23]
	v_mfma_f32_16x16x32_bf16 v[16:19], v[178:181], v[202:205], v[16:19]
	v_mfma_f32_16x16x32_bf16 v[4:7], v[170:173], v[210:213], v[4:7]
	v_mfma_f32_16x16x32_bf16 v[0:3], v[178:181], v[210:213], v[0:3]
	s_setprio 0
	s_barrier
	s_add_i32 s50, s50, 2
	s_add_u32 s52, s52, 0x100
	s_addc_u32 s53, s53, 0
	s_add_u32 s44, s44, 0x100
	s_addc_u32 s45, s45, 0
	s_cmp_gt_u32 s50, 5
	s_cbranch_scc0 .LBB0_2272
	s_and_b64 vcc, exec, s[12:13]
	s_cbranch_vccz .LBB0_2275
	s_barrier

.LBB0_2338:
	s_lshl_b32 s1, s1, 5
	s_and_b32 s1, s1, 0x60
	s_lshl_b32 s5, s0, 13
	s_lshl_b32 s16, s1, 7
	s_add_u32 s10, s54, 0x8000000
	s_mov_b64 s[12:13], 0x80
	s_addc_u32 s11, s55, 0
	s_add_i32 m0, s9, 0x18000
	v_lshl_add_u64 v[6:7], v[6:7], 0, s[12:13]
	s_waitcnt vmcnt(2)
	s_barrier
	global_load_lds_dwordx4 v[6:7], off
	v_lshl_add_u64 v[4:5], v[4:5], 0, s[12:13]
	s_add_i32 m0, s9, 0x1a000
	s_add_i32 s33, s9, 0x8000
	s_add_i32 s65, s9, 0xa000
	global_load_lds_dwordx4 v[4:5], off
	v_lshl_add_u64 v[0:1], v[0:1], 0, s[12:13]
	s_mov_b32 m0, s33
	s_add_u32 s14, s72, 0x80080
	global_load_lds_dwordx4 v[0:1], off
	v_lshl_add_u64 v[0:1], v[2:3], 0, s[12:13]
	s_mov_b32 m0, s65
	s_addc_u32 s15, s73, 0
	global_load_lds_dwordx4 v[0:1], off
	s_add_i32 m0, s9, 0x1c000
	s_nop 0
	global_load_lds_dwordx4 v128, s[14:15]
	s_add_i32 m0, s9, 0x1e000
	s_cmpk_lt_u32 s3, 0x100
	global_load_lds_dwordx4 v130, s[14:15]
	v_bfe_u32 v1, v8, 4, 2
	v_and_b32_e32 v0, 15, v8
	v_lshlrev_b32_e32 v2, 4, v1
	v_lshl_or_b32 v146, s0, 6, v0
	v_lshl_or_b32 v0, v0, 6, v2
	v_lshlrev_b32_e32 v2, 2, v8
	v_and_b32_e32 v2, 32, v2
	v_bitop3_b32 v3, v0, s5, v2 bitop3:0xde
	v_bitop3_b32 v147, v0, s16, v2 bitop3:0xde
	v_lshlrev_b32_e32 v0, 15, v9
	v_and_b32_e32 v0, 0xffff0000, v0
	v_lshl_or_b32 v148, v1, 2, s1
	v_lshl_add_u32 v0, v10, 12, v0
	v_and_b32_e32 v1, 1, v9
	v_lshl_or_b32 v0, v1, 6, v0
	v_lshl_add_u32 v132, v11, 1, v0
	v_lshlrev_b32_e32 v0, 15, v12
	v_and_b32_e32 v0, 0xffff0000, v0
	s_waitcnt vmcnt(6)
	v_lshl_add_u32 v0, v13, 12, v0
	v_and_b32_e32 v1, 1, v12
	s_cselect_b64 s[14:15], -1, 0
	v_lshl_or_b32 v0, v1, 6, v0
	s_add_i32 s68, 0, 0x10000
	s_add_i32 s69, 0, 0x14000
	s_sext_i32_i8 s24, s4
	v_mov_b32_e32 v133, v129
	v_lshl_add_u32 v134, v14, 1, v0
	v_mov_b32_e32 v135, v129
	v_mov_b64_e32 v[136:137], 0x200
	v_mov_b64_e32 v[138:139], 0x1ff
	v_add_u32_e32 v149, s68, v147
	v_add_u32_e32 v150, s69, v147
	v_add_u32_e32 v151, 0, v3
	s_mov_b64 s[16:17], 0x50010
	s_mov_b64 s[34:35], 0x50080
	s_mov_b64 s[36:37], 0x50090
	s_mov_b64 s[42:43], 0x58000
	s_mov_b64 s[48:49], 0x58010
	s_mov_b64 s[52:53], 0x58080
	s_mov_b64 s[54:55], 0x58090
	s_barrier
	s_branch .LBB0_2341

.LBB0_2348:
	ds_read_b128 v[140:143], v149
	ds_read_b128 v[152:155], v149 offset:1024
	ds_read_b128 v[156:159], v149 offset:2048
	ds_read_b128 v[160:163], v149 offset:3072
	ds_read_b128 v[164:167], v150
	ds_read_b128 v[168:171], v150 offset:1024
	ds_read_b128 v[172:175], v150 offset:2048
	ds_read_b128 v[176:179], v150 offset:3072
	s_add_u32 s3, s66, 0xfff80080
	s_addc_u32 s59, s67, -1
	s_cmp_eq_u32 s57, 28
	s_cselect_b32 s75, s0, s59
	s_cselect_b32 s74, s1, s3
	s_cselect_b32 s73, s44, s51
	s_cselect_b32 s72, s45, s50
	s_add_i32 m0, s9, 0xc000
	ds_read_b128 v[180:183], v151
	ds_read_b128 v[184:187], v151 offset:1024
	ds_read_b128 v[188:191], v151 offset:2048
	ds_read_b128 v[192:195], v151 offset:3072
	ds_read_b128 v[196:199], v151 offset:4096
	ds_read_b128 v[200:203], v151 offset:5120
	ds_read_b128 v[204:207], v151 offset:6144
	ds_read_b128 v[208:211], v151 offset:7168
	global_load_lds_dwordx4 v132, s[66:67]
	s_add_i32 m0, s9, 0xe000
	s_nop 0
	global_load_lds_dwordx4 v134, s[66:67]
	s_waitcnt vmcnt(8)
	s_waitcnt lgkmcnt(0)
	s_barrier
	s_setprio 1
	s_waitcnt lgkmcnt(0)
	v_mfma_f32_16x16x32_bf16 v[124:127], v[140:143], v[180:183], v[124:127]
	v_mfma_f32_16x16x32_bf16 v[120:123], v[156:159], v[180:183], v[120:123]
	v_mfma_f32_16x16x32_bf16 v[108:111], v[140:143], v[188:191], v[108:111]
	v_mfma_f32_16x16x32_bf16 v[104:107], v[156:159], v[188:191], v[104:107]
	v_mfma_f32_16x16x32_bf16 v[92:95], v[140:143], v[196:199], v[92:95]
	v_mfma_f32_16x16x32_bf16 v[88:91], v[156:159], v[196:199], v[88:91]
	v_mfma_f32_16x16x32_bf16 v[76:79], v[140:143], v[204:207], v[76:79]
	v_mfma_f32_16x16x32_bf16 v[72:75], v[156:159], v[204:207], v[72:75]
	v_mfma_f32_16x16x32_bf16 v[124:127], v[152:155], v[184:187], v[124:127]
	v_mfma_f32_16x16x32_bf16 v[120:123], v[160:163], v[184:187], v[120:123]
	v_mfma_f32_16x16x32_bf16 v[108:111], v[152:155], v[192:195], v[108:111]
	v_mfma_f32_16x16x32_bf16 v[104:107], v[160:163], v[192:195], v[104:107]
	v_mfma_f32_16x16x32_bf16 v[92:95], v[152:155], v[200:203], v[92:95]
	v_mfma_f32_16x16x32_bf16 v[88:91], v[160:163], v[200:203], v[88:91]
	v_mfma_f32_16x16x32_bf16 v[76:79], v[152:155], v[208:211], v[76:79]
	v_mfma_f32_16x16x32_bf16 v[72:75], v[160:163], v[208:211], v[72:75]
	s_setprio 0
	s_setprio 1
	v_mfma_f32_16x16x32_bf16 v[116:119], v[164:167], v[180:183], v[116:119]
	v_mfma_f32_16x16x32_bf16 v[112:115], v[172:175], v[180:183], v[112:115]
	v_mfma_f32_16x16x32_bf16 v[100:103], v[164:167], v[188:191], v[100:103]
	v_mfma_f32_16x16x32_bf16 v[96:99], v[172:175], v[188:191], v[96:99]
	v_mfma_f32_16x16x32_bf16 v[84:87], v[164:167], v[196:199], v[84:87]
	v_mfma_f32_16x16x32_bf16 v[80:83], v[172:175], v[196:199], v[80:83]
	v_mfma_f32_16x16x32_bf16 v[68:71], v[164:167], v[204:207], v[68:71]
	v_mfma_f32_16x16x32_bf16 v[64:67], v[172:175], v[204:207], v[64:67]
	v_mfma_f32_16x16x32_bf16 v[116:119], v[168:171], v[184:187], v[116:119]
	v_mfma_f32_16x16x32_bf16 v[112:115], v[176:179], v[184:187], v[112:115]
	v_mfma_f32_16x16x32_bf16 v[100:103], v[168:171], v[192:195], v[100:103]
	v_mfma_f32_16x16x32_bf16 v[96:99], v[176:179], v[192:195], v[96:99]
	v_mfma_f32_16x16x32_bf16 v[84:87], v[168:171], v[200:203], v[84:87]
	v_mfma_f32_16x16x32_bf16 v[80:83], v[176:179], v[200:203], v[80:83]
	v_mfma_f32_16x16x32_bf16 v[68:71], v[168:171], v[208:211], v[68:71]
	v_mfma_f32_16x16x32_bf16 v[64:67], v[176:179], v[208:211], v[64:67]
	s_setprio 0
	s_barrier
	s_add_i32 s3, s68, s8
	v_lshl_add_u64 v[144:145], s[72:73], 0, v[128:129]
	s_mov_b32 m0, s3
	ds_read_b128 v[180:183], v151 offset:16384
	ds_read_b128 v[184:187], v151 offset:17408
	ds_read_b128 v[188:191], v151 offset:18432
	ds_read_b128 v[192:195], v151 offset:19456
	ds_read_b128 v[196:199], v151 offset:20480
	ds_read_b128 v[200:203], v151 offset:21504
	ds_read_b128 v[204:207], v151 offset:22528
	ds_read_b128 v[208:211], v151 offset:23552
	global_load_lds_dwordx4 v[144:145], off
	s_add_i32 m0, s3, 0x2000
	s_add_u32 s70, s72, 0x80000
	v_lshl_add_u64 v[212:213], s[72:73], 0, v[130:131]
	s_addc_u32 s71, s73, 0
	s_add_i32 s3, s69, s8
	global_load_lds_dwordx4 v[212:213], off
	s_mov_b32 m0, s3
	v_lshl_add_u64 v[216:217], s[74:75], 0, v[130:131]
	global_load_lds_dwordx4 v128, s[70:71]
	s_add_i32 m0, s3, 0x2000
	s_nop 0
	global_load_lds_dwordx4 v130, s[70:71]
	v_lshl_add_u64 v[214:215], s[74:75], 0, v[128:129]
	s_mov_b32 m0, s9
	s_nop 0
	global_load_lds_dwordx4 v[214:215], off
	s_mov_b32 m0, s18
	s_nop 0
	global_load_lds_dwordx4 v[216:217], off
	s_waitcnt vmcnt(8)
	s_waitcnt lgkmcnt(0)
	s_barrier
	s_setprio 1
	s_waitcnt lgkmcnt(0)
	v_mfma_f32_16x16x32_bf16 v[60:63], v[140:143], v[180:183], v[60:63]
	v_mfma_f32_16x16x32_bf16 v[56:59], v[156:159], v[180:183], v[56:59]
	v_mfma_f32_16x16x32_bf16 v[44:47], v[140:143], v[188:191], v[44:47]
	v_mfma_f32_16x16x32_bf16 v[40:43], v[156:159], v[188:191], v[40:43]
	v_mfma_f32_16x16x32_bf16 v[28:31], v[140:143], v[196:199], v[28:31]
	v_mfma_f32_16x16x32_bf16 v[24:27], v[156:159], v[196:199], v[24:27]
	v_mfma_f32_16x16x32_bf16 v[12:15], v[140:143], v[204:207], v[12:15]
	v_mfma_f32_16x16x32_bf16 v[8:11], v[156:159], v[204:207], v[8:11]
	v_mfma_f32_16x16x32_bf16 v[60:63], v[152:155], v[184:187], v[60:63]
	v_mfma_f32_16x16x32_bf16 v[56:59], v[160:163], v[184:187], v[56:59]
	v_mfma_f32_16x16x32_bf16 v[44:47], v[152:155], v[192:195], v[44:47]
	v_mfma_f32_16x16x32_bf16 v[40:43], v[160:163], v[192:195], v[40:43]
	v_mfma_f32_16x16x32_bf16 v[28:31], v[152:155], v[200:203], v[28:31]
	v_mfma_f32_16x16x32_bf16 v[24:27], v[160:163], v[200:203], v[24:27]
	v_mfma_f32_16x16x32_bf16 v[12:15], v[152:155], v[208:211], v[12:15]
	v_mfma_f32_16x16x32_bf16 v[8:11], v[160:163], v[208:211], v[8:11]
	s_setprio 0
	s_setprio 1
	v_mfma_f32_16x16x32_bf16 v[52:55], v[164:167], v[180:183], v[52:55]
	v_mfma_f32_16x16x32_bf16 v[48:51], v[172:175], v[180:183], v[48:51]
	v_mfma_f32_16x16x32_bf16 v[36:39], v[164:167], v[188:191], v[36:39]
	v_mfma_f32_16x16x32_bf16 v[32:35], v[172:175], v[188:191], v[32:35]
	v_mfma_f32_16x16x32_bf16 v[20:23], v[164:167], v[196:199], v[20:23]
	v_mfma_f32_16x16x32_bf16 v[16:19], v[172:175], v[196:199], v[16:19]
	v_mfma_f32_16x16x32_bf16 v[4:7], v[164:167], v[204:207], v[4:7]
	v_mfma_f32_16x16x32_bf16 v[0:3], v[172:175], v[204:207], v[0:3]
	v_mfma_f32_16x16x32_bf16 v[52:55], v[168:171], v[184:187], v[52:55]
	v_mfma_f32_16x16x32_bf16 v[48:51], v[176:179], v[184:187], v[48:51]
	v_mfma_f32_16x16x32_bf16 v[36:39], v[168:171], v[192:195], v[36:39]
	v_mfma_f32_16x16x32_bf16 v[32:35], v[176:179], v[192:195], v[32:35]
	v_mfma_f32_16x16x32_bf16 v[20:23], v[168:171], v[200:203], v[20:23]
	v_mfma_f32_16x16x32_bf16 v[16:19], v[176:179], v[200:203], v[16:19]
	v_mfma_f32_16x16x32_bf16 v[4:7], v[168:171], v[208:211], v[4:7]
	v_mfma_f32_16x16x32_bf16 v[0:3], v[176:179], v[208:211], v[0:3]
	s_setprio 0
	s_barrier
	s_add_i32 s3, 0, 0x18000
	s_add_i32 s59, 0, 0x1c000
	v_add_u32_e32 v160, s3, v147
	v_add_u32_e32 v176, s59, v147
	ds_read_b128 v[140:143], v160
	ds_read_b128 v[152:155], v160 offset:1024
	ds_read_b128 v[156:159], v160 offset:2048
	ds_read_b128 v[160:163], v160 offset:3072
	ds_read_b128 v[164:167], v176
	ds_read_b128 v[168:171], v176 offset:1024
	ds_read_b128 v[172:175], v176 offset:2048
	ds_read_b128 v[176:179], v176 offset:3072
	s_add_u32 s70, s74, 0x80000
	s_addc_u32 s71, s75, 0
	s_mov_b32 m0, s19
	ds_read_b128 v[180:183], v151 offset:32768
	ds_read_b128 v[184:187], v151 offset:33792
	ds_read_b128 v[188:191], v151 offset:34816
	ds_read_b128 v[192:195], v151 offset:35840
	ds_read_b128 v[196:199], v151 offset:36864
	ds_read_b128 v[200:203], v151 offset:37888
	ds_read_b128 v[204:207], v151 offset:38912
	ds_read_b128 v[208:211], v151 offset:39936
	global_load_lds_dwordx4 v128, s[70:71]
	s_mov_b32 m0, s25
	s_nop 0
	global_load_lds_dwordx4 v130, s[70:71]
	s_waitcnt vmcnt(8)
	s_waitcnt lgkmcnt(0)
	s_barrier
	s_setprio 1
	s_waitcnt lgkmcnt(0)
	v_mfma_f32_16x16x32_bf16 v[124:127], v[140:143], v[180:183], v[124:127]
	v_mfma_f32_16x16x32_bf16 v[120:123], v[156:159], v[180:183], v[120:123]
	v_mfma_f32_16x16x32_bf16 v[108:111], v[140:143], v[188:191], v[108:111]
	v_mfma_f32_16x16x32_bf16 v[104:107], v[156:159], v[188:191], v[104:107]
	v_mfma_f32_16x16x32_bf16 v[92:95], v[140:143], v[196:199], v[92:95]
	v_mfma_f32_16x16x32_bf16 v[88:91], v[156:159], v[196:199], v[88:91]
	v_mfma_f32_16x16x32_bf16 v[76:79], v[140:143], v[204:207], v[76:79]
	v_mfma_f32_16x16x32_bf16 v[72:75], v[156:159], v[204:207], v[72:75]
	v_mfma_f32_16x16x32_bf16 v[124:127], v[152:155], v[184:187], v[124:127]
	v_mfma_f32_16x16x32_bf16 v[120:123], v[160:163], v[184:187], v[120:123]
	v_mfma_f32_16x16x32_bf16 v[108:111], v[152:155], v[192:195], v[108:111]
	v_mfma_f32_16x16x32_bf16 v[104:107], v[160:163], v[192:195], v[104:107]
	v_mfma_f32_16x16x32_bf16 v[92:95], v[152:155], v[200:203], v[92:95]
	v_mfma_f32_16x16x32_bf16 v[88:91], v[160:163], v[200:203], v[88:91]
	v_mfma_f32_16x16x32_bf16 v[76:79], v[152:155], v[208:211], v[76:79]
	v_mfma_f32_16x16x32_bf16 v[72:75], v[160:163], v[208:211], v[72:75]
	s_setprio 0
	s_setprio 1
	v_mfma_f32_16x16x32_bf16 v[116:119], v[164:167], v[180:183], v[116:119]
	v_mfma_f32_16x16x32_bf16 v[112:115], v[172:175], v[180:183], v[112:115]
	v_mfma_f32_16x16x32_bf16 v[100:103], v[164:167], v[188:191], v[100:103]
	v_mfma_f32_16x16x32_bf16 v[96:99], v[172:175], v[188:191], v[96:99]
	v_mfma_f32_16x16x32_bf16 v[84:87], v[164:167], v[196:199], v[84:87]
	v_mfma_f32_16x16x32_bf16 v[80:83], v[172:175], v[196:199], v[80:83]
	v_mfma_f32_16x16x32_bf16 v[68:71], v[164:167], v[204:207], v[68:71]
	v_mfma_f32_16x16x32_bf16 v[64:67], v[172:175], v[204:207], v[64:67]
	v_mfma_f32_16x16x32_bf16 v[116:119], v[168:171], v[184:187], v[116:119]
	v_mfma_f32_16x16x32_bf16 v[112:115], v[176:179], v[184:187], v[112:115]
	v_mfma_f32_16x16x32_bf16 v[100:103], v[168:171], v[192:195], v[100:103]
	v_mfma_f32_16x16x32_bf16 v[96:99], v[176:179], v[192:195], v[96:99]
	v_mfma_f32_16x16x32_bf16 v[84:87], v[168:171], v[200:203], v[84:87]
	v_mfma_f32_16x16x32_bf16 v[80:83], v[176:179], v[200:203], v[80:83]
	v_mfma_f32_16x16x32_bf16 v[68:71], v[168:171], v[208:211], v[68:71]
	v_mfma_f32_16x16x32_bf16 v[64:67], v[176:179], v[208:211], v[64:67]
	s_setprio 0
	s_barrier
	s_add_i32 s3, s3, s8
	v_lshl_add_u64 v[144:145], v[144:145], 0, s[12:13]
	s_mov_b32 m0, s3
	ds_read_b128 v[180:183], v151 offset:49152
	ds_read_b128 v[184:187], v151 offset:50176
	ds_read_b128 v[188:191], v151 offset:51200
	ds_read_b128 v[192:195], v151 offset:52224
	ds_read_b128 v[196:199], v151 offset:53248
	ds_read_b128 v[200:203], v151 offset:54272
	ds_read_b128 v[204:207], v151 offset:55296
	ds_read_b128 v[208:211], v151 offset:56320
	global_load_lds_dwordx4 v[144:145], off
	s_add_i32 m0, s3, 0x2000
	s_add_u32 s70, s72, 0x80080
	v_lshl_add_u64 v[144:145], v[212:213], 0, s[12:13]
	s_addc_u32 s71, s73, 0
	s_add_i32 s3, s59, s8
	global_load_lds_dwordx4 v[144:145], off
	s_mov_b32 m0, s3
	s_nop 0
	global_load_lds_dwordx4 v128, s[70:71]
	s_add_i32 m0, s3, 0x2000
	s_nop 0
	global_load_lds_dwordx4 v130, s[70:71]
	v_lshl_add_u64 v[144:145], v[214:215], 0, s[12:13]
	s_mov_b32 m0, s33
	s_nop 0
	global_load_lds_dwordx4 v[144:145], off
	v_lshl_add_u64 v[144:145], v[216:217], 0, s[12:13]
	s_mov_b32 m0, s65
	s_nop 0
	global_load_lds_dwordx4 v[144:145], off
	s_waitcnt vmcnt(8)
	s_waitcnt lgkmcnt(0)
	s_barrier
	s_setprio 1
	s_waitcnt lgkmcnt(0)
	v_mfma_f32_16x16x32_bf16 v[60:63], v[140:143], v[180:183], v[60:63]
	v_mfma_f32_16x16x32_bf16 v[56:59], v[156:159], v[180:183], v[56:59]
	v_mfma_f32_16x16x32_bf16 v[44:47], v[140:143], v[188:191], v[44:47]
	v_mfma_f32_16x16x32_bf16 v[40:43], v[156:159], v[188:191], v[40:43]
	v_mfma_f32_16x16x32_bf16 v[28:31], v[140:143], v[196:199], v[28:31]
	v_mfma_f32_16x16x32_bf16 v[24:27], v[156:159], v[196:199], v[24:27]
	v_mfma_f32_16x16x32_bf16 v[12:15], v[140:143], v[204:207], v[12:15]
	v_mfma_f32_16x16x32_bf16 v[8:11], v[156:159], v[204:207], v[8:11]
	v_mfma_f32_16x16x32_bf16 v[60:63], v[152:155], v[184:187], v[60:63]
	v_mfma_f32_16x16x32_bf16 v[56:59], v[160:163], v[184:187], v[56:59]
	v_mfma_f32_16x16x32_bf16 v[44:47], v[152:155], v[192:195], v[44:47]
	v_mfma_f32_16x16x32_bf16 v[40:43], v[160:163], v[192:195], v[40:43]
	v_mfma_f32_16x16x32_bf16 v[28:31], v[152:155], v[200:203], v[28:31]
	v_mfma_f32_16x16x32_bf16 v[24:27], v[160:163], v[200:203], v[24:27]
	v_mfma_f32_16x16x32_bf16 v[12:15], v[152:155], v[208:211], v[12:15]
	v_mfma_f32_16x16x32_bf16 v[8:11], v[160:163], v[208:211], v[8:11]
	s_setprio 0
	s_setprio 1
	v_mfma_f32_16x16x32_bf16 v[52:55], v[164:167], v[180:183], v[52:55]
	v_mfma_f32_16x16x32_bf16 v[48:51], v[172:175], v[180:183], v[48:51]
	v_mfma_f32_16x16x32_bf16 v[36:39], v[164:167], v[188:191], v[36:39]
	v_mfma_f32_16x16x32_bf16 v[32:35], v[172:175], v[188:191], v[32:35]
	v_mfma_f32_16x16x32_bf16 v[20:23], v[164:167], v[196:199], v[20:23]
	v_mfma_f32_16x16x32_bf16 v[16:19], v[172:175], v[196:199], v[16:19]
	v_mfma_f32_16x16x32_bf16 v[4:7], v[164:167], v[204:207], v[4:7]
	v_mfma_f32_16x16x32_bf16 v[0:3], v[172:175], v[204:207], v[0:3]
	v_mfma_f32_16x16x32_bf16 v[52:55], v[168:171], v[184:187], v[52:55]
	v_mfma_f32_16x16x32_bf16 v[48:51], v[176:179], v[184:187], v[48:51]
	v_mfma_f32_16x16x32_bf16 v[36:39], v[168:171], v[192:195], v[36:39]
	v_mfma_f32_16x16x32_bf16 v[32:35], v[176:179], v[192:195], v[32:35]
	v_mfma_f32_16x16x32_bf16 v[20:23], v[168:171], v[200:203], v[20:23]
	v_mfma_f32_16x16x32_bf16 v[16:19], v[176:179], v[200:203], v[16:19]
	v_mfma_f32_16x16x32_bf16 v[4:7], v[168:171], v[208:211], v[4:7]
	v_mfma_f32_16x16x32_bf16 v[0:3], v[176:179], v[208:211], v[0:3]
	s_setprio 0
	s_barrier
	s_add_i32 s57, s57, 2
	s_add_u32 s66, s66, 0x100
	s_addc_u32 s67, s67, 0
	s_add_u32 s50, s50, 0x100
	s_addc_u32 s51, s51, 0
	s_cmp_gt_u32 s57, 29
	s_cbranch_scc0 .LBB0_2348
	s_and_b64 vcc, exec, s[14:15]
	s_cbranch_vccz .LBB0_2351
	s_barrier

.LBB0_2469:
	s_lshl_b32 s1, s1, 5
	s_mov_b64 s[10:11], 0x80
	s_and_b32 s1, s1, 0x60
	s_add_i32 m0, s19, 0x18000
	v_lshl_add_u64 v[6:7], v[6:7], 0, s[10:11]
	s_lshl_b32 s5, s0, 13
	s_lshl_b32 s6, s1, 7
	s_waitcnt vmcnt(2)
	s_barrier
	global_load_lds_dwordx4 v[6:7], off
	v_lshl_add_u64 v[4:5], v[4:5], 0, s[10:11]
	s_add_i32 m0, s19, 0x1a000
	s_add_i32 s52, s19, 0x8000
	s_add_i32 s53, s19, 0xa000
	global_load_lds_dwordx4 v[4:5], off
	v_lshl_add_u64 v[0:1], v[0:1], 0, s[10:11]
	s_mov_b32 m0, s52
	s_add_u32 s12, s44, 0x80080
	global_load_lds_dwordx4 v[0:1], off
	v_lshl_add_u64 v[0:1], v[2:3], 0, s[10:11]
	s_mov_b32 m0, s53
	s_addc_u32 s13, s45, 0
	global_load_lds_dwordx4 v[0:1], off
	s_add_i32 m0, s19, 0x1c000
	s_nop 0
	global_load_lds_dwordx4 v130, s[12:13]
	s_add_i32 m0, s19, 0x1e000
	s_cmpk_lt_u32 s3, 0x100
	global_load_lds_dwordx4 v134, s[12:13]
	v_lshrrev_b32_e32 v0, 1, v8
	v_and_b32_e32 v0, 24, v0
	v_and_b32_e32 v1, 15, v8
	v_lshlrev_b32_e32 v2, 1, v0
	v_lshl_or_b32 v148, s0, 6, v1
	v_lshl_or_b32 v1, v1, 6, v2
	v_lshlrev_b32_e32 v2, 2, v8
	v_and_b32_e32 v2, 32, v2
	v_bitop3_b32 v3, v1, s5, v2 bitop3:0xde
	v_bitop3_b32 v149, v1, s6, v2 bitop3:0xde
	v_lshlrev_b32_e32 v1, 15, v9
	v_and_b32_e32 v1, 0xffff0000, v1
	v_lshl_add_u32 v1, v10, 12, v1
	v_and_b32_e32 v2, 1, v9
	v_lshl_or_b32 v1, v2, 6, v1
	v_lshl_add_u32 v138, v11, 1, v1
	v_lshlrev_b32_e32 v1, 15, v12
	v_and_b32_e32 v1, 0xffff0000, v1
	s_waitcnt vmcnt(6)
	v_lshl_add_u32 v1, v13, 12, v1
	v_and_b32_e32 v2, 1, v12
	s_cselect_b64 s[12:13], -1, 0
	v_lshl_or_b32 v1, v2, 6, v1
	s_add_i32 s54, 0, 0x10000
	s_add_i32 s55, 0, 0x14000
	s_sext_i32_i8 s24, s4
	v_mov_b32_e32 v139, v137
	v_lshl_add_u32 v140, v14, 1, v1
	v_mov_b32_e32 v141, v137
	v_mov_b64_e32 v[142:143], 0x800
	v_mov_b64_e32 v[144:145], 0x7ff
	v_add_u32_e32 v150, s54, v149
	v_add_u32_e32 v151, s55, v149
	v_add_u32_e32 v152, 0, v3
	s_lshl_b32 s6, s1, 1
	v_lshlrev_b32_e32 v136, 1, v0
	s_mov_b32 s56, s7
	s_barrier
	s_branch .LBB0_2472

.LBB0_2479:
	ds_read_b128 v[154:157], v150
	ds_read_b128 v[158:161], v150 offset:1024
	ds_read_b128 v[162:165], v150 offset:2048
	ds_read_b128 v[166:169], v150 offset:3072
	ds_read_b128 v[170:173], v151
	ds_read_b128 v[174:177], v151 offset:1024
	ds_read_b128 v[178:181], v151 offset:2048
	ds_read_b128 v[182:185], v151 offset:3072
	s_add_u32 s3, s42, 0xfff80080
	s_addc_u32 s44, s43, -1
	s_cmp_eq_u32 s51, 28
	s_cselect_b32 s49, s0, s44
	s_cselect_b32 s48, s1, s3
	s_cselect_b32 s45, s15, s50
	s_cselect_b32 s44, s17, s41
	s_add_i32 m0, s19, 0xc000
	ds_read_b128 v[186:189], v152
	ds_read_b128 v[190:193], v152 offset:1024
	ds_read_b128 v[194:197], v152 offset:2048
	ds_read_b128 v[198:201], v152 offset:3072
	ds_read_b128 v[202:205], v152 offset:4096
	ds_read_b128 v[206:209], v152 offset:5120
	ds_read_b128 v[210:213], v152 offset:6144
	ds_read_b128 v[214:217], v152 offset:7168
	global_load_lds_dwordx4 v138, s[42:43]
	s_add_i32 m0, s19, 0xe000
	s_nop 0
	global_load_lds_dwordx4 v140, s[42:43]
	s_waitcnt vmcnt(8)
	s_waitcnt lgkmcnt(0)
	s_barrier
	s_setprio 1
	s_waitcnt lgkmcnt(0)
	v_mfma_f32_16x16x32_bf16 v[124:127], v[154:157], v[186:189], v[124:127]
	v_mfma_f32_16x16x32_bf16 v[120:123], v[162:165], v[186:189], v[120:123]
	v_mfma_f32_16x16x32_bf16 v[108:111], v[154:157], v[194:197], v[108:111]
	v_mfma_f32_16x16x32_bf16 v[104:107], v[162:165], v[194:197], v[104:107]
	v_mfma_f32_16x16x32_bf16 v[92:95], v[154:157], v[202:205], v[92:95]
	v_mfma_f32_16x16x32_bf16 v[88:91], v[162:165], v[202:205], v[88:91]
	v_mfma_f32_16x16x32_bf16 v[76:79], v[154:157], v[210:213], v[76:79]
	v_mfma_f32_16x16x32_bf16 v[72:75], v[162:165], v[210:213], v[72:75]
	v_mfma_f32_16x16x32_bf16 v[124:127], v[158:161], v[190:193], v[124:127]
	v_mfma_f32_16x16x32_bf16 v[120:123], v[166:169], v[190:193], v[120:123]
	v_mfma_f32_16x16x32_bf16 v[108:111], v[158:161], v[198:201], v[108:111]
	v_mfma_f32_16x16x32_bf16 v[104:107], v[166:169], v[198:201], v[104:107]
	v_mfma_f32_16x16x32_bf16 v[92:95], v[158:161], v[206:209], v[92:95]
	v_mfma_f32_16x16x32_bf16 v[88:91], v[166:169], v[206:209], v[88:91]
	v_mfma_f32_16x16x32_bf16 v[76:79], v[158:161], v[214:217], v[76:79]
	v_mfma_f32_16x16x32_bf16 v[72:75], v[166:169], v[214:217], v[72:75]
	s_setprio 0
	s_setprio 1
	v_mfma_f32_16x16x32_bf16 v[116:119], v[170:173], v[186:189], v[116:119]
	v_mfma_f32_16x16x32_bf16 v[112:115], v[178:181], v[186:189], v[112:115]
	v_mfma_f32_16x16x32_bf16 v[100:103], v[170:173], v[194:197], v[100:103]
	v_mfma_f32_16x16x32_bf16 v[96:99], v[178:181], v[194:197], v[96:99]
	v_mfma_f32_16x16x32_bf16 v[84:87], v[170:173], v[202:205], v[84:87]
	v_mfma_f32_16x16x32_bf16 v[80:83], v[178:181], v[202:205], v[80:83]
	v_mfma_f32_16x16x32_bf16 v[68:71], v[170:173], v[210:213], v[68:71]
	v_mfma_f32_16x16x32_bf16 v[64:67], v[178:181], v[210:213], v[64:67]
	v_mfma_f32_16x16x32_bf16 v[116:119], v[174:177], v[190:193], v[116:119]
	v_mfma_f32_16x16x32_bf16 v[112:115], v[182:185], v[190:193], v[112:115]
	v_mfma_f32_16x16x32_bf16 v[100:103], v[174:177], v[198:201], v[100:103]
	v_mfma_f32_16x16x32_bf16 v[96:99], v[182:185], v[198:201], v[96:99]
	v_mfma_f32_16x16x32_bf16 v[84:87], v[174:177], v[206:209], v[84:87]
	v_mfma_f32_16x16x32_bf16 v[80:83], v[182:185], v[206:209], v[80:83]
	v_mfma_f32_16x16x32_bf16 v[68:71], v[174:177], v[214:217], v[68:71]
	v_mfma_f32_16x16x32_bf16 v[64:67], v[182:185], v[214:217], v[64:67]
	s_setprio 0
	s_barrier
	s_add_i32 s3, s54, s18
	v_lshl_add_u64 v[146:147], s[44:45], 0, v[130:131]
	s_mov_b32 m0, s3
	ds_read_b128 v[186:189], v152 offset:16384
	ds_read_b128 v[190:193], v152 offset:17408
	ds_read_b128 v[194:197], v152 offset:18432
	ds_read_b128 v[198:201], v152 offset:19456
	ds_read_b128 v[202:205], v152 offset:20480
	ds_read_b128 v[206:209], v152 offset:21504
	ds_read_b128 v[210:213], v152 offset:22528
	ds_read_b128 v[214:217], v152 offset:23552
	global_load_lds_dwordx4 v[146:147], off
	s_add_i32 m0, s3, 0x2000
	s_add_u32 s58, s44, 0x80000
	v_lshl_add_u64 v[218:219], s[44:45], 0, v[134:135]
	s_addc_u32 s59, s45, 0
	s_add_i32 s3, s55, s18
	global_load_lds_dwordx4 v[218:219], off
	s_mov_b32 m0, s3
	v_lshl_add_u64 v[222:223], s[48:49], 0, v[132:133]
	global_load_lds_dwordx4 v130, s[58:59]
	s_add_i32 m0, s3, 0x2000
	s_nop 0
	global_load_lds_dwordx4 v134, s[58:59]
	v_lshl_add_u64 v[220:221], s[48:49], 0, v[128:129]
	s_mov_b32 m0, s19
	s_nop 0
	global_load_lds_dwordx4 v[220:221], off
	s_mov_b32 m0, s25
	s_nop 0
	global_load_lds_dwordx4 v[222:223], off
	s_waitcnt vmcnt(8)
	s_waitcnt lgkmcnt(0)
	s_barrier
	s_setprio 1
	s_waitcnt lgkmcnt(0)
	v_mfma_f32_16x16x32_bf16 v[60:63], v[154:157], v[186:189], v[60:63]
	v_mfma_f32_16x16x32_bf16 v[56:59], v[162:165], v[186:189], v[56:59]
	v_mfma_f32_16x16x32_bf16 v[44:47], v[154:157], v[194:197], v[44:47]
	v_mfma_f32_16x16x32_bf16 v[40:43], v[162:165], v[194:197], v[40:43]
	v_mfma_f32_16x16x32_bf16 v[28:31], v[154:157], v[202:205], v[28:31]
	v_mfma_f32_16x16x32_bf16 v[24:27], v[162:165], v[202:205], v[24:27]
	v_mfma_f32_16x16x32_bf16 v[12:15], v[154:157], v[210:213], v[12:15]
	v_mfma_f32_16x16x32_bf16 v[8:11], v[162:165], v[210:213], v[8:11]
	v_mfma_f32_16x16x32_bf16 v[60:63], v[158:161], v[190:193], v[60:63]
	v_mfma_f32_16x16x32_bf16 v[56:59], v[166:169], v[190:193], v[56:59]
	v_mfma_f32_16x16x32_bf16 v[44:47], v[158:161], v[198:201], v[44:47]
	v_mfma_f32_16x16x32_bf16 v[40:43], v[166:169], v[198:201], v[40:43]
	v_mfma_f32_16x16x32_bf16 v[28:31], v[158:161], v[206:209], v[28:31]
	v_mfma_f32_16x16x32_bf16 v[24:27], v[166:169], v[206:209], v[24:27]
	v_mfma_f32_16x16x32_bf16 v[12:15], v[158:161], v[214:217], v[12:15]
	v_mfma_f32_16x16x32_bf16 v[8:11], v[166:169], v[214:217], v[8:11]
	s_setprio 0
	s_setprio 1
	v_mfma_f32_16x16x32_bf16 v[52:55], v[170:173], v[186:189], v[52:55]
	v_mfma_f32_16x16x32_bf16 v[48:51], v[178:181], v[186:189], v[48:51]
	v_mfma_f32_16x16x32_bf16 v[36:39], v[170:173], v[194:197], v[36:39]
	v_mfma_f32_16x16x32_bf16 v[32:35], v[178:181], v[194:197], v[32:35]
	v_mfma_f32_16x16x32_bf16 v[20:23], v[170:173], v[202:205], v[20:23]
	v_mfma_f32_16x16x32_bf16 v[16:19], v[178:181], v[202:205], v[16:19]
	v_mfma_f32_16x16x32_bf16 v[4:7], v[170:173], v[210:213], v[4:7]
	v_mfma_f32_16x16x32_bf16 v[0:3], v[178:181], v[210:213], v[0:3]
	v_mfma_f32_16x16x32_bf16 v[52:55], v[174:177], v[190:193], v[52:55]
	v_mfma_f32_16x16x32_bf16 v[48:51], v[182:185], v[190:193], v[48:51]
	v_mfma_f32_16x16x32_bf16 v[36:39], v[174:177], v[198:201], v[36:39]
	v_mfma_f32_16x16x32_bf16 v[32:35], v[182:185], v[198:201], v[32:35]
	v_mfma_f32_16x16x32_bf16 v[20:23], v[174:177], v[206:209], v[20:23]
	v_mfma_f32_16x16x32_bf16 v[16:19], v[182:185], v[206:209], v[16:19]
	v_mfma_f32_16x16x32_bf16 v[4:7], v[174:177], v[214:217], v[4:7]
	v_mfma_f32_16x16x32_bf16 v[0:3], v[182:185], v[214:217], v[0:3]
	s_setprio 0
	s_barrier
	s_add_i32 s3, 0, 0x18000
	v_add_u32_e32 v153, s3, v149
	s_add_i32 s57, 0, 0x1c000
	ds_read_b128 v[154:157], v153
	ds_read_b128 v[158:161], v153 offset:1024
	ds_read_b128 v[162:165], v153 offset:2048
	ds_read_b128 v[166:169], v153 offset:3072
	v_add_u32_e32 v153, s57, v149
	ds_read_b128 v[170:173], v153
	ds_read_b128 v[174:177], v153 offset:1024
	ds_read_b128 v[178:181], v153 offset:2048
	ds_read_b128 v[182:185], v153 offset:3072
	s_add_u32 s48, s48, 0x80000
	s_addc_u32 s49, s49, 0
	s_mov_b32 m0, s27
	ds_read_b128 v[186:189], v152 offset:32768
	ds_read_b128 v[190:193], v152 offset:33792
	ds_read_b128 v[194:197], v152 offset:34816
	ds_read_b128 v[198:201], v152 offset:35840
	ds_read_b128 v[202:205], v152 offset:36864
	ds_read_b128 v[206:209], v152 offset:37888
	ds_read_b128 v[210:213], v152 offset:38912
	ds_read_b128 v[214:217], v152 offset:39936
	global_load_lds_dwordx4 v128, s[48:49]
	s_mov_b32 m0, s33
	s_nop 0
	global_load_lds_dwordx4 v132, s[48:49]
	s_waitcnt vmcnt(8)
	s_waitcnt lgkmcnt(0)
	s_barrier
	s_setprio 1
	s_waitcnt lgkmcnt(0)
	v_mfma_f32_16x16x32_bf16 v[124:127], v[154:157], v[186:189], v[124:127]
	v_mfma_f32_16x16x32_bf16 v[120:123], v[162:165], v[186:189], v[120:123]
	v_mfma_f32_16x16x32_bf16 v[108:111], v[154:157], v[194:197], v[108:111]
	v_mfma_f32_16x16x32_bf16 v[104:107], v[162:165], v[194:197], v[104:107]
	v_mfma_f32_16x16x32_bf16 v[92:95], v[154:157], v[202:205], v[92:95]
	v_mfma_f32_16x16x32_bf16 v[88:91], v[162:165], v[202:205], v[88:91]
	v_mfma_f32_16x16x32_bf16 v[76:79], v[154:157], v[210:213], v[76:79]
	v_mfma_f32_16x16x32_bf16 v[72:75], v[162:165], v[210:213], v[72:75]
	v_mfma_f32_16x16x32_bf16 v[124:127], v[158:161], v[190:193], v[124:127]
	v_mfma_f32_16x16x32_bf16 v[120:123], v[166:169], v[190:193], v[120:123]
	v_mfma_f32_16x16x32_bf16 v[108:111], v[158:161], v[198:201], v[108:111]
	v_mfma_f32_16x16x32_bf16 v[104:107], v[166:169], v[198:201], v[104:107]
	v_mfma_f32_16x16x32_bf16 v[92:95], v[158:161], v[206:209], v[92:95]
	v_mfma_f32_16x16x32_bf16 v[88:91], v[166:169], v[206:209], v[88:91]
	v_mfma_f32_16x16x32_bf16 v[76:79], v[158:161], v[214:217], v[76:79]
	v_mfma_f32_16x16x32_bf16 v[72:75], v[166:169], v[214:217], v[72:75]
	s_setprio 0
	s_setprio 1
	v_mfma_f32_16x16x32_bf16 v[116:119], v[170:173], v[186:189], v[116:119]
	v_mfma_f32_16x16x32_bf16 v[112:115], v[178:181], v[186:189], v[112:115]
	v_mfma_f32_16x16x32_bf16 v[100:103], v[170:173], v[194:197], v[100:103]
	v_mfma_f32_16x16x32_bf16 v[96:99], v[178:181], v[194:197], v[96:99]
	v_mfma_f32_16x16x32_bf16 v[84:87], v[170:173], v[202:205], v[84:87]
	v_mfma_f32_16x16x32_bf16 v[80:83], v[178:181], v[202:205], v[80:83]
	v_mfma_f32_16x16x32_bf16 v[68:71], v[170:173], v[210:213], v[68:71]
	v_mfma_f32_16x16x32_bf16 v[64:67], v[178:181], v[210:213], v[64:67]
	v_mfma_f32_16x16x32_bf16 v[116:119], v[174:177], v[190:193], v[116:119]
	v_mfma_f32_16x16x32_bf16 v[112:115], v[182:185], v[190:193], v[112:115]
	v_mfma_f32_16x16x32_bf16 v[100:103], v[174:177], v[198:201], v[100:103]
	v_mfma_f32_16x16x32_bf16 v[96:99], v[182:185], v[198:201], v[96:99]
	v_mfma_f32_16x16x32_bf16 v[84:87], v[174:177], v[206:209], v[84:87]
	v_mfma_f32_16x16x32_bf16 v[80:83], v[182:185], v[206:209], v[80:83]
	v_mfma_f32_16x16x32_bf16 v[68:71], v[174:177], v[214:217], v[68:71]
	v_mfma_f32_16x16x32_bf16 v[64:67], v[182:185], v[214:217], v[64:67]
	s_setprio 0
	s_barrier
	s_add_i32 s3, s3, s18
	v_lshl_add_u64 v[146:147], v[146:147], 0, s[10:11]
	s_mov_b32 m0, s3
	ds_read_b128 v[186:189], v152 offset:49152
	ds_read_b128 v[190:193], v152 offset:50176
	ds_read_b128 v[194:197], v152 offset:51200
	ds_read_b128 v[198:201], v152 offset:52224
	ds_read_b128 v[202:205], v152 offset:53248
	ds_read_b128 v[206:209], v152 offset:54272
	ds_read_b128 v[210:213], v152 offset:55296
	ds_read_b128 v[214:217], v152 offset:56320
	global_load_lds_dwordx4 v[146:147], off
	s_add_i32 m0, s3, 0x2000
	s_add_u32 s44, s44, 0x80080
	v_lshl_add_u64 v[146:147], v[218:219], 0, s[10:11]
	s_addc_u32 s45, s45, 0
	s_add_i32 s3, s57, s18
	global_load_lds_dwordx4 v[146:147], off
	s_mov_b32 m0, s3
	s_nop 0
	global_load_lds_dwordx4 v130, s[44:45]
	s_add_i32 m0, s3, 0x2000
	s_nop 0
	global_load_lds_dwordx4 v134, s[44:45]
	v_lshl_add_u64 v[146:147], v[220:221], 0, s[10:11]
	s_mov_b32 m0, s52
	s_nop 0
	global_load_lds_dwordx4 v[146:147], off
	v_lshl_add_u64 v[146:147], v[222:223], 0, s[10:11]
	s_mov_b32 m0, s53
	s_nop 0
	global_load_lds_dwordx4 v[146:147], off
	s_waitcnt vmcnt(8)
	s_waitcnt lgkmcnt(0)
	s_barrier
	s_setprio 1
	s_waitcnt lgkmcnt(0)
	v_mfma_f32_16x16x32_bf16 v[60:63], v[154:157], v[186:189], v[60:63]
	v_mfma_f32_16x16x32_bf16 v[56:59], v[162:165], v[186:189], v[56:59]
	v_mfma_f32_16x16x32_bf16 v[44:47], v[154:157], v[194:197], v[44:47]
	v_mfma_f32_16x16x32_bf16 v[40:43], v[162:165], v[194:197], v[40:43]
	v_mfma_f32_16x16x32_bf16 v[28:31], v[154:157], v[202:205], v[28:31]
	v_mfma_f32_16x16x32_bf16 v[24:27], v[162:165], v[202:205], v[24:27]
	v_mfma_f32_16x16x32_bf16 v[12:15], v[154:157], v[210:213], v[12:15]
	v_mfma_f32_16x16x32_bf16 v[8:11], v[162:165], v[210:213], v[8:11]
	v_mfma_f32_16x16x32_bf16 v[60:63], v[158:161], v[190:193], v[60:63]
	v_mfma_f32_16x16x32_bf16 v[56:59], v[166:169], v[190:193], v[56:59]
	v_mfma_f32_16x16x32_bf16 v[44:47], v[158:161], v[198:201], v[44:47]
	v_mfma_f32_16x16x32_bf16 v[40:43], v[166:169], v[198:201], v[40:43]
	v_mfma_f32_16x16x32_bf16 v[28:31], v[158:161], v[206:209], v[28:31]
	v_mfma_f32_16x16x32_bf16 v[24:27], v[166:169], v[206:209], v[24:27]
	v_mfma_f32_16x16x32_bf16 v[12:15], v[158:161], v[214:217], v[12:15]
	v_mfma_f32_16x16x32_bf16 v[8:11], v[166:169], v[214:217], v[8:11]
	s_setprio 0
	s_setprio 1
	v_mfma_f32_16x16x32_bf16 v[52:55], v[170:173], v[186:189], v[52:55]
	v_mfma_f32_16x16x32_bf16 v[48:51], v[178:181], v[186:189], v[48:51]
	v_mfma_f32_16x16x32_bf16 v[36:39], v[170:173], v[194:197], v[36:39]
	v_mfma_f32_16x16x32_bf16 v[32:35], v[178:181], v[194:197], v[32:35]
	v_mfma_f32_16x16x32_bf16 v[20:23], v[170:173], v[202:205], v[20:23]
	v_mfma_f32_16x16x32_bf16 v[16:19], v[178:181], v[202:205], v[16:19]
	v_mfma_f32_16x16x32_bf16 v[4:7], v[170:173], v[210:213], v[4:7]
	v_mfma_f32_16x16x32_bf16 v[0:3], v[178:181], v[210:213], v[0:3]
	v_mfma_f32_16x16x32_bf16 v[52:55], v[174:177], v[190:193], v[52:55]
	v_mfma_f32_16x16x32_bf16 v[48:51], v[182:185], v[190:193], v[48:51]
	v_mfma_f32_16x16x32_bf16 v[36:39], v[174:177], v[198:201], v[36:39]
	v_mfma_f32_16x16x32_bf16 v[32:35], v[182:185], v[198:201], v[32:35]
	v_mfma_f32_16x16x32_bf16 v[20:23], v[174:177], v[206:209], v[20:23]
	v_mfma_f32_16x16x32_bf16 v[16:19], v[182:185], v[206:209], v[16:19]
	v_mfma_f32_16x16x32_bf16 v[4:7], v[174:177], v[214:217], v[4:7]
	v_mfma_f32_16x16x32_bf16 v[0:3], v[182:185], v[214:217], v[0:3]
	s_setprio 0
	s_barrier
	s_add_i32 s51, s51, 2
	s_add_u32 s42, s42, 0x100
	s_addc_u32 s43, s43, 0
	s_add_u32 s41, s41, 0x100
	s_addc_u32 s50, s50, 0
	s_cmp_gt_u32 s51, 29
	s_cbranch_scc0 .LBB0_2479
	s_and_b64 vcc, exec, s[12:13]
	s_cbranch_vccz .LBB0_2482
	s_barrier

.LBB0_2545:
	s_lshl_b32 s1, s1, 5
	s_mov_b64 s[8:9], 0x80
	s_and_b32 s1, s1, 0x60
	s_add_i32 m0, s27, 0x18000
	v_lshl_add_u64 v[6:7], v[6:7], 0, s[8:9]
	s_lshl_b32 s5, s0, 13
	s_lshl_b32 s12, s1, 7
	s_waitcnt vmcnt(2)
	s_barrier
	global_load_lds_dwordx4 v[6:7], off
	v_lshl_add_u64 v[4:5], v[4:5], 0, s[8:9]
	s_add_i32 m0, s27, 0x1a000
	s_add_i32 s56, s27, 0x8000
	s_add_i32 s57, s27, 0xa000
	global_load_lds_dwordx4 v[4:5], off
	v_lshl_add_u64 v[0:1], v[0:1], 0, s[8:9]
	s_mov_b32 m0, s56
	s_add_u32 s10, s52, 0x200080
	global_load_lds_dwordx4 v[0:1], off
	v_lshl_add_u64 v[0:1], v[2:3], 0, s[8:9]
	s_mov_b32 m0, s57
	s_addc_u32 s11, s53, 0
	global_load_lds_dwordx4 v[0:1], off
	s_add_i32 m0, s27, 0x1c000
	s_nop 0
	global_load_lds_dwordx4 v128, s[10:11]
	s_add_i32 m0, s27, 0x1e000
	s_cmpk_lt_u32 s3, 0x100
	global_load_lds_dwordx4 v130, s[10:11]
	v_bfe_u32 v1, v8, 4, 2
	v_and_b32_e32 v0, 15, v8
	v_lshlrev_b32_e32 v2, 4, v1
	v_lshl_or_b32 v146, s0, 6, v0
	v_lshl_or_b32 v0, v0, 6, v2
	v_lshlrev_b32_e32 v2, 2, v8
	v_and_b32_e32 v2, 32, v2
	v_bitop3_b32 v3, v0, s5, v2 bitop3:0xde
	v_bitop3_b32 v147, v0, s12, v2 bitop3:0xde
	v_lshlrev_b32_e32 v0, 17, v9
	v_and_b32_e32 v0, 0xfffc0000, v0
	v_lshl_or_b32 v148, v1, 2, s1
	v_lshl_add_u32 v0, v10, 14, v0
	v_and_b32_e32 v1, 1, v9
	v_lshl_or_b32 v0, v1, 6, v0
	v_lshl_add_u32 v132, v11, 1, v0
	v_lshlrev_b32_e32 v0, 17, v12
	v_and_b32_e32 v0, 0xfffc0000, v0
	s_waitcnt vmcnt(6)
	v_lshl_add_u32 v0, v13, 14, v0
	v_and_b32_e32 v1, 1, v12
	s_cselect_b64 s[10:11], -1, 0
	v_lshl_or_b32 v0, v1, 6, v0
	s_add_i32 s58, 0, 0x10000
	s_add_i32 s59, 0, 0x14000
	s_sext_i32_i8 s24, s4
	v_mov_b32_e32 v133, v129
	v_lshl_add_u32 v134, v14, 1, v0
	v_mov_b32_e32 v135, v129
	v_mov_b64_e32 v[136:137], 0x200
	v_mov_b64_e32 v[138:139], 0x1ff
	v_add_u32_e32 v149, s58, v147
	v_add_u32_e32 v150, s59, v147
	v_add_u32_e32 v151, 0, v3
	s_mov_b64 s[12:13], 0x80000
	s_mov_b32 s60, 0x80000
	s_mov_b64 s[14:15], 0x90000
	s_mov_b32 s61, 0x90000
	s_mov_b64 s[16:17], 0xa0000
	s_mov_b32 s62, 0xa0000
	s_mov_b64 s[18:19], 0xb0000
	s_mov_b32 s63, 0xb0000
	s_barrier
	s_branch .LBB0_2548

.LBB0_2555:
	ds_read_b128 v[140:143], v149
	ds_read_b128 v[152:155], v149 offset:1024
	ds_read_b128 v[156:159], v149 offset:2048
	ds_read_b128 v[160:163], v149 offset:3072
	ds_read_b128 v[164:167], v150
	ds_read_b128 v[168:171], v150 offset:1024
	ds_read_b128 v[172:175], v150 offset:2048
	ds_read_b128 v[176:179], v150 offset:3072
	s_add_u32 s3, s48, 0xffe00080
	s_addc_u32 s52, s49, -1
	s_cmpk_eq_i32 s64, 0x7c
	s_cselect_b32 s55, s0, s52
	s_cselect_b32 s54, s1, s3
	s_cselect_b32 s53, s35, s51
	s_cselect_b32 s52, s37, s50
	s_add_i32 m0, s27, 0xc000
	ds_read_b128 v[180:183], v151
	ds_read_b128 v[184:187], v151 offset:1024
	ds_read_b128 v[188:191], v151 offset:2048
	ds_read_b128 v[192:195], v151 offset:3072
	ds_read_b128 v[196:199], v151 offset:4096
	ds_read_b128 v[200:203], v151 offset:5120
	ds_read_b128 v[204:207], v151 offset:6144
	ds_read_b128 v[208:211], v151 offset:7168
	global_load_lds_dwordx4 v132, s[48:49]
	s_add_i32 m0, s27, 0xe000
	s_nop 0
	global_load_lds_dwordx4 v134, s[48:49]
	s_waitcnt vmcnt(8)
	s_waitcnt lgkmcnt(0)
	s_barrier
	s_setprio 1
	s_waitcnt lgkmcnt(0)
	v_mfma_f32_16x16x32_bf16 v[124:127], v[140:143], v[180:183], v[124:127]
	v_mfma_f32_16x16x32_bf16 v[120:123], v[156:159], v[180:183], v[120:123]
	v_mfma_f32_16x16x32_bf16 v[112:115], v[140:143], v[188:191], v[112:115]
	v_mfma_f32_16x16x32_bf16 v[104:107], v[156:159], v[188:191], v[104:107]
	v_mfma_f32_16x16x32_bf16 v[96:99], v[140:143], v[196:199], v[96:99]
	v_mfma_f32_16x16x32_bf16 v[88:91], v[156:159], v[196:199], v[88:91]
	v_mfma_f32_16x16x32_bf16 v[80:83], v[140:143], v[204:207], v[80:83]
	v_mfma_f32_16x16x32_bf16 v[72:75], v[156:159], v[204:207], v[72:75]
	v_mfma_f32_16x16x32_bf16 v[124:127], v[152:155], v[184:187], v[124:127]
	v_mfma_f32_16x16x32_bf16 v[120:123], v[160:163], v[184:187], v[120:123]
	v_mfma_f32_16x16x32_bf16 v[112:115], v[152:155], v[192:195], v[112:115]
	v_mfma_f32_16x16x32_bf16 v[104:107], v[160:163], v[192:195], v[104:107]
	v_mfma_f32_16x16x32_bf16 v[96:99], v[152:155], v[200:203], v[96:99]
	v_mfma_f32_16x16x32_bf16 v[88:91], v[160:163], v[200:203], v[88:91]
	v_mfma_f32_16x16x32_bf16 v[80:83], v[152:155], v[208:211], v[80:83]
	v_mfma_f32_16x16x32_bf16 v[72:75], v[160:163], v[208:211], v[72:75]
	s_setprio 0
	s_setprio 1
	v_mfma_f32_16x16x32_bf16 v[116:119], v[164:167], v[180:183], v[116:119]
	v_mfma_f32_16x16x32_bf16 v[108:111], v[172:175], v[180:183], v[108:111]
	v_mfma_f32_16x16x32_bf16 v[100:103], v[164:167], v[188:191], v[100:103]
	v_mfma_f32_16x16x32_bf16 v[92:95], v[172:175], v[188:191], v[92:95]
	v_mfma_f32_16x16x32_bf16 v[84:87], v[164:167], v[196:199], v[84:87]
	v_mfma_f32_16x16x32_bf16 v[76:79], v[172:175], v[196:199], v[76:79]
	v_mfma_f32_16x16x32_bf16 v[68:71], v[164:167], v[204:207], v[68:71]
	v_mfma_f32_16x16x32_bf16 v[64:67], v[172:175], v[204:207], v[64:67]
	v_mfma_f32_16x16x32_bf16 v[116:119], v[168:171], v[184:187], v[116:119]
	v_mfma_f32_16x16x32_bf16 v[108:111], v[176:179], v[184:187], v[108:111]
	v_mfma_f32_16x16x32_bf16 v[100:103], v[168:171], v[192:195], v[100:103]
	v_mfma_f32_16x16x32_bf16 v[92:95], v[176:179], v[192:195], v[92:95]
	v_mfma_f32_16x16x32_bf16 v[84:87], v[168:171], v[200:203], v[84:87]
	v_mfma_f32_16x16x32_bf16 v[76:79], v[176:179], v[200:203], v[76:79]
	v_mfma_f32_16x16x32_bf16 v[68:71], v[168:171], v[208:211], v[68:71]
	v_mfma_f32_16x16x32_bf16 v[64:67], v[176:179], v[208:211], v[64:67]
	s_setprio 0
	s_barrier
	s_add_i32 s3, s58, s25
	v_lshl_add_u64 v[144:145], s[52:53], 0, v[128:129]
	s_mov_b32 m0, s3
	ds_read_b128 v[180:183], v151 offset:16384
	ds_read_b128 v[184:187], v151 offset:17408
	ds_read_b128 v[188:191], v151 offset:18432
	ds_read_b128 v[192:195], v151 offset:19456
	ds_read_b128 v[196:199], v151 offset:20480
	ds_read_b128 v[200:203], v151 offset:21504
	ds_read_b128 v[204:207], v151 offset:22528
	ds_read_b128 v[208:211], v151 offset:23552
	global_load_lds_dwordx4 v[144:145], off
	s_add_i32 m0, s3, 0x2000
	s_add_u32 s66, s52, 0x200000
	v_lshl_add_u64 v[212:213], s[52:53], 0, v[130:131]
	s_addc_u32 s67, s53, 0
	s_add_i32 s3, s59, s25
	global_load_lds_dwordx4 v[212:213], off
	s_mov_b32 m0, s3
	v_lshl_add_u64 v[216:217], s[54:55], 0, v[130:131]
	global_load_lds_dwordx4 v128, s[66:67]
	s_add_i32 m0, s3, 0x2000
	s_nop 0
	global_load_lds_dwordx4 v130, s[66:67]
	v_lshl_add_u64 v[214:215], s[54:55], 0, v[128:129]
	s_mov_b32 m0, s27
	s_nop 0
	global_load_lds_dwordx4 v[214:215], off
	s_mov_b32 m0, s30
	s_nop 0
	global_load_lds_dwordx4 v[216:217], off
	s_waitcnt vmcnt(8)
	s_waitcnt lgkmcnt(0)
	s_barrier
	s_setprio 1
	s_waitcnt lgkmcnt(0)
	v_mfma_f32_16x16x32_bf16 v[60:63], v[140:143], v[180:183], v[60:63]
	v_mfma_f32_16x16x32_bf16 v[56:59], v[156:159], v[180:183], v[56:59]
	v_mfma_f32_16x16x32_bf16 v[48:51], v[140:143], v[188:191], v[48:51]
	v_mfma_f32_16x16x32_bf16 v[40:43], v[156:159], v[188:191], v[40:43]
	v_mfma_f32_16x16x32_bf16 v[32:35], v[140:143], v[196:199], v[32:35]
	v_mfma_f32_16x16x32_bf16 v[24:27], v[156:159], v[196:199], v[24:27]
	v_mfma_f32_16x16x32_bf16 v[16:19], v[140:143], v[204:207], v[16:19]
	v_mfma_f32_16x16x32_bf16 v[8:11], v[156:159], v[204:207], v[8:11]
	v_mfma_f32_16x16x32_bf16 v[60:63], v[152:155], v[184:187], v[60:63]
	v_mfma_f32_16x16x32_bf16 v[56:59], v[160:163], v[184:187], v[56:59]
	v_mfma_f32_16x16x32_bf16 v[48:51], v[152:155], v[192:195], v[48:51]
	v_mfma_f32_16x16x32_bf16 v[40:43], v[160:163], v[192:195], v[40:43]
	v_mfma_f32_16x16x32_bf16 v[32:35], v[152:155], v[200:203], v[32:35]
	v_mfma_f32_16x16x32_bf16 v[24:27], v[160:163], v[200:203], v[24:27]
	v_mfma_f32_16x16x32_bf16 v[16:19], v[152:155], v[208:211], v[16:19]
	v_mfma_f32_16x16x32_bf16 v[8:11], v[160:163], v[208:211], v[8:11]
	s_setprio 0
	s_setprio 1
	v_mfma_f32_16x16x32_bf16 v[52:55], v[164:167], v[180:183], v[52:55]
	v_mfma_f32_16x16x32_bf16 v[44:47], v[172:175], v[180:183], v[44:47]
	v_mfma_f32_16x16x32_bf16 v[36:39], v[164:167], v[188:191], v[36:39]
	v_mfma_f32_16x16x32_bf16 v[28:31], v[172:175], v[188:191], v[28:31]
	v_mfma_f32_16x16x32_bf16 v[20:23], v[164:167], v[196:199], v[20:23]
	v_mfma_f32_16x16x32_bf16 v[12:15], v[172:175], v[196:199], v[12:15]
	v_mfma_f32_16x16x32_bf16 v[4:7], v[164:167], v[204:207], v[4:7]
	v_mfma_f32_16x16x32_bf16 v[0:3], v[172:175], v[204:207], v[0:3]
	v_mfma_f32_16x16x32_bf16 v[52:55], v[168:171], v[184:187], v[52:55]
	v_mfma_f32_16x16x32_bf16 v[44:47], v[176:179], v[184:187], v[44:47]
	v_mfma_f32_16x16x32_bf16 v[36:39], v[168:171], v[192:195], v[36:39]
	v_mfma_f32_16x16x32_bf16 v[28:31], v[176:179], v[192:195], v[28:31]
	v_mfma_f32_16x16x32_bf16 v[20:23], v[168:171], v[200:203], v[20:23]
	v_mfma_f32_16x16x32_bf16 v[12:15], v[176:179], v[200:203], v[12:15]
	v_mfma_f32_16x16x32_bf16 v[4:7], v[168:171], v[208:211], v[4:7]
	v_mfma_f32_16x16x32_bf16 v[0:3], v[176:179], v[208:211], v[0:3]
	s_setprio 0
	s_barrier
	s_add_i32 s3, 0, 0x18000
	s_add_i32 s65, 0, 0x1c000
	v_add_u32_e32 v160, s3, v147
	v_add_u32_e32 v176, s65, v147
	ds_read_b128 v[140:143], v160
	ds_read_b128 v[152:155], v160 offset:1024
	ds_read_b128 v[156:159], v160 offset:2048
	ds_read_b128 v[160:163], v160 offset:3072
	ds_read_b128 v[164:167], v176
	ds_read_b128 v[168:171], v176 offset:1024
	ds_read_b128 v[172:175], v176 offset:2048
	ds_read_b128 v[176:179], v176 offset:3072
	s_add_u32 s54, s54, 0x200000
	s_addc_u32 s55, s55, 0
	s_mov_b32 m0, s31
	ds_read_b128 v[180:183], v151 offset:32768
	ds_read_b128 v[184:187], v151 offset:33792
	ds_read_b128 v[188:191], v151 offset:34816
	ds_read_b128 v[192:195], v151 offset:35840
	ds_read_b128 v[196:199], v151 offset:36864
	ds_read_b128 v[200:203], v151 offset:37888
	ds_read_b128 v[204:207], v151 offset:38912
	ds_read_b128 v[208:211], v151 offset:39936
	global_load_lds_dwordx4 v128, s[54:55]
	s_mov_b32 m0, s33
	s_nop 0
	global_load_lds_dwordx4 v130, s[54:55]
	s_waitcnt vmcnt(8)
	s_waitcnt lgkmcnt(0)
	s_barrier
	s_setprio 1
	s_waitcnt lgkmcnt(0)
	v_mfma_f32_16x16x32_bf16 v[124:127], v[140:143], v[180:183], v[124:127]
	v_mfma_f32_16x16x32_bf16 v[120:123], v[156:159], v[180:183], v[120:123]
	v_mfma_f32_16x16x32_bf16 v[112:115], v[140:143], v[188:191], v[112:115]
	v_mfma_f32_16x16x32_bf16 v[104:107], v[156:159], v[188:191], v[104:107]
	v_mfma_f32_16x16x32_bf16 v[96:99], v[140:143], v[196:199], v[96:99]
	v_mfma_f32_16x16x32_bf16 v[88:91], v[156:159], v[196:199], v[88:91]
	v_mfma_f32_16x16x32_bf16 v[80:83], v[140:143], v[204:207], v[80:83]
	v_mfma_f32_16x16x32_bf16 v[72:75], v[156:159], v[204:207], v[72:75]
	v_mfma_f32_16x16x32_bf16 v[124:127], v[152:155], v[184:187], v[124:127]
	v_mfma_f32_16x16x32_bf16 v[120:123], v[160:163], v[184:187], v[120:123]
	v_mfma_f32_16x16x32_bf16 v[112:115], v[152:155], v[192:195], v[112:115]
	v_mfma_f32_16x16x32_bf16 v[104:107], v[160:163], v[192:195], v[104:107]
	v_mfma_f32_16x16x32_bf16 v[96:99], v[152:155], v[200:203], v[96:99]
	v_mfma_f32_16x16x32_bf16 v[88:91], v[160:163], v[200:203], v[88:91]
	v_mfma_f32_16x16x32_bf16 v[80:83], v[152:155], v[208:211], v[80:83]
	v_mfma_f32_16x16x32_bf16 v[72:75], v[160:163], v[208:211], v[72:75]
	s_setprio 0
	s_setprio 1
	v_mfma_f32_16x16x32_bf16 v[116:119], v[164:167], v[180:183], v[116:119]
	v_mfma_f32_16x16x32_bf16 v[108:111], v[172:175], v[180:183], v[108:111]
	v_mfma_f32_16x16x32_bf16 v[100:103], v[164:167], v[188:191], v[100:103]
	v_mfma_f32_16x16x32_bf16 v[92:95], v[172:175], v[188:191], v[92:95]
	v_mfma_f32_16x16x32_bf16 v[84:87], v[164:167], v[196:199], v[84:87]
	v_mfma_f32_16x16x32_bf16 v[76:79], v[172:175], v[196:199], v[76:79]
	v_mfma_f32_16x16x32_bf16 v[68:71], v[164:167], v[204:207], v[68:71]
	v_mfma_f32_16x16x32_bf16 v[64:67], v[172:175], v[204:207], v[64:67]
	v_mfma_f32_16x16x32_bf16 v[116:119], v[168:171], v[184:187], v[116:119]
	v_mfma_f32_16x16x32_bf16 v[108:111], v[176:179], v[184:187], v[108:111]
	v_mfma_f32_16x16x32_bf16 v[100:103], v[168:171], v[192:195], v[100:103]
	v_mfma_f32_16x16x32_bf16 v[92:95], v[176:179], v[192:195], v[92:95]
	v_mfma_f32_16x16x32_bf16 v[84:87], v[168:171], v[200:203], v[84:87]
	v_mfma_f32_16x16x32_bf16 v[76:79], v[176:179], v[200:203], v[76:79]
	v_mfma_f32_16x16x32_bf16 v[68:71], v[168:171], v[208:211], v[68:71]
	v_mfma_f32_16x16x32_bf16 v[64:67], v[176:179], v[208:211], v[64:67]
	s_setprio 0
	s_barrier
	s_add_i32 s3, s3, s25
	v_lshl_add_u64 v[144:145], v[144:145], 0, s[8:9]
	s_mov_b32 m0, s3
	ds_read_b128 v[180:183], v151 offset:49152
	ds_read_b128 v[184:187], v151 offset:50176
	ds_read_b128 v[188:191], v151 offset:51200
	ds_read_b128 v[192:195], v151 offset:52224
	ds_read_b128 v[196:199], v151 offset:53248
	ds_read_b128 v[200:203], v151 offset:54272
	ds_read_b128 v[204:207], v151 offset:55296
	ds_read_b128 v[208:211], v151 offset:56320
	global_load_lds_dwordx4 v[144:145], off
	s_add_i32 m0, s3, 0x2000
	s_add_u32 s52, s52, 0x200080
	v_lshl_add_u64 v[144:145], v[212:213], 0, s[8:9]
	s_addc_u32 s53, s53, 0
	s_add_i32 s3, s65, s25
	global_load_lds_dwordx4 v[144:145], off
	s_mov_b32 m0, s3
	s_nop 0
	global_load_lds_dwordx4 v128, s[52:53]
	s_add_i32 m0, s3, 0x2000
	s_nop 0
	global_load_lds_dwordx4 v130, s[52:53]
	v_lshl_add_u64 v[144:145], v[214:215], 0, s[8:9]
	s_mov_b32 m0, s56
	s_nop 0
	global_load_lds_dwordx4 v[144:145], off
	v_lshl_add_u64 v[144:145], v[216:217], 0, s[8:9]
	s_mov_b32 m0, s57
	s_nop 0
	global_load_lds_dwordx4 v[144:145], off
	s_waitcnt vmcnt(8)
	s_waitcnt lgkmcnt(0)
	s_barrier
	s_setprio 1
	s_waitcnt lgkmcnt(0)
	v_mfma_f32_16x16x32_bf16 v[60:63], v[140:143], v[180:183], v[60:63]
	v_mfma_f32_16x16x32_bf16 v[56:59], v[156:159], v[180:183], v[56:59]
	v_mfma_f32_16x16x32_bf16 v[48:51], v[140:143], v[188:191], v[48:51]
	v_mfma_f32_16x16x32_bf16 v[40:43], v[156:159], v[188:191], v[40:43]
	v_mfma_f32_16x16x32_bf16 v[32:35], v[140:143], v[196:199], v[32:35]
	v_mfma_f32_16x16x32_bf16 v[24:27], v[156:159], v[196:199], v[24:27]
	v_mfma_f32_16x16x32_bf16 v[16:19], v[140:143], v[204:207], v[16:19]
	v_mfma_f32_16x16x32_bf16 v[8:11], v[156:159], v[204:207], v[8:11]
	v_mfma_f32_16x16x32_bf16 v[60:63], v[152:155], v[184:187], v[60:63]
	v_mfma_f32_16x16x32_bf16 v[56:59], v[160:163], v[184:187], v[56:59]
	v_mfma_f32_16x16x32_bf16 v[48:51], v[152:155], v[192:195], v[48:51]
	v_mfma_f32_16x16x32_bf16 v[40:43], v[160:163], v[192:195], v[40:43]
	v_mfma_f32_16x16x32_bf16 v[32:35], v[152:155], v[200:203], v[32:35]
	v_mfma_f32_16x16x32_bf16 v[24:27], v[160:163], v[200:203], v[24:27]
	v_mfma_f32_16x16x32_bf16 v[16:19], v[152:155], v[208:211], v[16:19]
	v_mfma_f32_16x16x32_bf16 v[8:11], v[160:163], v[208:211], v[8:11]
	s_setprio 0
	s_setprio 1
	v_mfma_f32_16x16x32_bf16 v[52:55], v[164:167], v[180:183], v[52:55]
	v_mfma_f32_16x16x32_bf16 v[44:47], v[172:175], v[180:183], v[44:47]
	v_mfma_f32_16x16x32_bf16 v[36:39], v[164:167], v[188:191], v[36:39]
	v_mfma_f32_16x16x32_bf16 v[28:31], v[172:175], v[188:191], v[28:31]
	v_mfma_f32_16x16x32_bf16 v[20:23], v[164:167], v[196:199], v[20:23]
	v_mfma_f32_16x16x32_bf16 v[12:15], v[172:175], v[196:199], v[12:15]
	v_mfma_f32_16x16x32_bf16 v[4:7], v[164:167], v[204:207], v[4:7]
	v_mfma_f32_16x16x32_bf16 v[0:3], v[172:175], v[204:207], v[0:3]
	v_mfma_f32_16x16x32_bf16 v[52:55], v[168:171], v[184:187], v[52:55]
	v_mfma_f32_16x16x32_bf16 v[44:47], v[176:179], v[184:187], v[44:47]
	v_mfma_f32_16x16x32_bf16 v[36:39], v[168:171], v[192:195], v[36:39]
	v_mfma_f32_16x16x32_bf16 v[28:31], v[176:179], v[192:195], v[28:31]
	v_mfma_f32_16x16x32_bf16 v[20:23], v[168:171], v[200:203], v[20:23]
	v_mfma_f32_16x16x32_bf16 v[12:15], v[176:179], v[200:203], v[12:15]
	v_mfma_f32_16x16x32_bf16 v[4:7], v[168:171], v[208:211], v[4:7]
	v_mfma_f32_16x16x32_bf16 v[0:3], v[176:179], v[208:211], v[0:3]
	s_setprio 0
	s_barrier
	s_add_i32 s64, s64, 2
	s_add_u32 s48, s48, 0x100
	s_addc_u32 s49, s49, 0
	s_add_u32 s50, s50, 0x100
	s_addc_u32 s51, s51, 0
	s_cmpk_gt_u32 s64, 0x7d
	s_cbranch_scc0 .LBB0_2555
	s_and_b64 vcc, exec, s[10:11]
	s_cbranch_vccz .LBB0_2558
	s_barrier
